# all flat_load/flat_store/flat_atomic ops (global-memory pointers only) turned into global_* ops: no lgkmcnt coupling or 15-op saturation on memory batches
# baseline (speedup 1.0000x reference)
.LBB0_98:
	v_ashrrev_i32_e32 v83, 31, v82
	v_lshlrev_b64 v[18:19], 12, v[82:83]
	v_lshl_add_u64 v[18:19], v[84:85], 0, v[18:19]
	global_load_dwordx4 v[78:81], v[18:19], off
	global_load_dwordx4 v[74:77], v[18:19], off offset:1024
	global_load_dwordx4 v[70:73], v[18:19], off offset:2048
	global_load_dwordx4 v[66:69], v[18:19], off offset:3072
	v_or_b32_e32 v92, 1, v82
	v_min_i32_e32 v18, 0x7fff, v92
	v_ashrrev_i32_e32 v19, 31, v18
	v_lshlrev_b64 v[18:19], 12, v[18:19]
	v_lshl_add_u64 v[18:19], v[84:85], 0, v[18:19]
	global_load_dwordx4 v[62:65], v[18:19], off
	global_load_dwordx4 v[58:61], v[18:19], off offset:1024
	global_load_dwordx4 v[54:57], v[18:19], off offset:2048
	global_load_dwordx4 v[50:53], v[18:19], off offset:3072
	v_or_b32_e32 v90, 2, v82
	v_min_i32_e32 v18, 0x7fff, v90
	v_ashrrev_i32_e32 v19, 31, v18
	v_lshlrev_b64 v[18:19], 12, v[18:19]
	v_lshl_add_u64 v[18:19], v[84:85], 0, v[18:19]
	v_or_b32_e32 v88, 3, v82
	global_load_dwordx4 v[46:49], v[18:19], off
	global_load_dwordx4 v[42:45], v[18:19], off offset:1024
	global_load_dwordx4 v[38:41], v[18:19], off offset:2048
	s_waitcnt lgkmcnt(0)
	global_load_dwordx4 v[34:37], v[18:19], off offset:3072
	v_min_i32_e32 v18, 0x7fff, v88
	v_ashrrev_i32_e32 v19, 31, v18
	v_lshlrev_b64 v[18:19], 12, v[18:19]
	v_lshl_add_u64 v[18:19], v[84:85], 0, v[18:19]
	global_load_dwordx4 v[30:33], v[18:19], off
	global_load_dwordx4 v[26:29], v[18:19], off offset:1024
	global_load_dwordx4 v[22:25], v[18:19], off offset:2048
	s_nop 0
	global_load_dwordx4 v[18:21], v[18:19], off offset:3072
	s_waitcnt vmcnt(0) lgkmcnt(0)
	v_pk_mul_f32 v[100:101], v[80:81], v[80:81]
	v_pk_mul_f32 v[102:103], v[78:79], v[78:79]
	v_mul_f32_e32 v16, v66, v66
	v_pk_mov_b32 v[104:105], v[102:103], v[100:101] op_sel:[1,0]
	v_mov_b32_e32 v103, v101
	v_pk_add_f32 v[100:101], v[104:105], v[102:103]
	v_pk_mul_f32 v[102:103], v[76:77], v[76:77]
	v_pk_mul_f32 v[104:105], v[74:75], v[74:75]
	v_mul_f32_e32 v89, v67, v67
	v_pk_mov_b32 v[106:107], v[104:105], v[102:103] op_sel:[1,0]
	v_mov_b32_e32 v105, v103
	v_pk_add_f32 v[102:103], v[106:107], v[104:105]
	v_pk_add_f32 v[100:101], v[100:101], v[100:101] op_sel:[0,1] op_sel_hi:[1,0]
	v_pk_add_f32 v[102:103], v[102:103], v[102:103] op_sel:[0,1] op_sel_hi:[1,0]
	v_mov_b32_e32 v101, v16
	v_mov_b32_e32 v103, v89
	v_mul_f32_e32 v16, v71, v71
	v_pk_add_f32 v[100:101], v[100:101], v[102:103]
	v_pk_fma_f32 v[102:103], v[70:71], v[70:71], v[16:17] op_sel_hi:[1,1,0]
	v_mul_f32_e32 v16, v73, v73
	v_mul_f32_e32 v91, v68, v68
	v_mul_f32_e32 v93, v69, v69
	v_pk_fma_f32 v[104:105], v[72:73], v[72:73], v[16:17] op_sel_hi:[1,1,0]
	v_mov_b32_e32 v103, v91
	v_mov_b32_e32 v105, v93
	v_pk_add_f32 v[102:103], v[102:103], v[104:105]
	s_nop 0
	v_pk_add_f32 v[100:101], v[100:101], v[102:103]
	s_nop 0
	v_add_f32_e32 v16, v100, v101
	ds_bpermute_b32 v89, v94, v16
	v_lshlrev_b64 v[100:101], 11, v[82:83]
	v_lshl_add_u64 v[100:101], v[86:87], 0, v[100:101]
	s_waitcnt lgkmcnt(0)
	v_add_f32_e32 v16, v16, v89
	ds_bpermute_b32 v89, v95, v16
	s_waitcnt lgkmcnt(0)
	v_add_f32_e32 v16, v16, v89
	ds_bpermute_b32 v89, v96, v16
	s_waitcnt lgkmcnt(0)
	v_add_f32_e32 v16, v16, v89
	ds_bpermute_b32 v89, v97, v16
	s_waitcnt lgkmcnt(0)
	v_add_f32_e32 v16, v16, v89
	ds_bpermute_b32 v89, v98, v16
	s_waitcnt lgkmcnt(0)
	v_add_f32_e32 v16, v16, v89
	ds_bpermute_b32 v89, v99, v16
	s_waitcnt lgkmcnt(0)
	v_add_f32_e32 v16, v16, v89
	v_fmamk_f32 v16, v16, 0x3a800000, v231
	v_cmp_gt_f32_e32 vcc, s33, v16
	v_mul_f32_e32 v83, 0x4b800000, v16
	s_nop 0
	v_cndmask_b32_e32 v16, v16, v83, vcc
	v_rsq_f32_e32 v16, v16
	s_nop 0
	v_mul_f32_e32 v83, 0x45800000, v16
	v_cndmask_b32_e32 v16, v16, v83, vcc
	v_mul_f32_e32 v78, v78, v16
	v_mul_f32_e32 v79, v79, v16
	v_mul_f32_e32 v74, v74, v16
	v_mul_f32_e32 v75, v75, v16
	v_mul_f32_e32 v70, v70, v16
	v_mul_f32_e32 v71, v71, v16
	v_mul_f32_e32 v66, v66, v16
	v_mul_f32_e32 v67, v67, v16
	v_mul_f32_e32 v78, v0, v78
	v_mul_f32_e32 v79, v1, v79
	v_mul_f32_e32 v74, v4, v74
	v_mul_f32_e32 v75, v5, v75
	v_mul_f32_e32 v70, v8, v70
	v_mul_f32_e32 v71, v9, v71
	v_mul_f32_e32 v66, v12, v66
	v_mul_f32_e32 v67, v13, v67
	v_cvt_pk_bf16_f32 v78, v78, v79
	v_mul_f32_e32 v79, v80, v16
	v_mul_f32_e32 v80, v81, v16
	v_cvt_pk_bf16_f32 v74, v74, v75
	v_mul_f32_e32 v75, v76, v16
	v_mul_f32_e32 v76, v77, v16
	v_cvt_pk_bf16_f32 v70, v70, v71
	v_mul_f32_e32 v71, v72, v16
	v_mul_f32_e32 v72, v73, v16
	v_cvt_pk_bf16_f32 v66, v66, v67
	v_mul_f32_e32 v67, v68, v16
	v_mul_f32_e32 v16, v69, v16
	v_mul_f32_e32 v67, v14, v67
	v_mul_f32_e32 v16, v15, v16
	v_cvt_pk_bf16_f32 v67, v67, v16
	global_store_dwordx2 v[100:101], v[66:67], off offset:1536
	v_mul_f32_e32 v16, v63, v63
	v_mul_f32_e32 v66, v65, v65
	v_fmac_f32_e32 v16, v62, v62
	v_fmac_f32_e32 v66, v64, v64
	v_add_f32_e32 v16, v16, v66
	v_mul_f32_e32 v66, v59, v59
	v_mul_f32_e32 v67, v61, v61
	v_fmac_f32_e32 v66, v58, v58
	v_fmac_f32_e32 v67, v60, v60
	v_add_f32_e32 v66, v66, v67
	v_add_f32_e32 v16, v16, v66
	v_mul_f32_e32 v66, v55, v55
	v_mul_f32_e32 v67, v57, v57
	v_fmac_f32_e32 v66, v54, v54
	v_fmac_f32_e32 v67, v56, v56
	v_add_f32_e32 v66, v66, v67
	v_add_f32_e32 v16, v16, v66
	v_mul_f32_e32 v66, v51, v51
	v_mul_f32_e32 v67, v53, v53
	v_fmac_f32_e32 v66, v50, v50
	v_fmac_f32_e32 v67, v52, v52
	v_add_f32_e32 v66, v66, v67
	v_add_f32_e32 v16, v16, v66
	ds_bpermute_b32 v66, v94, v16
	v_mul_f32_e32 v79, v2, v79
	v_mul_f32_e32 v75, v6, v75
	v_mul_f32_e32 v71, v10, v71
	v_cmp_gt_i32_e32 vcc, s47, v92
	s_waitcnt lgkmcnt(0)
	v_add_f32_e32 v16, v16, v66
	ds_bpermute_b32 v66, v95, v16
	v_mul_f32_e32 v80, v3, v80
	v_cvt_pk_bf16_f32 v79, v79, v80
	global_store_dwordx2 v[100:101], v[78:79], off
	v_mul_f32_e32 v76, v7, v76
	s_waitcnt lgkmcnt(0)
	v_add_f32_e32 v16, v16, v66
	ds_bpermute_b32 v66, v96, v16
	v_cvt_pk_bf16_f32 v75, v75, v76
	global_store_dwordx2 v[100:101], v[74:75], off offset:512
	v_mul_f32_e32 v72, v11, v72
	v_cvt_pk_bf16_f32 v71, v71, v72
	s_waitcnt lgkmcnt(0)
	v_add_f32_e32 v16, v16, v66
	ds_bpermute_b32 v66, v97, v16
	global_store_dwordx2 v[100:101], v[70:71], off offset:1024
	s_waitcnt lgkmcnt(0)
	v_add_f32_e32 v16, v16, v66
	ds_bpermute_b32 v66, v98, v16
	s_waitcnt lgkmcnt(0)
	v_add_f32_e32 v16, v16, v66
	ds_bpermute_b32 v66, v99, v16
	s_and_saveexec_b64 s[22:23], vcc
	s_cbranch_execz .LBB0_100
	s_waitcnt lgkmcnt(0)
	v_add_f32_e32 v16, v16, v66
	v_fmamk_f32 v16, v16, 0x3a800000, v231
	v_mul_f32_e32 v66, 0x4b800000, v16
	v_cmp_gt_f32_e32 vcc, s33, v16
	v_ashrrev_i32_e32 v93, 31, v92
	s_nop 0
	v_cndmask_b32_e32 v16, v16, v66, vcc
	v_rsq_f32_e32 v16, v16
	v_lshlrev_b64 v[66:67], 11, v[92:93]
	v_lshl_add_u64 v[66:67], v[86:87], 0, v[66:67]
	v_mul_f32_e32 v68, 0x45800000, v16
	v_cndmask_b32_e32 v16, v16, v68, vcc
	v_mul_f32_e32 v62, v62, v16
	v_mul_f32_e32 v63, v63, v16
	v_mul_f32_e32 v58, v58, v16
	v_mul_f32_e32 v59, v59, v16
	v_mul_f32_e32 v54, v54, v16
	v_mul_f32_e32 v55, v55, v16
	v_mul_f32_e32 v50, v50, v16
	v_mul_f32_e32 v51, v51, v16
	v_mul_f32_e32 v62, v0, v62
	v_mul_f32_e32 v63, v1, v63
	v_mul_f32_e32 v58, v4, v58
	v_mul_f32_e32 v59, v5, v59
	v_mul_f32_e32 v54, v8, v54
	v_mul_f32_e32 v55, v9, v55
	v_mul_f32_e32 v50, v12, v50
	v_mul_f32_e32 v51, v13, v51
	v_cvt_pk_bf16_f32 v62, v62, v63
	v_mul_f32_e32 v63, v64, v16
	v_cvt_pk_bf16_f32 v58, v58, v59
	v_mul_f32_e32 v59, v60, v16
	v_cvt_pk_bf16_f32 v54, v54, v55
	v_mul_f32_e32 v55, v56, v16
	v_cvt_pk_bf16_f32 v50, v50, v51
	v_mul_f32_e32 v51, v52, v16
	v_mul_f32_e32 v63, v2, v63
	v_mul_f32_e32 v64, v65, v16
	v_mul_f32_e32 v59, v6, v59
	v_mul_f32_e32 v60, v61, v16
	v_mul_f32_e32 v55, v10, v55
	v_mul_f32_e32 v56, v57, v16
	v_mul_f32_e32 v51, v14, v51
	v_mul_f32_e32 v16, v53, v16
	v_mul_f32_e32 v64, v3, v64
	v_cvt_pk_bf16_f32 v63, v63, v64
	global_store_dwordx2 v[66:67], v[62:63], off
	v_mul_f32_e32 v60, v7, v60
	v_cvt_pk_bf16_f32 v59, v59, v60
	global_store_dwordx2 v[66:67], v[58:59], off offset:512
	v_mul_f32_e32 v56, v11, v56
	v_cvt_pk_bf16_f32 v55, v55, v56
	global_store_dwordx2 v[66:67], v[54:55], off offset:1024
	v_mul_f32_e32 v16, v15, v16
	v_cvt_pk_bf16_f32 v51, v51, v16
	global_store_dwordx2 v[66:67], v[50:51], off offset:1536
.LBB0_100:
	s_or_b64 exec, exec, s[22:23]
	v_mul_f32_e32 v16, v47, v47
	v_mul_f32_e32 v50, v49, v49
	v_fmac_f32_e32 v16, v46, v46
	v_fmac_f32_e32 v50, v48, v48
	v_add_f32_e32 v16, v16, v50
	v_mul_f32_e32 v50, v43, v43
	v_mul_f32_e32 v51, v45, v45
	v_fmac_f32_e32 v50, v42, v42
	v_fmac_f32_e32 v51, v44, v44
	v_add_f32_e32 v50, v50, v51
	v_add_f32_e32 v16, v16, v50
	v_mul_f32_e32 v50, v39, v39
	v_mul_f32_e32 v51, v41, v41
	v_fmac_f32_e32 v50, v38, v38
	v_fmac_f32_e32 v51, v40, v40
	v_add_f32_e32 v50, v50, v51
	v_add_f32_e32 v16, v16, v50
	v_mul_f32_e32 v50, v35, v35
	v_mul_f32_e32 v51, v37, v37
	v_fmac_f32_e32 v50, v34, v34
	v_fmac_f32_e32 v51, v36, v36
	v_add_f32_e32 v50, v50, v51
	v_add_f32_e32 v16, v16, v50
	ds_bpermute_b32 v50, v94, v16
	v_cmp_gt_i32_e32 vcc, s47, v90
	s_waitcnt lgkmcnt(0)
	v_add_f32_e32 v16, v16, v50
	ds_bpermute_b32 v50, v95, v16
	s_waitcnt lgkmcnt(0)
	v_add_f32_e32 v16, v16, v50
	ds_bpermute_b32 v50, v96, v16
	s_waitcnt lgkmcnt(0)
	v_add_f32_e32 v16, v16, v50
	ds_bpermute_b32 v50, v97, v16
	s_waitcnt lgkmcnt(0)
	v_add_f32_e32 v16, v16, v50
	ds_bpermute_b32 v50, v98, v16
	s_waitcnt lgkmcnt(0)
	v_add_f32_e32 v16, v16, v50
	ds_bpermute_b32 v50, v99, v16
	s_and_saveexec_b64 s[22:23], vcc
	s_cbranch_execz .LBB0_102
	s_waitcnt lgkmcnt(0)
	v_add_f32_e32 v16, v16, v50
	v_fmamk_f32 v16, v16, 0x3a800000, v231
	v_mul_f32_e32 v50, 0x4b800000, v16
	v_cmp_gt_f32_e32 vcc, s33, v16
	v_ashrrev_i32_e32 v91, 31, v90
	s_nop 0
	v_cndmask_b32_e32 v16, v16, v50, vcc
	v_rsq_f32_e32 v16, v16
	v_lshlrev_b64 v[50:51], 11, v[90:91]
	v_lshl_add_u64 v[50:51], v[86:87], 0, v[50:51]
	v_mul_f32_e32 v52, 0x45800000, v16
	v_cndmask_b32_e32 v16, v16, v52, vcc
	v_mul_f32_e32 v46, v46, v16
	v_mul_f32_e32 v47, v47, v16
	v_mul_f32_e32 v42, v42, v16
	v_mul_f32_e32 v43, v43, v16
	v_mul_f32_e32 v38, v38, v16
	v_mul_f32_e32 v39, v39, v16
	v_mul_f32_e32 v34, v34, v16
	v_mul_f32_e32 v35, v35, v16
	v_mul_f32_e32 v46, v0, v46
	v_mul_f32_e32 v47, v1, v47
	v_mul_f32_e32 v42, v4, v42
	v_mul_f32_e32 v43, v5, v43
	v_mul_f32_e32 v38, v8, v38
	v_mul_f32_e32 v39, v9, v39
	v_mul_f32_e32 v34, v12, v34
	v_mul_f32_e32 v35, v13, v35
	v_cvt_pk_bf16_f32 v46, v46, v47
	v_mul_f32_e32 v47, v48, v16
	v_cvt_pk_bf16_f32 v42, v42, v43
	v_mul_f32_e32 v43, v44, v16
	v_cvt_pk_bf16_f32 v38, v38, v39
	v_mul_f32_e32 v39, v40, v16
	v_cvt_pk_bf16_f32 v34, v34, v35
	v_mul_f32_e32 v35, v36, v16
	v_mul_f32_e32 v47, v2, v47
	v_mul_f32_e32 v48, v49, v16
	v_mul_f32_e32 v43, v6, v43
	v_mul_f32_e32 v44, v45, v16
	v_mul_f32_e32 v39, v10, v39
	v_mul_f32_e32 v40, v41, v16
	v_mul_f32_e32 v35, v14, v35
	v_mul_f32_e32 v16, v37, v16
	v_mul_f32_e32 v48, v3, v48
	v_cvt_pk_bf16_f32 v47, v47, v48
	global_store_dwordx2 v[50:51], v[46:47], off
	v_mul_f32_e32 v44, v7, v44
	v_cvt_pk_bf16_f32 v43, v43, v44
	global_store_dwordx2 v[50:51], v[42:43], off offset:512
	v_mul_f32_e32 v40, v11, v40
	v_cvt_pk_bf16_f32 v39, v39, v40
	global_store_dwordx2 v[50:51], v[38:39], off offset:1024
	v_mul_f32_e32 v16, v15, v16
	v_cvt_pk_bf16_f32 v35, v35, v16
	global_store_dwordx2 v[50:51], v[34:35], off offset:1536
.LBB0_102:
	s_or_b64 exec, exec, s[22:23]
	v_mul_f32_e32 v16, v31, v31
	v_mul_f32_e32 v34, v33, v33
	v_fmac_f32_e32 v16, v30, v30
	v_fmac_f32_e32 v34, v32, v32
	v_add_f32_e32 v16, v16, v34
	v_mul_f32_e32 v34, v27, v27
	v_mul_f32_e32 v35, v29, v29
	v_fmac_f32_e32 v34, v26, v26
	v_fmac_f32_e32 v35, v28, v28
	v_add_f32_e32 v34, v34, v35
	v_add_f32_e32 v16, v16, v34
	v_mul_f32_e32 v34, v23, v23
	v_mul_f32_e32 v35, v25, v25
	v_fmac_f32_e32 v34, v22, v22
	v_fmac_f32_e32 v35, v24, v24
	v_add_f32_e32 v34, v34, v35
	v_add_f32_e32 v16, v16, v34
	v_mul_f32_e32 v34, v19, v19
	v_mul_f32_e32 v35, v21, v21
	v_fmac_f32_e32 v34, v18, v18
	v_fmac_f32_e32 v35, v20, v20
	v_add_f32_e32 v34, v34, v35
	v_add_f32_e32 v16, v16, v34
	ds_bpermute_b32 v34, v94, v16
	v_cmp_gt_i32_e32 vcc, s47, v88
	s_waitcnt lgkmcnt(0)
	v_add_f32_e32 v16, v16, v34
	ds_bpermute_b32 v34, v95, v16
	s_waitcnt lgkmcnt(0)
	v_add_f32_e32 v16, v16, v34
	ds_bpermute_b32 v34, v96, v16
	s_waitcnt lgkmcnt(0)
	v_add_f32_e32 v16, v16, v34
	ds_bpermute_b32 v34, v97, v16
	s_waitcnt lgkmcnt(0)
	v_add_f32_e32 v16, v16, v34
	ds_bpermute_b32 v34, v98, v16
	s_waitcnt lgkmcnt(0)
	v_add_f32_e32 v16, v16, v34
	ds_bpermute_b32 v34, v99, v16
	s_and_saveexec_b64 s[22:23], vcc
	s_cbranch_execz .LBB0_97
	s_waitcnt lgkmcnt(0)
	v_add_f32_e32 v16, v16, v34
	v_fmamk_f32 v16, v16, 0x3a800000, v231
	v_mul_f32_e32 v34, 0x4b800000, v16
	v_cmp_gt_f32_e32 vcc, s33, v16
	v_ashrrev_i32_e32 v89, 31, v88
	s_nop 0
	v_cndmask_b32_e32 v16, v16, v34, vcc
	v_rsq_f32_e32 v16, v16
	v_lshlrev_b64 v[34:35], 11, v[88:89]
	v_lshl_add_u64 v[34:35], v[86:87], 0, v[34:35]
	v_mul_f32_e32 v36, 0x45800000, v16
	v_cndmask_b32_e32 v16, v16, v36, vcc
	v_mul_f32_e32 v30, v30, v16
	v_mul_f32_e32 v31, v31, v16
	v_mul_f32_e32 v26, v26, v16
	v_mul_f32_e32 v27, v27, v16
	v_mul_f32_e32 v22, v22, v16
	v_mul_f32_e32 v23, v23, v16
	v_mul_f32_e32 v18, v18, v16
	v_mul_f32_e32 v19, v19, v16
	v_mul_f32_e32 v30, v0, v30
	v_mul_f32_e32 v31, v1, v31
	v_mul_f32_e32 v26, v4, v26
	v_mul_f32_e32 v27, v5, v27
	v_mul_f32_e32 v22, v8, v22
	v_mul_f32_e32 v23, v9, v23
	v_mul_f32_e32 v18, v12, v18
	v_mul_f32_e32 v19, v13, v19
	v_cvt_pk_bf16_f32 v30, v30, v31
	v_mul_f32_e32 v31, v32, v16
	v_cvt_pk_bf16_f32 v26, v26, v27
	v_mul_f32_e32 v27, v28, v16
	v_cvt_pk_bf16_f32 v22, v22, v23
	v_mul_f32_e32 v23, v24, v16
	v_cvt_pk_bf16_f32 v18, v18, v19
	v_mul_f32_e32 v19, v20, v16
	v_mul_f32_e32 v31, v2, v31
	v_mul_f32_e32 v32, v33, v16
	v_mul_f32_e32 v27, v6, v27
	v_mul_f32_e32 v28, v29, v16
	v_mul_f32_e32 v23, v10, v23
	v_mul_f32_e32 v24, v25, v16
	v_mul_f32_e32 v19, v14, v19
	v_mul_f32_e32 v16, v21, v16
	v_mul_f32_e32 v32, v3, v32
	v_cvt_pk_bf16_f32 v31, v31, v32
	global_store_dwordx2 v[34:35], v[30:31], off
	v_mul_f32_e32 v28, v7, v28
	v_cvt_pk_bf16_f32 v27, v27, v28
	global_store_dwordx2 v[34:35], v[26:27], off offset:512
	v_mul_f32_e32 v24, v11, v24
	v_cvt_pk_bf16_f32 v23, v23, v24
	global_store_dwordx2 v[34:35], v[22:23], off offset:1024
	v_mul_f32_e32 v16, v15, v16
	v_cvt_pk_bf16_f32 v19, v19, v16
	global_store_dwordx2 v[34:35], v[18:19], off offset:1536
	s_branch .LBB0_97

.LBB0_133:
	s_add_u32 s28, s22, 0x100
	s_addc_u32 s29, s23, 0
	s_add_i32 s85, 0, 0x10000
	v_add_u32_e32 v148, s85, v157
	ds_read_b128 v[130:133], v148
	ds_read_b128 v[134:137], v148 offset:1024
	ds_read_b128 v[138:141], v148 offset:2048
	ds_read_b128 v[148:151], v148 offset:3072
	s_cmp_eq_u32 s84, 40
	s_cselect_b32 s43, s17, s29
	s_cselect_b32 s42, s16, s28
	s_cselect_b32 s41, s19, s79
	s_cselect_b32 s40, s18, s34
	v_lshl_add_u64 v[188:189], s[22:23], 0, v[146:147]
	s_add_i32 m0, s54, 0xc000
	ds_read_b128 v[152:155], v159
	ds_read_b128 v[160:163], v159 offset:1024
	ds_read_b128 v[164:167], v159 offset:2048
	ds_read_b128 v[168:171], v159 offset:3072
	ds_read_b128 v[172:175], v159 offset:4096
	ds_read_b128 v[176:179], v159 offset:5120
	ds_read_b128 v[180:183], v159 offset:6144
	ds_read_b128 v[184:187], v159 offset:7168
	global_load_lds_dwordx4 v[188:189], off
	v_lshl_add_u64 v[188:189], s[22:23], 0, v[144:145]
	s_add_i32 m0, s54, 0xe000
	s_nop 0
	global_load_lds_dwordx4 v[188:189], off
	s_waitcnt lgkmcnt(8)
	s_barrier
	s_waitcnt lgkmcnt(0)
	s_setprio 1
	s_waitcnt lgkmcnt(0)
	v_mfma_f32_16x16x32_bf16 v[126:129], v[130:133], v[152:155], v[126:129]
	v_mfma_f32_16x16x32_bf16 v[122:125], v[138:141], v[152:155], v[122:125]
	v_mfma_f32_16x16x32_bf16 v[118:121], v[130:133], v[164:167], v[118:121]
	v_mfma_f32_16x16x32_bf16 v[106:109], v[138:141], v[164:167], v[106:109]
	v_mfma_f32_16x16x32_bf16 v[102:105], v[130:133], v[172:175], v[102:105]
	v_mfma_f32_16x16x32_bf16 v[90:93], v[138:141], v[172:175], v[90:93]
	v_mfma_f32_16x16x32_bf16 v[86:89], v[130:133], v[180:183], v[86:89]
	v_mfma_f32_16x16x32_bf16 v[74:77], v[138:141], v[180:183], v[74:77]
	v_mfma_f32_16x16x32_bf16 v[126:129], v[134:137], v[160:163], v[126:129]
	v_mfma_f32_16x16x32_bf16 v[122:125], v[148:151], v[160:163], v[122:125]
	v_mfma_f32_16x16x32_bf16 v[118:121], v[134:137], v[168:171], v[118:121]
	v_mfma_f32_16x16x32_bf16 v[106:109], v[148:151], v[168:171], v[106:109]
	v_mfma_f32_16x16x32_bf16 v[102:105], v[134:137], v[176:179], v[102:105]
	v_mfma_f32_16x16x32_bf16 v[90:93], v[148:151], v[176:179], v[90:93]
	v_mfma_f32_16x16x32_bf16 v[86:89], v[134:137], v[184:187], v[86:89]
	v_mfma_f32_16x16x32_bf16 v[74:77], v[148:151], v[184:187], v[74:77]
	s_setprio 0
	s_barrier
	s_add_i32 s86, 0, 0x14000
	v_add_u32_e32 v196, s86, v157
	s_add_i32 s22, s85, s50
	ds_read_b128 v[188:191], v196
	ds_read_b128 v[192:195], v196 offset:1024
	ds_read_b128 v[208:211], v196 offset:2048
	ds_read_b128 v[212:215], v196 offset:3072
	v_lshl_add_u64 v[196:197], s[40:41], 0, v[16:17]
	s_mov_b32 m0, s22
	v_lshl_add_u64 v[216:217], s[40:41], 0, v[142:143]
	global_load_lds_dwordx4 v[196:197], off
	s_add_i32 m0, s22, 0x2000
	s_nop 0
	global_load_lds_dwordx4 v[216:217], off
	s_barrier
	s_waitcnt lgkmcnt(0)
	s_setprio 1
	s_waitcnt lgkmcnt(0)
	v_mfma_f32_16x16x32_bf16 v[114:117], v[188:191], v[152:155], v[114:117]
	v_mfma_f32_16x16x32_bf16 v[110:113], v[208:211], v[152:155], v[110:113]
	v_mfma_f32_16x16x32_bf16 v[98:101], v[188:191], v[164:167], v[98:101]
	v_mfma_f32_16x16x32_bf16 v[94:97], v[208:211], v[164:167], v[94:97]
	v_mfma_f32_16x16x32_bf16 v[82:85], v[188:191], v[172:175], v[82:85]
	v_mfma_f32_16x16x32_bf16 v[78:81], v[208:211], v[172:175], v[78:81]
	v_mfma_f32_16x16x32_bf16 v[70:73], v[188:191], v[180:183], v[70:73]
	v_mfma_f32_16x16x32_bf16 v[66:69], v[208:211], v[180:183], v[66:69]
	v_mfma_f32_16x16x32_bf16 v[114:117], v[192:195], v[160:163], v[114:117]
	v_mfma_f32_16x16x32_bf16 v[110:113], v[212:215], v[160:163], v[110:113]
	v_mfma_f32_16x16x32_bf16 v[98:101], v[192:195], v[168:171], v[98:101]
	v_mfma_f32_16x16x32_bf16 v[94:97], v[212:215], v[168:171], v[94:97]
	v_mfma_f32_16x16x32_bf16 v[82:85], v[192:195], v[176:179], v[82:85]
	v_mfma_f32_16x16x32_bf16 v[78:81], v[212:215], v[176:179], v[78:81]
	v_mfma_f32_16x16x32_bf16 v[70:73], v[192:195], v[184:187], v[70:73]
	v_mfma_f32_16x16x32_bf16 v[66:69], v[212:215], v[184:187], v[66:69]
	s_setprio 0
	s_mov_b32 m0, s54
	v_lshl_add_u64 v[218:219], s[42:43], 0, v[16:17]
	s_barrier
	ds_read_b128 v[152:155], v159 offset:16384
	ds_read_b128 v[160:163], v159 offset:17408
	ds_read_b128 v[164:167], v159 offset:18432
	ds_read_b128 v[168:171], v159 offset:19456
	ds_read_b128 v[172:175], v159 offset:20480
	ds_read_b128 v[176:179], v159 offset:21504
	ds_read_b128 v[180:183], v159 offset:22528
	ds_read_b128 v[184:187], v159 offset:23552
	global_load_lds_dwordx4 v[218:219], off
	v_lshl_add_u64 v[220:221], s[42:43], 0, v[142:143]
	s_mov_b32 m0, s55
	s_nop 0
	global_load_lds_dwordx4 v[220:221], off
	s_barrier
	s_waitcnt lgkmcnt(0)
	s_setprio 1
	s_waitcnt lgkmcnt(0)
	v_mfma_f32_16x16x32_bf16 v[62:65], v[130:133], v[152:155], v[62:65]
	v_mfma_f32_16x16x32_bf16 v[58:61], v[138:141], v[152:155], v[58:61]
	v_mfma_f32_16x16x32_bf16 v[54:57], v[130:133], v[164:167], v[54:57]
	v_mfma_f32_16x16x32_bf16 v[50:53], v[138:141], v[164:167], v[50:53]
	v_mfma_f32_16x16x32_bf16 v[46:49], v[130:133], v[172:175], v[46:49]
	v_mfma_f32_16x16x32_bf16 v[38:41], v[138:141], v[172:175], v[38:41]
	v_mfma_f32_16x16x32_bf16 v[30:33], v[130:133], v[180:183], v[30:33]
	v_mfma_f32_16x16x32_bf16 v[18:21], v[138:141], v[180:183], v[18:21]
	v_mfma_f32_16x16x32_bf16 v[62:65], v[134:137], v[160:163], v[62:65]
	v_mfma_f32_16x16x32_bf16 v[58:61], v[148:151], v[160:163], v[58:61]
	v_mfma_f32_16x16x32_bf16 v[54:57], v[134:137], v[168:171], v[54:57]
	v_mfma_f32_16x16x32_bf16 v[50:53], v[148:151], v[168:171], v[50:53]
	v_mfma_f32_16x16x32_bf16 v[46:49], v[134:137], v[176:179], v[46:49]
	v_mfma_f32_16x16x32_bf16 v[38:41], v[148:151], v[176:179], v[38:41]
	v_mfma_f32_16x16x32_bf16 v[30:33], v[134:137], v[184:187], v[30:33]
	v_mfma_f32_16x16x32_bf16 v[18:21], v[148:151], v[184:187], v[18:21]
	s_setprio 0
	s_barrier
	s_add_u32 s22, s40, 0xb0000
	s_addc_u32 s23, s41, 0
	s_add_i32 s85, s86, s50
	v_lshl_add_u64 v[130:131], s[22:23], 0, v[16:17]
	s_mov_b32 m0, s85
	s_nop 0
	global_load_lds_dwordx4 v[130:131], off
	v_lshl_add_u64 v[130:131], s[22:23], 0, v[142:143]
	s_add_i32 m0, s85, 0x2000
	s_nop 0
	global_load_lds_dwordx4 v[130:131], off
	s_waitcnt vmcnt(6)
	s_barrier
	s_setprio 1
	v_mfma_f32_16x16x32_bf16 v[42:45], v[188:191], v[152:155], v[42:45]
	v_mfma_f32_16x16x32_bf16 v[34:37], v[208:211], v[152:155], v[34:37]
	v_mfma_f32_16x16x32_bf16 v[26:29], v[188:191], v[164:167], v[26:29]
	v_mfma_f32_16x16x32_bf16 v[22:25], v[208:211], v[164:167], v[22:25]
	v_mfma_f32_16x16x32_bf16 v[12:15], v[188:191], v[172:175], v[12:15]
	v_mfma_f32_16x16x32_bf16 v[8:11], v[208:211], v[172:175], v[8:11]
	v_mfma_f32_16x16x32_bf16 v[4:7], v[188:191], v[180:183], v[4:7]
	v_mfma_f32_16x16x32_bf16 v[0:3], v[208:211], v[180:183], v[0:3]
	v_mfma_f32_16x16x32_bf16 v[42:45], v[192:195], v[160:163], v[42:45]
	v_mfma_f32_16x16x32_bf16 v[34:37], v[212:215], v[160:163], v[34:37]
	v_mfma_f32_16x16x32_bf16 v[26:29], v[192:195], v[168:171], v[26:29]
	v_mfma_f32_16x16x32_bf16 v[22:25], v[212:215], v[168:171], v[22:25]
	v_mfma_f32_16x16x32_bf16 v[12:15], v[192:195], v[176:179], v[12:15]
	v_mfma_f32_16x16x32_bf16 v[8:11], v[212:215], v[176:179], v[8:11]
	v_mfma_f32_16x16x32_bf16 v[4:7], v[192:195], v[184:187], v[4:7]
	v_mfma_f32_16x16x32_bf16 v[0:3], v[212:215], v[184:187], v[0:3]
	s_setprio 0
	s_add_i32 s85, 0, 0x18000
	v_add_u32_e32 v148, s85, v157
	s_barrier
	ds_read_b128 v[130:133], v148
	ds_read_b128 v[134:137], v148 offset:1024
	ds_read_b128 v[138:141], v148 offset:2048
	ds_read_b128 v[148:151], v148 offset:3072
	s_add_u32 s22, s42, 0xb0000
	s_addc_u32 s23, s43, 0
	s_mov_b32 m0, s56
	v_lshl_add_u64 v[188:189], s[22:23], 0, v[16:17]
	ds_read_b128 v[152:155], v159 offset:32768
	ds_read_b128 v[160:163], v159 offset:33792
	ds_read_b128 v[164:167], v159 offset:34816
	ds_read_b128 v[168:171], v159 offset:35840
	ds_read_b128 v[172:175], v159 offset:36864
	ds_read_b128 v[176:179], v159 offset:37888
	ds_read_b128 v[180:183], v159 offset:38912
	ds_read_b128 v[184:187], v159 offset:39936
	global_load_lds_dwordx4 v[188:189], off
	v_lshl_add_u64 v[188:189], s[22:23], 0, v[142:143]
	s_mov_b32 m0, s57
	s_nop 0
	global_load_lds_dwordx4 v[188:189], off
	s_waitcnt lgkmcnt(8)
	s_barrier
	s_waitcnt lgkmcnt(0)
	s_setprio 1
	s_waitcnt lgkmcnt(0)
	v_mfma_f32_16x16x32_bf16 v[126:129], v[130:133], v[152:155], v[126:129]
	v_mfma_f32_16x16x32_bf16 v[122:125], v[138:141], v[152:155], v[122:125]
	v_mfma_f32_16x16x32_bf16 v[118:121], v[130:133], v[164:167], v[118:121]
	v_mfma_f32_16x16x32_bf16 v[106:109], v[138:141], v[164:167], v[106:109]
	v_mfma_f32_16x16x32_bf16 v[102:105], v[130:133], v[172:175], v[102:105]
	v_mfma_f32_16x16x32_bf16 v[90:93], v[138:141], v[172:175], v[90:93]
	v_mfma_f32_16x16x32_bf16 v[86:89], v[130:133], v[180:183], v[86:89]
	v_mfma_f32_16x16x32_bf16 v[74:77], v[138:141], v[180:183], v[74:77]
	v_mfma_f32_16x16x32_bf16 v[126:129], v[134:137], v[160:163], v[126:129]
	v_mfma_f32_16x16x32_bf16 v[122:125], v[148:151], v[160:163], v[122:125]
	v_mfma_f32_16x16x32_bf16 v[118:121], v[134:137], v[168:171], v[118:121]
	v_mfma_f32_16x16x32_bf16 v[106:109], v[148:151], v[168:171], v[106:109]
	v_mfma_f32_16x16x32_bf16 v[102:105], v[134:137], v[176:179], v[102:105]
	v_mfma_f32_16x16x32_bf16 v[90:93], v[148:151], v[176:179], v[90:93]
	v_mfma_f32_16x16x32_bf16 v[86:89], v[134:137], v[184:187], v[86:89]
	v_mfma_f32_16x16x32_bf16 v[74:77], v[148:151], v[184:187], v[74:77]
	s_setprio 0
	s_barrier
	s_add_i32 s42, 0, 0x1c000
	s_add_i32 s22, s85, s50
	v_add_u32_e32 v212, s42, v157
	v_lshl_add_u64 v[196:197], v[196:197], 0, s[10:11]
	s_mov_b32 m0, s22
	ds_read_b128 v[188:191], v212
	ds_read_b128 v[192:195], v212 offset:1024
	ds_read_b128 v[208:211], v212 offset:2048
	ds_read_b128 v[212:215], v212 offset:3072
	global_load_lds_dwordx4 v[196:197], off
	v_lshl_add_u64 v[196:197], v[216:217], 0, s[10:11]
	s_add_i32 m0, s22, 0x2000
	s_nop 0
	global_load_lds_dwordx4 v[196:197], off
	s_barrier
	s_waitcnt lgkmcnt(0)
	s_setprio 1
	s_waitcnt lgkmcnt(0)
	v_mfma_f32_16x16x32_bf16 v[114:117], v[188:191], v[152:155], v[114:117]
	v_mfma_f32_16x16x32_bf16 v[110:113], v[208:211], v[152:155], v[110:113]
	v_mfma_f32_16x16x32_bf16 v[98:101], v[188:191], v[164:167], v[98:101]
	v_mfma_f32_16x16x32_bf16 v[94:97], v[208:211], v[164:167], v[94:97]
	v_mfma_f32_16x16x32_bf16 v[82:85], v[188:191], v[172:175], v[82:85]
	v_mfma_f32_16x16x32_bf16 v[78:81], v[208:211], v[172:175], v[78:81]
	v_mfma_f32_16x16x32_bf16 v[70:73], v[188:191], v[180:183], v[70:73]
	v_mfma_f32_16x16x32_bf16 v[66:69], v[208:211], v[180:183], v[66:69]
	v_mfma_f32_16x16x32_bf16 v[114:117], v[192:195], v[160:163], v[114:117]
	v_mfma_f32_16x16x32_bf16 v[110:113], v[212:215], v[160:163], v[110:113]
	v_mfma_f32_16x16x32_bf16 v[98:101], v[192:195], v[168:171], v[98:101]
	v_mfma_f32_16x16x32_bf16 v[94:97], v[212:215], v[168:171], v[94:97]
	v_mfma_f32_16x16x32_bf16 v[82:85], v[192:195], v[176:179], v[82:85]
	v_mfma_f32_16x16x32_bf16 v[78:81], v[212:215], v[176:179], v[78:81]
	v_mfma_f32_16x16x32_bf16 v[70:73], v[192:195], v[184:187], v[70:73]
	v_mfma_f32_16x16x32_bf16 v[66:69], v[212:215], v[184:187], v[66:69]
	s_setprio 0
	s_mov_b32 m0, s58
	v_lshl_add_u64 v[196:197], v[218:219], 0, s[10:11]
	s_barrier
	ds_read_b128 v[152:155], v159 offset:49152
	ds_read_b128 v[160:163], v159 offset:50176
	ds_read_b128 v[164:167], v159 offset:51200
	ds_read_b128 v[168:171], v159 offset:52224
	ds_read_b128 v[172:175], v159 offset:53248
	ds_read_b128 v[176:179], v159 offset:54272
	ds_read_b128 v[180:183], v159 offset:55296
	ds_read_b128 v[184:187], v159 offset:56320
	global_load_lds_dwordx4 v[196:197], off
	v_lshl_add_u64 v[196:197], v[220:221], 0, s[10:11]
	s_mov_b32 m0, s59
	s_nop 0
	global_load_lds_dwordx4 v[196:197], off
	s_barrier
	s_waitcnt lgkmcnt(0)
	s_setprio 1
	s_waitcnt lgkmcnt(0)
	v_mfma_f32_16x16x32_bf16 v[62:65], v[130:133], v[152:155], v[62:65]
	v_mfma_f32_16x16x32_bf16 v[58:61], v[138:141], v[152:155], v[58:61]
	v_mfma_f32_16x16x32_bf16 v[54:57], v[130:133], v[164:167], v[54:57]
	v_mfma_f32_16x16x32_bf16 v[50:53], v[138:141], v[164:167], v[50:53]
	v_mfma_f32_16x16x32_bf16 v[46:49], v[130:133], v[172:175], v[46:49]
	v_mfma_f32_16x16x32_bf16 v[38:41], v[138:141], v[172:175], v[38:41]
	v_mfma_f32_16x16x32_bf16 v[30:33], v[130:133], v[180:183], v[30:33]
	v_mfma_f32_16x16x32_bf16 v[18:21], v[138:141], v[180:183], v[18:21]
	v_mfma_f32_16x16x32_bf16 v[62:65], v[134:137], v[160:163], v[62:65]
	v_mfma_f32_16x16x32_bf16 v[58:61], v[148:151], v[160:163], v[58:61]
	v_mfma_f32_16x16x32_bf16 v[54:57], v[134:137], v[168:171], v[54:57]
	v_mfma_f32_16x16x32_bf16 v[50:53], v[148:151], v[168:171], v[50:53]
	v_mfma_f32_16x16x32_bf16 v[46:49], v[134:137], v[176:179], v[46:49]
	v_mfma_f32_16x16x32_bf16 v[38:41], v[148:151], v[176:179], v[38:41]
	v_mfma_f32_16x16x32_bf16 v[30:33], v[134:137], v[184:187], v[30:33]
	v_mfma_f32_16x16x32_bf16 v[18:21], v[148:151], v[184:187], v[18:21]
	s_setprio 0
	s_barrier
	s_add_u32 s22, s40, 0xb0080
	s_addc_u32 s23, s41, 0
	s_add_i32 s40, s42, s50
	v_lshl_add_u64 v[130:131], s[22:23], 0, v[16:17]
	s_mov_b32 m0, s40
	s_nop 0
	global_load_lds_dwordx4 v[130:131], off
	v_lshl_add_u64 v[130:131], s[22:23], 0, v[142:143]
	s_add_i32 m0, s40, 0x2000
	s_nop 0
	global_load_lds_dwordx4 v[130:131], off
	s_waitcnt vmcnt(6)
	s_barrier
	s_setprio 1
	v_mfma_f32_16x16x32_bf16 v[42:45], v[188:191], v[152:155], v[42:45]
	v_mfma_f32_16x16x32_bf16 v[34:37], v[208:211], v[152:155], v[34:37]
	v_mfma_f32_16x16x32_bf16 v[26:29], v[188:191], v[164:167], v[26:29]
	v_mfma_f32_16x16x32_bf16 v[22:25], v[208:211], v[164:167], v[22:25]
	v_mfma_f32_16x16x32_bf16 v[12:15], v[188:191], v[172:175], v[12:15]
	v_mfma_f32_16x16x32_bf16 v[8:11], v[208:211], v[172:175], v[8:11]
	v_mfma_f32_16x16x32_bf16 v[4:7], v[188:191], v[180:183], v[4:7]
	v_mfma_f32_16x16x32_bf16 v[0:3], v[208:211], v[180:183], v[0:3]
	v_mfma_f32_16x16x32_bf16 v[42:45], v[192:195], v[160:163], v[42:45]
	v_mfma_f32_16x16x32_bf16 v[34:37], v[212:215], v[160:163], v[34:37]
	v_mfma_f32_16x16x32_bf16 v[26:29], v[192:195], v[168:171], v[26:29]
	v_mfma_f32_16x16x32_bf16 v[22:25], v[212:215], v[168:171], v[22:25]
	v_mfma_f32_16x16x32_bf16 v[12:15], v[192:195], v[176:179], v[12:15]
	v_mfma_f32_16x16x32_bf16 v[8:11], v[212:215], v[176:179], v[8:11]
	v_mfma_f32_16x16x32_bf16 v[4:7], v[192:195], v[184:187], v[4:7]
	v_mfma_f32_16x16x32_bf16 v[0:3], v[212:215], v[184:187], v[0:3]
	s_setprio 0
	s_add_i32 s84, s84, 2
	s_add_u32 s34, s34, 0x100
	s_addc_u32 s79, s79, 0
	s_cmp_gt_u32 s84, 41
	s_mov_b64 s[22:23], s[28:29]
	s_barrier
	s_cbranch_scc0 .LBB0_133
	v_lshl_or_b32 v132, s12, 8, v158
	v_lshl_add_u32 v130, s2, 8, v156
	v_ashrrev_i32_e32 v133, 31, v132
	v_lshlrev_b64 v[148:149], 2, v[132:133]
	v_ashrrev_i32_e32 v131, 31, v130
	v_lshl_add_u64 v[150:151], s[4:5], 0, v[148:149]
	v_lshlrev_b64 v[152:153], 12, v[130:131]
	v_lshl_add_u64 v[132:133], v[150:151], 0, v[152:153]
	global_load_dwordx4 v[160:163], v[132:133], off
	global_load_dwordx4 v[164:167], v[132:133], off offset:64
	global_load_dwordx4 v[168:171], v[132:133], off offset:512
	global_load_dwordx4 v[172:175], v[132:133], off offset:576
	v_or_b32_e32 v132, 16, v130
	v_ashrrev_i32_e32 v133, 31, v132
	v_lshlrev_b64 v[196:197], 12, v[132:133]
	v_lshl_add_u64 v[132:133], v[150:151], 0, v[196:197]
	global_load_dwordx4 v[176:179], v[132:133], off
	global_load_dwordx4 v[180:183], v[132:133], off offset:64
	global_load_dwordx4 v[184:187], v[132:133], off offset:512
	global_load_dwordx4 v[188:191], v[132:133], off offset:576
	v_or_b32_e32 v132, 32, v130
	v_ashrrev_i32_e32 v133, 31, v132
	v_or_b32_e32 v130, 48, v130
	v_lshlrev_b64 v[224:225], 12, v[132:133]
	v_ashrrev_i32_e32 v131, 31, v130
	v_lshl_add_u64 v[132:133], v[150:151], 0, v[224:225]
	v_lshlrev_b64 v[154:155], 12, v[130:131]
	global_load_dwordx4 v[192:195], v[132:133], off
	global_load_dwordx4 v[208:211], v[132:133], off offset:64
	global_load_dwordx4 v[212:215], v[132:133], off offset:512
	global_load_dwordx4 v[216:219], v[132:133], off offset:576
	v_lshl_add_u64 v[130:131], v[150:151], 0, v[154:155]
	global_load_dwordx4 v[220:223], v[130:131], off
	global_load_dwordx4 v[138:141], v[130:131], off offset:64
	global_load_dwordx4 v[134:137], v[130:131], off offset:512
	s_nop 0
	global_load_dwordx4 v[130:133], v[130:131], off offset:576
	s_waitcnt vmcnt(0) lgkmcnt(0)
	v_pk_fma_f32 v[126:127], v[126:127], 0.5, v[160:161] op_sel_hi:[1,0,1]
	v_lshl_add_u64 v[160:161], s[14:15], 0, v[152:153]
	v_lshl_add_u64 v[160:161], v[160:161], 0, v[148:149]
	v_pk_fma_f32 v[116:117], v[116:117], 0.5, v[170:171] op_sel_hi:[1,0,1]
	v_pk_fma_f32 v[114:115], v[114:115], 0.5, v[168:169] op_sel_hi:[1,0,1]
	global_store_dwordx4 v[160:161], v[114:117], off offset:512
	v_pk_fma_f32 v[112:113], v[112:113], 0.5, v[174:175] op_sel_hi:[1,0,1]
	v_pk_fma_f32 v[100:101], v[100:101], 0.5, v[186:187] op_sel_hi:[1,0,1]
	v_lshl_add_u64 v[114:115], s[14:15], 0, v[196:197]
	v_lshl_add_u64 v[114:115], v[114:115], 0, v[148:149]
	v_pk_fma_f32 v[98:99], v[98:99], 0.5, v[184:185] op_sel_hi:[1,0,1]
	global_store_dwordx4 v[114:115], v[98:101], off offset:512
	v_pk_fma_f32 v[110:111], v[110:111], 0.5, v[172:173] op_sel_hi:[1,0,1]
	v_pk_fma_f32 v[96:97], v[96:97], 0.5, v[190:191] op_sel_hi:[1,0,1]
	v_lshl_add_u64 v[98:99], s[14:15], 0, v[224:225]
	v_lshl_add_u64 v[98:99], v[98:99], 0, v[148:149]
	v_pk_fma_f32 v[84:85], v[84:85], 0.5, v[214:215] op_sel_hi:[1,0,1]
	v_pk_fma_f32 v[82:83], v[82:83], 0.5, v[212:213] op_sel_hi:[1,0,1]
	v_pk_fma_f32 v[94:95], v[94:95], 0.5, v[188:189] op_sel_hi:[1,0,1]
	global_store_dwordx4 v[98:99], v[82:85], off offset:512
	v_pk_fma_f32 v[80:81], v[80:81], 0.5, v[218:219] op_sel_hi:[1,0,1]
	v_pk_fma_f32 v[78:79], v[78:79], 0.5, v[216:217] op_sel_hi:[1,0,1]
	v_lshl_add_u64 v[82:83], s[14:15], 0, v[154:155]
	v_pk_fma_f32 v[128:129], v[128:129], 0.5, v[162:163] op_sel_hi:[1,0,1]
	v_pk_fma_f32 v[124:125], v[124:125], 0.5, v[166:167] op_sel_hi:[1,0,1]
	v_pk_fma_f32 v[122:123], v[122:123], 0.5, v[164:165] op_sel_hi:[1,0,1]
	global_store_dwordx4 v[160:161], v[110:113], off offset:576
	v_pk_fma_f32 v[108:109], v[108:109], 0.5, v[182:183] op_sel_hi:[1,0,1]
	v_pk_fma_f32 v[106:107], v[106:107], 0.5, v[180:181] op_sel_hi:[1,0,1]
	v_pk_fma_f32 v[112:113], v[120:121], 0.5, v[178:179] op_sel_hi:[1,0,1]
	v_pk_fma_f32 v[110:111], v[118:119], 0.5, v[176:177] op_sel_hi:[1,0,1]
	global_store_dwordx4 v[114:115], v[94:97], off offset:576
	v_pk_fma_f32 v[92:93], v[92:93], 0.5, v[210:211] op_sel_hi:[1,0,1]
	v_pk_fma_f32 v[90:91], v[90:91], 0.5, v[208:209] op_sel_hi:[1,0,1]
	v_pk_fma_f32 v[96:97], v[104:105], 0.5, v[194:195] op_sel_hi:[1,0,1]
	v_pk_fma_f32 v[94:95], v[102:103], 0.5, v[192:193] op_sel_hi:[1,0,1]
	global_store_dwordx4 v[98:99], v[78:81], off offset:576
	v_lshl_add_u64 v[82:83], v[82:83], 0, v[148:149]
	v_pk_fma_f32 v[76:77], v[76:77], 0.5, v[140:141] op_sel_hi:[1,0,1]
	v_pk_fma_f32 v[80:81], v[88:89], 0.5, v[222:223] op_sel_hi:[1,0,1]
	v_pk_fma_f32 v[78:79], v[86:87], 0.5, v[220:221] op_sel_hi:[1,0,1]
	v_pk_fma_f32 v[74:75], v[74:75], 0.5, v[138:139] op_sel_hi:[1,0,1]
	v_pk_fma_f32 v[72:73], v[72:73], 0.5, v[136:137] op_sel_hi:[1,0,1]
	v_pk_fma_f32 v[70:71], v[70:71], 0.5, v[134:135] op_sel_hi:[1,0,1]
	v_pk_fma_f32 v[68:69], v[68:69], 0.5, v[132:133] op_sel_hi:[1,0,1]
	v_pk_fma_f32 v[66:67], v[66:67], 0.5, v[130:131] op_sel_hi:[1,0,1]
	global_store_dwordx4 v[160:161], v[126:129], off
	global_store_dwordx4 v[160:161], v[122:125], off offset:64
	global_store_dwordx4 v[114:115], v[110:113], off
	global_store_dwordx4 v[114:115], v[106:109], off offset:64
	global_store_dwordx4 v[98:99], v[94:97], off
	global_store_dwordx4 v[98:99], v[90:93], off offset:64
	global_store_dwordx4 v[82:83], v[78:81], off
	global_store_dwordx4 v[82:83], v[74:77], off offset:64
	global_store_dwordx4 v[82:83], v[70:73], off offset:512
	global_store_dwordx4 v[82:83], v[66:69], off offset:576
	s_mov_b64 s[22:23], 0x80000
	v_lshl_add_u64 v[130:131], v[152:153], 0, s[22:23]
	s_mov_b64 s[22:23], 0x90000
	v_lshl_add_u64 v[132:133], v[152:153], 0, s[22:23]
	s_mov_b64 s[22:23], 0xa0000
	v_lshl_add_u64 v[134:135], v[152:153], 0, s[22:23]
	s_mov_b64 s[22:23], 0xb0000
	v_lshl_add_u64 v[136:137], v[152:153], 0, s[22:23]
	v_lshl_add_u64 v[78:79], v[150:151], 0, v[130:131]
	v_lshl_add_u64 v[94:95], v[150:151], 0, v[132:133]
	v_lshl_add_u64 v[110:111], v[150:151], 0, v[134:135]
	v_lshl_add_u64 v[126:127], v[150:151], 0, v[136:137]
	global_load_dwordx4 v[66:69], v[78:79], off
	global_load_dwordx4 v[70:73], v[78:79], off offset:64
	global_load_dwordx4 v[74:77], v[78:79], off offset:512
	v_lshl_add_u64 v[130:131], s[14:15], 0, v[130:131]
	global_load_dwordx4 v[78:81], v[78:79], off offset:576
	s_nop 0
	global_load_dwordx4 v[82:85], v[94:95], off
	global_load_dwordx4 v[86:89], v[94:95], off offset:64
	global_load_dwordx4 v[90:93], v[94:95], off offset:512
	v_lshl_add_u64 v[132:133], s[14:15], 0, v[132:133]
	global_load_dwordx4 v[94:97], v[94:95], off offset:576
	s_nop 0
	global_load_dwordx4 v[98:101], v[110:111], off
	global_load_dwordx4 v[102:105], v[110:111], off offset:64
	global_load_dwordx4 v[106:109], v[110:111], off offset:512
	v_lshl_add_u64 v[134:135], s[14:15], 0, v[134:135]
	global_load_dwordx4 v[110:113], v[110:111], off offset:576
	s_nop 0
	global_load_dwordx4 v[114:117], v[126:127], off
	global_load_dwordx4 v[118:121], v[126:127], off offset:64
	global_load_dwordx4 v[122:125], v[126:127], off offset:512
	s_nop 0
	global_load_dwordx4 v[126:129], v[126:127], off offset:576
	v_lshl_add_u64 v[136:137], s[14:15], 0, v[136:137]
	v_lshl_add_u64 v[130:131], v[130:131], 0, v[148:149]
	v_lshl_add_u64 v[132:133], v[132:133], 0, v[148:149]
	v_lshl_add_u64 v[134:135], v[134:135], 0, v[148:149]
	v_lshl_add_u64 v[136:137], v[136:137], 0, v[148:149]
	s_waitcnt vmcnt(0) lgkmcnt(0)
	v_pk_fma_f32 v[64:65], v[64:65], 0.5, v[68:69] op_sel_hi:[1,0,1]
	v_pk_fma_f32 v[62:63], v[62:63], 0.5, v[66:67] op_sel_hi:[1,0,1]
	v_pk_fma_f32 v[60:61], v[60:61], 0.5, v[72:73] op_sel_hi:[1,0,1]
	v_pk_fma_f32 v[58:59], v[58:59], 0.5, v[70:71] op_sel_hi:[1,0,1]
	v_pk_fma_f32 v[44:45], v[44:45], 0.5, v[76:77] op_sel_hi:[1,0,1]
	v_pk_fma_f32 v[42:43], v[42:43], 0.5, v[74:75] op_sel_hi:[1,0,1]
	v_pk_fma_f32 v[36:37], v[36:37], 0.5, v[80:81] op_sel_hi:[1,0,1]
	v_pk_fma_f32 v[34:35], v[34:35], 0.5, v[78:79] op_sel_hi:[1,0,1]
	v_pk_fma_f32 v[56:57], v[56:57], 0.5, v[84:85] op_sel_hi:[1,0,1]
	v_pk_fma_f32 v[54:55], v[54:55], 0.5, v[82:83] op_sel_hi:[1,0,1]
	v_pk_fma_f32 v[52:53], v[52:53], 0.5, v[88:89] op_sel_hi:[1,0,1]
	v_pk_fma_f32 v[50:51], v[50:51], 0.5, v[86:87] op_sel_hi:[1,0,1]
	v_pk_fma_f32 v[28:29], v[28:29], 0.5, v[92:93] op_sel_hi:[1,0,1]
	v_pk_fma_f32 v[26:27], v[26:27], 0.5, v[90:91] op_sel_hi:[1,0,1]
	v_pk_fma_f32 v[24:25], v[24:25], 0.5, v[96:97] op_sel_hi:[1,0,1]
	v_pk_fma_f32 v[22:23], v[22:23], 0.5, v[94:95] op_sel_hi:[1,0,1]
	v_pk_fma_f32 v[48:49], v[48:49], 0.5, v[100:101] op_sel_hi:[1,0,1]
	v_pk_fma_f32 v[46:47], v[46:47], 0.5, v[98:99] op_sel_hi:[1,0,1]
	v_pk_fma_f32 v[40:41], v[40:41], 0.5, v[104:105] op_sel_hi:[1,0,1]
	v_pk_fma_f32 v[38:39], v[38:39], 0.5, v[102:103] op_sel_hi:[1,0,1]
	v_pk_fma_f32 v[14:15], v[14:15], 0.5, v[108:109] op_sel_hi:[1,0,1]
	v_pk_fma_f32 v[12:13], v[12:13], 0.5, v[106:107] op_sel_hi:[1,0,1]
	v_pk_fma_f32 v[10:11], v[10:11], 0.5, v[112:113] op_sel_hi:[1,0,1]
	v_pk_fma_f32 v[8:9], v[8:9], 0.5, v[110:111] op_sel_hi:[1,0,1]
	v_pk_fma_f32 v[32:33], v[32:33], 0.5, v[116:117] op_sel_hi:[1,0,1]
	v_pk_fma_f32 v[30:31], v[30:31], 0.5, v[114:115] op_sel_hi:[1,0,1]
	v_pk_fma_f32 v[20:21], v[20:21], 0.5, v[120:121] op_sel_hi:[1,0,1]
	v_pk_fma_f32 v[18:19], v[18:19], 0.5, v[118:119] op_sel_hi:[1,0,1]
	v_pk_fma_f32 v[6:7], v[6:7], 0.5, v[124:125] op_sel_hi:[1,0,1]
	v_pk_fma_f32 v[4:5], v[4:5], 0.5, v[122:123] op_sel_hi:[1,0,1]
	v_pk_fma_f32 v[2:3], v[2:3], 0.5, v[128:129] op_sel_hi:[1,0,1]
	v_pk_fma_f32 v[0:1], v[0:1], 0.5, v[126:127] op_sel_hi:[1,0,1]
	global_store_dwordx4 v[130:131], v[62:65], off
	global_store_dwordx4 v[130:131], v[58:61], off offset:64
	global_store_dwordx4 v[130:131], v[42:45], off offset:512
	global_store_dwordx4 v[130:131], v[34:37], off offset:576
	global_store_dwordx4 v[132:133], v[54:57], off
	global_store_dwordx4 v[132:133], v[50:53], off offset:64
	global_store_dwordx4 v[132:133], v[26:29], off offset:512
	global_store_dwordx4 v[132:133], v[22:25], off offset:576
	global_store_dwordx4 v[134:135], v[46:49], off
	global_store_dwordx4 v[134:135], v[38:41], off offset:64
	global_store_dwordx4 v[134:135], v[12:15], off offset:512
	global_store_dwordx4 v[134:135], v[8:11], off offset:576
	global_store_dwordx4 v[136:137], v[30:33], off
	global_store_dwordx4 v[136:137], v[18:21], off offset:64
	global_store_dwordx4 v[136:137], v[4:7], off offset:512
	global_store_dwordx4 v[136:137], v[0:3], off offset:576
	s_and_b64 vcc, exec, s[38:39]
	s_mov_b32 s12, s82
	s_mov_b32 s2, s83
	s_mov_b64 s[28:29], s[18:19]
	s_mov_b64 s[22:23], s[16:17]
	s_mov_b32 s86, 0x38c0000
	s_cbranch_vccz .LBB0_122
	s_waitcnt vmcnt(0)
	s_cmpk_gt_u32 s48, 0xff
	s_cbranch_scc1 .LBB0_137
	s_barrier

.LBB0_147:
	s_add_u32 s18, s16, 0xfffc0080
	s_addc_u32 s19, s17, -1
	s_add_i32 s83, 0, 0x10000
	v_add_u32_e32 v140, s83, v143
	ds_read_b128 v[146:149], v140
	ds_read_b128 v[150:153], v140 offset:1024
	ds_read_b128 v[154:157], v140 offset:2048
	ds_read_b128 v[158:161], v140 offset:3072
	s_cmp_eq_u32 s82, 12
	s_cselect_b32 s23, s12, s19
	s_cselect_b32 s22, s29, s18
	s_cselect_b32 s19, s9, s79
	s_cselect_b32 s18, s34, s61
	v_lshl_add_u64 v[140:141], s[16:17], 0, v[138:139]
	s_add_i32 m0, s15, 0xc000
	ds_read_b128 v[162:165], v145
	ds_read_b128 v[166:169], v145 offset:1024
	ds_read_b128 v[170:173], v145 offset:2048
	ds_read_b128 v[174:177], v145 offset:3072
	ds_read_b128 v[178:181], v145 offset:4096
	ds_read_b128 v[182:185], v145 offset:5120
	ds_read_b128 v[186:189], v145 offset:6144
	ds_read_b128 v[190:193], v145 offset:7168
	global_load_lds_dwordx4 v[140:141], off
	v_lshl_add_u64 v[140:141], s[16:17], 0, v[136:137]
	s_add_i32 m0, s15, 0xe000
	s_nop 0
	global_load_lds_dwordx4 v[140:141], off
	s_waitcnt lgkmcnt(8)
	s_barrier
	s_waitcnt lgkmcnt(0)
	s_setprio 1
	s_waitcnt lgkmcnt(0)
	v_mfma_f32_16x16x32_bf16 v[126:129], v[146:149], v[162:165], v[126:129]
	v_mfma_f32_16x16x32_bf16 v[118:121], v[154:157], v[162:165], v[118:121]
	v_mfma_f32_16x16x32_bf16 v[110:113], v[146:149], v[170:173], v[110:113]
	v_mfma_f32_16x16x32_bf16 v[102:105], v[154:157], v[170:173], v[102:105]
	v_mfma_f32_16x16x32_bf16 v[94:97], v[146:149], v[178:181], v[94:97]
	v_mfma_f32_16x16x32_bf16 v[86:89], v[154:157], v[178:181], v[86:89]
	v_mfma_f32_16x16x32_bf16 v[78:81], v[146:149], v[186:189], v[78:81]
	v_mfma_f32_16x16x32_bf16 v[70:73], v[154:157], v[186:189], v[70:73]
	v_mfma_f32_16x16x32_bf16 v[126:129], v[150:153], v[166:169], v[126:129]
	v_mfma_f32_16x16x32_bf16 v[118:121], v[158:161], v[166:169], v[118:121]
	v_mfma_f32_16x16x32_bf16 v[110:113], v[150:153], v[174:177], v[110:113]
	v_mfma_f32_16x16x32_bf16 v[102:105], v[158:161], v[174:177], v[102:105]
	v_mfma_f32_16x16x32_bf16 v[94:97], v[150:153], v[182:185], v[94:97]
	v_mfma_f32_16x16x32_bf16 v[86:89], v[158:161], v[182:185], v[86:89]
	v_mfma_f32_16x16x32_bf16 v[78:81], v[150:153], v[190:193], v[78:81]
	v_mfma_f32_16x16x32_bf16 v[70:73], v[158:161], v[190:193], v[70:73]
	s_setprio 0
	s_barrier
	s_add_i32 s86, 0, 0x14000
	v_add_u32_e32 v140, s86, v143
	s_add_i32 s83, s83, s51
	ds_read_b128 v[194:197], v140
	ds_read_b128 v[208:211], v140 offset:1024
	ds_read_b128 v[212:215], v140 offset:2048
	ds_read_b128 v[216:219], v140 offset:3072
	v_lshl_add_u64 v[140:141], s[18:19], 0, v[16:17]
	s_mov_b32 m0, s83
	v_lshl_add_u64 v[220:221], s[18:19], 0, v[130:131]
	global_load_lds_dwordx4 v[140:141], off
	s_add_i32 m0, s83, 0x2000
	s_nop 0
	global_load_lds_dwordx4 v[220:221], off
	s_barrier
	s_waitcnt lgkmcnt(0)
	s_setprio 1
	s_waitcnt lgkmcnt(0)
	v_mfma_f32_16x16x32_bf16 v[122:125], v[194:197], v[162:165], v[122:125]
	v_mfma_f32_16x16x32_bf16 v[114:117], v[212:215], v[162:165], v[114:117]
	v_mfma_f32_16x16x32_bf16 v[106:109], v[194:197], v[170:173], v[106:109]
	v_mfma_f32_16x16x32_bf16 v[98:101], v[212:215], v[170:173], v[98:101]
	v_mfma_f32_16x16x32_bf16 v[90:93], v[194:197], v[178:181], v[90:93]
	v_mfma_f32_16x16x32_bf16 v[82:85], v[212:215], v[178:181], v[82:85]
	v_mfma_f32_16x16x32_bf16 v[74:77], v[194:197], v[186:189], v[74:77]
	v_mfma_f32_16x16x32_bf16 v[66:69], v[212:215], v[186:189], v[66:69]
	v_mfma_f32_16x16x32_bf16 v[122:125], v[208:211], v[166:169], v[122:125]
	v_mfma_f32_16x16x32_bf16 v[114:117], v[216:219], v[166:169], v[114:117]
	v_mfma_f32_16x16x32_bf16 v[106:109], v[208:211], v[174:177], v[106:109]
	v_mfma_f32_16x16x32_bf16 v[98:101], v[216:219], v[174:177], v[98:101]
	v_mfma_f32_16x16x32_bf16 v[90:93], v[208:211], v[182:185], v[90:93]
	v_mfma_f32_16x16x32_bf16 v[82:85], v[216:219], v[182:185], v[82:85]
	v_mfma_f32_16x16x32_bf16 v[74:77], v[208:211], v[190:193], v[74:77]
	v_mfma_f32_16x16x32_bf16 v[66:69], v[216:219], v[190:193], v[66:69]
	s_setprio 0
	s_mov_b32 m0, s15
	v_lshl_add_u64 v[222:223], s[22:23], 0, v[134:135]
	s_barrier
	ds_read_b128 v[162:165], v145 offset:16384
	ds_read_b128 v[166:169], v145 offset:17408
	ds_read_b128 v[170:173], v145 offset:18432
	ds_read_b128 v[174:177], v145 offset:19456
	ds_read_b128 v[178:181], v145 offset:20480
	ds_read_b128 v[182:185], v145 offset:21504
	ds_read_b128 v[186:189], v145 offset:22528
	ds_read_b128 v[190:193], v145 offset:23552
	global_load_lds_dwordx4 v[222:223], off
	v_lshl_add_u64 v[224:225], s[22:23], 0, v[132:133]
	s_mov_b32 m0, s54
	s_nop 0
	global_load_lds_dwordx4 v[224:225], off
	s_barrier
	s_waitcnt lgkmcnt(0)
	s_setprio 1
	s_waitcnt lgkmcnt(0)
	v_mfma_f32_16x16x32_bf16 v[62:65], v[146:149], v[162:165], v[62:65]
	v_mfma_f32_16x16x32_bf16 v[54:57], v[154:157], v[162:165], v[54:57]
	v_mfma_f32_16x16x32_bf16 v[46:49], v[146:149], v[170:173], v[46:49]
	v_mfma_f32_16x16x32_bf16 v[38:41], v[154:157], v[170:173], v[38:41]
	v_mfma_f32_16x16x32_bf16 v[30:33], v[146:149], v[178:181], v[30:33]
	v_mfma_f32_16x16x32_bf16 v[22:25], v[154:157], v[178:181], v[22:25]
	v_mfma_f32_16x16x32_bf16 v[12:15], v[146:149], v[186:189], v[12:15]
	v_mfma_f32_16x16x32_bf16 v[4:7], v[154:157], v[186:189], v[4:7]
	v_mfma_f32_16x16x32_bf16 v[62:65], v[150:153], v[166:169], v[62:65]
	v_mfma_f32_16x16x32_bf16 v[54:57], v[158:161], v[166:169], v[54:57]
	v_mfma_f32_16x16x32_bf16 v[46:49], v[150:153], v[174:177], v[46:49]
	v_mfma_f32_16x16x32_bf16 v[38:41], v[158:161], v[174:177], v[38:41]
	v_mfma_f32_16x16x32_bf16 v[30:33], v[150:153], v[182:185], v[30:33]
	v_mfma_f32_16x16x32_bf16 v[22:25], v[158:161], v[182:185], v[22:25]
	v_mfma_f32_16x16x32_bf16 v[12:15], v[150:153], v[190:193], v[12:15]
	v_mfma_f32_16x16x32_bf16 v[4:7], v[158:161], v[190:193], v[4:7]
	s_setprio 0
	s_barrier
	s_add_u32 s84, s18, 0x40000
	s_addc_u32 s85, s19, 0
	s_add_i32 s83, s86, s51
	v_lshl_add_u64 v[146:147], s[84:85], 0, v[16:17]
	s_mov_b32 m0, s83
	s_nop 0
	global_load_lds_dwordx4 v[146:147], off
	v_lshl_add_u64 v[146:147], s[84:85], 0, v[130:131]
	s_add_i32 m0, s83, 0x2000
	s_nop 0
	global_load_lds_dwordx4 v[146:147], off
	s_waitcnt vmcnt(6)
	s_barrier
	s_setprio 1
	v_mfma_f32_16x16x32_bf16 v[58:61], v[194:197], v[162:165], v[58:61]
	v_mfma_f32_16x16x32_bf16 v[50:53], v[212:215], v[162:165], v[50:53]
	v_mfma_f32_16x16x32_bf16 v[42:45], v[194:197], v[170:173], v[42:45]
	v_mfma_f32_16x16x32_bf16 v[34:37], v[212:215], v[170:173], v[34:37]
	v_mfma_f32_16x16x32_bf16 v[26:29], v[194:197], v[178:181], v[26:29]
	v_mfma_f32_16x16x32_bf16 v[18:21], v[212:215], v[178:181], v[18:21]
	v_mfma_f32_16x16x32_bf16 v[8:11], v[194:197], v[186:189], v[8:11]
	v_mfma_f32_16x16x32_bf16 v[0:3], v[212:215], v[186:189], v[0:3]
	v_mfma_f32_16x16x32_bf16 v[58:61], v[208:211], v[166:169], v[58:61]
	v_mfma_f32_16x16x32_bf16 v[50:53], v[216:219], v[166:169], v[50:53]
	v_mfma_f32_16x16x32_bf16 v[42:45], v[208:211], v[174:177], v[42:45]
	v_mfma_f32_16x16x32_bf16 v[34:37], v[216:219], v[174:177], v[34:37]
	v_mfma_f32_16x16x32_bf16 v[26:29], v[208:211], v[182:185], v[26:29]
	v_mfma_f32_16x16x32_bf16 v[18:21], v[216:219], v[182:185], v[18:21]
	v_mfma_f32_16x16x32_bf16 v[8:11], v[208:211], v[190:193], v[8:11]
	v_mfma_f32_16x16x32_bf16 v[0:3], v[216:219], v[190:193], v[0:3]
	s_setprio 0
	s_add_i32 s83, 0, 0x18000
	v_add_u32_e32 v158, s83, v143
	s_barrier
	ds_read_b128 v[146:149], v158
	ds_read_b128 v[150:153], v158 offset:1024
	ds_read_b128 v[154:157], v158 offset:2048
	ds_read_b128 v[158:161], v158 offset:3072
	s_add_u32 s22, s22, 0x40000
	s_addc_u32 s23, s23, 0
	s_mov_b32 m0, s55
	v_lshl_add_u64 v[194:195], s[22:23], 0, v[134:135]
	ds_read_b128 v[162:165], v145 offset:32768
	ds_read_b128 v[166:169], v145 offset:33792
	ds_read_b128 v[170:173], v145 offset:34816
	ds_read_b128 v[174:177], v145 offset:35840
	ds_read_b128 v[178:181], v145 offset:36864
	ds_read_b128 v[182:185], v145 offset:37888
	ds_read_b128 v[186:189], v145 offset:38912
	ds_read_b128 v[190:193], v145 offset:39936
	global_load_lds_dwordx4 v[194:195], off
	v_lshl_add_u64 v[194:195], s[22:23], 0, v[132:133]
	s_mov_b32 m0, s56
	s_nop 0
	global_load_lds_dwordx4 v[194:195], off
	s_waitcnt lgkmcnt(8)
	s_barrier
	s_waitcnt lgkmcnt(0)
	s_setprio 1
	s_waitcnt lgkmcnt(0)
	v_mfma_f32_16x16x32_bf16 v[126:129], v[146:149], v[162:165], v[126:129]
	v_mfma_f32_16x16x32_bf16 v[118:121], v[154:157], v[162:165], v[118:121]
	v_mfma_f32_16x16x32_bf16 v[110:113], v[146:149], v[170:173], v[110:113]
	v_mfma_f32_16x16x32_bf16 v[102:105], v[154:157], v[170:173], v[102:105]
	v_mfma_f32_16x16x32_bf16 v[94:97], v[146:149], v[178:181], v[94:97]
	v_mfma_f32_16x16x32_bf16 v[86:89], v[154:157], v[178:181], v[86:89]
	v_mfma_f32_16x16x32_bf16 v[78:81], v[146:149], v[186:189], v[78:81]
	v_mfma_f32_16x16x32_bf16 v[70:73], v[154:157], v[186:189], v[70:73]
	v_mfma_f32_16x16x32_bf16 v[126:129], v[150:153], v[166:169], v[126:129]
	v_mfma_f32_16x16x32_bf16 v[118:121], v[158:161], v[166:169], v[118:121]
	v_mfma_f32_16x16x32_bf16 v[110:113], v[150:153], v[174:177], v[110:113]
	v_mfma_f32_16x16x32_bf16 v[102:105], v[158:161], v[174:177], v[102:105]
	v_mfma_f32_16x16x32_bf16 v[94:97], v[150:153], v[182:185], v[94:97]
	v_mfma_f32_16x16x32_bf16 v[86:89], v[158:161], v[182:185], v[86:89]
	v_mfma_f32_16x16x32_bf16 v[78:81], v[150:153], v[190:193], v[78:81]
	v_mfma_f32_16x16x32_bf16 v[70:73], v[158:161], v[190:193], v[70:73]
	s_setprio 0
	s_barrier
	s_add_i32 s22, 0, 0x1c000
	s_add_i32 s23, s83, s51
	v_add_u32_e32 v216, s22, v143
	v_lshl_add_u64 v[140:141], v[140:141], 0, s[10:11]
	s_mov_b32 m0, s23
	ds_read_b128 v[194:197], v216
	ds_read_b128 v[208:211], v216 offset:1024
	ds_read_b128 v[212:215], v216 offset:2048
	ds_read_b128 v[216:219], v216 offset:3072
	global_load_lds_dwordx4 v[140:141], off
	v_lshl_add_u64 v[140:141], v[220:221], 0, s[10:11]
	s_add_i32 m0, s23, 0x2000
	s_nop 0
	global_load_lds_dwordx4 v[140:141], off
	s_barrier
	s_waitcnt lgkmcnt(0)
	s_setprio 1
	s_waitcnt lgkmcnt(0)
	v_mfma_f32_16x16x32_bf16 v[122:125], v[194:197], v[162:165], v[122:125]
	v_mfma_f32_16x16x32_bf16 v[114:117], v[212:215], v[162:165], v[114:117]
	v_mfma_f32_16x16x32_bf16 v[106:109], v[194:197], v[170:173], v[106:109]
	v_mfma_f32_16x16x32_bf16 v[98:101], v[212:215], v[170:173], v[98:101]
	v_mfma_f32_16x16x32_bf16 v[90:93], v[194:197], v[178:181], v[90:93]
	v_mfma_f32_16x16x32_bf16 v[82:85], v[212:215], v[178:181], v[82:85]
	v_mfma_f32_16x16x32_bf16 v[74:77], v[194:197], v[186:189], v[74:77]
	v_mfma_f32_16x16x32_bf16 v[66:69], v[212:215], v[186:189], v[66:69]
	v_mfma_f32_16x16x32_bf16 v[122:125], v[208:211], v[166:169], v[122:125]
	v_mfma_f32_16x16x32_bf16 v[114:117], v[216:219], v[166:169], v[114:117]
	v_mfma_f32_16x16x32_bf16 v[106:109], v[208:211], v[174:177], v[106:109]
	v_mfma_f32_16x16x32_bf16 v[98:101], v[216:219], v[174:177], v[98:101]
	v_mfma_f32_16x16x32_bf16 v[90:93], v[208:211], v[182:185], v[90:93]
	v_mfma_f32_16x16x32_bf16 v[82:85], v[216:219], v[182:185], v[82:85]
	v_mfma_f32_16x16x32_bf16 v[74:77], v[208:211], v[190:193], v[74:77]
	v_mfma_f32_16x16x32_bf16 v[66:69], v[216:219], v[190:193], v[66:69]
	s_setprio 0
	s_mov_b32 m0, s57
	v_lshl_add_u64 v[140:141], v[222:223], 0, s[10:11]
	s_barrier
	ds_read_b128 v[162:165], v145 offset:49152
	ds_read_b128 v[166:169], v145 offset:50176
	ds_read_b128 v[170:173], v145 offset:51200
	ds_read_b128 v[174:177], v145 offset:52224
	ds_read_b128 v[178:181], v145 offset:53248
	ds_read_b128 v[182:185], v145 offset:54272
	ds_read_b128 v[186:189], v145 offset:55296
	ds_read_b128 v[190:193], v145 offset:56320
	global_load_lds_dwordx4 v[140:141], off
	v_lshl_add_u64 v[140:141], v[224:225], 0, s[10:11]
	s_mov_b32 m0, s58
	s_nop 0
	global_load_lds_dwordx4 v[140:141], off
	s_barrier
	s_waitcnt lgkmcnt(0)
	s_setprio 1
	s_waitcnt lgkmcnt(0)
	v_mfma_f32_16x16x32_bf16 v[62:65], v[146:149], v[162:165], v[62:65]
	v_mfma_f32_16x16x32_bf16 v[54:57], v[154:157], v[162:165], v[54:57]
	v_mfma_f32_16x16x32_bf16 v[46:49], v[146:149], v[170:173], v[46:49]
	v_mfma_f32_16x16x32_bf16 v[38:41], v[154:157], v[170:173], v[38:41]
	v_mfma_f32_16x16x32_bf16 v[30:33], v[146:149], v[178:181], v[30:33]
	v_mfma_f32_16x16x32_bf16 v[22:25], v[154:157], v[178:181], v[22:25]
	v_mfma_f32_16x16x32_bf16 v[12:15], v[146:149], v[186:189], v[12:15]
	v_mfma_f32_16x16x32_bf16 v[4:7], v[154:157], v[186:189], v[4:7]
	v_mfma_f32_16x16x32_bf16 v[62:65], v[150:153], v[166:169], v[62:65]
	v_mfma_f32_16x16x32_bf16 v[54:57], v[158:161], v[166:169], v[54:57]
	v_mfma_f32_16x16x32_bf16 v[46:49], v[150:153], v[174:177], v[46:49]
	v_mfma_f32_16x16x32_bf16 v[38:41], v[158:161], v[174:177], v[38:41]
	v_mfma_f32_16x16x32_bf16 v[30:33], v[150:153], v[182:185], v[30:33]
	v_mfma_f32_16x16x32_bf16 v[22:25], v[158:161], v[182:185], v[22:25]
	v_mfma_f32_16x16x32_bf16 v[12:15], v[150:153], v[190:193], v[12:15]
	v_mfma_f32_16x16x32_bf16 v[4:7], v[158:161], v[190:193], v[4:7]
	s_setprio 0
	s_barrier
	s_add_u32 s18, s18, 0x40080
	s_addc_u32 s19, s19, 0
	s_add_i32 s22, s22, s51
	v_lshl_add_u64 v[140:141], s[18:19], 0, v[16:17]
	s_mov_b32 m0, s22
	s_nop 0
	global_load_lds_dwordx4 v[140:141], off
	v_lshl_add_u64 v[140:141], s[18:19], 0, v[130:131]
	s_add_i32 m0, s22, 0x2000
	s_nop 0
	global_load_lds_dwordx4 v[140:141], off
	s_waitcnt vmcnt(6)
	s_barrier
	s_setprio 1
	v_mfma_f32_16x16x32_bf16 v[58:61], v[194:197], v[162:165], v[58:61]
	v_mfma_f32_16x16x32_bf16 v[50:53], v[212:215], v[162:165], v[50:53]
	v_mfma_f32_16x16x32_bf16 v[42:45], v[194:197], v[170:173], v[42:45]
	v_mfma_f32_16x16x32_bf16 v[34:37], v[212:215], v[170:173], v[34:37]
	v_mfma_f32_16x16x32_bf16 v[26:29], v[194:197], v[178:181], v[26:29]
	v_mfma_f32_16x16x32_bf16 v[18:21], v[212:215], v[178:181], v[18:21]
	v_mfma_f32_16x16x32_bf16 v[8:11], v[194:197], v[186:189], v[8:11]
	v_mfma_f32_16x16x32_bf16 v[0:3], v[212:215], v[186:189], v[0:3]
	v_mfma_f32_16x16x32_bf16 v[58:61], v[208:211], v[166:169], v[58:61]
	v_mfma_f32_16x16x32_bf16 v[50:53], v[216:219], v[166:169], v[50:53]
	v_mfma_f32_16x16x32_bf16 v[42:45], v[208:211], v[174:177], v[42:45]
	v_mfma_f32_16x16x32_bf16 v[34:37], v[216:219], v[174:177], v[34:37]
	v_mfma_f32_16x16x32_bf16 v[26:29], v[208:211], v[182:185], v[26:29]
	v_mfma_f32_16x16x32_bf16 v[18:21], v[216:219], v[182:185], v[18:21]
	v_mfma_f32_16x16x32_bf16 v[8:11], v[208:211], v[190:193], v[8:11]
	v_mfma_f32_16x16x32_bf16 v[0:3], v[216:219], v[190:193], v[0:3]
	s_setprio 0
	s_add_i32 s82, s82, 2
	s_add_u32 s61, s61, 0x100
	s_addc_u32 s79, s79, 0
	s_add_u32 s16, s16, 0x100
	s_addc_u32 s17, s17, 0
	s_cmp_gt_u32 s82, 13
	s_barrier
	s_cbranch_scc0 .LBB0_147
	v_mul_f32_e32 v147, 0xbfb8aa3b, v126
	v_exp_f32_e32 v147, v147
	v_lshl_or_b32 v148, s2, 7, v144
	v_lshl_add_u32 v146, s14, 8, v142
	v_ashrrev_i32_e32 v149, 31, v148
	v_add_f32_e32 v147, 1.0, v147
	v_rcp_f32_e32 v147, v147
	v_mov_b64_e32 v[140:141], s[94:95]
	v_mad_i64_i32 v[150:151], s[16:17], v146, s65, v[140:141]
	v_mul_f32_e32 v126, v126, v147
	v_mul_f32_e32 v122, v126, v122
	v_mul_f32_e32 v126, 0xbfb8aa3b, v127
	v_exp_f32_e32 v126, v126
	s_nop 0
	v_add_f32_e32 v126, 1.0, v126
	v_rcp_f32_e32 v126, v126
	s_nop 0
	v_mul_f32_e32 v126, v127, v126
	v_mul_f32_e32 v123, v126, v123
	v_mul_f32_e32 v126, 0xbfb8aa3b, v128
	v_exp_f32_e32 v126, v126
	s_nop 0
	v_add_f32_e32 v126, 1.0, v126
	v_rcp_f32_e32 v126, v126
	s_nop 0
	v_mul_f32_e32 v126, v128, v126
	v_mul_f32_e32 v124, v126, v124
	v_mul_f32_e32 v126, 0xbfb8aa3b, v129
	v_exp_f32_e32 v126, v126
	s_nop 0
	v_add_f32_e32 v126, 1.0, v126
	v_rcp_f32_e32 v126, v126
	s_nop 0
	v_mul_f32_e32 v126, v129, v126
	v_mul_f32_e32 v125, v126, v125
	v_mul_f32_e32 v126, 0xbfb8aa3b, v118
	v_exp_f32_e32 v126, v126
	s_nop 0
	v_add_f32_e32 v126, 1.0, v126
	v_rcp_f32_e32 v126, v126
	s_nop 0
	v_mul_f32_e32 v118, v118, v126
	v_mul_f32_e32 v118, v118, v114
	v_mul_f32_e32 v114, 0xbfb8aa3b, v119
	v_exp_f32_e32 v114, v114
	s_nop 0
	v_add_f32_e32 v114, 1.0, v114
	v_rcp_f32_e32 v114, v114
	s_nop 0
	v_mul_f32_e32 v114, v119, v114
	v_mul_f32_e32 v119, v114, v115
	v_mul_f32_e32 v114, 0xbfb8aa3b, v120
	v_exp_f32_e32 v114, v114
	v_cvt_pk_bf16_f32 v118, v118, v119
	s_nop 0
	v_add_f32_e32 v114, 1.0, v114
	v_rcp_f32_e32 v114, v114
	s_nop 0
	v_mul_f32_e32 v114, v120, v114
	v_mul_f32_e32 v126, v114, v116
	v_mul_f32_e32 v114, 0xbfb8aa3b, v121
	v_exp_f32_e32 v114, v114
	v_cvt_pk_bf16_f32 v116, v122, v123
	s_nop 0
	v_add_f32_e32 v114, 1.0, v114
	v_rcp_f32_e32 v114, v114
	s_nop 0
	v_mul_f32_e32 v114, v121, v114
	v_mul_f32_e32 v127, v114, v117
	v_lshlrev_b64 v[114:115], 1, v[148:149]
	v_lshl_add_u64 v[120:121], v[150:151], 0, v[114:115]
	v_cvt_pk_bf16_f32 v117, v124, v125
	v_cvt_pk_bf16_f32 v119, v126, v127
	global_store_dwordx4 v[120:121], v[116:119], off
	s_nop 1
	v_mul_f32_e32 v118, 0xbfb8aa3b, v110
	v_exp_f32_e32 v118, v118
	v_or_b32_e32 v116, 16, v146
	v_mad_i64_i32 v[116:117], s[16:17], v116, s65, v[140:141]
	v_add_f32_e32 v118, 1.0, v118
	v_rcp_f32_e32 v118, v118
	s_nop 0
	v_mul_f32_e32 v110, v110, v118
	v_mul_f32_e32 v106, v110, v106
	v_mul_f32_e32 v110, 0xbfb8aa3b, v111
	v_exp_f32_e32 v110, v110
	s_nop 0
	v_add_f32_e32 v110, 1.0, v110
	v_rcp_f32_e32 v110, v110
	s_nop 0
	v_mul_f32_e32 v110, v111, v110
	v_mul_f32_e32 v107, v110, v107
	v_mul_f32_e32 v110, 0xbfb8aa3b, v112
	v_exp_f32_e32 v110, v110
	s_nop 0
	v_add_f32_e32 v110, 1.0, v110
	v_rcp_f32_e32 v110, v110
	s_nop 0
	v_mul_f32_e32 v110, v112, v110
	v_mul_f32_e32 v108, v110, v108
	v_mul_f32_e32 v110, 0xbfb8aa3b, v113
	v_exp_f32_e32 v110, v110
	s_nop 0
	v_add_f32_e32 v110, 1.0, v110
	v_rcp_f32_e32 v110, v110
	s_nop 0
	v_mul_f32_e32 v110, v113, v110
	v_mul_f32_e32 v109, v110, v109
	v_mul_f32_e32 v110, 0xbfb8aa3b, v102
	v_exp_f32_e32 v110, v110
	s_nop 0
	v_add_f32_e32 v110, 1.0, v110
	v_rcp_f32_e32 v110, v110
	s_nop 0
	v_mul_f32_e32 v102, v102, v110
	v_mul_f32_e32 v110, v102, v98
	v_mul_f32_e32 v98, 0xbfb8aa3b, v103
	v_exp_f32_e32 v98, v98
	s_nop 0
	v_add_f32_e32 v98, 1.0, v98
	v_rcp_f32_e32 v98, v98
	s_nop 0
	v_mul_f32_e32 v98, v103, v98
	v_mul_f32_e32 v111, v98, v99
	v_mul_f32_e32 v98, 0xbfb8aa3b, v104
	v_exp_f32_e32 v98, v98
	v_lshl_add_u64 v[102:103], v[116:117], 0, v[114:115]
	v_cvt_pk_bf16_f32 v99, v108, v109
	v_add_f32_e32 v98, 1.0, v98
	v_rcp_f32_e32 v98, v98
	s_nop 0
	v_mul_f32_e32 v98, v104, v98
	v_mul_f32_e32 v104, v98, v100
	v_mul_f32_e32 v98, 0xbfb8aa3b, v105
	v_exp_f32_e32 v98, v98
	v_cvt_pk_bf16_f32 v100, v110, v111
	s_nop 0
	v_add_f32_e32 v98, 1.0, v98
	v_rcp_f32_e32 v98, v98
	s_nop 0
	v_mul_f32_e32 v98, v105, v98
	v_mul_f32_e32 v101, v98, v101
	v_cvt_pk_bf16_f32 v98, v106, v107
	v_cvt_pk_bf16_f32 v101, v104, v101
	global_store_dwordx4 v[102:103], v[98:101], off
	s_nop 1
	v_mul_f32_e32 v100, 0xbfb8aa3b, v94
	v_exp_f32_e32 v100, v100
	v_or_b32_e32 v98, 32, v146
	v_mad_i64_i32 v[98:99], s[16:17], v98, s65, v[140:141]
	v_add_f32_e32 v100, 1.0, v100
	v_rcp_f32_e32 v100, v100
	s_nop 0
	v_mul_f32_e32 v94, v94, v100
	v_mul_f32_e32 v90, v94, v90
	v_mul_f32_e32 v94, 0xbfb8aa3b, v95
	v_exp_f32_e32 v94, v94
	s_nop 0
	v_add_f32_e32 v94, 1.0, v94
	v_rcp_f32_e32 v94, v94
	s_nop 0
	v_mul_f32_e32 v94, v95, v94
	v_mul_f32_e32 v91, v94, v91
	v_mul_f32_e32 v94, 0xbfb8aa3b, v96
	v_exp_f32_e32 v94, v94
	s_nop 0
	v_add_f32_e32 v94, 1.0, v94
	v_rcp_f32_e32 v94, v94
	s_nop 0
	v_mul_f32_e32 v94, v96, v94
	v_mul_f32_e32 v92, v94, v92
	v_mul_f32_e32 v94, 0xbfb8aa3b, v97
	v_exp_f32_e32 v94, v94
	s_nop 0
	v_add_f32_e32 v94, 1.0, v94
	v_rcp_f32_e32 v94, v94
	s_nop 0
	v_mul_f32_e32 v94, v97, v94
	v_mul_f32_e32 v93, v94, v93
	v_mul_f32_e32 v94, 0xbfb8aa3b, v86
	v_exp_f32_e32 v94, v94
	s_nop 0
	v_add_f32_e32 v94, 1.0, v94
	v_rcp_f32_e32 v94, v94
	s_nop 0
	v_mul_f32_e32 v86, v86, v94
	v_mul_f32_e32 v94, v86, v82
	v_mul_f32_e32 v82, 0xbfb8aa3b, v87
	v_exp_f32_e32 v82, v82
	s_nop 0
	v_add_f32_e32 v82, 1.0, v82
	v_rcp_f32_e32 v82, v82
	s_nop 0
	v_mul_f32_e32 v82, v87, v82
	v_mul_f32_e32 v95, v82, v83
	v_mul_f32_e32 v82, 0xbfb8aa3b, v88
	v_exp_f32_e32 v82, v82
	v_lshl_add_u64 v[86:87], v[98:99], 0, v[114:115]
	v_cvt_pk_bf16_f32 v83, v92, v93
	v_add_f32_e32 v82, 1.0, v82
	v_rcp_f32_e32 v82, v82
	s_nop 0
	v_mul_f32_e32 v82, v88, v82
	v_mul_f32_e32 v88, v82, v84
	v_mul_f32_e32 v82, 0xbfb8aa3b, v89
	v_exp_f32_e32 v82, v82
	v_cvt_pk_bf16_f32 v84, v94, v95
	s_nop 0
	v_add_f32_e32 v82, 1.0, v82
	v_rcp_f32_e32 v82, v82
	s_nop 0
	v_mul_f32_e32 v82, v89, v82
	v_mul_f32_e32 v85, v82, v85
	v_cvt_pk_bf16_f32 v82, v90, v91
	v_cvt_pk_bf16_f32 v85, v88, v85
	global_store_dwordx4 v[86:87], v[82:85], off
	s_nop 1
	v_mul_f32_e32 v84, 0xbfb8aa3b, v78
	v_exp_f32_e32 v84, v84
	v_or_b32_e32 v82, 48, v146
	v_mad_i64_i32 v[82:83], s[16:17], v82, s65, v[140:141]
	v_add_f32_e32 v84, 1.0, v84
	v_rcp_f32_e32 v84, v84
	s_nop 0
	v_mul_f32_e32 v78, v78, v84
	v_mul_f32_e32 v74, v78, v74
	v_mul_f32_e32 v78, 0xbfb8aa3b, v79
	v_exp_f32_e32 v78, v78
	s_nop 0
	v_add_f32_e32 v78, 1.0, v78
	v_rcp_f32_e32 v78, v78
	s_nop 0
	v_mul_f32_e32 v78, v79, v78
	v_mul_f32_e32 v75, v78, v75
	v_mul_f32_e32 v78, 0xbfb8aa3b, v80
	v_exp_f32_e32 v78, v78
	s_nop 0
	v_add_f32_e32 v78, 1.0, v78
	v_rcp_f32_e32 v78, v78
	s_nop 0
	v_mul_f32_e32 v78, v80, v78
	v_mul_f32_e32 v76, v78, v76
	v_mul_f32_e32 v78, 0xbfb8aa3b, v81
	v_exp_f32_e32 v78, v78
	s_nop 0
	v_add_f32_e32 v78, 1.0, v78
	v_rcp_f32_e32 v78, v78
	s_nop 0
	v_mul_f32_e32 v78, v81, v78
	v_mul_f32_e32 v77, v78, v77
	v_mul_f32_e32 v78, 0xbfb8aa3b, v70
	v_exp_f32_e32 v78, v78
	s_nop 0
	v_add_f32_e32 v78, 1.0, v78
	v_rcp_f32_e32 v78, v78
	s_nop 0
	v_mul_f32_e32 v70, v70, v78
	v_mul_f32_e32 v78, v70, v66
	v_mul_f32_e32 v66, 0xbfb8aa3b, v71
	v_exp_f32_e32 v66, v66
	s_nop 0
	v_add_f32_e32 v66, 1.0, v66
	v_rcp_f32_e32 v66, v66
	s_nop 0
	v_mul_f32_e32 v66, v71, v66
	v_mul_f32_e32 v79, v66, v67
	v_mul_f32_e32 v66, 0xbfb8aa3b, v72
	v_exp_f32_e32 v66, v66
	v_lshl_add_u64 v[70:71], v[82:83], 0, v[114:115]
	v_cvt_pk_bf16_f32 v67, v76, v77
	v_add_f32_e32 v66, 1.0, v66
	v_rcp_f32_e32 v66, v66
	s_nop 0
	v_mul_f32_e32 v66, v72, v66
	v_mul_f32_e32 v72, v66, v68
	v_mul_f32_e32 v66, 0xbfb8aa3b, v73
	v_exp_f32_e32 v66, v66
	v_cvt_pk_bf16_f32 v68, v78, v79
	s_nop 0
	v_add_f32_e32 v66, 1.0, v66
	v_rcp_f32_e32 v66, v66
	s_nop 0
	v_mul_f32_e32 v66, v73, v66
	v_mul_f32_e32 v69, v66, v69
	v_cvt_pk_bf16_f32 v66, v74, v75
	v_cvt_pk_bf16_f32 v69, v72, v69
	global_store_dwordx4 v[70:71], v[66:69], off
	s_nop 1
	v_mul_f32_e32 v68, 0xbfb8aa3b, v62
	v_exp_f32_e32 v68, v68
	v_add_u32_e32 v66, 0x80, v146
	v_mad_i64_i32 v[66:67], s[16:17], v66, s65, v[140:141]
	v_add_f32_e32 v68, 1.0, v68
	v_rcp_f32_e32 v68, v68
	s_nop 0
	v_mul_f32_e32 v62, v62, v68
	v_mul_f32_e32 v58, v62, v58
	v_mul_f32_e32 v62, 0xbfb8aa3b, v63
	v_exp_f32_e32 v62, v62
	s_nop 0
	v_add_f32_e32 v62, 1.0, v62
	v_rcp_f32_e32 v62, v62
	s_nop 0
	v_mul_f32_e32 v62, v63, v62
	v_mul_f32_e32 v59, v62, v59
	v_mul_f32_e32 v62, 0xbfb8aa3b, v64
	v_exp_f32_e32 v62, v62
	s_nop 0
	v_add_f32_e32 v62, 1.0, v62
	v_rcp_f32_e32 v62, v62
	s_nop 0
	v_mul_f32_e32 v62, v64, v62
	v_mul_f32_e32 v60, v62, v60
	v_mul_f32_e32 v62, 0xbfb8aa3b, v65
	v_exp_f32_e32 v62, v62
	s_nop 0
	v_add_f32_e32 v62, 1.0, v62
	v_rcp_f32_e32 v62, v62
	s_nop 0
	v_mul_f32_e32 v62, v65, v62
	v_mul_f32_e32 v61, v62, v61
	v_mul_f32_e32 v62, 0xbfb8aa3b, v54
	v_exp_f32_e32 v62, v62
	s_nop 0
	v_add_f32_e32 v62, 1.0, v62
	v_rcp_f32_e32 v62, v62
	s_nop 0
	v_mul_f32_e32 v54, v54, v62
	v_mul_f32_e32 v62, v54, v50
	v_mul_f32_e32 v50, 0xbfb8aa3b, v55
	v_exp_f32_e32 v50, v50
	s_nop 0
	v_add_f32_e32 v50, 1.0, v50
	v_rcp_f32_e32 v50, v50
	s_nop 0
	v_mul_f32_e32 v50, v55, v50
	v_mul_f32_e32 v63, v50, v51
	v_mul_f32_e32 v50, 0xbfb8aa3b, v56
	v_exp_f32_e32 v50, v50
	v_lshl_add_u64 v[54:55], v[66:67], 0, v[114:115]
	v_cvt_pk_bf16_f32 v51, v60, v61
	v_add_f32_e32 v50, 1.0, v50
	v_rcp_f32_e32 v50, v50
	s_nop 0
	v_mul_f32_e32 v50, v56, v50
	v_mul_f32_e32 v56, v50, v52
	v_mul_f32_e32 v50, 0xbfb8aa3b, v57
	v_exp_f32_e32 v50, v50
	v_cvt_pk_bf16_f32 v52, v62, v63
	s_nop 0
	v_add_f32_e32 v50, 1.0, v50
	v_rcp_f32_e32 v50, v50
	s_nop 0
	v_mul_f32_e32 v50, v57, v50
	v_mul_f32_e32 v53, v50, v53
	v_cvt_pk_bf16_f32 v50, v58, v59
	v_cvt_pk_bf16_f32 v53, v56, v53
	global_store_dwordx4 v[54:55], v[50:53], off
	s_nop 1
	v_mul_f32_e32 v52, 0xbfb8aa3b, v46
	v_exp_f32_e32 v52, v52
	v_add_u32_e32 v50, 0x90, v146
	v_mad_i64_i32 v[50:51], s[16:17], v50, s65, v[140:141]
	v_add_f32_e32 v52, 1.0, v52
	v_rcp_f32_e32 v52, v52
	s_nop 0
	v_mul_f32_e32 v46, v46, v52
	v_mul_f32_e32 v42, v46, v42
	v_mul_f32_e32 v46, 0xbfb8aa3b, v47
	v_exp_f32_e32 v46, v46
	s_nop 0
	v_add_f32_e32 v46, 1.0, v46
	v_rcp_f32_e32 v46, v46
	s_nop 0
	v_mul_f32_e32 v46, v47, v46
	v_mul_f32_e32 v43, v46, v43
	v_mul_f32_e32 v46, 0xbfb8aa3b, v48
	v_exp_f32_e32 v46, v46
	s_nop 0
	v_add_f32_e32 v46, 1.0, v46
	v_rcp_f32_e32 v46, v46
	s_nop 0
	v_mul_f32_e32 v46, v48, v46
	v_mul_f32_e32 v44, v46, v44
	v_mul_f32_e32 v46, 0xbfb8aa3b, v49
	v_exp_f32_e32 v46, v46
	s_nop 0
	v_add_f32_e32 v46, 1.0, v46
	v_rcp_f32_e32 v46, v46
	s_nop 0
	v_mul_f32_e32 v46, v49, v46
	v_mul_f32_e32 v45, v46, v45
	v_mul_f32_e32 v46, 0xbfb8aa3b, v38
	v_exp_f32_e32 v46, v46
	s_nop 0
	v_add_f32_e32 v46, 1.0, v46
	v_rcp_f32_e32 v46, v46
	s_nop 0
	v_mul_f32_e32 v38, v38, v46
	v_mul_f32_e32 v46, v38, v34
	v_mul_f32_e32 v34, 0xbfb8aa3b, v39
	v_exp_f32_e32 v34, v34
	s_nop 0
	v_add_f32_e32 v34, 1.0, v34
	v_rcp_f32_e32 v34, v34
	s_nop 0
	v_mul_f32_e32 v34, v39, v34
	v_mul_f32_e32 v47, v34, v35
	v_mul_f32_e32 v34, 0xbfb8aa3b, v40
	v_exp_f32_e32 v34, v34
	v_lshl_add_u64 v[38:39], v[50:51], 0, v[114:115]
	v_cvt_pk_bf16_f32 v35, v44, v45
	v_add_f32_e32 v34, 1.0, v34
	v_rcp_f32_e32 v34, v34
	s_nop 0
	v_mul_f32_e32 v34, v40, v34
	v_mul_f32_e32 v40, v34, v36
	v_mul_f32_e32 v34, 0xbfb8aa3b, v41
	v_exp_f32_e32 v34, v34
	v_cvt_pk_bf16_f32 v36, v46, v47
	s_nop 0
	v_add_f32_e32 v34, 1.0, v34
	v_rcp_f32_e32 v34, v34
	s_nop 0
	v_mul_f32_e32 v34, v41, v34
	v_mul_f32_e32 v37, v34, v37
	v_cvt_pk_bf16_f32 v34, v42, v43
	v_cvt_pk_bf16_f32 v37, v40, v37
	global_store_dwordx4 v[38:39], v[34:37], off
	s_nop 1
	v_mul_f32_e32 v36, 0xbfb8aa3b, v30
	v_exp_f32_e32 v36, v36
	v_add_u32_e32 v34, 0xa0, v146
	v_mad_i64_i32 v[34:35], s[16:17], v34, s65, v[140:141]
	v_add_f32_e32 v36, 1.0, v36
	v_rcp_f32_e32 v36, v36
	s_nop 0
	v_mul_f32_e32 v30, v30, v36
	v_mul_f32_e32 v26, v30, v26
	v_mul_f32_e32 v30, 0xbfb8aa3b, v31
	v_exp_f32_e32 v30, v30
	s_nop 0
	v_add_f32_e32 v30, 1.0, v30
	v_rcp_f32_e32 v30, v30
	s_nop 0
	v_mul_f32_e32 v30, v31, v30
	v_mul_f32_e32 v27, v30, v27
	v_mul_f32_e32 v30, 0xbfb8aa3b, v32
	v_exp_f32_e32 v30, v30
	s_nop 0
	v_add_f32_e32 v30, 1.0, v30
	v_rcp_f32_e32 v30, v30
	s_nop 0
	v_mul_f32_e32 v30, v32, v30
	v_mul_f32_e32 v28, v30, v28
	v_mul_f32_e32 v30, 0xbfb8aa3b, v33
	v_exp_f32_e32 v30, v30
	s_nop 0
	v_add_f32_e32 v30, 1.0, v30
	v_rcp_f32_e32 v30, v30
	s_nop 0
	v_mul_f32_e32 v30, v33, v30
	v_mul_f32_e32 v29, v30, v29
	v_mul_f32_e32 v30, 0xbfb8aa3b, v22
	v_exp_f32_e32 v30, v30
	s_nop 0
	v_add_f32_e32 v30, 1.0, v30
	v_rcp_f32_e32 v30, v30
	s_nop 0
	v_mul_f32_e32 v22, v22, v30
	v_mul_f32_e32 v30, v22, v18
	v_mul_f32_e32 v18, 0xbfb8aa3b, v23
	v_exp_f32_e32 v18, v18
	s_nop 0
	v_add_f32_e32 v18, 1.0, v18
	v_rcp_f32_e32 v18, v18
	s_nop 0
	v_mul_f32_e32 v18, v23, v18
	v_mul_f32_e32 v31, v18, v19
	v_mul_f32_e32 v18, 0xbfb8aa3b, v24
	v_exp_f32_e32 v18, v18
	v_lshl_add_u64 v[22:23], v[34:35], 0, v[114:115]
	v_cvt_pk_bf16_f32 v19, v28, v29
	v_add_f32_e32 v18, 1.0, v18
	v_rcp_f32_e32 v18, v18
	s_nop 0
	v_mul_f32_e32 v18, v24, v18
	v_mul_f32_e32 v24, v18, v20
	v_mul_f32_e32 v18, 0xbfb8aa3b, v25
	v_exp_f32_e32 v18, v18
	v_cvt_pk_bf16_f32 v20, v30, v31
	s_nop 0
	v_add_f32_e32 v18, 1.0, v18
	v_rcp_f32_e32 v18, v18
	s_nop 0
	v_mul_f32_e32 v18, v25, v18
	v_mul_f32_e32 v21, v18, v21
	v_cvt_pk_bf16_f32 v18, v26, v27
	v_cvt_pk_bf16_f32 v21, v24, v21
	global_store_dwordx4 v[22:23], v[18:21], off
	s_nop 1
	v_mul_f32_e32 v20, 0xbfb8aa3b, v12
	v_exp_f32_e32 v20, v20
	v_add_u32_e32 v18, 0xb0, v146
	v_mad_i64_i32 v[18:19], s[16:17], v18, s65, v[140:141]
	v_add_f32_e32 v20, 1.0, v20
	v_rcp_f32_e32 v20, v20
	s_nop 0
	v_mul_f32_e32 v12, v12, v20
	v_mul_f32_e32 v8, v12, v8
	v_mul_f32_e32 v12, 0xbfb8aa3b, v13
	v_exp_f32_e32 v12, v12
	s_nop 0
	v_add_f32_e32 v12, 1.0, v12
	v_rcp_f32_e32 v12, v12
	s_nop 0
	v_mul_f32_e32 v12, v13, v12
	v_mul_f32_e32 v9, v12, v9
	v_mul_f32_e32 v12, 0xbfb8aa3b, v14
	v_exp_f32_e32 v12, v12
	s_nop 0
	v_add_f32_e32 v12, 1.0, v12
	v_rcp_f32_e32 v12, v12
	s_nop 0
	v_mul_f32_e32 v12, v14, v12
	v_mul_f32_e32 v10, v12, v10
	v_mul_f32_e32 v12, 0xbfb8aa3b, v15
	v_exp_f32_e32 v12, v12
	s_nop 0
	v_add_f32_e32 v12, 1.0, v12
	v_rcp_f32_e32 v12, v12
	s_nop 0
	v_mul_f32_e32 v12, v15, v12
	v_mul_f32_e32 v11, v12, v11
	v_mul_f32_e32 v12, 0xbfb8aa3b, v4
	v_exp_f32_e32 v12, v12
	s_nop 0
	v_add_f32_e32 v12, 1.0, v12
	v_rcp_f32_e32 v12, v12
	s_nop 0
	v_mul_f32_e32 v4, v4, v12
	v_mul_f32_e32 v12, v4, v0
	v_mul_f32_e32 v0, 0xbfb8aa3b, v5
	v_exp_f32_e32 v0, v0
	s_nop 0
	v_add_f32_e32 v0, 1.0, v0
	v_rcp_f32_e32 v0, v0
	s_nop 0
	v_mul_f32_e32 v0, v5, v0
	v_mul_f32_e32 v13, v0, v1
	v_mul_f32_e32 v0, 0xbfb8aa3b, v6
	v_exp_f32_e32 v0, v0
	v_lshl_add_u64 v[4:5], v[18:19], 0, v[114:115]
	v_cvt_pk_bf16_f32 v1, v10, v11
	v_add_f32_e32 v0, 1.0, v0
	v_rcp_f32_e32 v0, v0
	s_nop 0
	v_mul_f32_e32 v0, v6, v0
	v_mul_f32_e32 v6, v0, v2
	v_mul_f32_e32 v0, 0xbfb8aa3b, v7
	v_exp_f32_e32 v0, v0
	v_cvt_pk_bf16_f32 v2, v12, v13
	s_nop 0
	v_add_f32_e32 v0, 1.0, v0
	v_rcp_f32_e32 v0, v0
	s_nop 0
	v_mul_f32_e32 v0, v7, v0
	v_mul_f32_e32 v3, v0, v3
	v_cvt_pk_bf16_f32 v0, v8, v9
	v_cvt_pk_bf16_f32 v3, v6, v3
	global_store_dwordx4 v[4:5], v[0:3], off
	s_and_b64 vcc, exec, s[38:39]
	s_mov_b32 s2, s8
	s_mov_b32 s14, s28
	s_mov_b64 s[16:17], s[42:43]
	s_mov_b64 s[18:19], s[40:41]
	s_cbranch_vccz .LBB0_144
	s_waitcnt vmcnt(0)
	s_cmpk_gt_u32 s48, 0xff
	s_cbranch_scc1 .LBB0_151
	s_barrier

.LBB0_174:
	s_add_u32 s40, s22, 0x100
	s_addc_u32 s41, s23, 0
	s_add_i32 s83, 0, 0x10000
	v_add_u32_e32 v148, s83, v157
	ds_read_b128 v[130:133], v148
	ds_read_b128 v[134:137], v148 offset:1024
	ds_read_b128 v[138:141], v148 offset:2048
	ds_read_b128 v[148:151], v148 offset:3072
	s_cmp_eq_u32 s82, 12
	s_cselect_b32 s49, s9, s41
	s_cselect_b32 s48, s12, s40
	s_cselect_b32 s43, s5, s79
	s_cselect_b32 s42, s34, s61
	v_lshl_add_u64 v[188:189], s[22:23], 0, v[146:147]
	s_add_i32 m0, s19, 0xc000
	ds_read_b128 v[152:155], v159
	ds_read_b128 v[160:163], v159 offset:1024
	ds_read_b128 v[164:167], v159 offset:2048
	ds_read_b128 v[168:171], v159 offset:3072
	ds_read_b128 v[172:175], v159 offset:4096
	ds_read_b128 v[176:179], v159 offset:5120
	ds_read_b128 v[180:183], v159 offset:6144
	ds_read_b128 v[184:187], v159 offset:7168
	global_load_lds_dwordx4 v[188:189], off
	v_lshl_add_u64 v[188:189], s[22:23], 0, v[144:145]
	s_add_i32 m0, s19, 0xe000
	s_nop 0
	global_load_lds_dwordx4 v[188:189], off
	s_waitcnt lgkmcnt(8)
	s_barrier
	s_waitcnt lgkmcnt(0)
	s_setprio 1
	s_waitcnt lgkmcnt(0)
	v_mfma_f32_16x16x32_bf16 v[126:129], v[130:133], v[152:155], v[126:129]
	v_mfma_f32_16x16x32_bf16 v[122:125], v[138:141], v[152:155], v[122:125]
	v_mfma_f32_16x16x32_bf16 v[118:121], v[130:133], v[164:167], v[118:121]
	v_mfma_f32_16x16x32_bf16 v[106:109], v[138:141], v[164:167], v[106:109]
	v_mfma_f32_16x16x32_bf16 v[102:105], v[130:133], v[172:175], v[102:105]
	v_mfma_f32_16x16x32_bf16 v[90:93], v[138:141], v[172:175], v[90:93]
	v_mfma_f32_16x16x32_bf16 v[86:89], v[130:133], v[180:183], v[86:89]
	v_mfma_f32_16x16x32_bf16 v[74:77], v[138:141], v[180:183], v[74:77]
	v_mfma_f32_16x16x32_bf16 v[126:129], v[134:137], v[160:163], v[126:129]
	v_mfma_f32_16x16x32_bf16 v[122:125], v[148:151], v[160:163], v[122:125]
	v_mfma_f32_16x16x32_bf16 v[118:121], v[134:137], v[168:171], v[118:121]
	v_mfma_f32_16x16x32_bf16 v[106:109], v[148:151], v[168:171], v[106:109]
	v_mfma_f32_16x16x32_bf16 v[102:105], v[134:137], v[176:179], v[102:105]
	v_mfma_f32_16x16x32_bf16 v[90:93], v[148:151], v[176:179], v[90:93]
	v_mfma_f32_16x16x32_bf16 v[86:89], v[134:137], v[184:187], v[86:89]
	v_mfma_f32_16x16x32_bf16 v[74:77], v[148:151], v[184:187], v[74:77]
	s_setprio 0
	s_barrier
	s_add_i32 s84, 0, 0x14000
	v_add_u32_e32 v196, s84, v157
	s_add_i32 s22, s83, s52
	ds_read_b128 v[188:191], v196
	ds_read_b128 v[192:195], v196 offset:1024
	ds_read_b128 v[208:211], v196 offset:2048
	ds_read_b128 v[212:215], v196 offset:3072
	v_lshl_add_u64 v[196:197], s[42:43], 0, v[16:17]
	s_mov_b32 m0, s22
	v_lshl_add_u64 v[216:217], s[42:43], 0, v[142:143]
	global_load_lds_dwordx4 v[196:197], off
	s_add_i32 m0, s22, 0x2000
	s_nop 0
	global_load_lds_dwordx4 v[216:217], off
	s_barrier
	s_waitcnt lgkmcnt(0)
	s_setprio 1
	s_waitcnt lgkmcnt(0)
	v_mfma_f32_16x16x32_bf16 v[114:117], v[188:191], v[152:155], v[114:117]
	v_mfma_f32_16x16x32_bf16 v[110:113], v[208:211], v[152:155], v[110:113]
	v_mfma_f32_16x16x32_bf16 v[98:101], v[188:191], v[164:167], v[98:101]
	v_mfma_f32_16x16x32_bf16 v[94:97], v[208:211], v[164:167], v[94:97]
	v_mfma_f32_16x16x32_bf16 v[82:85], v[188:191], v[172:175], v[82:85]
	v_mfma_f32_16x16x32_bf16 v[78:81], v[208:211], v[172:175], v[78:81]
	v_mfma_f32_16x16x32_bf16 v[70:73], v[188:191], v[180:183], v[70:73]
	v_mfma_f32_16x16x32_bf16 v[66:69], v[208:211], v[180:183], v[66:69]
	v_mfma_f32_16x16x32_bf16 v[114:117], v[192:195], v[160:163], v[114:117]
	v_mfma_f32_16x16x32_bf16 v[110:113], v[212:215], v[160:163], v[110:113]
	v_mfma_f32_16x16x32_bf16 v[98:101], v[192:195], v[168:171], v[98:101]
	v_mfma_f32_16x16x32_bf16 v[94:97], v[212:215], v[168:171], v[94:97]
	v_mfma_f32_16x16x32_bf16 v[82:85], v[192:195], v[176:179], v[82:85]
	v_mfma_f32_16x16x32_bf16 v[78:81], v[212:215], v[176:179], v[78:81]
	v_mfma_f32_16x16x32_bf16 v[70:73], v[192:195], v[184:187], v[70:73]
	v_mfma_f32_16x16x32_bf16 v[66:69], v[212:215], v[184:187], v[66:69]
	s_setprio 0
	s_mov_b32 m0, s19
	v_lshl_add_u64 v[218:219], s[48:49], 0, v[16:17]
	s_barrier
	ds_read_b128 v[152:155], v159 offset:16384
	ds_read_b128 v[160:163], v159 offset:17408
	ds_read_b128 v[164:167], v159 offset:18432
	ds_read_b128 v[168:171], v159 offset:19456
	ds_read_b128 v[172:175], v159 offset:20480
	ds_read_b128 v[176:179], v159 offset:21504
	ds_read_b128 v[180:183], v159 offset:22528
	ds_read_b128 v[184:187], v159 offset:23552
	global_load_lds_dwordx4 v[218:219], off
	v_lshl_add_u64 v[220:221], s[48:49], 0, v[142:143]
	s_mov_b32 m0, s54
	s_nop 0
	global_load_lds_dwordx4 v[220:221], off
	s_barrier
	s_waitcnt lgkmcnt(0)
	s_setprio 1
	s_waitcnt lgkmcnt(0)
	v_mfma_f32_16x16x32_bf16 v[62:65], v[130:133], v[152:155], v[62:65]
	v_mfma_f32_16x16x32_bf16 v[58:61], v[138:141], v[152:155], v[58:61]
	v_mfma_f32_16x16x32_bf16 v[54:57], v[130:133], v[164:167], v[54:57]
	v_mfma_f32_16x16x32_bf16 v[50:53], v[138:141], v[164:167], v[50:53]
	v_mfma_f32_16x16x32_bf16 v[46:49], v[130:133], v[172:175], v[46:49]
	v_mfma_f32_16x16x32_bf16 v[38:41], v[138:141], v[172:175], v[38:41]
	v_mfma_f32_16x16x32_bf16 v[30:33], v[130:133], v[180:183], v[30:33]
	v_mfma_f32_16x16x32_bf16 v[18:21], v[138:141], v[180:183], v[18:21]
	v_mfma_f32_16x16x32_bf16 v[62:65], v[134:137], v[160:163], v[62:65]
	v_mfma_f32_16x16x32_bf16 v[58:61], v[148:151], v[160:163], v[58:61]
	v_mfma_f32_16x16x32_bf16 v[54:57], v[134:137], v[168:171], v[54:57]
	v_mfma_f32_16x16x32_bf16 v[50:53], v[148:151], v[168:171], v[50:53]
	v_mfma_f32_16x16x32_bf16 v[46:49], v[134:137], v[176:179], v[46:49]
	v_mfma_f32_16x16x32_bf16 v[38:41], v[148:151], v[176:179], v[38:41]
	v_mfma_f32_16x16x32_bf16 v[30:33], v[134:137], v[184:187], v[30:33]
	v_mfma_f32_16x16x32_bf16 v[18:21], v[148:151], v[184:187], v[18:21]
	s_setprio 0
	s_barrier
	s_add_u32 s22, s42, 0x40000
	s_addc_u32 s23, s43, 0
	s_add_i32 s83, s84, s52
	v_lshl_add_u64 v[130:131], s[22:23], 0, v[16:17]
	s_mov_b32 m0, s83
	s_nop 0
	global_load_lds_dwordx4 v[130:131], off
	v_lshl_add_u64 v[130:131], s[22:23], 0, v[142:143]
	s_add_i32 m0, s83, 0x2000
	s_nop 0
	global_load_lds_dwordx4 v[130:131], off
	s_waitcnt vmcnt(6)
	s_barrier
	s_setprio 1
	v_mfma_f32_16x16x32_bf16 v[42:45], v[188:191], v[152:155], v[42:45]
	v_mfma_f32_16x16x32_bf16 v[34:37], v[208:211], v[152:155], v[34:37]
	v_mfma_f32_16x16x32_bf16 v[26:29], v[188:191], v[164:167], v[26:29]
	v_mfma_f32_16x16x32_bf16 v[22:25], v[208:211], v[164:167], v[22:25]
	v_mfma_f32_16x16x32_bf16 v[12:15], v[188:191], v[172:175], v[12:15]
	v_mfma_f32_16x16x32_bf16 v[8:11], v[208:211], v[172:175], v[8:11]
	v_mfma_f32_16x16x32_bf16 v[4:7], v[188:191], v[180:183], v[4:7]
	v_mfma_f32_16x16x32_bf16 v[0:3], v[208:211], v[180:183], v[0:3]
	v_mfma_f32_16x16x32_bf16 v[42:45], v[192:195], v[160:163], v[42:45]
	v_mfma_f32_16x16x32_bf16 v[34:37], v[212:215], v[160:163], v[34:37]
	v_mfma_f32_16x16x32_bf16 v[26:29], v[192:195], v[168:171], v[26:29]
	v_mfma_f32_16x16x32_bf16 v[22:25], v[212:215], v[168:171], v[22:25]
	v_mfma_f32_16x16x32_bf16 v[12:15], v[192:195], v[176:179], v[12:15]
	v_mfma_f32_16x16x32_bf16 v[8:11], v[212:215], v[176:179], v[8:11]
	v_mfma_f32_16x16x32_bf16 v[4:7], v[192:195], v[184:187], v[4:7]
	v_mfma_f32_16x16x32_bf16 v[0:3], v[212:215], v[184:187], v[0:3]
	s_setprio 0
	s_add_i32 s83, 0, 0x18000
	v_add_u32_e32 v148, s83, v157
	s_barrier
	ds_read_b128 v[130:133], v148
	ds_read_b128 v[134:137], v148 offset:1024
	ds_read_b128 v[138:141], v148 offset:2048
	ds_read_b128 v[148:151], v148 offset:3072
	s_add_u32 s22, s48, 0x40000
	s_addc_u32 s23, s49, 0
	s_mov_b32 m0, s55
	v_lshl_add_u64 v[188:189], s[22:23], 0, v[16:17]
	ds_read_b128 v[152:155], v159 offset:32768
	ds_read_b128 v[160:163], v159 offset:33792
	ds_read_b128 v[164:167], v159 offset:34816
	ds_read_b128 v[168:171], v159 offset:35840
	ds_read_b128 v[172:175], v159 offset:36864
	ds_read_b128 v[176:179], v159 offset:37888
	ds_read_b128 v[180:183], v159 offset:38912
	ds_read_b128 v[184:187], v159 offset:39936
	global_load_lds_dwordx4 v[188:189], off
	v_lshl_add_u64 v[188:189], s[22:23], 0, v[142:143]
	s_mov_b32 m0, s56
	s_nop 0
	global_load_lds_dwordx4 v[188:189], off
	s_waitcnt lgkmcnt(8)
	s_barrier
	s_waitcnt lgkmcnt(0)
	s_setprio 1
	s_waitcnt lgkmcnt(0)
	v_mfma_f32_16x16x32_bf16 v[126:129], v[130:133], v[152:155], v[126:129]
	v_mfma_f32_16x16x32_bf16 v[122:125], v[138:141], v[152:155], v[122:125]
	v_mfma_f32_16x16x32_bf16 v[118:121], v[130:133], v[164:167], v[118:121]
	v_mfma_f32_16x16x32_bf16 v[106:109], v[138:141], v[164:167], v[106:109]
	v_mfma_f32_16x16x32_bf16 v[102:105], v[130:133], v[172:175], v[102:105]
	v_mfma_f32_16x16x32_bf16 v[90:93], v[138:141], v[172:175], v[90:93]
	v_mfma_f32_16x16x32_bf16 v[86:89], v[130:133], v[180:183], v[86:89]
	v_mfma_f32_16x16x32_bf16 v[74:77], v[138:141], v[180:183], v[74:77]
	v_mfma_f32_16x16x32_bf16 v[126:129], v[134:137], v[160:163], v[126:129]
	v_mfma_f32_16x16x32_bf16 v[122:125], v[148:151], v[160:163], v[122:125]
	v_mfma_f32_16x16x32_bf16 v[118:121], v[134:137], v[168:171], v[118:121]
	v_mfma_f32_16x16x32_bf16 v[106:109], v[148:151], v[168:171], v[106:109]
	v_mfma_f32_16x16x32_bf16 v[102:105], v[134:137], v[176:179], v[102:105]
	v_mfma_f32_16x16x32_bf16 v[90:93], v[148:151], v[176:179], v[90:93]
	v_mfma_f32_16x16x32_bf16 v[86:89], v[134:137], v[184:187], v[86:89]
	v_mfma_f32_16x16x32_bf16 v[74:77], v[148:151], v[184:187], v[74:77]
	s_setprio 0
	s_barrier
	s_add_i32 s48, 0, 0x1c000
	s_add_i32 s22, s83, s52
	v_add_u32_e32 v212, s48, v157
	v_lshl_add_u64 v[196:197], v[196:197], 0, s[10:11]
	s_mov_b32 m0, s22
	ds_read_b128 v[188:191], v212
	ds_read_b128 v[192:195], v212 offset:1024
	ds_read_b128 v[208:211], v212 offset:2048
	ds_read_b128 v[212:215], v212 offset:3072
	global_load_lds_dwordx4 v[196:197], off
	v_lshl_add_u64 v[196:197], v[216:217], 0, s[10:11]
	s_add_i32 m0, s22, 0x2000
	s_nop 0
	global_load_lds_dwordx4 v[196:197], off
	s_barrier
	s_waitcnt lgkmcnt(0)
	s_setprio 1
	s_waitcnt lgkmcnt(0)
	v_mfma_f32_16x16x32_bf16 v[114:117], v[188:191], v[152:155], v[114:117]
	v_mfma_f32_16x16x32_bf16 v[110:113], v[208:211], v[152:155], v[110:113]
	v_mfma_f32_16x16x32_bf16 v[98:101], v[188:191], v[164:167], v[98:101]
	v_mfma_f32_16x16x32_bf16 v[94:97], v[208:211], v[164:167], v[94:97]
	v_mfma_f32_16x16x32_bf16 v[82:85], v[188:191], v[172:175], v[82:85]
	v_mfma_f32_16x16x32_bf16 v[78:81], v[208:211], v[172:175], v[78:81]
	v_mfma_f32_16x16x32_bf16 v[70:73], v[188:191], v[180:183], v[70:73]
	v_mfma_f32_16x16x32_bf16 v[66:69], v[208:211], v[180:183], v[66:69]
	v_mfma_f32_16x16x32_bf16 v[114:117], v[192:195], v[160:163], v[114:117]
	v_mfma_f32_16x16x32_bf16 v[110:113], v[212:215], v[160:163], v[110:113]
	v_mfma_f32_16x16x32_bf16 v[98:101], v[192:195], v[168:171], v[98:101]
	v_mfma_f32_16x16x32_bf16 v[94:97], v[212:215], v[168:171], v[94:97]
	v_mfma_f32_16x16x32_bf16 v[82:85], v[192:195], v[176:179], v[82:85]
	v_mfma_f32_16x16x32_bf16 v[78:81], v[212:215], v[176:179], v[78:81]
	v_mfma_f32_16x16x32_bf16 v[70:73], v[192:195], v[184:187], v[70:73]
	v_mfma_f32_16x16x32_bf16 v[66:69], v[212:215], v[184:187], v[66:69]
	s_setprio 0
	s_mov_b32 m0, s57
	v_lshl_add_u64 v[196:197], v[218:219], 0, s[10:11]
	s_barrier
	ds_read_b128 v[152:155], v159 offset:49152
	ds_read_b128 v[160:163], v159 offset:50176
	ds_read_b128 v[164:167], v159 offset:51200
	ds_read_b128 v[168:171], v159 offset:52224
	ds_read_b128 v[172:175], v159 offset:53248
	ds_read_b128 v[176:179], v159 offset:54272
	ds_read_b128 v[180:183], v159 offset:55296
	ds_read_b128 v[184:187], v159 offset:56320
	global_load_lds_dwordx4 v[196:197], off
	v_lshl_add_u64 v[196:197], v[220:221], 0, s[10:11]
	s_mov_b32 m0, s58
	s_nop 0
	global_load_lds_dwordx4 v[196:197], off
	s_barrier
	s_waitcnt lgkmcnt(0)
	s_setprio 1
	s_waitcnt lgkmcnt(0)
	v_mfma_f32_16x16x32_bf16 v[62:65], v[130:133], v[152:155], v[62:65]
	v_mfma_f32_16x16x32_bf16 v[58:61], v[138:141], v[152:155], v[58:61]
	v_mfma_f32_16x16x32_bf16 v[54:57], v[130:133], v[164:167], v[54:57]
	v_mfma_f32_16x16x32_bf16 v[50:53], v[138:141], v[164:167], v[50:53]
	v_mfma_f32_16x16x32_bf16 v[46:49], v[130:133], v[172:175], v[46:49]
	v_mfma_f32_16x16x32_bf16 v[38:41], v[138:141], v[172:175], v[38:41]
	v_mfma_f32_16x16x32_bf16 v[30:33], v[130:133], v[180:183], v[30:33]
	v_mfma_f32_16x16x32_bf16 v[18:21], v[138:141], v[180:183], v[18:21]
	v_mfma_f32_16x16x32_bf16 v[62:65], v[134:137], v[160:163], v[62:65]
	v_mfma_f32_16x16x32_bf16 v[58:61], v[148:151], v[160:163], v[58:61]
	v_mfma_f32_16x16x32_bf16 v[54:57], v[134:137], v[168:171], v[54:57]
	v_mfma_f32_16x16x32_bf16 v[50:53], v[148:151], v[168:171], v[50:53]
	v_mfma_f32_16x16x32_bf16 v[46:49], v[134:137], v[176:179], v[46:49]
	v_mfma_f32_16x16x32_bf16 v[38:41], v[148:151], v[176:179], v[38:41]
	v_mfma_f32_16x16x32_bf16 v[30:33], v[134:137], v[184:187], v[30:33]
	v_mfma_f32_16x16x32_bf16 v[18:21], v[148:151], v[184:187], v[18:21]
	s_setprio 0
	s_barrier
	s_add_u32 s22, s42, 0x40080
	s_addc_u32 s23, s43, 0
	s_add_i32 s42, s48, s52
	v_lshl_add_u64 v[130:131], s[22:23], 0, v[16:17]
	s_mov_b32 m0, s42
	s_nop 0
	global_load_lds_dwordx4 v[130:131], off
	v_lshl_add_u64 v[130:131], s[22:23], 0, v[142:143]
	s_add_i32 m0, s42, 0x2000
	s_nop 0
	global_load_lds_dwordx4 v[130:131], off
	s_waitcnt vmcnt(6)
	s_barrier
	s_setprio 1
	v_mfma_f32_16x16x32_bf16 v[42:45], v[188:191], v[152:155], v[42:45]
	v_mfma_f32_16x16x32_bf16 v[34:37], v[208:211], v[152:155], v[34:37]
	v_mfma_f32_16x16x32_bf16 v[26:29], v[188:191], v[164:167], v[26:29]
	v_mfma_f32_16x16x32_bf16 v[22:25], v[208:211], v[164:167], v[22:25]
	v_mfma_f32_16x16x32_bf16 v[12:15], v[188:191], v[172:175], v[12:15]
	v_mfma_f32_16x16x32_bf16 v[8:11], v[208:211], v[172:175], v[8:11]
	v_mfma_f32_16x16x32_bf16 v[4:7], v[188:191], v[180:183], v[4:7]
	v_mfma_f32_16x16x32_bf16 v[0:3], v[208:211], v[180:183], v[0:3]
	v_mfma_f32_16x16x32_bf16 v[42:45], v[192:195], v[160:163], v[42:45]
	v_mfma_f32_16x16x32_bf16 v[34:37], v[212:215], v[160:163], v[34:37]
	v_mfma_f32_16x16x32_bf16 v[26:29], v[192:195], v[168:171], v[26:29]
	v_mfma_f32_16x16x32_bf16 v[22:25], v[212:215], v[168:171], v[22:25]
	v_mfma_f32_16x16x32_bf16 v[12:15], v[192:195], v[176:179], v[12:15]
	v_mfma_f32_16x16x32_bf16 v[8:11], v[212:215], v[176:179], v[8:11]
	v_mfma_f32_16x16x32_bf16 v[4:7], v[192:195], v[184:187], v[4:7]
	v_mfma_f32_16x16x32_bf16 v[0:3], v[212:215], v[184:187], v[0:3]
	s_setprio 0
	s_add_i32 s82, s82, 2
	s_add_u32 s61, s61, 0x100
	s_addc_u32 s79, s79, 0
	s_cmp_gt_u32 s82, 13
	s_mov_b64 s[22:23], s[40:41]
	s_barrier
	s_cbranch_scc0 .LBB0_174
	v_lshl_or_b32 v132, s2, 8, v158
	v_lshl_add_u32 v130, s18, 8, v156
	v_ashrrev_i32_e32 v133, 31, v132
	v_lshlrev_b64 v[148:149], 2, v[132:133]
	v_ashrrev_i32_e32 v131, 31, v130
	v_lshl_add_u64 v[150:151], s[20:21], 0, v[148:149]
	v_lshlrev_b64 v[152:153], 12, v[130:131]
	v_lshl_add_u64 v[132:133], v[150:151], 0, v[152:153]
	global_load_dwordx4 v[160:163], v[132:133], off
	global_load_dwordx4 v[164:167], v[132:133], off offset:64
	global_load_dwordx4 v[168:171], v[132:133], off offset:512
	global_load_dwordx4 v[172:175], v[132:133], off offset:576
	v_or_b32_e32 v132, 16, v130
	v_ashrrev_i32_e32 v133, 31, v132
	v_lshlrev_b64 v[196:197], 12, v[132:133]
	v_lshl_add_u64 v[132:133], v[150:151], 0, v[196:197]
	global_load_dwordx4 v[176:179], v[132:133], off
	global_load_dwordx4 v[180:183], v[132:133], off offset:64
	global_load_dwordx4 v[184:187], v[132:133], off offset:512
	global_load_dwordx4 v[188:191], v[132:133], off offset:576
	v_or_b32_e32 v132, 32, v130
	v_ashrrev_i32_e32 v133, 31, v132
	v_or_b32_e32 v130, 48, v130
	v_lshlrev_b64 v[224:225], 12, v[132:133]
	v_ashrrev_i32_e32 v131, 31, v130
	v_lshl_add_u64 v[132:133], v[150:151], 0, v[224:225]
	v_lshlrev_b64 v[154:155], 12, v[130:131]
	global_load_dwordx4 v[192:195], v[132:133], off
	global_load_dwordx4 v[208:211], v[132:133], off offset:64
	global_load_dwordx4 v[212:215], v[132:133], off offset:512
	global_load_dwordx4 v[216:219], v[132:133], off offset:576
	v_lshl_add_u64 v[130:131], v[150:151], 0, v[154:155]
	global_load_dwordx4 v[220:223], v[130:131], off
	global_load_dwordx4 v[138:141], v[130:131], off offset:64
	global_load_dwordx4 v[134:137], v[130:131], off offset:512
	s_nop 0
	global_load_dwordx4 v[130:133], v[130:131], off offset:576
	s_waitcnt vmcnt(0) lgkmcnt(0)
	v_pk_add_f32 v[126:127], v[126:127], v[160:161]
	v_lshl_add_u64 v[160:161], s[20:21], 0, v[152:153]
	v_lshl_add_u64 v[160:161], v[160:161], 0, v[148:149]
	v_pk_add_f32 v[116:117], v[116:117], v[170:171]
	v_pk_add_f32 v[114:115], v[114:115], v[168:169]
	global_store_dwordx4 v[160:161], v[114:117], off offset:512
	v_pk_add_f32 v[112:113], v[112:113], v[174:175]
	v_pk_add_f32 v[100:101], v[100:101], v[186:187]
	v_lshl_add_u64 v[114:115], s[20:21], 0, v[196:197]
	v_lshl_add_u64 v[114:115], v[114:115], 0, v[148:149]
	v_pk_add_f32 v[98:99], v[98:99], v[184:185]
	global_store_dwordx4 v[114:115], v[98:101], off offset:512
	v_pk_add_f32 v[110:111], v[110:111], v[172:173]
	v_pk_add_f32 v[96:97], v[96:97], v[190:191]
	v_lshl_add_u64 v[98:99], s[20:21], 0, v[224:225]
	v_lshl_add_u64 v[98:99], v[98:99], 0, v[148:149]
	v_pk_add_f32 v[84:85], v[84:85], v[214:215]
	v_pk_add_f32 v[82:83], v[82:83], v[212:213]
	v_pk_add_f32 v[94:95], v[94:95], v[188:189]
	global_store_dwordx4 v[98:99], v[82:85], off offset:512
	v_pk_add_f32 v[80:81], v[80:81], v[218:219]
	v_pk_add_f32 v[78:79], v[78:79], v[216:217]
	v_lshl_add_u64 v[82:83], s[20:21], 0, v[154:155]
	v_pk_add_f32 v[128:129], v[128:129], v[162:163]
	v_pk_add_f32 v[124:125], v[124:125], v[166:167]
	v_pk_add_f32 v[122:123], v[122:123], v[164:165]
	global_store_dwordx4 v[160:161], v[110:113], off offset:576
	v_pk_add_f32 v[108:109], v[108:109], v[182:183]
	v_pk_add_f32 v[106:107], v[106:107], v[180:181]
	v_pk_add_f32 v[112:113], v[120:121], v[178:179]
	v_pk_add_f32 v[110:111], v[118:119], v[176:177]
	global_store_dwordx4 v[114:115], v[94:97], off offset:576
	v_pk_add_f32 v[92:93], v[92:93], v[210:211]
	v_pk_add_f32 v[90:91], v[90:91], v[208:209]
	v_pk_add_f32 v[96:97], v[104:105], v[194:195]
	v_pk_add_f32 v[94:95], v[102:103], v[192:193]
	global_store_dwordx4 v[98:99], v[78:81], off offset:576
	v_lshl_add_u64 v[82:83], v[82:83], 0, v[148:149]
	v_pk_add_f32 v[76:77], v[76:77], v[140:141]
	v_pk_add_f32 v[80:81], v[88:89], v[222:223]
	v_pk_add_f32 v[78:79], v[86:87], v[220:221]
	v_pk_add_f32 v[74:75], v[74:75], v[138:139]
	v_pk_add_f32 v[72:73], v[72:73], v[136:137]
	v_pk_add_f32 v[70:71], v[70:71], v[134:135]
	v_pk_add_f32 v[68:69], v[68:69], v[132:133]
	v_pk_add_f32 v[66:67], v[66:67], v[130:131]
	global_store_dwordx4 v[160:161], v[126:129], off
	global_store_dwordx4 v[160:161], v[122:125], off offset:64
	global_store_dwordx4 v[114:115], v[110:113], off
	global_store_dwordx4 v[114:115], v[106:109], off offset:64
	global_store_dwordx4 v[98:99], v[94:97], off
	global_store_dwordx4 v[98:99], v[90:93], off offset:64
	global_store_dwordx4 v[82:83], v[78:81], off
	global_store_dwordx4 v[82:83], v[74:77], off offset:64
	global_store_dwordx4 v[82:83], v[70:73], off offset:512
	global_store_dwordx4 v[82:83], v[66:69], off offset:576
	s_mov_b64 s[22:23], 0x80000
	v_lshl_add_u64 v[130:131], v[152:153], 0, s[22:23]
	s_mov_b64 s[22:23], 0x90000
	v_lshl_add_u64 v[132:133], v[152:153], 0, s[22:23]
	s_mov_b64 s[22:23], 0xa0000
	v_lshl_add_u64 v[134:135], v[152:153], 0, s[22:23]
	s_mov_b64 s[22:23], 0xb0000
	v_lshl_add_u64 v[136:137], v[152:153], 0, s[22:23]
	v_lshl_add_u64 v[78:79], v[150:151], 0, v[130:131]
	v_lshl_add_u64 v[94:95], v[150:151], 0, v[132:133]
	v_lshl_add_u64 v[110:111], v[150:151], 0, v[134:135]
	v_lshl_add_u64 v[126:127], v[150:151], 0, v[136:137]
	global_load_dwordx4 v[66:69], v[78:79], off
	global_load_dwordx4 v[70:73], v[78:79], off offset:64
	global_load_dwordx4 v[74:77], v[78:79], off offset:512
	v_lshl_add_u64 v[130:131], s[20:21], 0, v[130:131]
	global_load_dwordx4 v[78:81], v[78:79], off offset:576
	s_nop 0
	global_load_dwordx4 v[82:85], v[94:95], off
	global_load_dwordx4 v[86:89], v[94:95], off offset:64
	global_load_dwordx4 v[90:93], v[94:95], off offset:512
	v_lshl_add_u64 v[132:133], s[20:21], 0, v[132:133]
	global_load_dwordx4 v[94:97], v[94:95], off offset:576
	s_nop 0
	global_load_dwordx4 v[98:101], v[110:111], off
	global_load_dwordx4 v[102:105], v[110:111], off offset:64
	global_load_dwordx4 v[106:109], v[110:111], off offset:512
	v_lshl_add_u64 v[134:135], s[20:21], 0, v[134:135]
	global_load_dwordx4 v[110:113], v[110:111], off offset:576
	s_nop 0
	global_load_dwordx4 v[114:117], v[126:127], off
	global_load_dwordx4 v[118:121], v[126:127], off offset:64
	global_load_dwordx4 v[122:125], v[126:127], off offset:512
	s_nop 0
	global_load_dwordx4 v[126:129], v[126:127], off offset:576
	v_lshl_add_u64 v[136:137], s[20:21], 0, v[136:137]
	v_lshl_add_u64 v[130:131], v[130:131], 0, v[148:149]
	v_lshl_add_u64 v[132:133], v[132:133], 0, v[148:149]
	v_lshl_add_u64 v[134:135], v[134:135], 0, v[148:149]
	v_lshl_add_u64 v[136:137], v[136:137], 0, v[148:149]
	s_waitcnt vmcnt(0) lgkmcnt(0)
	v_pk_add_f32 v[64:65], v[64:65], v[68:69]
	v_pk_add_f32 v[62:63], v[62:63], v[66:67]
	v_pk_add_f32 v[60:61], v[60:61], v[72:73]
	v_pk_add_f32 v[58:59], v[58:59], v[70:71]
	v_pk_add_f32 v[44:45], v[44:45], v[76:77]
	v_pk_add_f32 v[42:43], v[42:43], v[74:75]
	v_pk_add_f32 v[36:37], v[36:37], v[80:81]
	v_pk_add_f32 v[34:35], v[34:35], v[78:79]
	v_pk_add_f32 v[56:57], v[56:57], v[84:85]
	v_pk_add_f32 v[54:55], v[54:55], v[82:83]
	v_pk_add_f32 v[52:53], v[52:53], v[88:89]
	v_pk_add_f32 v[50:51], v[50:51], v[86:87]
	v_pk_add_f32 v[28:29], v[28:29], v[92:93]
	v_pk_add_f32 v[26:27], v[26:27], v[90:91]
	v_pk_add_f32 v[24:25], v[24:25], v[96:97]
	v_pk_add_f32 v[22:23], v[22:23], v[94:95]
	v_pk_add_f32 v[48:49], v[48:49], v[100:101]
	v_pk_add_f32 v[46:47], v[46:47], v[98:99]
	v_pk_add_f32 v[40:41], v[40:41], v[104:105]
	v_pk_add_f32 v[38:39], v[38:39], v[102:103]
	v_pk_add_f32 v[14:15], v[14:15], v[108:109]
	v_pk_add_f32 v[12:13], v[12:13], v[106:107]
	v_pk_add_f32 v[10:11], v[10:11], v[112:113]
	v_pk_add_f32 v[8:9], v[8:9], v[110:111]
	v_pk_add_f32 v[32:33], v[32:33], v[116:117]
	v_pk_add_f32 v[30:31], v[30:31], v[114:115]
	v_pk_add_f32 v[20:21], v[20:21], v[120:121]
	v_pk_add_f32 v[18:19], v[18:19], v[118:119]
	v_pk_add_f32 v[6:7], v[6:7], v[124:125]
	v_pk_add_f32 v[4:5], v[4:5], v[122:123]
	v_pk_add_f32 v[2:3], v[2:3], v[128:129]
	v_pk_add_f32 v[0:1], v[0:1], v[126:127]
	global_store_dwordx4 v[130:131], v[62:65], off
	global_store_dwordx4 v[130:131], v[58:61], off offset:64
	global_store_dwordx4 v[130:131], v[42:45], off offset:512
	global_store_dwordx4 v[130:131], v[34:37], off offset:576
	global_store_dwordx4 v[132:133], v[54:57], off
	global_store_dwordx4 v[132:133], v[50:53], off offset:64
	global_store_dwordx4 v[132:133], v[26:29], off offset:512
	global_store_dwordx4 v[132:133], v[22:25], off offset:576
	global_store_dwordx4 v[134:135], v[46:49], off
	global_store_dwordx4 v[134:135], v[38:41], off offset:64
	global_store_dwordx4 v[134:135], v[12:15], off offset:512
	global_store_dwordx4 v[134:135], v[8:11], off offset:576
	global_store_dwordx4 v[136:137], v[30:33], off
	global_store_dwordx4 v[136:137], v[18:21], off offset:64
	global_store_dwordx4 v[136:137], v[4:7], off offset:512
	global_store_dwordx4 v[136:137], v[0:3], off offset:576
	v_readlane_b32 s82, v255, 5
	s_and_b64 vcc, exec, s[38:39]
	s_mov_b32 s2, s4
	s_mov_b32 s18, s8
	s_mov_b64 s[40:41], s[16:17]
	s_mov_b64 s[22:23], s[14:15]
	v_readlane_b32 s83, v255, 6
	s_cbranch_vccz .LBB0_167
	s_waitcnt vmcnt(0)
	s_cmpk_gt_u32 s35, 0xff
	s_cbranch_scc1 .LBB0_178
	s_barrier

.LBB0_183:
	v_ashrrev_i32_e32 v83, 31, v82
	v_lshlrev_b64 v[18:19], 12, v[82:83]
	v_lshl_add_u64 v[18:19], v[84:85], 0, v[18:19]
	global_load_dwordx4 v[78:81], v[18:19], off
	global_load_dwordx4 v[74:77], v[18:19], off offset:1024
	global_load_dwordx4 v[70:73], v[18:19], off offset:2048
	global_load_dwordx4 v[66:69], v[18:19], off offset:3072
	v_or_b32_e32 v92, 1, v82
	v_min_i32_e32 v18, 0x3fff, v92
	v_ashrrev_i32_e32 v19, 31, v18
	v_lshlrev_b64 v[18:19], 12, v[18:19]
	v_lshl_add_u64 v[18:19], v[84:85], 0, v[18:19]
	global_load_dwordx4 v[62:65], v[18:19], off
	global_load_dwordx4 v[58:61], v[18:19], off offset:1024
	global_load_dwordx4 v[54:57], v[18:19], off offset:2048
	global_load_dwordx4 v[50:53], v[18:19], off offset:3072
	v_or_b32_e32 v90, 2, v82
	v_min_i32_e32 v18, 0x3fff, v90
	v_ashrrev_i32_e32 v19, 31, v18
	v_lshlrev_b64 v[18:19], 12, v[18:19]
	v_lshl_add_u64 v[18:19], v[84:85], 0, v[18:19]
	v_or_b32_e32 v88, 3, v82
	global_load_dwordx4 v[46:49], v[18:19], off
	global_load_dwordx4 v[42:45], v[18:19], off offset:1024
	global_load_dwordx4 v[38:41], v[18:19], off offset:2048
	s_waitcnt lgkmcnt(0)
	global_load_dwordx4 v[34:37], v[18:19], off offset:3072
	v_min_i32_e32 v18, 0x3fff, v88
	v_ashrrev_i32_e32 v19, 31, v18
	v_lshlrev_b64 v[18:19], 12, v[18:19]
	v_lshl_add_u64 v[18:19], v[84:85], 0, v[18:19]
	global_load_dwordx4 v[30:33], v[18:19], off
	global_load_dwordx4 v[26:29], v[18:19], off offset:1024
	global_load_dwordx4 v[22:25], v[18:19], off offset:2048
	s_nop 0
	global_load_dwordx4 v[18:21], v[18:19], off offset:3072
	s_waitcnt vmcnt(0) lgkmcnt(0)
	v_pk_mul_f32 v[100:101], v[80:81], v[80:81]
	v_pk_mul_f32 v[102:103], v[78:79], v[78:79]
	v_mul_f32_e32 v16, v66, v66
	v_pk_mov_b32 v[104:105], v[102:103], v[100:101] op_sel:[1,0]
	v_mov_b32_e32 v103, v101
	v_pk_add_f32 v[100:101], v[104:105], v[102:103]
	v_pk_mul_f32 v[102:103], v[76:77], v[76:77]
	v_pk_mul_f32 v[104:105], v[74:75], v[74:75]
	v_mul_f32_e32 v89, v67, v67
	v_pk_mov_b32 v[106:107], v[104:105], v[102:103] op_sel:[1,0]
	v_mov_b32_e32 v105, v103
	v_pk_add_f32 v[102:103], v[106:107], v[104:105]
	v_pk_add_f32 v[100:101], v[100:101], v[100:101] op_sel:[0,1] op_sel_hi:[1,0]
	v_pk_add_f32 v[102:103], v[102:103], v[102:103] op_sel:[0,1] op_sel_hi:[1,0]
	v_mov_b32_e32 v101, v16
	v_mov_b32_e32 v103, v89
	v_mul_f32_e32 v16, v71, v71
	v_pk_add_f32 v[100:101], v[100:101], v[102:103]
	v_pk_fma_f32 v[102:103], v[70:71], v[70:71], v[16:17] op_sel_hi:[1,1,0]
	v_mul_f32_e32 v16, v73, v73
	v_mul_f32_e32 v91, v68, v68
	v_mul_f32_e32 v93, v69, v69
	v_pk_fma_f32 v[104:105], v[72:73], v[72:73], v[16:17] op_sel_hi:[1,1,0]
	v_mov_b32_e32 v103, v91
	v_mov_b32_e32 v105, v93
	v_pk_add_f32 v[102:103], v[102:103], v[104:105]
	s_nop 0
	v_pk_add_f32 v[100:101], v[100:101], v[102:103]
	s_nop 0
	v_add_f32_e32 v16, v100, v101
	ds_bpermute_b32 v89, v94, v16
	v_lshlrev_b64 v[100:101], 11, v[82:83]
	v_lshl_add_u64 v[100:101], v[86:87], 0, v[100:101]
	s_waitcnt lgkmcnt(0)
	v_add_f32_e32 v16, v16, v89
	ds_bpermute_b32 v89, v95, v16
	s_waitcnt lgkmcnt(0)
	v_add_f32_e32 v16, v16, v89
	ds_bpermute_b32 v89, v96, v16
	s_waitcnt lgkmcnt(0)
	v_add_f32_e32 v16, v16, v89
	ds_bpermute_b32 v89, v97, v16
	s_waitcnt lgkmcnt(0)
	v_add_f32_e32 v16, v16, v89
	ds_bpermute_b32 v89, v98, v16
	s_waitcnt lgkmcnt(0)
	v_add_f32_e32 v16, v16, v89
	ds_bpermute_b32 v89, v99, v16
	s_waitcnt lgkmcnt(0)
	v_add_f32_e32 v16, v16, v89
	v_fmamk_f32 v16, v16, 0x3a800000, v231
	v_cmp_gt_f32_e32 vcc, s33, v16
	v_mul_f32_e32 v83, 0x4b800000, v16
	s_nop 0
	v_cndmask_b32_e32 v16, v16, v83, vcc
	v_rsq_f32_e32 v16, v16
	s_nop 0
	v_mul_f32_e32 v83, 0x45800000, v16
	v_cndmask_b32_e32 v16, v16, v83, vcc
	v_mul_f32_e32 v78, v78, v16
	v_mul_f32_e32 v79, v79, v16
	v_mul_f32_e32 v74, v74, v16
	v_mul_f32_e32 v75, v75, v16
	v_mul_f32_e32 v70, v70, v16
	v_mul_f32_e32 v71, v71, v16
	v_mul_f32_e32 v66, v66, v16
	v_mul_f32_e32 v67, v67, v16
	v_mul_f32_e32 v78, v0, v78
	v_mul_f32_e32 v79, v1, v79
	v_mul_f32_e32 v74, v4, v74
	v_mul_f32_e32 v75, v5, v75
	v_mul_f32_e32 v70, v8, v70
	v_mul_f32_e32 v71, v9, v71
	v_mul_f32_e32 v66, v12, v66
	v_mul_f32_e32 v67, v13, v67
	v_cvt_pk_bf16_f32 v78, v78, v79
	v_mul_f32_e32 v79, v80, v16
	v_mul_f32_e32 v80, v81, v16
	v_cvt_pk_bf16_f32 v74, v74, v75
	v_mul_f32_e32 v75, v76, v16
	v_mul_f32_e32 v76, v77, v16
	v_cvt_pk_bf16_f32 v70, v70, v71
	v_mul_f32_e32 v71, v72, v16
	v_mul_f32_e32 v72, v73, v16
	v_cvt_pk_bf16_f32 v66, v66, v67
	v_mul_f32_e32 v67, v68, v16
	v_mul_f32_e32 v16, v69, v16
	v_mul_f32_e32 v67, v14, v67
	v_mul_f32_e32 v16, v15, v16
	v_cvt_pk_bf16_f32 v67, v67, v16
	global_store_dwordx2 v[100:101], v[66:67], off offset:1536
	v_mul_f32_e32 v16, v63, v63
	v_mul_f32_e32 v66, v65, v65
	v_fmac_f32_e32 v16, v62, v62
	v_fmac_f32_e32 v66, v64, v64
	v_add_f32_e32 v16, v16, v66
	v_mul_f32_e32 v66, v59, v59
	v_mul_f32_e32 v67, v61, v61
	v_fmac_f32_e32 v66, v58, v58
	v_fmac_f32_e32 v67, v60, v60
	v_add_f32_e32 v66, v66, v67
	v_add_f32_e32 v16, v16, v66
	v_mul_f32_e32 v66, v55, v55
	v_mul_f32_e32 v67, v57, v57
	v_fmac_f32_e32 v66, v54, v54
	v_fmac_f32_e32 v67, v56, v56
	v_add_f32_e32 v66, v66, v67
	v_add_f32_e32 v16, v16, v66
	v_mul_f32_e32 v66, v51, v51
	v_mul_f32_e32 v67, v53, v53
	v_fmac_f32_e32 v66, v50, v50
	v_fmac_f32_e32 v67, v52, v52
	v_add_f32_e32 v66, v66, v67
	v_add_f32_e32 v16, v16, v66
	ds_bpermute_b32 v66, v94, v16
	v_mul_f32_e32 v79, v2, v79
	v_mul_f32_e32 v75, v6, v75
	v_mul_f32_e32 v71, v10, v71
	v_cmp_gt_i32_e32 vcc, s62, v92
	s_waitcnt lgkmcnt(0)
	v_add_f32_e32 v16, v16, v66
	ds_bpermute_b32 v66, v95, v16
	v_mul_f32_e32 v80, v3, v80
	v_cvt_pk_bf16_f32 v79, v79, v80
	global_store_dwordx2 v[100:101], v[78:79], off
	v_mul_f32_e32 v76, v7, v76
	s_waitcnt lgkmcnt(0)
	v_add_f32_e32 v16, v16, v66
	ds_bpermute_b32 v66, v96, v16
	v_cvt_pk_bf16_f32 v75, v75, v76
	global_store_dwordx2 v[100:101], v[74:75], off offset:512
	v_mul_f32_e32 v72, v11, v72
	v_cvt_pk_bf16_f32 v71, v71, v72
	s_waitcnt lgkmcnt(0)
	v_add_f32_e32 v16, v16, v66
	ds_bpermute_b32 v66, v97, v16
	global_store_dwordx2 v[100:101], v[70:71], off offset:1024
	s_waitcnt lgkmcnt(0)
	v_add_f32_e32 v16, v16, v66
	ds_bpermute_b32 v66, v98, v16
	s_waitcnt lgkmcnt(0)
	v_add_f32_e32 v16, v16, v66
	ds_bpermute_b32 v66, v99, v16
	s_and_saveexec_b64 s[14:15], vcc
	s_cbranch_execz .LBB0_185
	s_waitcnt lgkmcnt(0)
	v_add_f32_e32 v16, v16, v66
	v_fmamk_f32 v16, v16, 0x3a800000, v231
	v_mul_f32_e32 v66, 0x4b800000, v16
	v_cmp_gt_f32_e32 vcc, s33, v16
	v_ashrrev_i32_e32 v93, 31, v92
	s_nop 0
	v_cndmask_b32_e32 v16, v16, v66, vcc
	v_rsq_f32_e32 v16, v16
	v_lshlrev_b64 v[66:67], 11, v[92:93]
	v_lshl_add_u64 v[66:67], v[86:87], 0, v[66:67]
	v_mul_f32_e32 v68, 0x45800000, v16
	v_cndmask_b32_e32 v16, v16, v68, vcc
	v_mul_f32_e32 v62, v62, v16
	v_mul_f32_e32 v63, v63, v16
	v_mul_f32_e32 v58, v58, v16
	v_mul_f32_e32 v59, v59, v16
	v_mul_f32_e32 v54, v54, v16
	v_mul_f32_e32 v55, v55, v16
	v_mul_f32_e32 v50, v50, v16
	v_mul_f32_e32 v51, v51, v16
	v_mul_f32_e32 v62, v0, v62
	v_mul_f32_e32 v63, v1, v63
	v_mul_f32_e32 v58, v4, v58
	v_mul_f32_e32 v59, v5, v59
	v_mul_f32_e32 v54, v8, v54
	v_mul_f32_e32 v55, v9, v55
	v_mul_f32_e32 v50, v12, v50
	v_mul_f32_e32 v51, v13, v51
	v_cvt_pk_bf16_f32 v62, v62, v63
	v_mul_f32_e32 v63, v64, v16
	v_cvt_pk_bf16_f32 v58, v58, v59
	v_mul_f32_e32 v59, v60, v16
	v_cvt_pk_bf16_f32 v54, v54, v55
	v_mul_f32_e32 v55, v56, v16
	v_cvt_pk_bf16_f32 v50, v50, v51
	v_mul_f32_e32 v51, v52, v16
	v_mul_f32_e32 v63, v2, v63
	v_mul_f32_e32 v64, v65, v16
	v_mul_f32_e32 v59, v6, v59
	v_mul_f32_e32 v60, v61, v16
	v_mul_f32_e32 v55, v10, v55
	v_mul_f32_e32 v56, v57, v16
	v_mul_f32_e32 v51, v14, v51
	v_mul_f32_e32 v16, v53, v16
	v_mul_f32_e32 v64, v3, v64
	v_cvt_pk_bf16_f32 v63, v63, v64
	global_store_dwordx2 v[66:67], v[62:63], off
	v_mul_f32_e32 v60, v7, v60
	v_cvt_pk_bf16_f32 v59, v59, v60
	global_store_dwordx2 v[66:67], v[58:59], off offset:512
	v_mul_f32_e32 v56, v11, v56
	v_cvt_pk_bf16_f32 v55, v55, v56
	global_store_dwordx2 v[66:67], v[54:55], off offset:1024
	v_mul_f32_e32 v16, v15, v16
	v_cvt_pk_bf16_f32 v51, v51, v16
	global_store_dwordx2 v[66:67], v[50:51], off offset:1536
.LBB0_185:
	s_or_b64 exec, exec, s[14:15]
	v_mul_f32_e32 v16, v47, v47
	v_mul_f32_e32 v50, v49, v49
	v_fmac_f32_e32 v16, v46, v46
	v_fmac_f32_e32 v50, v48, v48
	v_add_f32_e32 v16, v16, v50
	v_mul_f32_e32 v50, v43, v43
	v_mul_f32_e32 v51, v45, v45
	v_fmac_f32_e32 v50, v42, v42
	v_fmac_f32_e32 v51, v44, v44
	v_add_f32_e32 v50, v50, v51
	v_add_f32_e32 v16, v16, v50
	v_mul_f32_e32 v50, v39, v39
	v_mul_f32_e32 v51, v41, v41
	v_fmac_f32_e32 v50, v38, v38
	v_fmac_f32_e32 v51, v40, v40
	v_add_f32_e32 v50, v50, v51
	v_add_f32_e32 v16, v16, v50
	v_mul_f32_e32 v50, v35, v35
	v_mul_f32_e32 v51, v37, v37
	v_fmac_f32_e32 v50, v34, v34
	v_fmac_f32_e32 v51, v36, v36
	v_add_f32_e32 v50, v50, v51
	v_add_f32_e32 v16, v16, v50
	ds_bpermute_b32 v50, v94, v16
	v_cmp_gt_i32_e32 vcc, s62, v90
	s_waitcnt lgkmcnt(0)
	v_add_f32_e32 v16, v16, v50
	ds_bpermute_b32 v50, v95, v16
	s_waitcnt lgkmcnt(0)
	v_add_f32_e32 v16, v16, v50
	ds_bpermute_b32 v50, v96, v16
	s_waitcnt lgkmcnt(0)
	v_add_f32_e32 v16, v16, v50
	ds_bpermute_b32 v50, v97, v16
	s_waitcnt lgkmcnt(0)
	v_add_f32_e32 v16, v16, v50
	ds_bpermute_b32 v50, v98, v16
	s_waitcnt lgkmcnt(0)
	v_add_f32_e32 v16, v16, v50
	ds_bpermute_b32 v50, v99, v16
	s_and_saveexec_b64 s[14:15], vcc
	s_cbranch_execz .LBB0_187
	s_waitcnt lgkmcnt(0)
	v_add_f32_e32 v16, v16, v50
	v_fmamk_f32 v16, v16, 0x3a800000, v231
	v_mul_f32_e32 v50, 0x4b800000, v16
	v_cmp_gt_f32_e32 vcc, s33, v16
	v_ashrrev_i32_e32 v91, 31, v90
	s_nop 0
	v_cndmask_b32_e32 v16, v16, v50, vcc
	v_rsq_f32_e32 v16, v16
	v_lshlrev_b64 v[50:51], 11, v[90:91]
	v_lshl_add_u64 v[50:51], v[86:87], 0, v[50:51]
	v_mul_f32_e32 v52, 0x45800000, v16
	v_cndmask_b32_e32 v16, v16, v52, vcc
	v_mul_f32_e32 v46, v46, v16
	v_mul_f32_e32 v47, v47, v16
	v_mul_f32_e32 v42, v42, v16
	v_mul_f32_e32 v43, v43, v16
	v_mul_f32_e32 v38, v38, v16
	v_mul_f32_e32 v39, v39, v16
	v_mul_f32_e32 v34, v34, v16
	v_mul_f32_e32 v35, v35, v16
	v_mul_f32_e32 v46, v0, v46
	v_mul_f32_e32 v47, v1, v47
	v_mul_f32_e32 v42, v4, v42
	v_mul_f32_e32 v43, v5, v43
	v_mul_f32_e32 v38, v8, v38
	v_mul_f32_e32 v39, v9, v39
	v_mul_f32_e32 v34, v12, v34
	v_mul_f32_e32 v35, v13, v35
	v_cvt_pk_bf16_f32 v46, v46, v47
	v_mul_f32_e32 v47, v48, v16
	v_cvt_pk_bf16_f32 v42, v42, v43
	v_mul_f32_e32 v43, v44, v16
	v_cvt_pk_bf16_f32 v38, v38, v39
	v_mul_f32_e32 v39, v40, v16
	v_cvt_pk_bf16_f32 v34, v34, v35
	v_mul_f32_e32 v35, v36, v16
	v_mul_f32_e32 v47, v2, v47
	v_mul_f32_e32 v48, v49, v16
	v_mul_f32_e32 v43, v6, v43
	v_mul_f32_e32 v44, v45, v16
	v_mul_f32_e32 v39, v10, v39
	v_mul_f32_e32 v40, v41, v16
	v_mul_f32_e32 v35, v14, v35
	v_mul_f32_e32 v16, v37, v16
	v_mul_f32_e32 v48, v3, v48
	v_cvt_pk_bf16_f32 v47, v47, v48
	global_store_dwordx2 v[50:51], v[46:47], off
	v_mul_f32_e32 v44, v7, v44
	v_cvt_pk_bf16_f32 v43, v43, v44
	global_store_dwordx2 v[50:51], v[42:43], off offset:512
	v_mul_f32_e32 v40, v11, v40
	v_cvt_pk_bf16_f32 v39, v39, v40
	global_store_dwordx2 v[50:51], v[38:39], off offset:1024
	v_mul_f32_e32 v16, v15, v16
	v_cvt_pk_bf16_f32 v35, v35, v16
	global_store_dwordx2 v[50:51], v[34:35], off offset:1536
.LBB0_187:
	s_or_b64 exec, exec, s[14:15]
	v_mul_f32_e32 v16, v31, v31
	v_mul_f32_e32 v34, v33, v33
	v_fmac_f32_e32 v16, v30, v30
	v_fmac_f32_e32 v34, v32, v32
	v_add_f32_e32 v16, v16, v34
	v_mul_f32_e32 v34, v27, v27
	v_mul_f32_e32 v35, v29, v29
	v_fmac_f32_e32 v34, v26, v26
	v_fmac_f32_e32 v35, v28, v28
	v_add_f32_e32 v34, v34, v35
	v_add_f32_e32 v16, v16, v34
	v_mul_f32_e32 v34, v23, v23
	v_mul_f32_e32 v35, v25, v25
	v_fmac_f32_e32 v34, v22, v22
	v_fmac_f32_e32 v35, v24, v24
	v_add_f32_e32 v34, v34, v35
	v_add_f32_e32 v16, v16, v34
	v_mul_f32_e32 v34, v19, v19
	v_mul_f32_e32 v35, v21, v21
	v_fmac_f32_e32 v34, v18, v18
	v_fmac_f32_e32 v35, v20, v20
	v_add_f32_e32 v34, v34, v35
	v_add_f32_e32 v16, v16, v34
	ds_bpermute_b32 v34, v94, v16
	v_cmp_gt_i32_e32 vcc, s62, v88
	s_waitcnt lgkmcnt(0)
	v_add_f32_e32 v16, v16, v34
	ds_bpermute_b32 v34, v95, v16
	s_waitcnt lgkmcnt(0)
	v_add_f32_e32 v16, v16, v34
	ds_bpermute_b32 v34, v96, v16
	s_waitcnt lgkmcnt(0)
	v_add_f32_e32 v16, v16, v34
	ds_bpermute_b32 v34, v97, v16
	s_waitcnt lgkmcnt(0)
	v_add_f32_e32 v16, v16, v34
	ds_bpermute_b32 v34, v98, v16
	s_waitcnt lgkmcnt(0)
	v_add_f32_e32 v16, v16, v34
	ds_bpermute_b32 v34, v99, v16
	s_and_saveexec_b64 s[14:15], vcc
	s_cbranch_execz .LBB0_182
	s_waitcnt lgkmcnt(0)
	v_add_f32_e32 v16, v16, v34
	v_fmamk_f32 v16, v16, 0x3a800000, v231
	v_mul_f32_e32 v34, 0x4b800000, v16
	v_cmp_gt_f32_e32 vcc, s33, v16
	v_ashrrev_i32_e32 v89, 31, v88
	s_nop 0
	v_cndmask_b32_e32 v16, v16, v34, vcc
	v_rsq_f32_e32 v16, v16
	v_lshlrev_b64 v[34:35], 11, v[88:89]
	v_lshl_add_u64 v[34:35], v[86:87], 0, v[34:35]
	v_mul_f32_e32 v36, 0x45800000, v16
	v_cndmask_b32_e32 v16, v16, v36, vcc
	v_mul_f32_e32 v30, v30, v16
	v_mul_f32_e32 v31, v31, v16
	v_mul_f32_e32 v26, v26, v16
	v_mul_f32_e32 v27, v27, v16
	v_mul_f32_e32 v22, v22, v16
	v_mul_f32_e32 v23, v23, v16
	v_mul_f32_e32 v18, v18, v16
	v_mul_f32_e32 v19, v19, v16
	v_mul_f32_e32 v30, v0, v30
	v_mul_f32_e32 v31, v1, v31
	v_mul_f32_e32 v26, v4, v26
	v_mul_f32_e32 v27, v5, v27
	v_mul_f32_e32 v22, v8, v22
	v_mul_f32_e32 v23, v9, v23
	v_mul_f32_e32 v18, v12, v18
	v_mul_f32_e32 v19, v13, v19
	v_cvt_pk_bf16_f32 v30, v30, v31
	v_mul_f32_e32 v31, v32, v16
	v_cvt_pk_bf16_f32 v26, v26, v27
	v_mul_f32_e32 v27, v28, v16
	v_cvt_pk_bf16_f32 v22, v22, v23
	v_mul_f32_e32 v23, v24, v16
	v_cvt_pk_bf16_f32 v18, v18, v19
	v_mul_f32_e32 v19, v20, v16
	v_mul_f32_e32 v31, v2, v31
	v_mul_f32_e32 v32, v33, v16
	v_mul_f32_e32 v27, v6, v27
	v_mul_f32_e32 v28, v29, v16
	v_mul_f32_e32 v23, v10, v23
	v_mul_f32_e32 v24, v25, v16
	v_mul_f32_e32 v19, v14, v19
	v_mul_f32_e32 v16, v21, v16
	v_mul_f32_e32 v32, v3, v32
	v_cvt_pk_bf16_f32 v31, v31, v32
	global_store_dwordx2 v[34:35], v[30:31], off
	v_mul_f32_e32 v28, v7, v28
	v_cvt_pk_bf16_f32 v27, v27, v28
	global_store_dwordx2 v[34:35], v[26:27], off offset:512
	v_mul_f32_e32 v24, v11, v24
	v_cvt_pk_bf16_f32 v23, v23, v24
	global_store_dwordx2 v[34:35], v[22:23], off offset:1024
	v_mul_f32_e32 v16, v15, v16
	v_cvt_pk_bf16_f32 v19, v19, v16
	global_store_dwordx2 v[34:35], v[18:19], off offset:1536
	s_branch .LBB0_182

.LBB0_234:
	v_lshlrev_b64 v[194:195], 11, v[220:221]
	v_pk_mul_f32 v[142:143], v[142:143], v[0:1]
	v_lshl_add_u64 v[0:1], s[96:97], 0, v[194:195]
	v_pk_mul_f32 v[144:145], v[144:145], v[2:3]
	v_pk_mul_f32 v[138:139], v[138:139], v[4:5]
	v_pk_mul_f32 v[140:141], v[140:141], v[6:7]
	s_andn2_b64 vcc, exec, s[18:19]
	v_lshl_add_u64 v[0:1], v[218:219], 1, v[0:1]
	s_cbranch_vccnz .LBB0_236
	v_cvt_pk_bf16_f32 v2, v142, v143
	v_cvt_pk_bf16_f32 v3, v144, v145
	v_cvt_pk_bf16_f32 v4, v138, v139
	v_cvt_pk_bf16_f32 v5, v140, v141
	global_store_dwordx4 v[0:1], v[2:5], off
	s_nop 1
	v_mul_f32_e32 v2, 0xbfb8aa3b, v248
	v_exp_f32_e32 v2, v2
	s_nop 0
	v_add_f32_e32 v2, 1.0, v2
	v_rcp_f32_e32 v8, v2
	v_mul_f32_e32 v2, 0xbfb8aa3b, v247
	v_exp_f32_e32 v2, v2
	s_nop 0
	v_add_f32_e32 v2, 1.0, v2
	v_rcp_f32_e32 v9, v2
	v_mul_f32_e32 v2, 0xbfb8aa3b, v246
	v_exp_f32_e32 v2, v2
	s_nop 0
	v_add_f32_e32 v2, 1.0, v2
	v_rcp_f32_e32 v10, v2
	v_mul_f32_e32 v2, 0xbfb8aa3b, v245
	v_exp_f32_e32 v2, v2
	s_nop 0
	v_add_f32_e32 v2, 1.0, v2
	v_rcp_f32_e32 v11, v2
	v_mul_f32_e32 v2, 0xbfb8aa3b, v244
	v_exp_f32_e32 v2, v2
	s_nop 0
	v_add_f32_e32 v2, 1.0, v2
	v_rcp_f32_e32 v12, v2
	v_mul_f32_e32 v2, 0xbfb8aa3b, v227
	v_exp_f32_e32 v2, v2
	s_nop 0
	v_add_f32_e32 v2, 1.0, v2
	v_rcp_f32_e32 v13, v2
	v_mul_f32_e32 v2, 0xbfb8aa3b, v225
	v_exp_f32_e32 v2, v2
	s_nop 0
	v_add_f32_e32 v2, 1.0, v2
	v_rcp_f32_e32 v14, v2
	v_mul_f32_e32 v2, 0xbfb8aa3b, v223
	v_exp_f32_e32 v2, v2
	s_nop 0
	v_add_f32_e32 v2, 1.0, v2
	v_rcp_f32_e32 v15, v2
.LBB0_236:
	v_cndmask_b32_e64 v2, 0, 1, s[16:17]
	v_pk_mul_f32 v[110:111], v[110:111], v[8:9]
	v_pk_mul_f32 v[112:113], v[112:113], v[10:11]
	v_pk_mul_f32 v[106:107], v[106:107], v[12:13]
	v_cmp_ne_u32_e64 s[42:43], 1, v2
	s_andn2_b64 vcc, exec, s[16:17]
	v_pk_mul_f32 v[108:109], v[108:109], v[14:15]
	s_cbranch_vccnz .LBB0_238
	v_cvt_pk_bf16_f32 v2, v110, v111
	v_cvt_pk_bf16_f32 v3, v112, v113
	v_cvt_pk_bf16_f32 v4, v106, v107
	v_cvt_pk_bf16_f32 v5, v108, v109
	global_store_dwordx4 v[0:1], v[2:5], off offset:256

.LBB0_244:
	v_ashrrev_i32_e32 v227, 31, v226
	v_lshlrev_b64 v[178:179], 11, v[226:227]
	v_pk_mul_f32 v[134:135], v[134:135], v[0:1]
	v_lshl_add_u64 v[0:1], s[96:97], 0, v[178:179]
	v_pk_mul_f32 v[136:137], v[136:137], v[2:3]
	v_pk_mul_f32 v[130:131], v[130:131], v[4:5]
	v_pk_mul_f32 v[132:133], v[132:133], v[6:7]
	s_andn2_b64 vcc, exec, s[16:17]
	v_lshl_add_u64 v[0:1], v[218:219], 1, v[0:1]
	s_cbranch_vccnz .LBB0_246
	v_cvt_pk_bf16_f32 v2, v134, v135
	v_cvt_pk_bf16_f32 v3, v136, v137
	v_cvt_pk_bf16_f32 v4, v130, v131
	v_cvt_pk_bf16_f32 v5, v132, v133
	global_store_dwordx4 v[0:1], v[2:5], off
	s_nop 1
	v_mul_f32_e32 v2, 0xbfb8aa3b, v190
	v_exp_f32_e32 v2, v2
	s_nop 0
	v_add_f32_e32 v2, 1.0, v2
	v_rcp_f32_e32 v8, v2
	v_mul_f32_e32 v2, 0xbfb8aa3b, v189
	v_exp_f32_e32 v2, v2
	s_nop 0
	v_add_f32_e32 v2, 1.0, v2
	v_rcp_f32_e32 v9, v2
	v_mul_f32_e32 v2, 0xbfb8aa3b, v188
	v_exp_f32_e32 v2, v2
	s_nop 0
	v_add_f32_e32 v2, 1.0, v2
	v_rcp_f32_e32 v10, v2
	v_mul_f32_e32 v2, 0xbfb8aa3b, v187
	v_exp_f32_e32 v2, v2
	s_nop 0
	v_add_f32_e32 v2, 1.0, v2
	v_rcp_f32_e32 v11, v2
	v_mul_f32_e32 v2, 0xbfb8aa3b, v186
	v_exp_f32_e32 v2, v2
	s_nop 0
	v_add_f32_e32 v2, 1.0, v2
	v_rcp_f32_e32 v12, v2
	v_mul_f32_e32 v2, 0xbfb8aa3b, v184
	v_exp_f32_e32 v2, v2
	s_nop 0
	v_add_f32_e32 v2, 1.0, v2
	v_rcp_f32_e32 v13, v2
	v_mul_f32_e32 v2, 0xbfb8aa3b, v183
	v_exp_f32_e32 v2, v2
	s_nop 0
	v_add_f32_e32 v2, 1.0, v2
	v_rcp_f32_e32 v14, v2
	v_mul_f32_e32 v2, 0xbfb8aa3b, v182
	v_exp_f32_e32 v2, v2
	s_nop 0
	v_add_f32_e32 v2, 1.0, v2
	v_rcp_f32_e32 v15, v2
.LBB0_246:
	v_pk_mul_f32 v[102:103], v[102:103], v[8:9]
	v_pk_mul_f32 v[104:105], v[104:105], v[10:11]
	v_pk_mul_f32 v[98:99], v[98:99], v[12:13]
	s_and_b64 vcc, exec, s[42:43]
	v_pk_mul_f32 v[100:101], v[100:101], v[14:15]
	s_cbranch_vccnz .LBB0_248
	v_cvt_pk_bf16_f32 v2, v102, v103
	v_cvt_pk_bf16_f32 v3, v104, v105
	v_cvt_pk_bf16_f32 v4, v98, v99
	v_cvt_pk_bf16_f32 v5, v100, v101
	global_store_dwordx4 v[0:1], v[2:5], off offset:256

.LBB0_254:
	v_ashrrev_i32_e32 v225, 31, v224
	v_lshlrev_b64 v[162:163], 11, v[224:225]
	v_pk_mul_f32 v[126:127], v[126:127], v[0:1]
	v_lshl_add_u64 v[0:1], s[96:97], 0, v[162:163]
	v_pk_mul_f32 v[128:129], v[128:129], v[2:3]
	v_pk_mul_f32 v[122:123], v[122:123], v[4:5]
	v_pk_mul_f32 v[124:125], v[124:125], v[6:7]
	s_andn2_b64 vcc, exec, s[16:17]
	v_lshl_add_u64 v[0:1], v[218:219], 1, v[0:1]
	s_cbranch_vccnz .LBB0_256
	v_cvt_pk_bf16_f32 v2, v126, v127
	v_cvt_pk_bf16_f32 v3, v128, v129
	v_cvt_pk_bf16_f32 v4, v122, v123
	v_cvt_pk_bf16_f32 v5, v124, v125
	global_store_dwordx4 v[0:1], v[2:5], off
	s_nop 1
	v_mul_f32_e32 v2, 0xbfb8aa3b, v174
	v_exp_f32_e32 v2, v2
	s_nop 0
	v_add_f32_e32 v2, 1.0, v2
	v_rcp_f32_e32 v8, v2
	v_mul_f32_e32 v2, 0xbfb8aa3b, v173
	v_exp_f32_e32 v2, v2
	s_nop 0
	v_add_f32_e32 v2, 1.0, v2
	v_rcp_f32_e32 v9, v2
	v_mul_f32_e32 v2, 0xbfb8aa3b, v172
	v_exp_f32_e32 v2, v2
	s_nop 0
	v_add_f32_e32 v2, 1.0, v2
	v_rcp_f32_e32 v10, v2
	v_mul_f32_e32 v2, 0xbfb8aa3b, v171
	v_exp_f32_e32 v2, v2
	s_nop 0
	v_add_f32_e32 v2, 1.0, v2
	v_rcp_f32_e32 v11, v2
	v_mul_f32_e32 v2, 0xbfb8aa3b, v170
	v_exp_f32_e32 v2, v2
	s_nop 0
	v_add_f32_e32 v2, 1.0, v2
	v_rcp_f32_e32 v12, v2
	v_mul_f32_e32 v2, 0xbfb8aa3b, v168
	v_exp_f32_e32 v2, v2
	s_nop 0
	v_add_f32_e32 v2, 1.0, v2
	v_rcp_f32_e32 v13, v2
	v_mul_f32_e32 v2, 0xbfb8aa3b, v167
	v_exp_f32_e32 v2, v2
	s_nop 0
	v_add_f32_e32 v2, 1.0, v2
	v_rcp_f32_e32 v14, v2
	v_mul_f32_e32 v2, 0xbfb8aa3b, v166
	v_exp_f32_e32 v2, v2
	s_nop 0
	v_add_f32_e32 v2, 1.0, v2
	v_rcp_f32_e32 v15, v2
.LBB0_256:
	v_pk_mul_f32 v[94:95], v[94:95], v[8:9]
	v_pk_mul_f32 v[96:97], v[96:97], v[10:11]
	v_pk_mul_f32 v[90:91], v[90:91], v[12:13]
	s_and_b64 vcc, exec, s[42:43]
	v_pk_mul_f32 v[92:93], v[92:93], v[14:15]
	s_cbranch_vccnz .LBB0_258
	v_cvt_pk_bf16_f32 v2, v94, v95
	v_cvt_pk_bf16_f32 v3, v96, v97
	v_cvt_pk_bf16_f32 v4, v90, v91
	v_cvt_pk_bf16_f32 v5, v92, v93
	global_store_dwordx4 v[0:1], v[2:5], off offset:256

.LBB0_264:
	v_ashrrev_i32_e32 v223, 31, v222
	s_waitcnt vmcnt(0) lgkmcnt(0)
	v_lshlrev_b64 v[146:147], 11, v[222:223]
	v_pk_mul_f32 v[118:119], v[118:119], v[0:1]
	v_lshl_add_u64 v[0:1], s[96:97], 0, v[146:147]
	v_pk_mul_f32 v[120:121], v[120:121], v[2:3]
	v_pk_mul_f32 v[114:115], v[114:115], v[4:5]
	v_pk_mul_f32 v[116:117], v[116:117], v[6:7]
	s_andn2_b64 vcc, exec, s[16:17]
	v_lshl_add_u64 v[0:1], v[218:219], 1, v[0:1]
	s_cbranch_vccnz .LBB0_266
	v_cvt_pk_bf16_f32 v2, v118, v119
	v_cvt_pk_bf16_f32 v3, v120, v121
	v_cvt_pk_bf16_f32 v4, v114, v115
	v_cvt_pk_bf16_f32 v5, v116, v117
	global_store_dwordx4 v[0:1], v[2:5], off
	s_nop 1
	v_mul_f32_e32 v2, 0xbfb8aa3b, v158
	v_exp_f32_e32 v2, v2
	s_nop 0
	v_add_f32_e32 v2, 1.0, v2
	v_rcp_f32_e32 v8, v2
	v_mul_f32_e32 v2, 0xbfb8aa3b, v157
	v_exp_f32_e32 v2, v2
	s_nop 0
	v_add_f32_e32 v2, 1.0, v2
	v_rcp_f32_e32 v9, v2
	v_mul_f32_e32 v2, 0xbfb8aa3b, v156
	v_exp_f32_e32 v2, v2
	s_nop 0
	v_add_f32_e32 v2, 1.0, v2
	v_rcp_f32_e32 v10, v2
	v_mul_f32_e32 v2, 0xbfb8aa3b, v155
	v_exp_f32_e32 v2, v2
	s_nop 0
	v_add_f32_e32 v2, 1.0, v2
	v_rcp_f32_e32 v11, v2
	v_mul_f32_e32 v2, 0xbfb8aa3b, v154
	v_exp_f32_e32 v2, v2
	s_nop 0
	v_add_f32_e32 v2, 1.0, v2
	v_rcp_f32_e32 v12, v2
	v_mul_f32_e32 v2, 0xbfb8aa3b, v152
	v_exp_f32_e32 v2, v2
	s_nop 0
	v_add_f32_e32 v2, 1.0, v2
	v_rcp_f32_e32 v13, v2
	v_mul_f32_e32 v2, 0xbfb8aa3b, v151
	v_exp_f32_e32 v2, v2
	s_nop 0
	v_add_f32_e32 v2, 1.0, v2
	v_rcp_f32_e32 v14, v2
	v_mul_f32_e32 v2, 0xbfb8aa3b, v150
	v_exp_f32_e32 v2, v2
	s_nop 0
	v_add_f32_e32 v2, 1.0, v2
	v_rcp_f32_e32 v15, v2
.LBB0_266:
	v_pk_mul_f32 v[86:87], v[86:87], v[8:9]
	v_pk_mul_f32 v[88:89], v[88:89], v[10:11]
	v_pk_mul_f32 v[82:83], v[82:83], v[12:13]
	s_and_b64 vcc, exec, s[42:43]
	v_pk_mul_f32 v[84:85], v[84:85], v[14:15]
	s_cbranch_vccnz .LBB0_268
	v_cvt_pk_bf16_f32 v2, v86, v87
	v_cvt_pk_bf16_f32 v3, v88, v89
	v_cvt_pk_bf16_f32 v4, v82, v83
	v_cvt_pk_bf16_f32 v5, v84, v85
	global_store_dwordx4 v[0:1], v[2:5], off offset:256

.LBB0_290:
	v_ashrrev_i32_e32 v227, 31, v226
	v_lshlrev_b64 v[194:195], 11, v[226:227]
	v_pk_mul_f32 v[78:79], v[78:79], v[0:1]
	v_lshl_add_u64 v[0:1], s[96:97], 0, v[194:195]
	v_pk_mul_f32 v[80:81], v[80:81], v[2:3]
	v_pk_mul_f32 v[74:75], v[74:75], v[4:5]
	v_pk_mul_f32 v[76:77], v[76:77], v[6:7]
	s_andn2_b64 vcc, exec, s[14:15]
	v_lshl_add_u64 v[0:1], v[218:219], 1, v[0:1]
	s_cbranch_vccnz .LBB0_292
	v_cvt_pk_bf16_f32 v2, v78, v79
	v_cvt_pk_bf16_f32 v3, v80, v81
	v_cvt_pk_bf16_f32 v4, v74, v75
	v_cvt_pk_bf16_f32 v5, v76, v77
	global_store_dwordx4 v[0:1], v[2:5], off
	s_nop 1
	v_mul_f32_e32 v2, 0xbfb8aa3b, v248
	v_exp_f32_e32 v2, v2
	s_nop 0
	v_add_f32_e32 v2, 1.0, v2
	v_rcp_f32_e32 v8, v2
	v_mul_f32_e32 v2, 0xbfb8aa3b, v247
	v_exp_f32_e32 v2, v2
	s_nop 0
	v_add_f32_e32 v2, 1.0, v2
	v_rcp_f32_e32 v9, v2
	v_mul_f32_e32 v2, 0xbfb8aa3b, v246
	v_exp_f32_e32 v2, v2
	s_nop 0
	v_add_f32_e32 v2, 1.0, v2
	v_rcp_f32_e32 v10, v2
	v_mul_f32_e32 v2, 0xbfb8aa3b, v245
	v_exp_f32_e32 v2, v2
	s_nop 0
	v_add_f32_e32 v2, 1.0, v2
	v_rcp_f32_e32 v11, v2
	v_mul_f32_e32 v2, 0xbfb8aa3b, v244
	v_exp_f32_e32 v2, v2
	s_nop 0
	v_add_f32_e32 v2, 1.0, v2
	v_rcp_f32_e32 v12, v2
	v_mul_f32_e32 v2, 0xbfb8aa3b, v225
	v_exp_f32_e32 v2, v2
	s_nop 0
	v_add_f32_e32 v2, 1.0, v2
	v_rcp_f32_e32 v13, v2
	v_mul_f32_e32 v2, 0xbfb8aa3b, v223
	v_exp_f32_e32 v2, v2
	s_nop 0
	v_add_f32_e32 v2, 1.0, v2
	v_rcp_f32_e32 v14, v2
	v_mul_f32_e32 v2, 0xbfb8aa3b, v221
	v_exp_f32_e32 v2, v2
	s_nop 0
	v_add_f32_e32 v2, 1.0, v2
	v_rcp_f32_e32 v15, v2
.LBB0_292:
	v_pk_mul_f32 v[46:47], v[46:47], v[8:9]
	v_pk_mul_f32 v[48:49], v[48:49], v[10:11]
	v_pk_mul_f32 v[42:43], v[42:43], v[12:13]
	s_and_b64 vcc, exec, s[42:43]
	v_pk_mul_f32 v[44:45], v[44:45], v[14:15]
	s_cbranch_vccnz .LBB0_294
	v_cvt_pk_bf16_f32 v2, v46, v47
	v_cvt_pk_bf16_f32 v3, v48, v49
	v_cvt_pk_bf16_f32 v4, v42, v43
	v_cvt_pk_bf16_f32 v5, v44, v45
	global_store_dwordx4 v[0:1], v[2:5], off offset:256

.LBB0_300:
	v_ashrrev_i32_e32 v225, 31, v224
	v_lshlrev_b64 v[178:179], 11, v[224:225]
	v_pk_mul_f32 v[70:71], v[70:71], v[0:1]
	v_lshl_add_u64 v[0:1], s[96:97], 0, v[178:179]
	v_pk_mul_f32 v[72:73], v[72:73], v[2:3]
	v_pk_mul_f32 v[66:67], v[66:67], v[4:5]
	v_pk_mul_f32 v[68:69], v[68:69], v[6:7]
	s_andn2_b64 vcc, exec, s[14:15]
	v_lshl_add_u64 v[0:1], v[218:219], 1, v[0:1]
	s_cbranch_vccnz .LBB0_302
	v_cvt_pk_bf16_f32 v2, v70, v71
	v_cvt_pk_bf16_f32 v3, v72, v73
	v_cvt_pk_bf16_f32 v4, v66, v67
	v_cvt_pk_bf16_f32 v5, v68, v69
	global_store_dwordx4 v[0:1], v[2:5], off
	s_nop 1
	v_mul_f32_e32 v2, 0xbfb8aa3b, v190
	v_exp_f32_e32 v2, v2
	s_nop 0
	v_add_f32_e32 v2, 1.0, v2
	v_rcp_f32_e32 v8, v2
	v_mul_f32_e32 v2, 0xbfb8aa3b, v189
	v_exp_f32_e32 v2, v2
	s_nop 0
	v_add_f32_e32 v2, 1.0, v2
	v_rcp_f32_e32 v9, v2
	v_mul_f32_e32 v2, 0xbfb8aa3b, v188
	v_exp_f32_e32 v2, v2
	s_nop 0
	v_add_f32_e32 v2, 1.0, v2
	v_rcp_f32_e32 v10, v2
	v_mul_f32_e32 v2, 0xbfb8aa3b, v187
	v_exp_f32_e32 v2, v2
	s_nop 0
	v_add_f32_e32 v2, 1.0, v2
	v_rcp_f32_e32 v11, v2
	v_mul_f32_e32 v2, 0xbfb8aa3b, v186
	v_exp_f32_e32 v2, v2
	s_nop 0
	v_add_f32_e32 v2, 1.0, v2
	v_rcp_f32_e32 v12, v2
	v_mul_f32_e32 v2, 0xbfb8aa3b, v184
	v_exp_f32_e32 v2, v2
	s_nop 0
	v_add_f32_e32 v2, 1.0, v2
	v_rcp_f32_e32 v13, v2
	v_mul_f32_e32 v2, 0xbfb8aa3b, v183
	v_exp_f32_e32 v2, v2
	s_nop 0
	v_add_f32_e32 v2, 1.0, v2
	v_rcp_f32_e32 v14, v2
	v_mul_f32_e32 v2, 0xbfb8aa3b, v182
	v_exp_f32_e32 v2, v2
	s_nop 0
	v_add_f32_e32 v2, 1.0, v2
	v_rcp_f32_e32 v15, v2
.LBB0_302:
	v_pk_mul_f32 v[38:39], v[38:39], v[8:9]
	v_pk_mul_f32 v[40:41], v[40:41], v[10:11]
	v_pk_mul_f32 v[34:35], v[34:35], v[12:13]
	s_and_b64 vcc, exec, s[42:43]
	v_pk_mul_f32 v[36:37], v[36:37], v[14:15]
	s_cbranch_vccnz .LBB0_304
	v_cvt_pk_bf16_f32 v2, v38, v39
	v_cvt_pk_bf16_f32 v3, v40, v41
	v_cvt_pk_bf16_f32 v4, v34, v35
	v_cvt_pk_bf16_f32 v5, v36, v37
	global_store_dwordx4 v[0:1], v[2:5], off offset:256

.LBB0_310:
	v_ashrrev_i32_e32 v223, 31, v222
	v_lshlrev_b64 v[162:163], 11, v[222:223]
	v_pk_mul_f32 v[62:63], v[62:63], v[0:1]
	v_lshl_add_u64 v[0:1], s[96:97], 0, v[162:163]
	v_pk_mul_f32 v[64:65], v[64:65], v[2:3]
	v_pk_mul_f32 v[58:59], v[58:59], v[4:5]
	v_pk_mul_f32 v[60:61], v[60:61], v[6:7]
	s_andn2_b64 vcc, exec, s[14:15]
	v_lshl_add_u64 v[0:1], v[218:219], 1, v[0:1]
	s_cbranch_vccnz .LBB0_312
	v_cvt_pk_bf16_f32 v2, v62, v63
	v_cvt_pk_bf16_f32 v3, v64, v65
	v_cvt_pk_bf16_f32 v4, v58, v59
	v_cvt_pk_bf16_f32 v5, v60, v61
	global_store_dwordx4 v[0:1], v[2:5], off
	s_nop 1
	v_mul_f32_e32 v2, 0xbfb8aa3b, v174
	v_exp_f32_e32 v2, v2
	s_nop 0
	v_add_f32_e32 v2, 1.0, v2
	v_rcp_f32_e32 v8, v2
	v_mul_f32_e32 v2, 0xbfb8aa3b, v173
	v_exp_f32_e32 v2, v2
	s_nop 0
	v_add_f32_e32 v2, 1.0, v2
	v_rcp_f32_e32 v9, v2
	v_mul_f32_e32 v2, 0xbfb8aa3b, v172
	v_exp_f32_e32 v2, v2
	s_nop 0
	v_add_f32_e32 v2, 1.0, v2
	v_rcp_f32_e32 v10, v2
	v_mul_f32_e32 v2, 0xbfb8aa3b, v171
	v_exp_f32_e32 v2, v2
	s_nop 0
	v_add_f32_e32 v2, 1.0, v2
	v_rcp_f32_e32 v11, v2
	v_mul_f32_e32 v2, 0xbfb8aa3b, v170
	v_exp_f32_e32 v2, v2
	s_nop 0
	v_add_f32_e32 v2, 1.0, v2
	v_rcp_f32_e32 v12, v2
	v_mul_f32_e32 v2, 0xbfb8aa3b, v168
	v_exp_f32_e32 v2, v2
	s_nop 0
	v_add_f32_e32 v2, 1.0, v2
	v_rcp_f32_e32 v13, v2
	v_mul_f32_e32 v2, 0xbfb8aa3b, v167
	v_exp_f32_e32 v2, v2
	s_nop 0
	v_add_f32_e32 v2, 1.0, v2
	v_rcp_f32_e32 v14, v2
	v_mul_f32_e32 v2, 0xbfb8aa3b, v166
	v_exp_f32_e32 v2, v2
	s_nop 0
	v_add_f32_e32 v2, 1.0, v2
	v_rcp_f32_e32 v15, v2
.LBB0_312:
	v_pk_mul_f32 v[30:31], v[30:31], v[8:9]
	v_pk_mul_f32 v[32:33], v[32:33], v[10:11]
	v_pk_mul_f32 v[26:27], v[26:27], v[12:13]
	s_and_b64 vcc, exec, s[42:43]
	v_pk_mul_f32 v[28:29], v[28:29], v[14:15]
	s_cbranch_vccnz .LBB0_314
	v_cvt_pk_bf16_f32 v2, v30, v31
	v_cvt_pk_bf16_f32 v3, v32, v33
	v_cvt_pk_bf16_f32 v4, v26, v27
	v_cvt_pk_bf16_f32 v5, v28, v29
	global_store_dwordx4 v[0:1], v[2:5], off offset:256

.LBB0_320:
	v_ashrrev_i32_e32 v221, 31, v220
	s_waitcnt vmcnt(0) lgkmcnt(0)
	v_lshlrev_b64 v[146:147], 11, v[220:221]
	v_pk_mul_f32 v[54:55], v[54:55], v[0:1]
	v_lshl_add_u64 v[0:1], s[96:97], 0, v[146:147]
	v_pk_mul_f32 v[56:57], v[56:57], v[2:3]
	v_pk_mul_f32 v[50:51], v[50:51], v[4:5]
	v_pk_mul_f32 v[52:53], v[52:53], v[6:7]
	s_andn2_b64 vcc, exec, s[14:15]
	v_lshl_add_u64 v[0:1], v[218:219], 1, v[0:1]
	s_cbranch_vccnz .LBB0_322
	v_cvt_pk_bf16_f32 v2, v54, v55
	v_cvt_pk_bf16_f32 v3, v56, v57
	v_cvt_pk_bf16_f32 v4, v50, v51
	v_cvt_pk_bf16_f32 v5, v52, v53
	global_store_dwordx4 v[0:1], v[2:5], off
	s_nop 1
	v_mul_f32_e32 v2, 0xbfb8aa3b, v158
	v_exp_f32_e32 v2, v2
	s_nop 0
	v_add_f32_e32 v2, 1.0, v2
	v_rcp_f32_e32 v8, v2
	v_mul_f32_e32 v2, 0xbfb8aa3b, v157
	v_exp_f32_e32 v2, v2
	s_nop 0
	v_add_f32_e32 v2, 1.0, v2
	v_rcp_f32_e32 v9, v2
	v_mul_f32_e32 v2, 0xbfb8aa3b, v156
	v_exp_f32_e32 v2, v2
	s_nop 0
	v_add_f32_e32 v2, 1.0, v2
	v_rcp_f32_e32 v10, v2
	v_mul_f32_e32 v2, 0xbfb8aa3b, v155
	v_exp_f32_e32 v2, v2
	s_nop 0
	v_add_f32_e32 v2, 1.0, v2
	v_rcp_f32_e32 v11, v2
	v_mul_f32_e32 v2, 0xbfb8aa3b, v154
	v_exp_f32_e32 v2, v2
	s_nop 0
	v_add_f32_e32 v2, 1.0, v2
	v_rcp_f32_e32 v12, v2
	v_mul_f32_e32 v2, 0xbfb8aa3b, v152
	v_exp_f32_e32 v2, v2
	s_nop 0
	v_add_f32_e32 v2, 1.0, v2
	v_rcp_f32_e32 v13, v2
	v_mul_f32_e32 v2, 0xbfb8aa3b, v151
	v_exp_f32_e32 v2, v2
	s_nop 0
	v_add_f32_e32 v2, 1.0, v2
	v_rcp_f32_e32 v14, v2
	v_mul_f32_e32 v2, 0xbfb8aa3b, v150
	v_exp_f32_e32 v2, v2
	s_nop 0
	v_add_f32_e32 v2, 1.0, v2
	v_rcp_f32_e32 v15, v2
.LBB0_322:
	v_pk_mul_f32 v[22:23], v[22:23], v[8:9]
	v_pk_mul_f32 v[24:25], v[24:25], v[10:11]
	v_pk_mul_f32 v[18:19], v[18:19], v[12:13]
	s_and_b64 vcc, exec, s[42:43]
	v_pk_mul_f32 v[20:21], v[20:21], v[14:15]
	s_cbranch_vccnz .LBB0_324
	v_cvt_pk_bf16_f32 v2, v22, v23
	v_cvt_pk_bf16_f32 v3, v24, v25
	v_cvt_pk_bf16_f32 v4, v18, v19
	v_cvt_pk_bf16_f32 v5, v20, v21
	global_store_dwordx4 v[0:1], v[2:5], off offset:256

.LBB0_520:
	s_lshl_b32 s37, s37, 8
	v_lshrrev_b32_e32 v5, 4, v3
	v_lshl_or_b32 v3, v3, 2, s37
	v_or_b32_e32 v24, s34, v3
	v_readlane_b32 s54, v255, 30
	v_ashrrev_i32_e32 v25, 31, v24
	v_readlane_b32 s55, v255, 31
	s_cmp_gt_u32 s12, 63
	v_and_b32_e32 v1, 15, v1
	v_lshl_add_u64 v[24:25], v[24:25], 2, s[54:55]
	global_load_dword v120, v[24:25], off
	s_cselect_b64 s[54:55], -1, 0
	s_lshl_b32 s5, s5, 2
	v_lshlrev_b32_e32 v24, 2, v5
	s_movk_i32 s12, 0x88
	s_add_u32 s5, s30, s5
	v_mad_u32_u24 v3, v1, s12, v24
	s_addc_u32 s12, s31, 0
	s_lshl_b32 s4, s4, 2
	s_add_u32 s4, s5, s4
	s_addc_u32 s5, s12, 0
	v_lshlrev_b32_e32 v16, 2, v1
	v_lshl_add_u64 v[92:93], s[4:5], 0, v[16:17]
	s_sub_i32 s4, s13, 54
	s_cmp_lt_u32 s4, 9
	s_cselect_b32 s4, 15, 16
	v_writelane_b32 v255, s4, 35
	s_lshl_b32 s2, s2, 10
	v_writelane_b32 v255, s2, 37
	s_sub_i32 s2, s13, 48
	s_cmp_lt_u32 s2, 9
	s_cselect_b32 s2, 15, 16
	v_writelane_b32 v255, s2, 39
	s_lshl_b32 s2, s60, 10
	v_writelane_b32 v255, s2, 41
	s_sub_i32 s2, s13, 42
	s_cmp_lt_u32 s2, 9
	s_cselect_b32 s2, 15, 16
	v_writelane_b32 v255, s2, 43
	s_lshl_b32 s2, s61, 10
	v_writelane_b32 v255, s2, 45
	s_sub_i32 s2, s13, 36
	s_cmp_lt_u32 s2, 9
	s_cselect_b32 s2, 15, 16
	v_writelane_b32 v255, s2, 47
	s_lshl_b32 s2, s79, 10
	v_writelane_b32 v255, s2, 49
	s_sub_i32 s2, s13, 30
	s_cmp_lt_u32 s2, 9
	s_cselect_b32 s89, 15, 16
	s_lshl_b32 s12, s82, 10
	s_sub_i32 s2, s13, 24
	s_cmp_lt_u32 s2, 9
	s_cselect_b32 s34, 15, 16
	s_lshl_b32 s79, s83, 10
	s_sub_i32 s2, s13, 18
	s_cmp_lt_u32 s2, 9
	s_cselect_b32 s2, 15, 16
	s_lshl_b32 s37, s84, 10
	s_add_i32 s4, s13, -12
	s_cmp_lt_u32 s4, 9
	s_cselect_b32 s82, 15, 16
	s_lshl_b32 s83, s85, 10
	s_add_i32 s4, s13, -6
	s_cmp_lt_u32 s4, 9
	v_lshlrev_b32_e32 v7, 6, v1
	s_cselect_b32 s84, 15, 16
	s_lshl_b32 s4, s86, 10
	v_lshlrev_b32_e32 v123, 1, v3
	v_sub_u32_e32 v3, v3, v7
	s_cmp_lt_u32 s13, 9
	v_mov_b32_e32 v19, v17
	v_lshlrev_b32_e32 v121, 3, v5
	v_mul_u32_u24_e32 v122, 0x110, v1
	v_lshlrev_b32_e32 v124, 1, v1
	v_lshlrev_b32_e32 v125, 1, v3
	v_mul_u32_u24_e32 v126, 0x90, v1
	v_lshlrev_b32_e32 v127, 7, v5
	v_mov_b32_e32 v3, v17
	v_mov_b32_e32 v1, v17
	v_mov_b32_e32 v7, v17
	v_mov_b32_e32 v5, v17
	v_mov_b32_e32 v11, v17
	v_mov_b32_e32 v9, v17
	v_mov_b32_e32 v15, v17
	v_mov_b32_e32 v13, v17
	v_mov_b32_e32 v21, v17
	v_lshl_add_u64 v[112:113], s[44:45], 0, v[18:19]
	s_cselect_b32 s5, 15, 16
	s_lshl_b32 s85, s87, 10
	v_mov_b32_e32 v23, v17
	v_mov_b32_e32 v16, v17
	v_mov_b32_e32 v18, v17
	v_lshl_add_u64 v[94:95], s[44:45], 0, v[2:3]
	v_lshl_add_u64 v[96:97], s[44:45], 0, v[0:1]
	v_lshl_add_u64 v[98:99], s[44:45], 0, v[6:7]
	v_lshl_add_u64 v[100:101], s[44:45], 0, v[4:5]
	v_lshl_add_u64 v[102:103], s[44:45], 0, v[10:11]
	v_lshl_add_u64 v[104:105], s[44:45], 0, v[8:9]
	v_lshl_add_u64 v[106:107], s[44:45], 0, v[14:15]
	v_lshl_add_u64 v[108:109], s[44:45], 0, v[12:13]
	v_lshl_add_u64 v[110:111], s[44:45], 0, v[20:21]
	s_cmp_eq_u32 s13, 2
	v_lshl_add_u64 v[114:115], s[44:45], 0, v[22:23]
	v_add_u32_e32 v116, s35, v24
	v_mov_b64_e32 v[0:1], v[16:17]
	v_mov_b64_e32 v[4:5], v[16:17]
	v_mov_b64_e32 v[8:9], v[16:17]
	v_mov_b64_e32 v[12:13], v[16:17]
	v_mov_b64_e32 v[22:23], v[18:19]
	v_mov_b64_e32 v[26:27], v[18:19]
	v_mov_b64_e32 v[30:31], v[18:19]
	s_waitcnt lgkmcnt(0)
	v_mov_b64_e32 v[34:35], v[18:19]
	s_cselect_b32 s13, 15, 16
	s_lshl_b32 s86, s88, 10
	s_mov_b32 s35, 0
	v_mov_b64_e32 v[2:3], v[18:19]
	v_mov_b64_e32 v[6:7], v[18:19]
	v_mov_b64_e32 v[10:11], v[18:19]
	v_mov_b64_e32 v[14:15], v[18:19]
	v_mov_b64_e32 v[20:21], v[16:17]
	v_mov_b64_e32 v[24:25], v[16:17]
	v_mov_b64_e32 v[28:29], v[16:17]
	v_mov_b64_e32 v[32:33], v[16:17]
	s_mov_b32 s87, 0
	s_waitcnt vmcnt(0)
	s_barrier
	s_branch .LBB0_523

.LBB0_566:
	s_waitcnt vmcnt(0)
	v_mov_b32_e32 v0, v228
	s_barrier
	s_nop 0
	v_cmp_eq_u32_e32 vcc, 0, v0
	s_and_saveexec_b64 s[8:9], vcc
	v_readlane_b32 s19, v255, 27
	s_cbranch_execz .LBB0_568
	v_readlane_b32 s4, v255, 18
	v_readlane_b32 s5, v255, 19
	s_and_b32 s2, s4, 7
	s_lshl_b32 s2, s2, 4
	s_lshr_b32 s4, s4, 3
	s_or_b32 s4, s4, s2
	s_ashr_i32 s4, s4, 3
	s_ashr_i32 s5, s4, 31
	s_lshl_b64 s[4:5], s[4:5], 2
	s_add_u32 s4, s19, s4
	v_readlane_b32 s2, v255, 26
	s_addc_u32 s5, s2, s5
	buffer_wbl2 sc1
	s_waitcnt vmcnt(0)
	v_mov_b64_e32 v[0:1], s[4:5]
	global_atomic_add v[0:1], v230, off

.LBB0_569:
	s_add_u32 s2, s44, s8
	s_addc_u32 s4, s45, s9
	s_add_u32 s92, s2, 0x1d504800
	s_waitcnt vmcnt(0)
	v_mov_b32_e32 v0, v228
	s_addc_u32 s93, s4, 0
	v_mov_b32_e32 v78, 0
	v_cmp_eq_u32_e64 s[38:39], 0, v0
	s_and_saveexec_b64 s[4:5], s[38:39]
	s_cbranch_execz .LBB0_571
	v_mov_b64_e32 v[0:1], s[92:93]
	global_atomic_add v78, v[0:1], v230, off sc0

.LBB0_575:
	s_or_b64 exec, exec, s[4:5]
	v_mov_b32_e32 v0, s85
	s_waitcnt lgkmcnt(0)
	s_barrier
	ds_read_b32 v0, v0
	s_waitcnt lgkmcnt(0)
	s_barrier
	v_readfirstlane_b32 s28, v0
	s_cmpk_gt_i32 s28, 0x37f
	s_cselect_b64 s[54:55], -1, 0
	s_and_b64 vcc, exec, s[54:55]
	s_cbranch_vccnz .LBB0_572
	s_and_saveexec_b64 s[4:5], s[38:39]
	s_cbranch_execz .LBB0_579
	v_mov_b64_e32 v[0:1], s[92:93]
	s_waitcnt vmcnt(0)
	global_atomic_add v78, v[0:1], v230, off sc0
	s_or_b64 exec, exec, s[4:5]
	s_cmpk_gt_i32 s28, 0xff
	s_mov_b64 s[4:5], -1
	s_cbranch_scc1 .LBB0_580

.LBB0_605:
	s_and_b64 vcc, exec, s[4:5]
	s_cbranch_vccz .LBB0_675
	s_add_i32 s2, s28, 0xfffffe80
	s_lshl_b32 s18, s2, 6
	s_mul_i32 s52, s2, 0x8c000
	s_and_b32 s19, s18, 0xfc0
	s_lshl_b64 s[4:5], s[52:53], 1
	v_mov_b32_e32 v0, v228
	s_add_u32 s4, s94, s4
	s_addc_u32 s5, s95, s5
	v_ashrrev_i32_e32 v1, 31, v0
	v_lshl_add_u64 v[2:3], v[0:1], 1, s[4:5]
	s_mov_b64 s[4:5], 0x2000
	s_movk_i32 s2, 0x7f
	v_lshl_add_u64 v[2:3], v[2:3], 0, s[4:5]
	v_cmp_lt_u32_e32 vcc, s2, v0
	s_and_saveexec_b64 s[4:5], vcc
	s_xor_b64 s[42:43], exec, s[4:5]
	s_cbranch_execz .LBB0_669
	v_ashrrev_i32_e32 v4, 7, v0
	s_cmp_lg_u32 s19, 0
	s_cselect_b64 s[8:9], -1, 0
	v_cmp_lt_i32_e32 vcc, 1, v4
	s_mov_b64 s[4:5], 0
	s_mov_b64 s[16:17], 0
	s_and_saveexec_b64 s[14:15], vcc
	s_xor_b64 s[14:15], exec, s[14:15]
	s_cbranch_execz .LBB0_626
	v_cmp_eq_u32_e32 vcc, 2, v4
	s_mov_b64 s[16:17], -1
	s_and_saveexec_b64 s[56:57], vcc
	s_cbranch_execz .LBB0_625
	v_cndmask_b32_e64 v1, 0, 1, s[8:9]
	v_mov_b32_e32 v16, 0
	v_cmp_ne_u32_e64 s[40:41], 1, v1
	s_andn2_b64 vcc, exec, s[8:9]
	v_mov_b32_e32 v20, 0
	s_cbranch_vccnz .LBB0_611
	v_add_co_u32_e32 v4, vcc, 0xfffe1600, v2
	s_nop 1
	v_addc_co_u32_e32 v5, vcc, -1, v3, vcc
	global_load_ushort v1, v[4:5], off
	s_waitcnt vmcnt(0) lgkmcnt(0)
	v_lshlrev_b32_e32 v20, 16, v1
.LBB0_611:
	s_and_b64 vcc, exec, s[40:41]
	s_cbranch_vccnz .LBB0_613
	v_add_co_u32_e32 v4, vcc, 0xfffe5c00, v2
	s_nop 1
	v_addc_co_u32_e32 v5, vcc, -1, v3, vcc
	global_load_ushort v1, v[4:5], off
	s_waitcnt vmcnt(0) lgkmcnt(0)
	v_lshlrev_b32_e32 v16, 16, v1
.LBB0_613:
	v_mov_b32_e32 v10, 0
	s_and_b64 vcc, exec, s[40:41]
	v_mov_b32_e32 v14, 0
	s_cbranch_vccnz .LBB0_615
	v_add_co_u32_e32 v4, vcc, 0xfffea200, v2
	s_nop 1
	v_addc_co_u32_e32 v5, vcc, -1, v3, vcc
	global_load_ushort v1, v[4:5], off
	s_waitcnt vmcnt(0) lgkmcnt(0)
	v_lshlrev_b32_e32 v14, 16, v1
.LBB0_615:
	s_and_b64 vcc, exec, s[40:41]
	s_cbranch_vccnz .LBB0_617
	v_add_co_u32_e32 v4, vcc, 0xfffee800, v2
	s_nop 1
	v_addc_co_u32_e32 v5, vcc, -1, v3, vcc
	global_load_ushort v1, v[4:5], off
	s_waitcnt vmcnt(0) lgkmcnt(0)
	v_lshlrev_b32_e32 v10, 16, v1
.LBB0_617:
	v_mov_b32_e32 v1, 0
	s_and_b64 vcc, exec, s[40:41]
	v_mov_b32_e32 v8, 0
	s_cbranch_vccnz .LBB0_619
	v_add_co_u32_e32 v4, vcc, 0xffff2e00, v2
	s_nop 1
	v_addc_co_u32_e32 v5, vcc, -1, v3, vcc
	global_load_ushort v4, v[4:5], off
	s_waitcnt vmcnt(0) lgkmcnt(0)
	v_lshlrev_b32_e32 v8, 16, v4
.LBB0_619:
	s_and_b64 vcc, exec, s[40:41]
	s_cbranch_vccnz .LBB0_621
	v_add_co_u32_e32 v4, vcc, 0xffff7400, v2
	s_nop 1
	v_addc_co_u32_e32 v5, vcc, -1, v3, vcc
	global_load_ushort v1, v[4:5], off
	s_waitcnt vmcnt(0) lgkmcnt(0)
	v_lshlrev_b32_e32 v1, 16, v1
.LBB0_621:
	s_and_b64 vcc, exec, s[40:41]
	s_cbranch_vccnz .LBB0_623
	v_add_co_u32_e32 v4, vcc, 0xffffba00, v2
	s_mov_b32 s16, 0x41000000
	s_nop 0
	v_addc_co_u32_e32 v5, vcc, -1, v3, vcc
	global_load_ushort v4, v[4:5], off
	s_waitcnt vmcnt(0) lgkmcnt(0)
	v_lshlrev_b32_e32 v4, 16, v4
	s_branch .LBB0_624

.LBB0_624:
	v_add_co_u32_e32 v6, vcc, 0x4000, v2
	global_load_ushort v5, v[2:3], off
	s_nop 0
	v_addc_co_u32_e32 v7, vcc, 0, v3, vcc
	v_add_co_u32_e32 v12, vcc, 0x8000, v2
	global_load_ushort v6, v[6:7], off offset:1536
	s_nop 0
	v_addc_co_u32_e32 v13, vcc, 0, v3, vcc
	global_load_ushort v7, v[12:13], off offset:3072
	v_add_co_u32_e32 v12, vcc, 0xd000, v2
	s_mov_b32 s2, 0x8c000
	s_nop 0
	v_addc_co_u32_e32 v13, vcc, 0, v3, vcc
	global_load_ushort v9, v[12:13], off offset:512
	v_add_co_u32_e32 v12, vcc, 0x11000, v2
	s_waitcnt vmcnt(0) lgkmcnt(0)
	v_lshlrev_b32_e32 v5, 16, v5
	v_addc_co_u32_e32 v13, vcc, 0, v3, vcc
	global_load_ushort v11, v[12:13], off offset:2048
	v_add_co_u32_e32 v12, vcc, 0x15000, v2
	v_lshlrev_b32_e32 v6, 16, v6
	s_nop 0
	v_addc_co_u32_e32 v13, vcc, 0, v3, vcc
	v_add_co_u32_e32 v18, vcc, s63, v2
	global_load_ushort v12, v[12:13], off offset:3584
	s_nop 0
	v_addc_co_u32_e32 v19, vcc, 0, v3, vcc
	global_load_ushort v13, v[18:19], off offset:1024
	v_add_co_u32_e32 v18, vcc, s64, v2
	v_lshlrev_b32_e32 v7, 16, v7
	s_nop 0
	v_addc_co_u32_e32 v19, vcc, 0, v3, vcc
	global_load_ushort v15, v[18:19], off offset:2560
	v_add_co_u32_e32 v18, vcc, 0x23000, v2
	v_lshlrev_b32_e32 v9, 16, v9
	s_nop 0
	v_addc_co_u32_e32 v19, vcc, 0, v3, vcc
	v_add_co_u32_e32 v22, vcc, 0x27000, v2
	global_load_ushort v18, v[18:19], off
	s_nop 0
	v_addc_co_u32_e32 v23, vcc, 0, v3, vcc
	global_load_ushort v19, v[22:23], off offset:1536
	v_add_co_u32_e32 v22, vcc, 0x2b000, v2
	s_waitcnt vmcnt(0) lgkmcnt(0)
	v_lshlrev_b32_e32 v11, 16, v11
	v_addc_co_u32_e32 v23, vcc, 0, v3, vcc
	global_load_ushort v21, v[22:23], off offset:3072
	v_add_co_u32_e32 v22, vcc, 0x30000, v2
	v_lshlrev_b32_e32 v12, 16, v12
	s_nop 0
	v_addc_co_u32_e32 v23, vcc, 0, v3, vcc
	v_add_co_u32_e32 v24, vcc, 0x34000, v2
	global_load_ushort v22, v[22:23], off offset:512
	s_nop 0
	v_addc_co_u32_e32 v25, vcc, 0, v3, vcc
	global_load_ushort v23, v[24:25], off offset:2048
	v_add_co_u32_e32 v24, vcc, 0x38000, v2
	v_lshlrev_b32_e32 v13, 16, v13
	s_nop 0
	v_addc_co_u32_e32 v25, vcc, 0, v3, vcc
	v_add_co_u32_e32 v26, vcc, 0x3d000, v2
	global_load_ushort v24, v[24:25], off offset:3584
	s_nop 0
	v_addc_co_u32_e32 v27, vcc, 0, v3, vcc
	global_load_ushort v25, v[26:27], off offset:1024
	v_add_co_u32_e32 v26, vcc, 0x41000, v2
	v_lshlrev_b32_e32 v15, 16, v15
	s_nop 0
	v_addc_co_u32_e32 v27, vcc, 0, v3, vcc
	v_add_co_u32_e32 v28, vcc, 0x46000, v2
	global_load_ushort v26, v[26:27], off offset:2560
	s_nop 0
	v_addc_co_u32_e32 v29, vcc, 0, v3, vcc
	global_load_ushort v27, v[28:29], off
	v_add_co_u32_e32 v28, vcc, 0x4a000, v2
	v_lshlrev_b32_e32 v18, 16, v18
	s_nop 0
	v_addc_co_u32_e32 v29, vcc, 0, v3, vcc
	v_add_co_u32_e32 v30, vcc, 0x4e000, v2
	global_load_ushort v28, v[28:29], off offset:1536
	s_nop 0
	v_addc_co_u32_e32 v31, vcc, 0, v3, vcc
	global_load_ushort v29, v[30:31], off offset:3072
	v_add_co_u32_e32 v30, vcc, 0x53000, v2
	v_lshlrev_b32_e32 v19, 16, v19
	s_nop 0
	v_addc_co_u32_e32 v31, vcc, 0, v3, vcc
	v_add_co_u32_e32 v32, vcc, 0x57000, v2
	global_load_ushort v30, v[30:31], off offset:512
	s_nop 0
	v_addc_co_u32_e32 v33, vcc, 0, v3, vcc
	global_load_ushort v31, v[32:33], off offset:2048
	v_add_co_u32_e32 v32, vcc, 0x5b000, v2
	s_waitcnt vmcnt(0) lgkmcnt(0)
	v_lshlrev_b32_e32 v21, 16, v21
	v_addc_co_u32_e32 v33, vcc, 0, v3, vcc
	v_add_co_u32_e32 v34, vcc, 0x60000, v2
	global_load_ushort v32, v[32:33], off offset:3584
	s_nop 0
	v_addc_co_u32_e32 v35, vcc, 0, v3, vcc
	global_load_ushort v33, v[34:35], off offset:1024
	v_add_co_u32_e32 v34, vcc, 0x64000, v2
	v_lshlrev_b32_e32 v22, 16, v22
	s_nop 0
	v_addc_co_u32_e32 v35, vcc, 0, v3, vcc
	v_add_co_u32_e32 v36, vcc, 0x69000, v2
	global_load_ushort v34, v[34:35], off offset:2560
	s_nop 0
	v_addc_co_u32_e32 v37, vcc, 0, v3, vcc
	global_load_ushort v35, v[36:37], off
	v_add_co_u32_e32 v36, vcc, 0x6d000, v2
	v_lshlrev_b32_e32 v23, 16, v23
	s_nop 0
	v_addc_co_u32_e32 v37, vcc, 0, v3, vcc
	v_add_co_u32_e32 v38, vcc, 0x71000, v2
	global_load_ushort v36, v[36:37], off offset:1536
	s_nop 0
	v_addc_co_u32_e32 v39, vcc, 0, v3, vcc
	global_load_ushort v37, v[38:39], off offset:3072
	v_add_co_u32_e32 v38, vcc, 0x76000, v2
	v_lshlrev_b32_e32 v24, 16, v24
	s_nop 0
	v_addc_co_u32_e32 v39, vcc, 0, v3, vcc
	v_add_co_u32_e32 v40, vcc, 0x7a000, v2
	global_load_ushort v38, v[38:39], off offset:512
	s_nop 0
	v_addc_co_u32_e32 v41, vcc, 0, v3, vcc
	global_load_ushort v39, v[40:41], off offset:2048
	v_add_co_u32_e32 v40, vcc, 0x7e000, v2
	v_lshlrev_b32_e32 v25, 16, v25
	s_nop 0
	v_addc_co_u32_e32 v41, vcc, 0, v3, vcc
	v_add_co_u32_e32 v42, vcc, 0x83000, v2
	global_load_ushort v40, v[40:41], off offset:3584
	s_nop 0
	v_addc_co_u32_e32 v43, vcc, 0, v3, vcc
	global_load_ushort v41, v[42:43], off offset:1024
	v_add_co_u32_e32 v42, vcc, 0x87000, v2
	v_lshlrev_b32_e32 v26, 16, v26
	s_nop 0
	v_addc_co_u32_e32 v43, vcc, 0, v3, vcc
	v_add_co_u32_e32 v44, vcc, s2, v2
	global_load_ushort v42, v[42:43], off offset:2560
	s_nop 0
	v_addc_co_u32_e32 v45, vcc, 0, v3, vcc
	global_load_ushort v43, v[44:45], off
	v_add_co_u32_e32 v44, vcc, 0x90000, v2
	s_min_u32 s2, s19, 7
	s_nop 0
	v_addc_co_u32_e32 v45, vcc, 0, v3, vcc
	v_add_co_u32_e32 v46, vcc, 0x94000, v2
	global_load_ushort v44, v[44:45], off offset:1536
	s_nop 0
	v_addc_co_u32_e32 v47, vcc, 0, v3, vcc
	global_load_ushort v45, v[46:47], off offset:3072
	v_add_co_u32_e32 v46, vcc, 0x99000, v2
	s_add_i32 s2, s2, 1
	s_nop 0
	v_addc_co_u32_e32 v47, vcc, 0, v3, vcc
	v_add_co_u32_e32 v48, vcc, 0x9d000, v2
	global_load_ushort v46, v[46:47], off offset:512
	s_nop 0
	v_addc_co_u32_e32 v49, vcc, 0, v3, vcc
	global_load_ushort v47, v[48:49], off offset:2048
	v_add_co_u32_e32 v48, vcc, 0xa1000, v2
	v_cvt_f32_ubyte0_e32 v77, s2
	s_nop 0
	v_addc_co_u32_e32 v49, vcc, 0, v3, vcc
	v_add_co_u32_e32 v50, vcc, 0xa6000, v2
	global_load_ushort v48, v[48:49], off offset:3584
	s_nop 0
	v_addc_co_u32_e32 v51, vcc, 0, v3, vcc
	global_load_ushort v49, v[50:51], off offset:1024
	v_add_co_u32_e32 v50, vcc, 0xaa000, v2
	s_min_u32 s2, s19, 6
	s_nop 0
	v_addc_co_u32_e32 v51, vcc, 0, v3, vcc
	v_add_co_u32_e32 v52, vcc, 0xaf000, v2
	global_load_ushort v50, v[50:51], off offset:2560
	s_nop 0
	v_addc_co_u32_e32 v53, vcc, 0, v3, vcc
	global_load_ushort v51, v[52:53], off
	v_add_co_u32_e32 v52, vcc, 0xb3000, v2
	s_add_i32 s2, s2, 2
	s_nop 0
	v_addc_co_u32_e32 v53, vcc, 0, v3, vcc
	v_add_co_u32_e32 v54, vcc, 0xb7000, v2
	global_load_ushort v52, v[52:53], off offset:1536
	s_nop 0
	v_addc_co_u32_e32 v55, vcc, 0, v3, vcc
	global_load_ushort v53, v[54:55], off offset:3072
	v_add_co_u32_e32 v54, vcc, 0xbc000, v2
	v_lshlrev_b32_e32 v27, 16, v27
	s_nop 0
	v_addc_co_u32_e32 v55, vcc, 0, v3, vcc
	v_add_co_u32_e32 v56, vcc, 0xc0000, v2
	global_load_ushort v54, v[54:55], off offset:512
	s_nop 0
	v_addc_co_u32_e32 v57, vcc, 0, v3, vcc
	global_load_ushort v55, v[56:57], off offset:2048
	v_add_co_u32_e32 v56, vcc, 0xc4000, v2
	v_lshlrev_b32_e32 v28, 16, v28
	s_nop 0
	v_addc_co_u32_e32 v57, vcc, 0, v3, vcc
	v_add_co_u32_e32 v58, vcc, 0xc9000, v2
	global_load_ushort v56, v[56:57], off offset:3584
	s_nop 0
	v_addc_co_u32_e32 v59, vcc, 0, v3, vcc
	global_load_ushort v57, v[58:59], off offset:1024
	v_add_co_u32_e32 v58, vcc, 0xcd000, v2
	v_lshlrev_b32_e32 v29, 16, v29
	s_nop 0
	v_addc_co_u32_e32 v59, vcc, 0, v3, vcc
	v_add_co_u32_e32 v60, vcc, 0xd2000, v2
	global_load_ushort v58, v[58:59], off offset:2560
	s_nop 0
	v_addc_co_u32_e32 v61, vcc, 0, v3, vcc
	global_load_ushort v62, v[60:61], off
	v_add_co_u32_e32 v60, vcc, 0xf5000, v2
	v_lshlrev_b32_e32 v30, 16, v30
	s_nop 0
	v_addc_co_u32_e32 v61, vcc, 0, v3, vcc
	global_load_ushort v59, v[60:61], off
	v_lshlrev_b32_e32 v31, 16, v31
	s_waitcnt vmcnt(0) lgkmcnt(0)
	v_lshlrev_b32_e32 v32, 16, v32
	v_lshlrev_b32_e32 v33, 16, v33
	v_lshlrev_b32_e32 v34, 16, v34
	v_lshlrev_b32_e32 v35, 16, v35
	v_lshlrev_b32_e32 v36, 16, v36
	v_lshlrev_b32_e32 v37, 16, v37
	v_lshlrev_b32_e32 v38, 16, v38
	v_lshlrev_b32_e32 v39, 16, v39
	v_lshlrev_b32_e32 v40, 16, v40
	v_lshlrev_b32_e32 v41, 16, v41
	v_lshlrev_b32_e32 v42, 16, v42
	v_lshlrev_b32_e32 v43, 16, v43
	v_lshlrev_b32_e32 v44, 16, v44
	v_lshlrev_b32_e32 v45, 16, v45
	v_lshlrev_b32_e32 v46, 16, v46
	v_lshlrev_b32_e32 v47, 16, v47
	v_lshlrev_b32_e32 v48, 16, v48
	v_lshlrev_b32_e32 v49, 16, v49
	v_lshlrev_b32_e32 v50, 16, v50
	v_lshlrev_b32_e32 v51, 16, v51
	v_lshlrev_b32_e32 v52, 16, v52
	v_lshlrev_b32_e32 v53, 16, v53
	v_lshlrev_b32_e32 v54, 16, v54
	v_lshlrev_b32_e32 v55, 16, v55
	v_lshlrev_b32_e32 v56, 16, v56
	v_lshlrev_b32_e32 v57, 16, v57
	v_lshlrev_b32_e32 v58, 16, v58
	v_lshlrev_b32_e32 v60, 16, v62
	v_add_co_u32_e32 v62, vcc, 0xd6000, v2
	v_lshlrev_b32_e32 v59, 16, v59
	s_nop 0
	v_addc_co_u32_e32 v63, vcc, 0, v3, vcc
	global_load_ushort v64, v[62:63], off offset:1536
	v_add_co_u32_e32 v62, vcc, 0xf9000, v2
	s_nop 1
	v_addc_co_u32_e32 v63, vcc, 0, v3, vcc
	global_load_ushort v61, v[62:63], off offset:1536
	s_waitcnt vmcnt(0) lgkmcnt(0)
	v_lshlrev_b32_e32 v62, 16, v64
	v_add_co_u32_e32 v64, vcc, 0xda000, v2
	v_lshlrev_b32_e32 v61, 16, v61
	s_nop 0
	v_addc_co_u32_e32 v65, vcc, 0, v3, vcc
	global_load_ushort v66, v[64:65], off offset:3072
	v_add_co_u32_e32 v64, vcc, 0xfd000, v2
	s_nop 1
	v_addc_co_u32_e32 v65, vcc, 0, v3, vcc
	global_load_ushort v63, v[64:65], off offset:3072
	s_waitcnt vmcnt(0) lgkmcnt(0)
	v_lshlrev_b32_e32 v64, 16, v66
	v_add_co_u32_e32 v66, vcc, 0xdf000, v2
	v_lshlrev_b32_e32 v63, 16, v63
	s_nop 0
	v_addc_co_u32_e32 v67, vcc, 0, v3, vcc
	global_load_ushort v68, v[66:67], off offset:512
	v_add_co_u32_e32 v66, vcc, 0x102000, v2
	s_nop 1
	v_addc_co_u32_e32 v67, vcc, 0, v3, vcc
	global_load_ushort v65, v[66:67], off offset:512
	s_waitcnt vmcnt(0) lgkmcnt(0)
	v_lshlrev_b32_e32 v66, 16, v68
	v_add_co_u32_e32 v68, vcc, 0xe3000, v2
	v_lshlrev_b32_e32 v65, 16, v65
	s_nop 0
	v_addc_co_u32_e32 v69, vcc, 0, v3, vcc
	global_load_ushort v70, v[68:69], off offset:2048
	v_add_co_u32_e32 v68, vcc, 0x106000, v2
	s_nop 1
	v_addc_co_u32_e32 v69, vcc, 0, v3, vcc
	global_load_ushort v67, v[68:69], off offset:2048
	s_waitcnt vmcnt(0) lgkmcnt(0)
	v_lshlrev_b32_e32 v68, 16, v70
	v_add_co_u32_e32 v70, vcc, 0xe7000, v2
	v_lshlrev_b32_e32 v67, 16, v67
	s_nop 0
	v_addc_co_u32_e32 v71, vcc, 0, v3, vcc
	global_load_ushort v72, v[70:71], off offset:3584
	v_add_co_u32_e32 v70, vcc, 0x10a000, v2
	s_nop 1
	v_addc_co_u32_e32 v71, vcc, 0, v3, vcc
	global_load_ushort v69, v[70:71], off offset:3584
	s_waitcnt vmcnt(0) lgkmcnt(0)
	v_lshlrev_b32_e32 v70, 16, v72
	v_add_co_u32_e32 v72, vcc, 0xec000, v2
	v_lshlrev_b32_e32 v69, 16, v69
	s_nop 0
	v_addc_co_u32_e32 v73, vcc, 0, v3, vcc
	global_load_ushort v74, v[72:73], off offset:1024
	v_add_co_u32_e32 v72, vcc, 0x10f000, v2
	s_nop 1
	v_addc_co_u32_e32 v73, vcc, 0, v3, vcc
	global_load_ushort v71, v[72:73], off offset:1024
	s_waitcnt vmcnt(0) lgkmcnt(0)
	v_lshlrev_b32_e32 v72, 16, v74
	v_add_co_u32_e32 v74, vcc, 0xf0000, v2
	v_lshlrev_b32_e32 v71, 16, v71
	s_nop 0
	v_addc_co_u32_e32 v75, vcc, 0, v3, vcc
	global_load_ushort v76, v[74:75], off offset:2560
	v_add_co_u32_e32 v74, vcc, 0x113000, v2
	s_nop 1
	v_addc_co_u32_e32 v75, vcc, 0, v3, vcc
	global_load_ushort v73, v[74:75], off offset:2560
	v_add_f32_e32 v75, 0, v5
	v_add_f32_e32 v75, v4, v75
	v_add_f32_e32 v75, v1, v75
	v_add_f32_e32 v75, v8, v75
	v_add_f32_e32 v75, v10, v75
	v_add_f32_e32 v75, v14, v75
	v_add_f32_e32 v75, v16, v75
	v_sub_f32_e32 v16, v7, v16
	v_sub_f32_e32 v14, v9, v14
	v_sub_f32_e32 v10, v11, v10
	v_sub_f32_e32 v8, v12, v8
	v_sub_f32_e32 v1, v13, v1
	v_sub_f32_e32 v4, v15, v4
	s_waitcnt vmcnt(0) lgkmcnt(0)
	v_lshlrev_b32_e32 v74, 16, v76
	v_add_f32_e32 v76, v20, v75
	v_div_scale_f32 v79, s[22:23], v77, v77, v76
	v_rcp_f32_e32 v80, v79
	v_sub_f32_e32 v20, v6, v20
	v_lshl_add_u32 v75, v0, 1, 0
	v_add_f32_e32 v20, v20, v76
	v_fma_f32 v81, -v79, v80, 1.0
	v_fmac_f32_e32 v80, v81, v80
	v_div_scale_f32 v81, vcc, v76, v77, v76
	v_mul_f32_e32 v82, v81, v80
	v_fma_f32 v83, -v79, v82, v81
	v_fmac_f32_e32 v82, v83, v80
	v_fma_f32 v79, -v79, v82, v81
	v_div_fmas_f32 v79, v79, v80, v82
	v_div_fixup_f32 v77, v79, v77, v76
	v_sub_f32_e32 v77, v77, v5
	v_cvt_pk_bf16_f32 v77, v77, v17
	v_cvt_f32_ubyte0_e32 v76, s2
	ds_write_b16 v75, v77
	v_div_scale_f32 v77, s[22:23], v76, v76, v20
	v_rcp_f32_e32 v79, v77
	s_min_u32 s2, s19, 5
	s_add_i32 s2, s2, 3
	v_add_f32_e32 v16, v16, v20
	v_fma_f32 v80, -v77, v79, 1.0
	v_fmac_f32_e32 v79, v80, v79
	v_div_scale_f32 v80, vcc, v20, v76, v20
	v_mul_f32_e32 v81, v80, v79
	v_fma_f32 v82, -v77, v81, v80
	v_fmac_f32_e32 v81, v82, v79
	v_fma_f32 v77, -v77, v81, v80
	v_div_fmas_f32 v77, v77, v79, v81
	v_div_fixup_f32 v76, v77, v76, v20
	v_sub_f32_e32 v76, v76, v6
	v_cvt_pk_bf16_f32 v76, v76, v17
	v_cvt_f32_ubyte0_e32 v20, s2
	ds_write_b16 v75, v76 offset:1040
	v_div_scale_f32 v76, s[22:23], v20, v20, v16
	v_rcp_f32_e32 v77, v76
	s_min_u32 s2, s19, 4
	s_add_i32 s2, s2, 4
	v_add_f32_e32 v14, v14, v16
	v_fma_f32 v79, -v76, v77, 1.0
	v_fmac_f32_e32 v77, v79, v77
	v_div_scale_f32 v79, vcc, v16, v20, v16
	v_mul_f32_e32 v80, v79, v77
	v_fma_f32 v81, -v76, v80, v79
	v_fmac_f32_e32 v80, v81, v77
	v_fma_f32 v76, -v76, v80, v79
	v_div_fmas_f32 v76, v76, v77, v80
	v_div_fixup_f32 v20, v76, v20, v16
	v_sub_f32_e32 v20, v20, v7
	v_cvt_pk_bf16_f32 v20, v20, v17
	v_cvt_f32_ubyte0_e32 v16, s2
	ds_write_b16 v75, v20 offset:2080
	v_div_scale_f32 v20, s[22:23], v16, v16, v14
	v_rcp_f32_e32 v76, v20
	s_min_u32 s2, s19, 3
	s_add_i32 s2, s2, 5
	v_add_f32_e32 v10, v10, v14
	v_fma_f32 v77, -v20, v76, 1.0
	v_fmac_f32_e32 v76, v77, v76
	v_div_scale_f32 v77, vcc, v14, v16, v14
	v_mul_f32_e32 v79, v77, v76
	v_fma_f32 v80, -v20, v79, v77
	v_fmac_f32_e32 v79, v80, v76
	v_fma_f32 v20, -v20, v79, v77
	v_div_fmas_f32 v20, v20, v76, v79
	v_div_fixup_f32 v16, v20, v16, v14
	v_sub_f32_e32 v16, v16, v9
	v_cvt_pk_bf16_f32 v16, v16, v17
	v_cvt_f32_ubyte0_e32 v14, s2
	ds_write_b16 v75, v16 offset:3120
	v_div_scale_f32 v16, s[22:23], v14, v14, v10
	v_rcp_f32_e32 v20, v16
	s_min_u32 s2, s19, 2
	s_add_i32 s2, s2, 6
	v_add_f32_e32 v8, v8, v10
	v_fma_f32 v76, -v16, v20, 1.0
	v_fmac_f32_e32 v20, v76, v20
	v_div_scale_f32 v76, vcc, v10, v14, v10
	v_mul_f32_e32 v77, v76, v20
	v_fma_f32 v79, -v16, v77, v76
	v_fmac_f32_e32 v77, v79, v20
	v_fma_f32 v16, -v16, v77, v76
	v_div_fmas_f32 v16, v16, v20, v77
	v_div_fixup_f32 v14, v16, v14, v10
	v_sub_f32_e32 v14, v14, v11
	v_cvt_pk_bf16_f32 v14, v14, v17
	v_cvt_f32_ubyte0_e32 v10, s2
	ds_write_b16 v75, v14 offset:4160
	v_div_scale_f32 v14, s[22:23], v10, v10, v8
	v_rcp_f32_e32 v16, v14
	v_add_f32_e32 v1, v1, v8
	s_mov_b32 s2, 0x3e000000
	v_lshlrev_b32_e32 v73, 16, v73
	v_fma_f32 v20, -v14, v16, 1.0
	v_fmac_f32_e32 v16, v20, v16
	v_div_scale_f32 v20, vcc, v8, v10, v8
	v_mul_f32_e32 v76, v20, v16
	v_fma_f32 v77, -v14, v76, v20
	v_fmac_f32_e32 v76, v77, v16
	v_fma_f32 v14, -v14, v76, v20
	v_div_fmas_f32 v14, v14, v16, v76
	v_div_fixup_f32 v10, v14, v10, v8
	v_sub_f32_e32 v10, v10, v12
	v_cvt_pk_bf16_f32 v10, v10, v17
	v_div_scale_f32 v8, s[22:23], s16, s16, v1
	ds_write_b16 v75, v10 offset:5200
	v_rcp_f32_e32 v10, v8
	s_nop 0
	v_fma_f32 v14, -v8, v10, 1.0
	v_fmac_f32_e32 v10, v14, v10
	v_div_scale_f32 v14, vcc, v1, s16, v1
	v_mul_f32_e32 v16, v14, v10
	v_fma_f32 v20, -v8, v16, v14
	v_fmac_f32_e32 v16, v20, v10
	v_fma_f32 v8, -v8, v16, v14
	v_div_fmas_f32 v8, v8, v10, v16
	v_div_fixup_f32 v8, v8, s16, v1
	v_add_f32_e32 v1, v4, v1
	v_fma_f32 v4, v1, s2, -v15
	v_cvt_pk_bf16_f32 v4, v4, v17
	ds_write_b16 v75, v4 offset:7280
	v_sub_f32_e32 v4, v18, v5
	v_add_f32_e32 v1, v4, v1
	v_fma_f32 v4, v1, s2, -v18
	v_cvt_pk_bf16_f32 v4, v4, v17
	ds_write_b16 v75, v4 offset:8320
	v_sub_f32_e32 v4, v19, v6
	v_add_f32_e32 v1, v4, v1
	v_fma_f32 v4, v1, s2, -v19
	v_cvt_pk_bf16_f32 v4, v4, v17
	ds_write_b16 v75, v4 offset:9360
	v_sub_f32_e32 v4, v21, v7
	v_add_f32_e32 v1, v4, v1
	v_fma_f32 v4, v1, s2, -v21
	v_cvt_pk_bf16_f32 v4, v4, v17
	ds_write_b16 v75, v4 offset:10400
	v_sub_f32_e32 v4, v22, v9
	v_add_f32_e32 v1, v4, v1
	v_fma_f32 v4, v1, s2, -v22
	v_cvt_pk_bf16_f32 v4, v4, v17
	ds_write_b16 v75, v4 offset:11440
	v_sub_f32_e32 v4, v23, v11
	v_add_f32_e32 v1, v4, v1
	v_fma_f32 v4, v1, s2, -v23
	v_cvt_pk_bf16_f32 v4, v4, v17
	ds_write_b16 v75, v4 offset:12480
	v_sub_f32_e32 v4, v24, v12
	v_add_f32_e32 v1, v4, v1
	v_fma_f32 v4, v1, s2, -v24
	v_cvt_pk_bf16_f32 v4, v4, v17
	ds_write_b16 v75, v4 offset:13520
	v_sub_f32_e32 v4, v25, v13
	v_add_f32_e32 v1, v4, v1
	v_fma_f32 v4, v1, s2, -v25
	v_cvt_pk_bf16_f32 v4, v4, v17
	ds_write_b16 v75, v4 offset:14560
	v_sub_f32_e32 v4, v26, v15
	v_add_f32_e32 v1, v4, v1
	v_fma_f32 v4, v1, s2, -v26
	v_cvt_pk_bf16_f32 v4, v4, v17
	ds_write_b16 v75, v4 offset:15600
	v_sub_f32_e32 v4, v27, v18
	v_add_f32_e32 v1, v4, v1
	v_fma_f32 v4, v1, s2, -v27
	v_cvt_pk_bf16_f32 v4, v4, v17
	ds_write_b16 v75, v4 offset:16640
	v_sub_f32_e32 v4, v28, v19
	v_add_f32_e32 v1, v4, v1
	v_fma_f32 v4, v1, s2, -v28
	v_cvt_pk_bf16_f32 v4, v4, v17
	ds_write_b16 v75, v4 offset:17680
	v_sub_f32_e32 v4, v29, v21
	v_add_f32_e32 v1, v4, v1
	v_fma_f32 v4, v1, s2, -v29
	v_cvt_pk_bf16_f32 v4, v4, v17
	ds_write_b16 v75, v4 offset:18720
	v_sub_f32_e32 v4, v30, v22
	v_add_f32_e32 v1, v4, v1
	v_fma_f32 v4, v1, s2, -v30
	v_cvt_pk_bf16_f32 v4, v4, v17
	ds_write_b16 v75, v4 offset:19760
	v_sub_f32_e32 v4, v31, v23
	v_add_f32_e32 v1, v4, v1
	v_fma_f32 v4, v1, s2, -v31
	v_cvt_pk_bf16_f32 v4, v4, v17
	ds_write_b16 v75, v4 offset:20800
	v_sub_f32_e32 v4, v32, v24
	v_add_f32_e32 v1, v4, v1
	v_fma_f32 v4, v1, s2, -v32
	v_cvt_pk_bf16_f32 v4, v4, v17
	ds_write_b16 v75, v4 offset:21840
	v_sub_f32_e32 v4, v33, v25
	v_add_f32_e32 v1, v4, v1
	v_fma_f32 v4, v1, s2, -v33
	v_cvt_pk_bf16_f32 v4, v4, v17
	ds_write_b16 v75, v4 offset:22880
	v_sub_f32_e32 v4, v34, v26
	v_add_f32_e32 v1, v4, v1
	v_fma_f32 v4, v1, s2, -v34
	v_cvt_pk_bf16_f32 v4, v4, v17
	ds_write_b16 v75, v4 offset:23920
	v_sub_f32_e32 v4, v35, v27
	v_add_f32_e32 v1, v4, v1
	v_fma_f32 v4, v1, s2, -v35
	v_cvt_pk_bf16_f32 v4, v4, v17
	ds_write_b16 v75, v4 offset:24960
	v_sub_f32_e32 v4, v36, v28
	v_add_f32_e32 v1, v4, v1
	v_fma_f32 v4, v1, s2, -v36
	v_cvt_pk_bf16_f32 v4, v4, v17
	ds_write_b16 v75, v4 offset:26000
	v_sub_f32_e32 v4, v37, v29
	v_add_f32_e32 v1, v4, v1
	v_fma_f32 v4, v1, s2, -v37
	v_cvt_pk_bf16_f32 v4, v4, v17
	ds_write_b16 v75, v4 offset:27040
	v_sub_f32_e32 v4, v38, v30
	v_add_f32_e32 v1, v4, v1
	v_fma_f32 v4, v1, s2, -v38
	v_cvt_pk_bf16_f32 v4, v4, v17
	ds_write_b16 v75, v4 offset:28080
	v_sub_f32_e32 v4, v39, v31
	v_add_f32_e32 v1, v4, v1
	v_fma_f32 v4, v1, s2, -v39
	v_cvt_pk_bf16_f32 v4, v4, v17
	ds_write_b16 v75, v4 offset:29120
	v_sub_f32_e32 v4, v40, v32
	v_add_f32_e32 v1, v4, v1
	v_fma_f32 v4, v1, s2, -v40
	v_cvt_pk_bf16_f32 v4, v4, v17
	ds_write_b16 v75, v4 offset:30160
	v_sub_f32_e32 v4, v41, v33
	v_add_f32_e32 v1, v4, v1
	v_fma_f32 v4, v1, s2, -v41
	v_cvt_pk_bf16_f32 v4, v4, v17
	ds_write_b16 v75, v4 offset:31200
	v_sub_f32_e32 v4, v42, v34
	v_add_f32_e32 v1, v4, v1
	v_fma_f32 v4, v1, s2, -v42
	v_cvt_pk_bf16_f32 v4, v4, v17
	ds_write_b16 v75, v4 offset:32240
	v_sub_f32_e32 v4, v43, v35
	v_add_f32_e32 v1, v4, v1
	v_fma_f32 v4, v1, s2, -v43
	v_cvt_pk_bf16_f32 v4, v4, v17
	ds_write_b16 v75, v4 offset:33280
	v_sub_f32_e32 v4, v44, v36
	v_add_f32_e32 v1, v4, v1
	v_fma_f32 v4, v1, s2, -v44
	v_cvt_pk_bf16_f32 v4, v4, v17
	ds_write_b16 v75, v4 offset:34320
	v_sub_f32_e32 v4, v45, v37
	v_add_f32_e32 v1, v4, v1
	v_fma_f32 v4, v1, s2, -v45
	v_cvt_pk_bf16_f32 v4, v4, v17
	ds_write_b16 v75, v4 offset:35360
	v_sub_f32_e32 v4, v46, v38
	v_add_f32_e32 v1, v4, v1
	v_fma_f32 v4, v1, s2, -v46
	v_cvt_pk_bf16_f32 v4, v4, v17
	ds_write_b16 v75, v4 offset:36400
	v_sub_f32_e32 v4, v47, v39
	v_add_f32_e32 v1, v4, v1
	v_fma_f32 v4, v1, s2, -v47
	v_cvt_pk_bf16_f32 v4, v4, v17
	ds_write_b16 v75, v4 offset:37440
	v_sub_f32_e32 v4, v48, v40
	v_add_f32_e32 v1, v4, v1
	v_fma_f32 v4, v1, s2, -v48
	v_cvt_pk_bf16_f32 v4, v4, v17
	ds_write_b16 v75, v4 offset:38480
	v_sub_f32_e32 v4, v49, v41
	v_add_f32_e32 v1, v4, v1
	v_fma_f32 v4, v1, s2, -v49
	v_cvt_pk_bf16_f32 v4, v4, v17
	ds_write_b16 v75, v4 offset:39520
	v_sub_f32_e32 v4, v50, v42
	v_add_f32_e32 v1, v4, v1
	v_fma_f32 v4, v1, s2, -v50
	v_cvt_pk_bf16_f32 v4, v4, v17
	ds_write_b16 v75, v4 offset:40560
	v_sub_f32_e32 v4, v51, v43
	v_add_f32_e32 v1, v4, v1
	v_fma_f32 v4, v1, s2, -v51
	v_cvt_pk_bf16_f32 v4, v4, v17
	ds_write_b16 v75, v4 offset:41600
	v_sub_f32_e32 v4, v52, v44
	v_add_f32_e32 v1, v4, v1
	v_fma_f32 v4, v1, s2, -v52
	v_cvt_pk_bf16_f32 v4, v4, v17
	ds_write_b16 v75, v4 offset:42640
	v_sub_f32_e32 v4, v53, v45
	v_add_f32_e32 v1, v4, v1
	v_fma_f32 v4, v1, s2, -v53
	v_cvt_pk_bf16_f32 v4, v4, v17
	ds_write_b16 v75, v4 offset:43680
	v_sub_f32_e32 v4, v54, v46
	v_add_f32_e32 v1, v4, v1
	v_fma_f32 v4, v1, s2, -v54
	v_cvt_pk_bf16_f32 v4, v4, v17
	ds_write_b16 v75, v4 offset:44720
	v_sub_f32_e32 v4, v55, v47
	v_add_f32_e32 v1, v4, v1
	v_fma_f32 v4, v1, s2, -v55
	v_cvt_pk_bf16_f32 v4, v4, v17
	ds_write_b16 v75, v4 offset:45760
	v_sub_f32_e32 v4, v56, v48
	v_add_f32_e32 v1, v4, v1
	v_fma_f32 v4, v1, s2, -v56
	v_cvt_pk_bf16_f32 v4, v4, v17
	ds_write_b16 v75, v4 offset:46800
	v_sub_f32_e32 v4, v57, v49
	v_add_f32_e32 v1, v4, v1
	v_fma_f32 v4, v1, s2, -v57
	v_cvt_pk_bf16_f32 v4, v4, v17
	ds_write_b16 v75, v4 offset:47840
	v_sub_f32_e32 v4, v58, v50
	v_add_f32_e32 v1, v4, v1
	v_fma_f32 v4, v1, s2, -v58
	v_cvt_pk_bf16_f32 v4, v4, v17
	ds_write_b16 v75, v4 offset:48880
	v_sub_f32_e32 v4, v60, v51
	v_add_f32_e32 v1, v4, v1
	v_fma_f32 v4, v1, s2, -v60
	v_cvt_pk_bf16_f32 v4, v4, v17
	ds_write_b16 v75, v4 offset:49920
	v_sub_f32_e32 v4, v62, v52
	v_add_f32_e32 v1, v4, v1
	v_fma_f32 v4, v1, s2, -v62
	v_cvt_pk_bf16_f32 v4, v4, v17
	ds_write_b16 v75, v4 offset:50960
	v_sub_f32_e32 v4, v64, v53
	v_add_f32_e32 v1, v4, v1
	v_fma_f32 v4, v1, s2, -v64
	v_cvt_pk_bf16_f32 v4, v4, v17
	ds_write_b16 v75, v4 offset:52000
	v_sub_f32_e32 v4, v66, v54
	v_add_f32_e32 v1, v4, v1
	v_fma_f32 v4, v1, s2, -v66
	v_cvt_pk_bf16_f32 v4, v4, v17
	ds_write_b16 v75, v4 offset:53040
	v_sub_f32_e32 v4, v68, v55
	v_add_f32_e32 v1, v4, v1
	v_fma_f32 v4, v1, s2, -v68
	v_cvt_pk_bf16_f32 v4, v4, v17
	ds_write_b16 v75, v4 offset:54080
	v_sub_f32_e32 v4, v70, v56
	v_add_f32_e32 v1, v4, v1
	v_fma_f32 v4, v1, s2, -v70
	v_cvt_pk_bf16_f32 v4, v4, v17
	ds_write_b16 v75, v4 offset:55120
	v_sub_f32_e32 v4, v72, v57
	v_add_f32_e32 v1, v4, v1
	v_fma_f32 v4, v1, s2, -v72
	v_cvt_pk_bf16_f32 v4, v4, v17
	ds_write_b16 v75, v4 offset:56160
	v_sub_f32_e32 v4, v74, v58
	v_add_f32_e32 v1, v4, v1
	v_fma_f32 v4, v1, s2, -v74
	v_cvt_pk_bf16_f32 v4, v4, v17
	ds_write_b16 v75, v4 offset:57200
	v_sub_f32_e32 v4, v59, v60
	v_add_f32_e32 v1, v4, v1
	v_fma_f32 v4, v1, s2, -v59
	v_cvt_pk_bf16_f32 v4, v4, v17
	ds_write_b16 v75, v4 offset:58240
	v_sub_f32_e32 v4, v61, v62
	v_add_f32_e32 v1, v4, v1
	v_fma_f32 v4, v1, s2, -v61
	v_cvt_pk_bf16_f32 v4, v4, v17
	ds_write_b16 v75, v4 offset:59280
	v_sub_f32_e32 v4, v63, v64
	v_add_f32_e32 v1, v4, v1
	v_fma_f32 v4, v1, s2, -v63
	v_cvt_pk_bf16_f32 v4, v4, v17
	ds_write_b16 v75, v4 offset:60320
	v_sub_f32_e32 v4, v65, v66
	v_add_f32_e32 v1, v4, v1
	v_fma_f32 v4, v1, s2, -v65
	v_cvt_pk_bf16_f32 v4, v4, v17
	ds_write_b16 v75, v4 offset:61360
	v_sub_f32_e32 v4, v67, v68
	v_add_f32_e32 v1, v4, v1
	v_fma_f32 v4, v1, s2, -v67
	v_cvt_pk_bf16_f32 v4, v4, v17
	ds_write_b16 v75, v4 offset:62400
	v_sub_f32_e32 v4, v69, v70
	v_add_f32_e32 v1, v4, v1
	v_fma_f32 v4, v1, s2, -v69
	v_cvt_pk_bf16_f32 v4, v4, v17
	ds_write_b16 v75, v4 offset:63440
	v_sub_f32_e32 v4, v71, v72
	v_add_f32_e32 v1, v4, v1
	v_fma_f32 v4, v1, s2, -v71
	v_cvt_pk_bf16_f32 v4, v4, v17
	ds_write_b16 v75, v4 offset:64480
	v_sub_f32_e32 v4, v73, v74
	v_add_f32_e32 v1, v4, v1
	v_sub_f32_e32 v8, v8, v13
	v_fma_f32 v1, v1, s2, -v73
	s_xor_b64 s[16:17], exec, -1
	v_cvt_pk_bf16_f32 v8, v8, v17
	ds_write_b16 v75, v8 offset:6240
	v_cvt_pk_bf16_f32 v1, v1, v17

.LBB0_626:
	s_andn2_saveexec_b64 s[14:15], s[14:15]
	v_cmp_ne_u32_e32 vcc, 1, v4
	s_andn2_b64 s[4:5], s[16:17], exec
	s_and_b64 s[16:17], vcc, exec
	s_or_b64 s[16:17], s[4:5], s[16:17]
	s_mov_b64 s[4:5], exec
	s_or_b64 exec, exec, s[14:15]
	v_cndmask_b32_e64 v4, 0, 1, s[8:9]
	v_cmp_ne_u32_e64 s[40:41], 1, v4
	s_and_saveexec_b64 s[8:9], s[16:17]
	s_cbranch_execz .LBB0_661
	v_mov_b32_e32 v38, 0
	s_and_b64 vcc, exec, s[40:41]
	v_mov_b32_e32 v42, 0
	s_cbranch_vccnz .LBB0_631
	v_add_co_u32_e32 v4, vcc, 0xfffbe600, v2
	s_nop 1
	v_addc_co_u32_e32 v5, vcc, -1, v3, vcc
	global_load_ushort v1, v[4:5], off
	s_waitcnt vmcnt(0) lgkmcnt(0)
	v_lshlrev_b32_e32 v42, 16, v1
.LBB0_631:
	s_and_b64 vcc, exec, s[40:41]
	s_cbranch_vccnz .LBB0_633
	v_add_co_u32_e32 v4, vcc, 0xfffc2c00, v2
	s_nop 1
	v_addc_co_u32_e32 v5, vcc, -1, v3, vcc
	global_load_ushort v1, v[4:5], off
	s_waitcnt vmcnt(0) lgkmcnt(0)
	v_lshlrev_b32_e32 v38, 16, v1
.LBB0_633:
	v_mov_b32_e32 v32, 0
	s_and_b64 vcc, exec, s[40:41]
	v_mov_b32_e32 v37, 0
	s_cbranch_vccnz .LBB0_635
	v_add_co_u32_e32 v4, vcc, 0xfffc7200, v2
	s_nop 1
	v_addc_co_u32_e32 v5, vcc, -1, v3, vcc
	global_load_ushort v1, v[4:5], off
	s_waitcnt vmcnt(0) lgkmcnt(0)
	v_lshlrev_b32_e32 v37, 16, v1
.LBB0_635:
	s_and_b64 vcc, exec, s[40:41]
	s_cbranch_vccnz .LBB0_637
	v_add_co_u32_e32 v4, vcc, 0xfffcb800, v2
	s_nop 1
	v_addc_co_u32_e32 v5, vcc, -1, v3, vcc
	global_load_ushort v1, v[4:5], off
	s_waitcnt vmcnt(0) lgkmcnt(0)
	v_lshlrev_b32_e32 v32, 16, v1
.LBB0_637:
	v_mov_b32_e32 v28, 0
	s_and_b64 vcc, exec, s[40:41]
	v_mov_b32_e32 v30, 0
	s_cbranch_vccnz .LBB0_639
	v_add_co_u32_e32 v4, vcc, 0xfffcfe00, v2
	s_nop 1
	v_addc_co_u32_e32 v5, vcc, -1, v3, vcc
	global_load_ushort v1, v[4:5], off
	s_waitcnt vmcnt(0) lgkmcnt(0)
	v_lshlrev_b32_e32 v30, 16, v1
.LBB0_639:
	s_and_b64 vcc, exec, s[40:41]
	s_cbranch_vccnz .LBB0_641
	v_add_co_u32_e32 v4, vcc, 0xfffd4400, v2
	s_nop 1
	v_addc_co_u32_e32 v5, vcc, -1, v3, vcc
	global_load_ushort v1, v[4:5], off
	s_waitcnt vmcnt(0) lgkmcnt(0)
	v_lshlrev_b32_e32 v28, 16, v1
.LBB0_641:
	v_mov_b32_e32 v21, 0
	s_and_b64 vcc, exec, s[40:41]
	v_mov_b32_e32 v26, 0
	s_cbranch_vccnz .LBB0_643
	v_add_co_u32_e32 v4, vcc, 0xfffd8a00, v2
	s_nop 1
	v_addc_co_u32_e32 v5, vcc, -1, v3, vcc
	global_load_ushort v1, v[4:5], off
	s_waitcnt vmcnt(0) lgkmcnt(0)
	v_lshlrev_b32_e32 v26, 16, v1
.LBB0_643:
	s_and_b64 vcc, exec, s[40:41]
	s_cbranch_vccnz .LBB0_645
	v_add_co_u32_e32 v4, vcc, 0xfffdd000, v2
	s_nop 1
	v_addc_co_u32_e32 v5, vcc, -1, v3, vcc
	global_load_ushort v1, v[4:5], off
	s_waitcnt vmcnt(0) lgkmcnt(0)
	v_lshlrev_b32_e32 v21, 16, v1
.LBB0_645:
	v_mov_b32_e32 v16, 0
	s_and_b64 vcc, exec, s[40:41]
	v_mov_b32_e32 v20, 0
	s_cbranch_vccnz .LBB0_647
	v_add_co_u32_e32 v4, vcc, 0xfffe1600, v2
	s_nop 1
	v_addc_co_u32_e32 v5, vcc, -1, v3, vcc
	global_load_ushort v1, v[4:5], off
	s_waitcnt vmcnt(0) lgkmcnt(0)
	v_lshlrev_b32_e32 v20, 16, v1

.LBB0_657:
	s_and_b64 vcc, exec, s[40:41]
	s_cbranch_vccnz .LBB0_659
	v_add_co_u32_e32 v4, vcc, 0xffffba00, v2
	s_mov_b32 s14, 0x41800000
	s_nop 0
	v_addc_co_u32_e32 v5, vcc, -1, v3, vcc
	global_load_ushort v4, v[4:5], off
	s_waitcnt vmcnt(0) lgkmcnt(0)
	v_lshlrev_b32_e32 v4, 16, v4
	s_branch .LBB0_660

.LBB0_660:
	v_add_co_u32_e32 v6, vcc, 0x4000, v2
	global_load_ushort v5, v[2:3], off
	s_nop 0
	v_addc_co_u32_e32 v7, vcc, 0, v3, vcc
	v_add_co_u32_e32 v12, vcc, 0x8000, v2
	global_load_ushort v6, v[6:7], off offset:1536
	s_nop 0
	v_addc_co_u32_e32 v13, vcc, 0, v3, vcc
	global_load_ushort v7, v[12:13], off offset:3072
	v_add_co_u32_e32 v12, vcc, 0xd000, v2
	s_mov_b32 s2, 0x8c000
	s_nop 0
	v_addc_co_u32_e32 v13, vcc, 0, v3, vcc
	global_load_ushort v9, v[12:13], off offset:512
	v_add_co_u32_e32 v12, vcc, 0x11000, v2
	s_andn2_b64 s[4:5], s[4:5], exec
	s_nop 0
	v_addc_co_u32_e32 v13, vcc, 0, v3, vcc
	global_load_ushort v11, v[12:13], off offset:2048
	v_add_co_u32_e32 v12, vcc, 0x15000, v2
	s_waitcnt vmcnt(0) lgkmcnt(0)
	v_lshlrev_b32_e32 v5, 16, v5
	v_addc_co_u32_e32 v13, vcc, 0, v3, vcc
	v_add_co_u32_e32 v18, vcc, s63, v2
	global_load_ushort v12, v[12:13], off offset:3584
	s_nop 0
	v_addc_co_u32_e32 v19, vcc, 0, v3, vcc
	global_load_ushort v13, v[18:19], off offset:1024
	v_add_co_u32_e32 v18, vcc, s64, v2
	v_lshlrev_b32_e32 v6, 16, v6
	s_nop 0
	v_addc_co_u32_e32 v19, vcc, 0, v3, vcc
	global_load_ushort v15, v[18:19], off offset:2560
	v_add_co_u32_e32 v18, vcc, 0x23000, v2
	v_lshlrev_b32_e32 v7, 16, v7
	s_nop 0
	v_addc_co_u32_e32 v19, vcc, 0, v3, vcc
	v_add_co_u32_e32 v22, vcc, 0x27000, v2
	global_load_ushort v18, v[18:19], off
	s_nop 0
	v_addc_co_u32_e32 v23, vcc, 0, v3, vcc
	global_load_ushort v19, v[22:23], off offset:1536
	v_add_co_u32_e32 v22, vcc, 0x2b000, v2
	v_lshlrev_b32_e32 v9, 16, v9
	s_nop 0
	v_addc_co_u32_e32 v23, vcc, 0, v3, vcc
	v_add_co_u32_e32 v24, vcc, 0x30000, v2
	global_load_ushort v22, v[22:23], off offset:3072
	s_nop 0
	v_addc_co_u32_e32 v25, vcc, 0, v3, vcc
	global_load_ushort v23, v[24:25], off offset:512
	v_add_co_u32_e32 v24, vcc, 0x34000, v2
	v_lshlrev_b32_e32 v11, 16, v11
	s_nop 0
	v_addc_co_u32_e32 v25, vcc, 0, v3, vcc
	v_add_co_u32_e32 v34, vcc, 0x38000, v2
	global_load_ushort v24, v[24:25], off offset:2048
	s_nop 0
	v_addc_co_u32_e32 v35, vcc, 0, v3, vcc
	global_load_ushort v25, v[34:35], off offset:3584
	v_add_co_u32_e32 v34, vcc, 0x3d000, v2
	s_waitcnt vmcnt(0) lgkmcnt(0)
	v_lshlrev_b32_e32 v12, 16, v12
	v_addc_co_u32_e32 v35, vcc, 0, v3, vcc
	global_load_ushort v27, v[34:35], off offset:1024
	v_add_co_u32_e32 v34, vcc, 0x41000, v2
	v_lshlrev_b32_e32 v13, 16, v13
	s_nop 0
	v_addc_co_u32_e32 v35, vcc, 0, v3, vcc
	global_load_ushort v29, v[34:35], off offset:2560
	v_add_co_u32_e32 v34, vcc, 0x46000, v2
	v_lshlrev_b32_e32 v15, 16, v15
	s_nop 0
	v_addc_co_u32_e32 v35, vcc, 0, v3, vcc
	global_load_ushort v31, v[34:35], off
	v_add_co_u32_e32 v34, vcc, 0x4a000, v2
	v_lshlrev_b32_e32 v18, 16, v18
	s_nop 0
	v_addc_co_u32_e32 v35, vcc, 0, v3, vcc
	global_load_ushort v33, v[34:35], off offset:1536
	v_add_co_u32_e32 v34, vcc, 0x4e000, v2
	v_lshlrev_b32_e32 v19, 16, v19
	s_nop 0
	v_addc_co_u32_e32 v35, vcc, 0, v3, vcc
	v_add_co_u32_e32 v40, vcc, 0x53000, v2
	global_load_ushort v34, v[34:35], off offset:3072
	s_nop 0
	v_addc_co_u32_e32 v41, vcc, 0, v3, vcc
	global_load_ushort v35, v[40:41], off offset:512
	v_add_co_u32_e32 v40, vcc, 0x57000, v2
	v_lshlrev_b32_e32 v22, 16, v22
	s_nop 0
	v_addc_co_u32_e32 v41, vcc, 0, v3, vcc
	global_load_ushort v36, v[40:41], off offset:2048
	v_add_co_u32_e32 v40, vcc, 0x5b000, v2
	v_lshlrev_b32_e32 v23, 16, v23
	s_nop 0
	v_addc_co_u32_e32 v41, vcc, 0, v3, vcc
	global_load_ushort v39, v[40:41], off offset:3584
	v_add_co_u32_e32 v40, vcc, 0x60000, v2
	v_lshlrev_b32_e32 v24, 16, v24
	s_nop 0
	v_addc_co_u32_e32 v41, vcc, 0, v3, vcc
	v_add_co_u32_e32 v44, vcc, 0x64000, v2
	global_load_ushort v40, v[40:41], off offset:1024
	s_nop 0
	v_addc_co_u32_e32 v45, vcc, 0, v3, vcc
	global_load_ushort v41, v[44:45], off offset:2560
	v_add_co_u32_e32 v44, vcc, 0x69000, v2
	v_lshlrev_b32_e32 v25, 16, v25
	s_nop 0
	v_addc_co_u32_e32 v45, vcc, 0, v3, vcc
	global_load_ushort v43, v[44:45], off
	v_add_co_u32_e32 v44, vcc, 0x6d000, v2
	s_waitcnt vmcnt(0) lgkmcnt(0)
	v_lshlrev_b32_e32 v27, 16, v27
	v_addc_co_u32_e32 v45, vcc, 0, v3, vcc
	v_add_co_u32_e32 v46, vcc, 0x71000, v2
	global_load_ushort v44, v[44:45], off offset:1536
	s_nop 0
	v_addc_co_u32_e32 v47, vcc, 0, v3, vcc
	global_load_ushort v45, v[46:47], off offset:3072
	v_add_co_u32_e32 v46, vcc, 0x76000, v2
	v_lshlrev_b32_e32 v29, 16, v29
	s_nop 0
	v_addc_co_u32_e32 v47, vcc, 0, v3, vcc
	v_add_co_u32_e32 v48, vcc, 0x7a000, v2
	global_load_ushort v46, v[46:47], off offset:512
	s_nop 0
	v_addc_co_u32_e32 v49, vcc, 0, v3, vcc
	global_load_ushort v47, v[48:49], off offset:2048
	v_add_co_u32_e32 v48, vcc, 0x7e000, v2
	v_lshlrev_b32_e32 v31, 16, v31
	s_nop 0
	v_addc_co_u32_e32 v49, vcc, 0, v3, vcc
	v_add_co_u32_e32 v50, vcc, 0x83000, v2
	global_load_ushort v48, v[48:49], off offset:3584
	s_nop 0
	v_addc_co_u32_e32 v51, vcc, 0, v3, vcc
	global_load_ushort v49, v[50:51], off offset:1024
	v_add_co_u32_e32 v50, vcc, 0x87000, v2
	v_lshlrev_b32_e32 v33, 16, v33
	s_nop 0
	v_addc_co_u32_e32 v51, vcc, 0, v3, vcc
	v_add_co_u32_e32 v52, vcc, s2, v2
	global_load_ushort v50, v[50:51], off offset:2560
	s_nop 0
	v_addc_co_u32_e32 v53, vcc, 0, v3, vcc
	global_load_ushort v51, v[52:53], off
	v_add_co_u32_e32 v52, vcc, 0x90000, v2
	s_mov_b32 s2, 0xaf000
	s_nop 0
	v_addc_co_u32_e32 v53, vcc, 0, v3, vcc
	v_add_co_u32_e32 v54, vcc, 0x94000, v2
	global_load_ushort v52, v[52:53], off offset:1536
	s_nop 0
	v_addc_co_u32_e32 v55, vcc, 0, v3, vcc
	global_load_ushort v53, v[54:55], off offset:3072
	v_add_co_u32_e32 v54, vcc, 0x99000, v2
	v_lshlrev_b32_e32 v34, 16, v34
	s_nop 0
	v_addc_co_u32_e32 v55, vcc, 0, v3, vcc
	v_add_co_u32_e32 v56, vcc, 0x9d000, v2
	global_load_ushort v54, v[54:55], off offset:512
	s_nop 0
	v_addc_co_u32_e32 v57, vcc, 0, v3, vcc
	global_load_ushort v55, v[56:57], off offset:2048
	v_add_co_u32_e32 v56, vcc, 0xa1000, v2
	v_lshlrev_b32_e32 v35, 16, v35
	s_nop 0
	v_addc_co_u32_e32 v57, vcc, 0, v3, vcc
	v_add_co_u32_e32 v58, vcc, 0xa6000, v2
	global_load_ushort v56, v[56:57], off offset:3584
	s_nop 0
	v_addc_co_u32_e32 v59, vcc, 0, v3, vcc
	global_load_ushort v57, v[58:59], off offset:1024
	v_add_co_u32_e32 v58, vcc, 0xaa000, v2
	v_lshlrev_b32_e32 v36, 16, v36
	s_nop 0
	v_addc_co_u32_e32 v59, vcc, 0, v3, vcc
	v_add_co_u32_e32 v60, vcc, 0xd2000, v2
	global_load_ushort v58, v[58:59], off offset:2560
	s_nop 0
	v_addc_co_u32_e32 v61, vcc, 0, v3, vcc
	global_load_ushort v59, v[60:61], off
	v_add_co_u32_e32 v60, vcc, 0xd6000, v2
	v_lshlrev_b32_e32 v39, 16, v39
	s_nop 0
	v_addc_co_u32_e32 v61, vcc, 0, v3, vcc
	v_add_co_u32_e32 v62, vcc, 0xda000, v2
	global_load_ushort v60, v[60:61], off offset:1536
	s_nop 0
	v_addc_co_u32_e32 v63, vcc, 0, v3, vcc
	global_load_ushort v61, v[62:63], off offset:3072
	v_add_co_u32_e32 v62, vcc, 0xdf000, v2
	v_lshlrev_b32_e32 v40, 16, v40
	s_nop 0
	v_addc_co_u32_e32 v63, vcc, 0, v3, vcc
	v_add_co_u32_e32 v64, vcc, 0xe3000, v2
	global_load_ushort v62, v[62:63], off offset:512
	s_nop 0
	v_addc_co_u32_e32 v65, vcc, 0, v3, vcc
	global_load_ushort v63, v[64:65], off offset:2048
	v_add_co_u32_e32 v64, vcc, 0xe7000, v2
	v_lshlrev_b32_e32 v41, 16, v41
	s_nop 0
	v_addc_co_u32_e32 v65, vcc, 0, v3, vcc
	v_add_co_u32_e32 v66, vcc, 0xec000, v2
	global_load_ushort v64, v[64:65], off offset:3584
	s_nop 0
	v_addc_co_u32_e32 v67, vcc, 0, v3, vcc
	global_load_ushort v65, v[66:67], off offset:1024
	v_add_co_u32_e32 v66, vcc, 0xf0000, v2
	v_lshlrev_b32_e32 v43, 16, v43
	s_nop 0
	v_addc_co_u32_e32 v67, vcc, 0, v3, vcc
	v_add_co_u32_e32 v68, vcc, s2, v2
	global_load_ushort v66, v[66:67], off offset:2560
	s_nop 0
	v_addc_co_u32_e32 v69, vcc, 0, v3, vcc
	global_load_ushort v70, v[68:69], off
	s_mov_b32 s2, 0xf5000
	v_add_co_u32_e32 v68, vcc, s2, v2
	s_mov_b32 s2, 0xb3000
	s_nop 0
	v_addc_co_u32_e32 v69, vcc, 0, v3, vcc
	global_load_ushort v67, v[68:69], off
	s_waitcnt vmcnt(0) lgkmcnt(0)
	v_lshlrev_b32_e32 v44, 16, v44
	v_lshlrev_b32_e32 v45, 16, v45
	v_lshlrev_b32_e32 v46, 16, v46
	v_lshlrev_b32_e32 v47, 16, v47
	v_lshlrev_b32_e32 v48, 16, v48
	v_lshlrev_b32_e32 v49, 16, v49
	v_lshlrev_b32_e32 v50, 16, v50
	v_lshlrev_b32_e32 v51, 16, v51
	v_lshlrev_b32_e32 v52, 16, v52
	v_lshlrev_b32_e32 v53, 16, v53
	v_lshlrev_b32_e32 v54, 16, v54
	v_lshlrev_b32_e32 v55, 16, v55
	v_lshlrev_b32_e32 v56, 16, v56
	v_lshlrev_b32_e32 v57, 16, v57
	v_lshlrev_b32_e32 v58, 16, v58
	v_lshlrev_b32_e32 v59, 16, v59
	v_lshlrev_b32_e32 v60, 16, v60
	v_lshlrev_b32_e32 v61, 16, v61
	v_lshlrev_b32_e32 v62, 16, v62
	v_lshlrev_b32_e32 v63, 16, v63
	v_lshlrev_b32_e32 v64, 16, v64
	v_lshlrev_b32_e32 v65, 16, v65
	v_lshlrev_b32_e32 v66, 16, v66
	v_lshlrev_b32_e32 v68, 16, v70
	v_add_co_u32_e32 v70, vcc, s2, v2
	s_mov_b32 s2, 0xf9000
	s_nop 0
	v_addc_co_u32_e32 v71, vcc, 0, v3, vcc
	global_load_ushort v72, v[70:71], off offset:1536
	v_add_co_u32_e32 v70, vcc, s2, v2
	s_mov_b32 s2, 0xb7000
	s_nop 0
	v_addc_co_u32_e32 v71, vcc, 0, v3, vcc
	global_load_ushort v69, v[70:71], off offset:1536
	v_lshlrev_b32_e32 v67, 16, v67
	s_waitcnt vmcnt(0) lgkmcnt(0)
	v_lshlrev_b32_e32 v70, 16, v72
	v_add_co_u32_e32 v72, vcc, s2, v2
	s_mov_b32 s2, 0xfd000
	s_nop 0
	v_addc_co_u32_e32 v73, vcc, 0, v3, vcc
	global_load_ushort v74, v[72:73], off offset:3072
	v_add_co_u32_e32 v72, vcc, s2, v2
	s_mov_b32 s2, 0xbc000
	s_nop 0
	v_addc_co_u32_e32 v73, vcc, 0, v3, vcc
	global_load_ushort v71, v[72:73], off offset:3072
	v_lshlrev_b32_e32 v69, 16, v69
	s_waitcnt vmcnt(0) lgkmcnt(0)
	v_lshlrev_b32_e32 v72, 16, v74
	v_add_co_u32_e32 v74, vcc, s2, v2
	s_mov_b32 s2, 0x102000
	s_nop 0
	v_addc_co_u32_e32 v75, vcc, 0, v3, vcc
	global_load_ushort v76, v[74:75], off offset:512
	v_add_co_u32_e32 v74, vcc, s2, v2
	s_mov_b32 s2, 0xc0000
	s_nop 0
	v_addc_co_u32_e32 v75, vcc, 0, v3, vcc
	global_load_ushort v73, v[74:75], off offset:512
	v_lshlrev_b32_e32 v71, 16, v71
	s_waitcnt vmcnt(0) lgkmcnt(0)
	v_lshlrev_b32_e32 v74, 16, v76
	v_add_co_u32_e32 v76, vcc, s2, v2
	s_mov_b32 s2, 0x106000
	s_nop 0
	v_addc_co_u32_e32 v77, vcc, 0, v3, vcc
	global_load_ushort v79, v[76:77], off offset:2048
	v_add_co_u32_e32 v76, vcc, s2, v2
	s_mov_b32 s2, 0xc4000
	s_nop 0
	v_addc_co_u32_e32 v77, vcc, 0, v3, vcc
	v_add_co_u32_e32 v80, vcc, s2, v2
	s_mov_b32 s2, 0x10a000
	s_nop 0
	v_addc_co_u32_e32 v81, vcc, 0, v3, vcc
	global_load_ushort v75, v[76:77], off offset:2048
	v_lshlrev_b32_e32 v73, 16, v73
	s_waitcnt vmcnt(0) lgkmcnt(0)
	v_lshlrev_b32_e32 v76, 16, v79
	global_load_ushort v79, v[80:81], off offset:3584
	v_add_co_u32_e32 v80, vcc, s2, v2
	s_mov_b32 s2, 0xc9000
	s_nop 0
	v_addc_co_u32_e32 v81, vcc, 0, v3, vcc
	global_load_ushort v77, v[80:81], off offset:3584
	v_add_co_u32_e32 v80, vcc, s2, v2
	s_mov_b32 s2, 0x10f000
	s_nop 0
	v_addc_co_u32_e32 v81, vcc, 0, v3, vcc
	global_load_ushort v82, v[80:81], off offset:1024
	v_add_co_u32_e32 v80, vcc, s2, v2
	s_mov_b32 s2, 0xcd000
	s_nop 0
	v_addc_co_u32_e32 v81, vcc, 0, v3, vcc
	global_load_ushort v80, v[80:81], off offset:1024
	v_lshlrev_b32_e32 v75, 16, v75
	s_waitcnt vmcnt(0) lgkmcnt(0)
	v_lshlrev_b32_e32 v79, 16, v79
	v_lshlrev_b32_e32 v77, 16, v77
	v_lshlrev_b32_e32 v81, 16, v82
	v_add_co_u32_e32 v82, vcc, s2, v2
	s_mov_b32 s2, 0x113000
	s_nop 0
	v_addc_co_u32_e32 v83, vcc, 0, v3, vcc
	global_load_ushort v84, v[82:83], off offset:2560
	v_add_co_u32_e32 v82, vcc, s2, v2
	s_min_u32 s2, s19, 15
	s_nop 0
	v_addc_co_u32_e32 v83, vcc, 0, v3, vcc
	global_load_ushort v82, v[82:83], off offset:2560
	s_add_i32 s2, s2, 1
	v_cvt_f32_ubyte0_e32 v86, s2
	s_min_u32 s2, s19, 14
	s_add_i32 s2, s2, 2
	v_lshlrev_b32_e32 v80, 16, v80
	s_waitcnt vmcnt(0) lgkmcnt(0)
	v_lshlrev_b32_e32 v83, 16, v84
	v_add_f32_e32 v84, 0, v5
	v_add_f32_e32 v84, v4, v84
	v_add_f32_e32 v84, v1, v84
	v_add_f32_e32 v84, v8, v84
	v_add_f32_e32 v84, v10, v84
	v_add_f32_e32 v84, v14, v84
	v_add_f32_e32 v84, v16, v84
	v_add_f32_e32 v84, v20, v84
	v_add_f32_e32 v84, v21, v84
	v_add_f32_e32 v84, v26, v84
	v_add_f32_e32 v84, v28, v84
	v_add_f32_e32 v84, v30, v84
	v_add_f32_e32 v84, v32, v84
	v_add_f32_e32 v84, v37, v84
	v_add_f32_e32 v84, v38, v84
	v_add_f32_e32 v85, v42, v84
	v_div_scale_f32 v87, s[16:17], v86, v86, v85
	v_rcp_f32_e32 v88, v87
	v_sub_f32_e32 v42, v6, v42
	v_lshl_add_u32 v84, v0, 1, 0
	v_add_f32_e32 v42, v42, v85
	v_fma_f32 v89, -v87, v88, 1.0
	v_fmac_f32_e32 v88, v89, v88
	v_div_scale_f32 v89, vcc, v85, v86, v85
	v_mul_f32_e32 v90, v89, v88
	v_fma_f32 v91, -v87, v90, v89
	v_fmac_f32_e32 v90, v91, v88
	v_fma_f32 v87, -v87, v90, v89
	v_div_fmas_f32 v87, v87, v88, v90
	v_div_fixup_f32 v86, v87, v86, v85
	v_sub_f32_e32 v86, v86, v5
	v_cvt_pk_bf16_f32 v86, v86, v17
	v_cvt_f32_ubyte0_e32 v85, s2
	ds_write_b16 v84, v86
	v_div_scale_f32 v86, s[16:17], v85, v85, v42
	v_rcp_f32_e32 v87, v86
	s_min_u32 s2, s19, 13
	v_sub_f32_e32 v38, v7, v38
	s_add_i32 s2, s2, 3
	v_fma_f32 v88, -v86, v87, 1.0
	v_fmac_f32_e32 v87, v88, v87
	v_div_scale_f32 v88, vcc, v42, v85, v42
	v_mul_f32_e32 v89, v88, v87
	v_fma_f32 v90, -v86, v89, v88
	v_fmac_f32_e32 v89, v90, v87
	v_fma_f32 v86, -v86, v89, v88
	v_div_fmas_f32 v86, v86, v87, v89
	v_div_fixup_f32 v85, v86, v85, v42
	v_sub_f32_e32 v85, v85, v6
	v_cvt_pk_bf16_f32 v85, v85, v17
	v_add_f32_e32 v38, v38, v42
	v_cvt_f32_ubyte0_e32 v42, s2
	ds_write_b16 v84, v85 offset:1040
	v_div_scale_f32 v85, s[16:17], v42, v42, v38
	v_rcp_f32_e32 v86, v85
	s_min_u32 s2, s19, 12
	v_sub_f32_e32 v37, v9, v37
	s_add_i32 s2, s2, 4
	v_fma_f32 v87, -v85, v86, 1.0
	v_fmac_f32_e32 v86, v87, v86
	v_div_scale_f32 v87, vcc, v38, v42, v38
	v_mul_f32_e32 v88, v87, v86
	v_fma_f32 v89, -v85, v88, v87
	v_fmac_f32_e32 v88, v89, v86
	v_fma_f32 v85, -v85, v88, v87
	v_div_fmas_f32 v85, v85, v86, v88
	v_div_fixup_f32 v42, v85, v42, v38
	v_sub_f32_e32 v42, v42, v7
	v_cvt_pk_bf16_f32 v42, v42, v17
	v_add_f32_e32 v37, v37, v38
	v_cvt_f32_ubyte0_e32 v38, s2
	ds_write_b16 v84, v42 offset:2080
	v_div_scale_f32 v42, s[16:17], v38, v38, v37
	v_rcp_f32_e32 v85, v42
	s_min_u32 s2, s19, 11
	v_sub_f32_e32 v32, v11, v32
	s_add_i32 s2, s2, 5
	v_fma_f32 v86, -v42, v85, 1.0
	v_fmac_f32_e32 v85, v86, v85
	v_div_scale_f32 v86, vcc, v37, v38, v37
	v_mul_f32_e32 v87, v86, v85
	v_fma_f32 v88, -v42, v87, v86
	v_fmac_f32_e32 v87, v88, v85
	v_fma_f32 v42, -v42, v87, v86
	v_div_fmas_f32 v42, v42, v85, v87
	v_div_fixup_f32 v38, v42, v38, v37
	v_sub_f32_e32 v38, v38, v9
	v_cvt_pk_bf16_f32 v38, v38, v17
	v_add_f32_e32 v32, v32, v37
	v_cvt_f32_ubyte0_e32 v37, s2
	ds_write_b16 v84, v38 offset:3120
	v_div_scale_f32 v38, s[16:17], v37, v37, v32
	v_rcp_f32_e32 v42, v38
	s_min_u32 s2, s19, 10
	v_sub_f32_e32 v30, v12, v30
	s_add_i32 s2, s2, 6
	v_fma_f32 v85, -v38, v42, 1.0
	v_fmac_f32_e32 v42, v85, v42
	v_div_scale_f32 v85, vcc, v32, v37, v32
	v_mul_f32_e32 v86, v85, v42
	v_fma_f32 v87, -v38, v86, v85
	v_fmac_f32_e32 v86, v87, v42
	v_fma_f32 v38, -v38, v86, v85
	v_div_fmas_f32 v38, v38, v42, v86
	v_div_fixup_f32 v37, v38, v37, v32
	v_sub_f32_e32 v37, v37, v11
	v_cvt_pk_bf16_f32 v37, v37, v17
	v_add_f32_e32 v30, v30, v32
	v_cvt_f32_ubyte0_e32 v32, s2
	ds_write_b16 v84, v37 offset:4160
	v_div_scale_f32 v37, s[16:17], v32, v32, v30
	v_rcp_f32_e32 v38, v37
	s_min_u32 s2, s19, 9
	v_sub_f32_e32 v28, v13, v28
	s_add_i32 s2, s2, 7
	v_fma_f32 v42, -v37, v38, 1.0
	v_fmac_f32_e32 v38, v42, v38
	v_div_scale_f32 v42, vcc, v30, v32, v30
	v_mul_f32_e32 v85, v42, v38
	v_fma_f32 v86, -v37, v85, v42
	v_fmac_f32_e32 v85, v86, v38
	v_fma_f32 v37, -v37, v85, v42
	v_div_fmas_f32 v37, v37, v38, v85
	v_div_fixup_f32 v32, v37, v32, v30
	v_sub_f32_e32 v32, v32, v12
	v_cvt_pk_bf16_f32 v32, v32, v17
	v_add_f32_e32 v28, v28, v30
	v_cvt_f32_ubyte0_e32 v30, s2
	ds_write_b16 v84, v32 offset:5200
	v_div_scale_f32 v32, s[16:17], v30, v30, v28
	v_rcp_f32_e32 v37, v32
	s_min_u32 s2, s19, 8
	v_sub_f32_e32 v26, v15, v26
	s_add_i32 s2, s2, 8
	v_fma_f32 v38, -v32, v37, 1.0
	v_fmac_f32_e32 v37, v38, v37
	v_div_scale_f32 v38, vcc, v28, v30, v28
	v_mul_f32_e32 v42, v38, v37
	v_fma_f32 v85, -v32, v42, v38
	v_fmac_f32_e32 v42, v85, v37
	v_fma_f32 v32, -v32, v42, v38
	v_div_fmas_f32 v32, v32, v37, v42
	v_div_fixup_f32 v30, v32, v30, v28
	v_sub_f32_e32 v30, v30, v13
	v_cvt_pk_bf16_f32 v30, v30, v17
	v_add_f32_e32 v26, v26, v28
	v_cvt_f32_ubyte0_e32 v28, s2
	ds_write_b16 v84, v30 offset:6240
	v_div_scale_f32 v30, s[16:17], v28, v28, v26
	v_rcp_f32_e32 v32, v30
	s_min_u32 s2, s19, 7
	v_sub_f32_e32 v21, v18, v21
	s_add_i32 s2, s2, 9
	v_fma_f32 v37, -v30, v32, 1.0
	v_fmac_f32_e32 v32, v37, v32
	v_div_scale_f32 v37, vcc, v26, v28, v26
	v_mul_f32_e32 v38, v37, v32
	v_fma_f32 v42, -v30, v38, v37
	v_fmac_f32_e32 v38, v42, v32
	v_fma_f32 v30, -v30, v38, v37
	v_div_fmas_f32 v30, v30, v32, v38
	v_div_fixup_f32 v28, v30, v28, v26
	v_sub_f32_e32 v28, v28, v15
	v_cvt_pk_bf16_f32 v28, v28, v17
	v_add_f32_e32 v21, v21, v26
	v_cvt_f32_ubyte0_e32 v26, s2
	ds_write_b16 v84, v28 offset:7280
	v_div_scale_f32 v28, s[16:17], v26, v26, v21
	v_rcp_f32_e32 v30, v28
	s_min_u32 s2, s19, 6
	v_sub_f32_e32 v20, v19, v20
	s_add_i32 s2, s2, 10
	v_fma_f32 v32, -v28, v30, 1.0
	v_fmac_f32_e32 v30, v32, v30
	v_div_scale_f32 v32, vcc, v21, v26, v21
	v_mul_f32_e32 v37, v32, v30
	v_fma_f32 v38, -v28, v37, v32
	v_fmac_f32_e32 v37, v38, v30
	v_fma_f32 v28, -v28, v37, v32
	v_div_fmas_f32 v28, v28, v30, v37
	v_div_fixup_f32 v26, v28, v26, v21
	v_sub_f32_e32 v26, v26, v18
	v_cvt_pk_bf16_f32 v26, v26, v17
	v_add_f32_e32 v20, v20, v21
	v_cvt_f32_ubyte0_e32 v21, s2
	ds_write_b16 v84, v26 offset:8320
	v_div_scale_f32 v26, s[16:17], v21, v21, v20
	v_rcp_f32_e32 v28, v26
	s_min_u32 s2, s19, 5
	v_sub_f32_e32 v16, v22, v16
	s_add_i32 s2, s2, 11
	v_fma_f32 v30, -v26, v28, 1.0
	v_fmac_f32_e32 v28, v30, v28
	v_div_scale_f32 v30, vcc, v20, v21, v20
	v_mul_f32_e32 v32, v30, v28
	v_fma_f32 v37, -v26, v32, v30
	v_fmac_f32_e32 v32, v37, v28
	v_fma_f32 v26, -v26, v32, v30
	v_div_fmas_f32 v26, v26, v28, v32
	v_div_fixup_f32 v21, v26, v21, v20
	v_sub_f32_e32 v21, v21, v19
	v_cvt_pk_bf16_f32 v21, v21, v17
	v_add_f32_e32 v16, v16, v20
	v_cvt_f32_ubyte0_e32 v20, s2
	ds_write_b16 v84, v21 offset:9360
	v_div_scale_f32 v21, s[16:17], v20, v20, v16
	v_rcp_f32_e32 v26, v21
	s_min_u32 s2, s19, 4
	v_sub_f32_e32 v14, v23, v14
	s_add_i32 s2, s2, 12
	v_fma_f32 v28, -v21, v26, 1.0
	v_fmac_f32_e32 v26, v28, v26
	v_div_scale_f32 v28, vcc, v16, v20, v16
	v_mul_f32_e32 v30, v28, v26
	v_fma_f32 v32, -v21, v30, v28
	v_fmac_f32_e32 v30, v32, v26
	v_fma_f32 v21, -v21, v30, v28
	v_div_fmas_f32 v21, v21, v26, v30
	v_div_fixup_f32 v20, v21, v20, v16
	v_sub_f32_e32 v20, v20, v22
	v_cvt_pk_bf16_f32 v20, v20, v17
	v_add_f32_e32 v14, v14, v16
	v_cvt_f32_ubyte0_e32 v16, s2
	ds_write_b16 v84, v20 offset:10400
	v_div_scale_f32 v20, s[16:17], v16, v16, v14
	v_rcp_f32_e32 v21, v20
	s_min_u32 s2, s19, 3
	v_sub_f32_e32 v10, v24, v10
	s_add_i32 s2, s2, 13
	v_fma_f32 v26, -v20, v21, 1.0
	v_fmac_f32_e32 v21, v26, v21
	v_div_scale_f32 v26, vcc, v14, v16, v14
	v_mul_f32_e32 v28, v26, v21
	v_fma_f32 v30, -v20, v28, v26
	v_fmac_f32_e32 v28, v30, v21
	v_fma_f32 v20, -v20, v28, v26
	v_div_fmas_f32 v20, v20, v21, v28
	v_div_fixup_f32 v16, v20, v16, v14
	v_sub_f32_e32 v16, v16, v23
	v_cvt_pk_bf16_f32 v16, v16, v17
	v_add_f32_e32 v10, v10, v14
	v_cvt_f32_ubyte0_e32 v14, s2
	ds_write_b16 v84, v16 offset:11440
	v_div_scale_f32 v16, s[16:17], v14, v14, v10
	v_rcp_f32_e32 v20, v16
	s_min_u32 s2, s19, 2
	v_sub_f32_e32 v8, v25, v8
	s_add_i32 s2, s2, 14
	v_fma_f32 v21, -v16, v20, 1.0
	v_fmac_f32_e32 v20, v21, v20
	v_div_scale_f32 v21, vcc, v10, v14, v10
	v_mul_f32_e32 v26, v21, v20
	v_fma_f32 v28, -v16, v26, v21
	v_fmac_f32_e32 v26, v28, v20
	v_fma_f32 v16, -v16, v26, v21
	v_div_fmas_f32 v16, v16, v20, v26
	v_div_fixup_f32 v14, v16, v14, v10
	v_sub_f32_e32 v14, v14, v24
	v_cvt_pk_bf16_f32 v14, v14, v17
	v_add_f32_e32 v8, v8, v10
	v_cvt_f32_ubyte0_e32 v10, s2
	ds_write_b16 v84, v14 offset:12480
	v_div_scale_f32 v14, s[16:17], v10, v10, v8
	v_rcp_f32_e32 v16, v14
	v_sub_f32_e32 v1, v27, v1
	v_add_f32_e32 v1, v1, v8
	v_sub_f32_e32 v4, v29, v4
	v_fma_f32 v20, -v14, v16, 1.0
	v_fmac_f32_e32 v16, v20, v16
	v_div_scale_f32 v20, vcc, v8, v10, v8
	v_mul_f32_e32 v21, v20, v16
	v_fma_f32 v26, -v14, v21, v20
	v_fmac_f32_e32 v21, v26, v16
	v_fma_f32 v14, -v14, v21, v20
	v_div_fmas_f32 v14, v14, v16, v21
	v_div_fixup_f32 v10, v14, v10, v8
	v_sub_f32_e32 v10, v10, v25
	v_cvt_pk_bf16_f32 v10, v10, v17
	v_div_scale_f32 v8, s[16:17], s14, s14, v1
	ds_write_b16 v84, v10 offset:13520
	v_rcp_f32_e32 v10, v8
	s_mov_b32 s2, 0x3d800000
	v_lshlrev_b32_e32 v82, 16, v82
	v_fma_f32 v14, -v8, v10, 1.0
	v_fmac_f32_e32 v10, v14, v10
	v_div_scale_f32 v14, vcc, v1, s14, v1
	v_mul_f32_e32 v16, v14, v10
	v_fma_f32 v20, -v8, v16, v14
	v_fmac_f32_e32 v16, v20, v10
	v_fma_f32 v8, -v8, v16, v14
	v_div_fmas_f32 v8, v8, v10, v16
	v_div_fixup_f32 v8, v8, s14, v1
	v_add_f32_e32 v1, v4, v1
	v_fma_f32 v4, v1, s2, -v29
	v_cvt_pk_bf16_f32 v4, v4, v17
	ds_write_b16 v84, v4 offset:15600
	v_sub_f32_e32 v4, v31, v5
	v_add_f32_e32 v1, v4, v1
	v_fma_f32 v4, v1, s2, -v31
	v_cvt_pk_bf16_f32 v4, v4, v17
	ds_write_b16 v84, v4 offset:16640
	v_sub_f32_e32 v4, v33, v6
	v_add_f32_e32 v1, v4, v1
	v_fma_f32 v4, v1, s2, -v33
	v_cvt_pk_bf16_f32 v4, v4, v17
	ds_write_b16 v84, v4 offset:17680
	v_sub_f32_e32 v4, v34, v7
	v_add_f32_e32 v1, v4, v1
	v_fma_f32 v4, v1, s2, -v34
	v_cvt_pk_bf16_f32 v4, v4, v17
	ds_write_b16 v84, v4 offset:18720
	v_sub_f32_e32 v4, v35, v9
	v_add_f32_e32 v1, v4, v1
	v_fma_f32 v4, v1, s2, -v35
	v_cvt_pk_bf16_f32 v4, v4, v17
	ds_write_b16 v84, v4 offset:19760
	v_sub_f32_e32 v4, v36, v11
	v_add_f32_e32 v1, v4, v1
	v_fma_f32 v4, v1, s2, -v36
	v_cvt_pk_bf16_f32 v4, v4, v17
	ds_write_b16 v84, v4 offset:20800
	v_sub_f32_e32 v4, v39, v12
	v_add_f32_e32 v1, v4, v1
	v_fma_f32 v4, v1, s2, -v39
	v_cvt_pk_bf16_f32 v4, v4, v17
	ds_write_b16 v84, v4 offset:21840
	v_sub_f32_e32 v4, v40, v13
	v_add_f32_e32 v1, v4, v1
	v_fma_f32 v4, v1, s2, -v40
	v_cvt_pk_bf16_f32 v4, v4, v17
	ds_write_b16 v84, v4 offset:22880
	v_sub_f32_e32 v4, v41, v15
	v_add_f32_e32 v1, v4, v1
	v_fma_f32 v4, v1, s2, -v41
	v_cvt_pk_bf16_f32 v4, v4, v17
	ds_write_b16 v84, v4 offset:23920
	v_sub_f32_e32 v4, v43, v18
	v_add_f32_e32 v1, v4, v1
	v_fma_f32 v4, v1, s2, -v43
	v_cvt_pk_bf16_f32 v4, v4, v17
	ds_write_b16 v84, v4 offset:24960
	v_sub_f32_e32 v4, v44, v19
	v_add_f32_e32 v1, v4, v1
	v_fma_f32 v4, v1, s2, -v44
	v_cvt_pk_bf16_f32 v4, v4, v17
	ds_write_b16 v84, v4 offset:26000
	v_sub_f32_e32 v4, v45, v22
	v_add_f32_e32 v1, v4, v1
	v_fma_f32 v4, v1, s2, -v45
	v_cvt_pk_bf16_f32 v4, v4, v17
	ds_write_b16 v84, v4 offset:27040
	v_sub_f32_e32 v4, v46, v23
	v_add_f32_e32 v1, v4, v1
	v_fma_f32 v4, v1, s2, -v46
	v_cvt_pk_bf16_f32 v4, v4, v17
	ds_write_b16 v84, v4 offset:28080
	v_sub_f32_e32 v4, v47, v24
	v_add_f32_e32 v1, v4, v1
	v_fma_f32 v4, v1, s2, -v47
	v_cvt_pk_bf16_f32 v4, v4, v17
	ds_write_b16 v84, v4 offset:29120
	v_sub_f32_e32 v4, v48, v25
	v_add_f32_e32 v1, v4, v1
	v_fma_f32 v4, v1, s2, -v48
	v_cvt_pk_bf16_f32 v4, v4, v17
	ds_write_b16 v84, v4 offset:30160
	v_sub_f32_e32 v4, v49, v27
	v_add_f32_e32 v1, v4, v1
	v_fma_f32 v4, v1, s2, -v49
	v_cvt_pk_bf16_f32 v4, v4, v17
	ds_write_b16 v84, v4 offset:31200
	v_sub_f32_e32 v4, v50, v29
	v_add_f32_e32 v1, v4, v1
	v_fma_f32 v4, v1, s2, -v50
	v_cvt_pk_bf16_f32 v4, v4, v17
	ds_write_b16 v84, v4 offset:32240
	v_sub_f32_e32 v4, v51, v31
	v_add_f32_e32 v1, v4, v1
	v_fma_f32 v4, v1, s2, -v51
	v_cvt_pk_bf16_f32 v4, v4, v17
	ds_write_b16 v84, v4 offset:33280
	v_sub_f32_e32 v4, v52, v33
	v_add_f32_e32 v1, v4, v1
	v_fma_f32 v4, v1, s2, -v52
	v_cvt_pk_bf16_f32 v4, v4, v17
	ds_write_b16 v84, v4 offset:34320
	v_sub_f32_e32 v4, v53, v34
	v_add_f32_e32 v1, v4, v1
	v_fma_f32 v4, v1, s2, -v53
	v_cvt_pk_bf16_f32 v4, v4, v17
	ds_write_b16 v84, v4 offset:35360
	v_sub_f32_e32 v4, v54, v35
	v_add_f32_e32 v1, v4, v1
	v_fma_f32 v4, v1, s2, -v54
	v_cvt_pk_bf16_f32 v4, v4, v17
	ds_write_b16 v84, v4 offset:36400
	v_sub_f32_e32 v4, v55, v36
	v_add_f32_e32 v1, v4, v1
	v_fma_f32 v4, v1, s2, -v55
	v_cvt_pk_bf16_f32 v4, v4, v17
	ds_write_b16 v84, v4 offset:37440
	v_sub_f32_e32 v4, v56, v39
	v_add_f32_e32 v1, v4, v1
	v_fma_f32 v4, v1, s2, -v56
	v_cvt_pk_bf16_f32 v4, v4, v17
	ds_write_b16 v84, v4 offset:38480
	v_sub_f32_e32 v4, v57, v40
	v_add_f32_e32 v1, v4, v1
	v_fma_f32 v4, v1, s2, -v57
	v_cvt_pk_bf16_f32 v4, v4, v17
	ds_write_b16 v84, v4 offset:39520
	v_sub_f32_e32 v4, v58, v41
	v_add_f32_e32 v1, v4, v1
	v_fma_f32 v4, v1, s2, -v58
	v_cvt_pk_bf16_f32 v4, v4, v17
	ds_write_b16 v84, v4 offset:40560
	v_sub_f32_e32 v4, v68, v43
	v_add_f32_e32 v1, v4, v1
	v_fma_f32 v4, v1, s2, -v68
	v_cvt_pk_bf16_f32 v4, v4, v17
	ds_write_b16 v84, v4 offset:41600
	v_sub_f32_e32 v4, v70, v44
	v_add_f32_e32 v1, v4, v1
	v_fma_f32 v4, v1, s2, -v70
	v_cvt_pk_bf16_f32 v4, v4, v17
	ds_write_b16 v84, v4 offset:42640
	v_sub_f32_e32 v4, v72, v45
	v_add_f32_e32 v1, v4, v1
	v_fma_f32 v4, v1, s2, -v72
	v_cvt_pk_bf16_f32 v4, v4, v17
	ds_write_b16 v84, v4 offset:43680
	v_sub_f32_e32 v4, v74, v46
	v_add_f32_e32 v1, v4, v1
	v_fma_f32 v4, v1, s2, -v74
	v_cvt_pk_bf16_f32 v4, v4, v17
	ds_write_b16 v84, v4 offset:44720
	v_sub_f32_e32 v4, v76, v47
	v_add_f32_e32 v1, v4, v1
	v_fma_f32 v4, v1, s2, -v76
	v_cvt_pk_bf16_f32 v4, v4, v17
	ds_write_b16 v84, v4 offset:45760
	v_sub_f32_e32 v4, v79, v48
	v_add_f32_e32 v1, v4, v1
	v_fma_f32 v4, v1, s2, -v79
	v_cvt_pk_bf16_f32 v4, v4, v17
	ds_write_b16 v84, v4 offset:46800
	v_sub_f32_e32 v4, v81, v49
	v_add_f32_e32 v1, v4, v1
	v_fma_f32 v4, v1, s2, -v81
	v_cvt_pk_bf16_f32 v4, v4, v17
	ds_write_b16 v84, v4 offset:47840
	v_sub_f32_e32 v4, v83, v50
	v_add_f32_e32 v1, v4, v1
	v_fma_f32 v4, v1, s2, -v83
	v_cvt_pk_bf16_f32 v4, v4, v17
	ds_write_b16 v84, v4 offset:48880
	v_sub_f32_e32 v4, v59, v51
	v_add_f32_e32 v1, v4, v1
	v_fma_f32 v4, v1, s2, -v59
	v_cvt_pk_bf16_f32 v4, v4, v17
	ds_write_b16 v84, v4 offset:49920
	v_sub_f32_e32 v4, v60, v52
	v_add_f32_e32 v1, v4, v1
	v_fma_f32 v4, v1, s2, -v60
	v_cvt_pk_bf16_f32 v4, v4, v17
	ds_write_b16 v84, v4 offset:50960
	v_sub_f32_e32 v4, v61, v53
	v_add_f32_e32 v1, v4, v1
	v_fma_f32 v4, v1, s2, -v61
	v_cvt_pk_bf16_f32 v4, v4, v17
	ds_write_b16 v84, v4 offset:52000
	v_sub_f32_e32 v4, v62, v54
	v_add_f32_e32 v1, v4, v1
	v_fma_f32 v4, v1, s2, -v62
	v_cvt_pk_bf16_f32 v4, v4, v17
	ds_write_b16 v84, v4 offset:53040
	v_sub_f32_e32 v4, v63, v55
	v_add_f32_e32 v1, v4, v1
	v_fma_f32 v4, v1, s2, -v63
	v_cvt_pk_bf16_f32 v4, v4, v17
	ds_write_b16 v84, v4 offset:54080
	v_sub_f32_e32 v4, v64, v56
	v_add_f32_e32 v1, v4, v1
	v_fma_f32 v4, v1, s2, -v64
	v_cvt_pk_bf16_f32 v4, v4, v17
	ds_write_b16 v84, v4 offset:55120
	v_sub_f32_e32 v4, v65, v57
	v_add_f32_e32 v1, v4, v1
	v_fma_f32 v4, v1, s2, -v65
	v_cvt_pk_bf16_f32 v4, v4, v17
	ds_write_b16 v84, v4 offset:56160
	v_sub_f32_e32 v4, v66, v58
	v_add_f32_e32 v1, v4, v1
	v_fma_f32 v4, v1, s2, -v66
	v_cvt_pk_bf16_f32 v4, v4, v17
	ds_write_b16 v84, v4 offset:57200
	v_sub_f32_e32 v4, v67, v68
	v_add_f32_e32 v1, v4, v1
	v_fma_f32 v4, v1, s2, -v67
	v_cvt_pk_bf16_f32 v4, v4, v17
	ds_write_b16 v84, v4 offset:58240
	v_sub_f32_e32 v4, v69, v70
	v_add_f32_e32 v1, v4, v1
	v_fma_f32 v4, v1, s2, -v69
	v_cvt_pk_bf16_f32 v4, v4, v17
	ds_write_b16 v84, v4 offset:59280
	v_sub_f32_e32 v4, v71, v72
	v_add_f32_e32 v1, v4, v1
	v_fma_f32 v4, v1, s2, -v71
	v_cvt_pk_bf16_f32 v4, v4, v17
	ds_write_b16 v84, v4 offset:60320
	v_sub_f32_e32 v4, v73, v74
	v_add_f32_e32 v1, v4, v1
	v_fma_f32 v4, v1, s2, -v73
	v_cvt_pk_bf16_f32 v4, v4, v17
	ds_write_b16 v84, v4 offset:61360
	v_sub_f32_e32 v4, v75, v76
	v_add_f32_e32 v1, v4, v1
	v_fma_f32 v4, v1, s2, -v75
	v_cvt_pk_bf16_f32 v4, v4, v17
	ds_write_b16 v84, v4 offset:62400
	v_sub_f32_e32 v4, v77, v79
	v_add_f32_e32 v1, v4, v1
	v_fma_f32 v4, v1, s2, -v77
	v_cvt_pk_bf16_f32 v4, v4, v17
	ds_write_b16 v84, v4 offset:63440
	v_sub_f32_e32 v4, v80, v81
	v_add_f32_e32 v1, v4, v1
	v_fma_f32 v4, v1, s2, -v80
	v_cvt_pk_bf16_f32 v4, v4, v17
	ds_write_b16 v84, v4 offset:64480
	v_sub_f32_e32 v4, v82, v83
	v_add_f32_e32 v1, v4, v1
	v_sub_f32_e32 v8, v8, v27
	v_fma_f32 v1, v1, s2, -v82
	v_cvt_pk_bf16_f32 v8, v8, v17
	ds_write_b16 v84, v8 offset:14560
	v_cvt_pk_bf16_f32 v1, v1, v17
.LBB0_661:
	s_or_b64 exec, exec, s[8:9]
	s_and_saveexec_b64 s[8:9], s[4:5]
	s_xor_b64 s[4:5], exec, s[8:9]
	s_cbranch_execz .LBB0_668
	v_mov_b32_e32 v1, 0
	s_and_b64 vcc, exec, s[40:41]
	v_mov_b32_e32 v8, 0
	s_cbranch_vccnz .LBB0_664
	v_add_co_u32_e32 v4, vcc, 0xffff2e00, v2
	s_nop 1
	v_addc_co_u32_e32 v5, vcc, -1, v3, vcc
	global_load_ushort v4, v[4:5], off
	s_waitcnt vmcnt(0) lgkmcnt(0)
	v_lshlrev_b32_e32 v8, 16, v4

.LBB0_666:
	s_and_b64 vcc, exec, s[40:41]
	s_cbranch_vccnz .LBB0_751
	v_add_co_u32_e32 v4, vcc, 0xffffba00, v2
	s_mov_b32 s2, 4.0
	s_nop 0
	v_addc_co_u32_e32 v5, vcc, -1, v3, vcc
	global_load_ushort v4, v[4:5], off
	s_waitcnt vmcnt(0) lgkmcnt(0)
	v_lshlrev_b32_e32 v4, 16, v4
	s_branch .LBB0_752

.LBB0_670:
	s_cmp_eq_u32 s19, 0
	s_cbranch_scc1 .LBB0_672
	v_add_co_u32_e32 v4, vcc, 0xffffba00, v2
	s_mov_b32 s2, 2.0
	s_nop 0
	v_addc_co_u32_e32 v5, vcc, -1, v3, vcc
	global_load_ushort v1, v[4:5], off
	s_waitcnt vmcnt(0) lgkmcnt(0)
	v_lshlrev_b32_e32 v1, 16, v1
	s_branch .LBB0_673

.LBB0_673:
	v_add_co_u32_e32 v6, vcc, 0x4000, v2
	global_load_ushort v4, v[2:3], off
	s_nop 0
	v_addc_co_u32_e32 v7, vcc, 0, v3, vcc
	global_load_ushort v5, v[6:7], off offset:1536
	v_add_co_u32_e32 v6, vcc, 0x8000, v2
	s_mov_b32 s8, 0x8c000
	s_nop 0
	v_addc_co_u32_e32 v7, vcc, 0, v3, vcc
	v_add_co_u32_e32 v8, vcc, 0xd000, v2
	global_load_ushort v6, v[6:7], off offset:3072
	s_nop 0
	v_addc_co_u32_e32 v9, vcc, 0, v3, vcc
	global_load_ushort v7, v[8:9], off offset:512
	v_add_co_u32_e32 v8, vcc, 0x11000, v2
	s_waitcnt vmcnt(0) lgkmcnt(0)
	v_lshlrev_b32_e32 v4, 16, v4
	v_addc_co_u32_e32 v9, vcc, 0, v3, vcc
	v_add_co_u32_e32 v10, vcc, 0x15000, v2
	global_load_ushort v8, v[8:9], off offset:2048
	s_nop 0
	v_addc_co_u32_e32 v11, vcc, 0, v3, vcc
	global_load_ushort v9, v[10:11], off offset:3584
	v_add_co_u32_e32 v10, vcc, s63, v2
	v_lshlrev_b32_e32 v5, 16, v5
	s_nop 0
	v_addc_co_u32_e32 v11, vcc, 0, v3, vcc
	v_add_co_u32_e32 v12, vcc, s64, v2
	global_load_ushort v10, v[10:11], off offset:1024
	s_nop 0
	v_addc_co_u32_e32 v13, vcc, 0, v3, vcc
	global_load_ushort v11, v[12:13], off offset:2560
	v_add_co_u32_e32 v12, vcc, 0x23000, v2
	v_lshlrev_b32_e32 v6, 16, v6
	s_nop 0
	v_addc_co_u32_e32 v13, vcc, 0, v3, vcc
	v_add_co_u32_e32 v14, vcc, 0x27000, v2
	global_load_ushort v12, v[12:13], off
	s_nop 0
	v_addc_co_u32_e32 v15, vcc, 0, v3, vcc
	global_load_ushort v13, v[14:15], off offset:1536
	v_add_co_u32_e32 v14, vcc, 0x2b000, v2
	v_lshlrev_b32_e32 v7, 16, v7
	s_nop 0
	v_addc_co_u32_e32 v15, vcc, 0, v3, vcc
	v_add_co_u32_e32 v18, vcc, 0x30000, v2
	global_load_ushort v14, v[14:15], off offset:3072
	s_nop 0
	v_addc_co_u32_e32 v19, vcc, 0, v3, vcc
	global_load_ushort v15, v[18:19], off offset:512
	v_add_co_u32_e32 v18, vcc, 0x34000, v2
	s_waitcnt vmcnt(0) lgkmcnt(0)
	v_lshlrev_b32_e32 v8, 16, v8
	v_addc_co_u32_e32 v19, vcc, 0, v3, vcc
	global_load_ushort v16, v[18:19], off offset:2048
	v_add_co_u32_e32 v18, vcc, 0x38000, v2
	v_lshlrev_b32_e32 v9, 16, v9
	s_nop 0
	v_addc_co_u32_e32 v19, vcc, 0, v3, vcc
	v_add_co_u32_e32 v20, vcc, 0x3d000, v2
	global_load_ushort v18, v[18:19], off offset:3584
	s_nop 0
	v_addc_co_u32_e32 v21, vcc, 0, v3, vcc
	global_load_ushort v19, v[20:21], off offset:1024
	v_add_co_u32_e32 v20, vcc, 0x41000, v2
	v_lshlrev_b32_e32 v10, 16, v10
	s_nop 0
	v_addc_co_u32_e32 v21, vcc, 0, v3, vcc
	v_add_co_u32_e32 v22, vcc, 0x46000, v2
	global_load_ushort v20, v[20:21], off offset:2560
	s_nop 0
	v_addc_co_u32_e32 v23, vcc, 0, v3, vcc
	global_load_ushort v21, v[22:23], off
	v_add_co_u32_e32 v22, vcc, 0x4a000, v2
	v_lshlrev_b32_e32 v11, 16, v11
	s_nop 0
	v_addc_co_u32_e32 v23, vcc, 0, v3, vcc
	v_add_co_u32_e32 v24, vcc, 0x4e000, v2
	global_load_ushort v22, v[22:23], off offset:1536
	s_nop 0
	v_addc_co_u32_e32 v25, vcc, 0, v3, vcc
	global_load_ushort v23, v[24:25], off offset:3072
	v_add_co_u32_e32 v24, vcc, 0x53000, v2
	v_lshlrev_b32_e32 v12, 16, v12
	s_nop 0
	v_addc_co_u32_e32 v25, vcc, 0, v3, vcc
	v_add_co_u32_e32 v26, vcc, 0x57000, v2
	global_load_ushort v24, v[24:25], off offset:512
	s_nop 0
	v_addc_co_u32_e32 v27, vcc, 0, v3, vcc
	global_load_ushort v25, v[26:27], off offset:2048
	v_add_co_u32_e32 v26, vcc, 0x5b000, v2
	v_lshlrev_b32_e32 v13, 16, v13
	s_nop 0
	v_addc_co_u32_e32 v27, vcc, 0, v3, vcc
	v_add_co_u32_e32 v28, vcc, 0x60000, v2
	global_load_ushort v26, v[26:27], off offset:3584
	s_nop 0
	v_addc_co_u32_e32 v29, vcc, 0, v3, vcc
	global_load_ushort v27, v[28:29], off offset:1024
	v_add_co_u32_e32 v28, vcc, 0x64000, v2
	v_lshlrev_b32_e32 v14, 16, v14
	s_nop 0
	v_addc_co_u32_e32 v29, vcc, 0, v3, vcc
	v_add_co_u32_e32 v30, vcc, 0x69000, v2
	global_load_ushort v28, v[28:29], off offset:2560
	s_nop 0
	v_addc_co_u32_e32 v31, vcc, 0, v3, vcc
	global_load_ushort v29, v[30:31], off
	v_add_co_u32_e32 v30, vcc, 0x6d000, v2
	v_lshlrev_b32_e32 v15, 16, v15
	s_nop 0
	v_addc_co_u32_e32 v31, vcc, 0, v3, vcc
	v_add_co_u32_e32 v32, vcc, 0x71000, v2
	global_load_ushort v30, v[30:31], off offset:1536
	s_nop 0
	v_addc_co_u32_e32 v33, vcc, 0, v3, vcc
	global_load_ushort v31, v[32:33], off offset:3072
	v_add_co_u32_e32 v32, vcc, 0x76000, v2
	s_waitcnt vmcnt(0) lgkmcnt(0)
	v_lshlrev_b32_e32 v16, 16, v16
	v_addc_co_u32_e32 v33, vcc, 0, v3, vcc
	v_add_co_u32_e32 v34, vcc, 0x7a000, v2
	global_load_ushort v32, v[32:33], off offset:512
	s_nop 0
	v_addc_co_u32_e32 v35, vcc, 0, v3, vcc
	global_load_ushort v33, v[34:35], off offset:2048
	v_add_co_u32_e32 v34, vcc, 0x7e000, v2
	v_lshlrev_b32_e32 v18, 16, v18
	s_nop 0
	v_addc_co_u32_e32 v35, vcc, 0, v3, vcc
	v_add_co_u32_e32 v36, vcc, 0x83000, v2
	global_load_ushort v34, v[34:35], off offset:3584
	s_nop 0
	v_addc_co_u32_e32 v37, vcc, 0, v3, vcc
	global_load_ushort v35, v[36:37], off offset:1024
	v_add_co_u32_e32 v36, vcc, 0x87000, v2
	v_lshlrev_b32_e32 v19, 16, v19
	s_nop 0
	v_addc_co_u32_e32 v37, vcc, 0, v3, vcc
	v_add_co_u32_e32 v38, vcc, s8, v2
	global_load_ushort v36, v[36:37], off offset:2560
	s_nop 0
	v_addc_co_u32_e32 v39, vcc, 0, v3, vcc
	global_load_ushort v37, v[38:39], off
	v_add_co_u32_e32 v38, vcc, 0x90000, v2
	s_mov_b32 s8, 0xf5000
	s_nop 0
	v_addc_co_u32_e32 v39, vcc, 0, v3, vcc
	v_add_co_u32_e32 v40, vcc, 0x94000, v2
	global_load_ushort v38, v[38:39], off offset:1536
	s_nop 0
	v_addc_co_u32_e32 v41, vcc, 0, v3, vcc
	global_load_ushort v39, v[40:41], off offset:3072
	v_add_co_u32_e32 v40, vcc, 0x99000, v2
	v_lshlrev_b32_e32 v20, 16, v20
	s_nop 0
	v_addc_co_u32_e32 v41, vcc, 0, v3, vcc
	v_add_co_u32_e32 v42, vcc, 0x9d000, v2
	global_load_ushort v40, v[40:41], off offset:512
	s_nop 0
	v_addc_co_u32_e32 v43, vcc, 0, v3, vcc
	global_load_ushort v41, v[42:43], off offset:2048
	v_add_co_u32_e32 v42, vcc, 0xa1000, v2
	v_lshlrev_b32_e32 v21, 16, v21
	s_nop 0
	v_addc_co_u32_e32 v43, vcc, 0, v3, vcc
	v_add_co_u32_e32 v44, vcc, 0xa6000, v2
	global_load_ushort v42, v[42:43], off offset:3584
	s_nop 0
	v_addc_co_u32_e32 v45, vcc, 0, v3, vcc
	global_load_ushort v43, v[44:45], off offset:1024
	v_add_co_u32_e32 v44, vcc, 0xaa000, v2
	v_lshlrev_b32_e32 v22, 16, v22
	s_nop 0
	v_addc_co_u32_e32 v45, vcc, 0, v3, vcc
	v_add_co_u32_e32 v46, vcc, 0xaf000, v2
	global_load_ushort v44, v[44:45], off offset:2560
	s_nop 0
	v_addc_co_u32_e32 v47, vcc, 0, v3, vcc
	global_load_ushort v45, v[46:47], off
	v_add_co_u32_e32 v46, vcc, 0xb3000, v2
	v_lshlrev_b32_e32 v23, 16, v23
	s_nop 0
	v_addc_co_u32_e32 v47, vcc, 0, v3, vcc
	v_add_co_u32_e32 v48, vcc, 0xb7000, v2
	global_load_ushort v46, v[46:47], off offset:1536
	s_nop 0
	v_addc_co_u32_e32 v49, vcc, 0, v3, vcc
	global_load_ushort v47, v[48:49], off offset:3072
	v_add_co_u32_e32 v48, vcc, 0xbc000, v2
	v_lshlrev_b32_e32 v24, 16, v24
	s_nop 0
	v_addc_co_u32_e32 v49, vcc, 0, v3, vcc
	v_add_co_u32_e32 v50, vcc, 0xc0000, v2
	global_load_ushort v48, v[48:49], off offset:512
	s_nop 0
	v_addc_co_u32_e32 v51, vcc, 0, v3, vcc
	global_load_ushort v49, v[50:51], off offset:2048
	v_add_co_u32_e32 v50, vcc, 0xc4000, v2
	v_lshlrev_b32_e32 v25, 16, v25
	s_nop 0
	v_addc_co_u32_e32 v51, vcc, 0, v3, vcc
	v_add_co_u32_e32 v52, vcc, 0xc9000, v2
	global_load_ushort v50, v[50:51], off offset:3584
	s_nop 0
	v_addc_co_u32_e32 v53, vcc, 0, v3, vcc
	global_load_ushort v51, v[52:53], off offset:1024
	v_add_co_u32_e32 v52, vcc, 0xcd000, v2
	v_lshlrev_b32_e32 v26, 16, v26
	s_nop 0
	v_addc_co_u32_e32 v53, vcc, 0, v3, vcc
	v_add_co_u32_e32 v54, vcc, 0xd2000, v2
	global_load_ushort v52, v[52:53], off offset:2560
	s_nop 0
	v_addc_co_u32_e32 v55, vcc, 0, v3, vcc
	global_load_ushort v53, v[54:55], off
	v_add_co_u32_e32 v54, vcc, 0xd6000, v2
	v_lshlrev_b32_e32 v27, 16, v27
	s_nop 0
	v_addc_co_u32_e32 v55, vcc, 0, v3, vcc
	v_add_co_u32_e32 v56, vcc, 0xda000, v2
	global_load_ushort v54, v[54:55], off offset:1536
	s_nop 0
	v_addc_co_u32_e32 v57, vcc, 0, v3, vcc
	global_load_ushort v55, v[56:57], off offset:3072
	v_add_co_u32_e32 v56, vcc, 0xdf000, v2
	v_lshlrev_b32_e32 v28, 16, v28
	s_nop 0
	v_addc_co_u32_e32 v57, vcc, 0, v3, vcc
	v_add_co_u32_e32 v58, vcc, 0xe3000, v2
	global_load_ushort v56, v[56:57], off offset:512
	s_nop 0
	v_addc_co_u32_e32 v59, vcc, 0, v3, vcc
	global_load_ushort v57, v[58:59], off offset:2048
	v_add_co_u32_e32 v58, vcc, 0xe7000, v2
	v_lshlrev_b32_e32 v29, 16, v29
	s_nop 0
	v_addc_co_u32_e32 v59, vcc, 0, v3, vcc
	v_add_co_u32_e32 v60, vcc, 0xec000, v2
	global_load_ushort v58, v[58:59], off offset:3584
	s_nop 0
	v_addc_co_u32_e32 v61, vcc, 0, v3, vcc
	global_load_ushort v59, v[60:61], off offset:1024
	v_add_co_u32_e32 v60, vcc, 0xf0000, v2
	v_lshlrev_b32_e32 v30, 16, v30
	s_nop 0
	v_addc_co_u32_e32 v61, vcc, 0, v3, vcc
	v_add_co_u32_e32 v62, vcc, s8, v2
	global_load_ushort v60, v[60:61], off offset:2560
	s_nop 0
	v_addc_co_u32_e32 v63, vcc, 0, v3, vcc
	global_load_ushort v64, v[62:63], off
	s_mov_b32 s8, 0xfd000
	v_add_co_u32_e32 v62, vcc, s8, v2
	s_mov_b32 s8, 0xf9000
	s_nop 0
	v_addc_co_u32_e32 v63, vcc, 0, v3, vcc
	global_load_ushort v61, v[62:63], off offset:3072
	v_lshlrev_b32_e32 v31, 16, v31
	s_waitcnt vmcnt(0) lgkmcnt(0)
	v_lshlrev_b32_e32 v32, 16, v32
	v_lshlrev_b32_e32 v33, 16, v33
	v_lshlrev_b32_e32 v34, 16, v34
	v_lshlrev_b32_e32 v35, 16, v35
	v_lshlrev_b32_e32 v36, 16, v36
	v_lshlrev_b32_e32 v37, 16, v37
	v_lshlrev_b32_e32 v38, 16, v38
	v_lshlrev_b32_e32 v39, 16, v39
	v_lshlrev_b32_e32 v40, 16, v40
	v_lshlrev_b32_e32 v41, 16, v41
	v_lshlrev_b32_e32 v42, 16, v42
	v_lshlrev_b32_e32 v43, 16, v43
	v_lshlrev_b32_e32 v44, 16, v44
	v_lshlrev_b32_e32 v45, 16, v45
	v_lshlrev_b32_e32 v46, 16, v46
	v_lshlrev_b32_e32 v47, 16, v47
	v_lshlrev_b32_e32 v48, 16, v48
	v_lshlrev_b32_e32 v49, 16, v49
	v_lshlrev_b32_e32 v50, 16, v50
	v_lshlrev_b32_e32 v51, 16, v51
	v_lshlrev_b32_e32 v52, 16, v52
	v_lshlrev_b32_e32 v53, 16, v53
	v_lshlrev_b32_e32 v54, 16, v54
	v_lshlrev_b32_e32 v55, 16, v55
	v_lshlrev_b32_e32 v56, 16, v56
	v_lshlrev_b32_e32 v57, 16, v57
	v_lshlrev_b32_e32 v58, 16, v58
	v_lshlrev_b32_e32 v59, 16, v59
	v_lshlrev_b32_e32 v60, 16, v60
	v_lshlrev_b32_e32 v62, 16, v64
	v_add_co_u32_e32 v64, vcc, s8, v2
	s_mov_b32 s8, 0x102000
	s_nop 0
	v_addc_co_u32_e32 v65, vcc, 0, v3, vcc
	global_load_ushort v66, v[64:65], off offset:1536
	v_add_co_u32_e32 v64, vcc, s8, v2
	s_mov_b32 s8, 0x106000
	s_nop 0
	v_addc_co_u32_e32 v65, vcc, 0, v3, vcc
	global_load_ushort v63, v[64:65], off offset:512
	v_lshlrev_b32_e32 v61, 16, v61
	s_waitcnt vmcnt(0) lgkmcnt(0)
	v_lshlrev_b32_e32 v64, 16, v66
	v_add_co_u32_e32 v66, vcc, s8, v2
	s_mov_b32 s8, 0x10f000
	s_nop 0
	v_addc_co_u32_e32 v67, vcc, 0, v3, vcc
	global_load_ushort v68, v[66:67], off offset:2048
	v_add_co_u32_e32 v66, vcc, s8, v2
	s_mov_b32 s8, 0x10a000
	s_nop 0
	v_addc_co_u32_e32 v67, vcc, 0, v3, vcc
	global_load_ushort v65, v[66:67], off offset:1024
	v_lshlrev_b32_e32 v63, 16, v63
	s_waitcnt vmcnt(0) lgkmcnt(0)
	v_lshlrev_b32_e32 v66, 16, v68
	v_add_co_u32_e32 v68, vcc, s8, v2
	s_mov_b32 s8, 0x113000
	s_nop 0
	v_addc_co_u32_e32 v69, vcc, 0, v3, vcc
	global_load_ushort v67, v[68:69], off offset:3584
	v_add_co_u32_e32 v2, vcc, s8, v2
	v_lshlrev_b32_e32 v65, 16, v65
	s_nop 0
	v_addc_co_u32_e32 v3, vcc, 0, v3, vcc
	global_load_ushort v2, v[2:3], off offset:2560
	v_lshl_add_u32 v68, v0, 1, 0
	s_waitcnt vmcnt(0) lgkmcnt(0)
	v_lshlrev_b32_e32 v3, 16, v67
	v_add_f32_e32 v67, 0, v4
	v_add_f32_e32 v67, v1, v67
	v_div_scale_f32 v69, s[8:9], s2, s2, v67
	v_rcp_f32_e32 v70, v69
	v_sub_f32_e32 v1, v5, v1
	v_add_f32_e32 v1, v67, v1
	v_lshlrev_b32_e32 v2, 16, v2
	v_fma_f32 v71, -v69, v70, 1.0
	v_fmac_f32_e32 v70, v71, v70
	v_div_scale_f32 v71, vcc, v67, s2, v67
	v_mul_f32_e32 v72, v71, v70
	v_fma_f32 v73, -v69, v72, v71
	v_fmac_f32_e32 v72, v73, v70
	v_fma_f32 v69, -v69, v72, v71
	v_div_fmas_f32 v69, v69, v70, v72
	v_div_fixup_f32 v69, v69, s2, v67
	v_sub_f32_e32 v69, v69, v4
	v_sub_f32_e32 v4, v6, v4
	v_fma_f32 v67, v1, 0.5, -v5
	v_add_f32_e32 v1, v1, v4
	v_fma_f32 v4, v1, 0.5, -v6
	v_cvt_pk_bf16_f32 v4, v4, v17
	ds_write_b16 v68, v4 offset:2080
	v_sub_f32_e32 v4, v7, v5
	v_add_f32_e32 v1, v1, v4
	v_fma_f32 v4, v1, 0.5, -v7
	v_cvt_pk_bf16_f32 v4, v4, v17
	ds_write_b16 v68, v4 offset:3120
	v_sub_f32_e32 v4, v8, v6
	v_add_f32_e32 v1, v1, v4
	v_fma_f32 v4, v1, 0.5, -v8
	v_cvt_pk_bf16_f32 v4, v4, v17
	ds_write_b16 v68, v4 offset:4160
	v_sub_f32_e32 v4, v9, v7
	v_add_f32_e32 v1, v1, v4
	v_fma_f32 v4, v1, 0.5, -v9
	v_cvt_pk_bf16_f32 v4, v4, v17
	ds_write_b16 v68, v4 offset:5200
	v_sub_f32_e32 v4, v10, v8
	v_add_f32_e32 v1, v1, v4
	v_fma_f32 v4, v1, 0.5, -v10
	v_cvt_pk_bf16_f32 v4, v4, v17
	ds_write_b16 v68, v4 offset:6240
	v_sub_f32_e32 v4, v11, v9
	v_add_f32_e32 v1, v1, v4
	v_fma_f32 v4, v1, 0.5, -v11
	v_cvt_pk_bf16_f32 v4, v4, v17
	ds_write_b16 v68, v4 offset:7280
	v_sub_f32_e32 v4, v12, v10
	v_add_f32_e32 v1, v1, v4
	v_fma_f32 v4, v1, 0.5, -v12
	v_cvt_pk_bf16_f32 v4, v4, v17
	ds_write_b16 v68, v4 offset:8320
	v_sub_f32_e32 v4, v13, v11
	v_add_f32_e32 v1, v1, v4
	v_fma_f32 v4, v1, 0.5, -v13
	v_cvt_pk_bf16_f32 v4, v4, v17
	ds_write_b16 v68, v4 offset:9360
	v_sub_f32_e32 v4, v14, v12
	v_add_f32_e32 v1, v1, v4
	v_fma_f32 v4, v1, 0.5, -v14
	v_cvt_pk_bf16_f32 v4, v4, v17
	ds_write_b16 v68, v4 offset:10400
	v_sub_f32_e32 v4, v15, v13
	v_add_f32_e32 v1, v1, v4
	v_fma_f32 v4, v1, 0.5, -v15
	v_cvt_pk_bf16_f32 v4, v4, v17
	ds_write_b16 v68, v4 offset:11440
	v_sub_f32_e32 v4, v16, v14
	v_add_f32_e32 v1, v1, v4
	v_fma_f32 v4, v1, 0.5, -v16
	v_cvt_pk_bf16_f32 v4, v4, v17
	ds_write_b16 v68, v4 offset:12480
	v_sub_f32_e32 v4, v18, v15
	v_add_f32_e32 v1, v1, v4
	v_fma_f32 v4, v1, 0.5, -v18
	v_cvt_pk_bf16_f32 v4, v4, v17
	ds_write_b16 v68, v4 offset:13520
	v_sub_f32_e32 v4, v19, v16
	v_add_f32_e32 v1, v1, v4
	v_fma_f32 v4, v1, 0.5, -v19
	v_cvt_pk_bf16_f32 v4, v4, v17
	ds_write_b16 v68, v4 offset:14560
	v_sub_f32_e32 v4, v20, v18
	v_add_f32_e32 v1, v1, v4
	v_fma_f32 v4, v1, 0.5, -v20
	v_cvt_pk_bf16_f32 v4, v4, v17
	ds_write_b16 v68, v4 offset:15600
	v_sub_f32_e32 v4, v21, v19
	v_add_f32_e32 v1, v1, v4
	v_fma_f32 v4, v1, 0.5, -v21
	v_cvt_pk_bf16_f32 v4, v4, v17
	ds_write_b16 v68, v4 offset:16640
	v_sub_f32_e32 v4, v22, v20
	v_add_f32_e32 v1, v1, v4
	v_fma_f32 v4, v1, 0.5, -v22
	v_cvt_pk_bf16_f32 v4, v4, v17
	ds_write_b16 v68, v4 offset:17680
	v_sub_f32_e32 v4, v23, v21
	v_add_f32_e32 v1, v1, v4
	v_fma_f32 v4, v1, 0.5, -v23
	v_cvt_pk_bf16_f32 v4, v4, v17
	ds_write_b16 v68, v4 offset:18720
	v_sub_f32_e32 v4, v24, v22
	v_add_f32_e32 v1, v1, v4
	v_fma_f32 v4, v1, 0.5, -v24
	v_cvt_pk_bf16_f32 v4, v4, v17
	ds_write_b16 v68, v4 offset:19760
	v_sub_f32_e32 v4, v25, v23
	v_add_f32_e32 v1, v1, v4
	v_fma_f32 v4, v1, 0.5, -v25
	v_cvt_pk_bf16_f32 v4, v4, v17
	ds_write_b16 v68, v4 offset:20800
	v_sub_f32_e32 v4, v26, v24
	v_add_f32_e32 v1, v1, v4
	v_fma_f32 v4, v1, 0.5, -v26
	v_cvt_pk_bf16_f32 v4, v4, v17
	ds_write_b16 v68, v4 offset:21840
	v_sub_f32_e32 v4, v27, v25
	v_add_f32_e32 v1, v1, v4
	v_fma_f32 v4, v1, 0.5, -v27
	v_cvt_pk_bf16_f32 v4, v4, v17
	ds_write_b16 v68, v4 offset:22880
	v_sub_f32_e32 v4, v28, v26
	v_add_f32_e32 v1, v1, v4
	v_fma_f32 v4, v1, 0.5, -v28
	v_cvt_pk_bf16_f32 v4, v4, v17
	ds_write_b16 v68, v4 offset:23920
	v_sub_f32_e32 v4, v29, v27
	v_add_f32_e32 v1, v1, v4
	v_fma_f32 v4, v1, 0.5, -v29
	v_cvt_pk_bf16_f32 v4, v4, v17
	ds_write_b16 v68, v4 offset:24960
	v_sub_f32_e32 v4, v30, v28
	v_add_f32_e32 v1, v1, v4
	v_fma_f32 v4, v1, 0.5, -v30
	v_cvt_pk_bf16_f32 v4, v4, v17
	ds_write_b16 v68, v4 offset:26000
	v_sub_f32_e32 v4, v31, v29
	v_add_f32_e32 v1, v1, v4
	v_fma_f32 v4, v1, 0.5, -v31
	v_cvt_pk_bf16_f32 v4, v4, v17
	ds_write_b16 v68, v4 offset:27040
	v_sub_f32_e32 v4, v32, v30
	v_add_f32_e32 v1, v1, v4
	v_fma_f32 v4, v1, 0.5, -v32
	v_cvt_pk_bf16_f32 v4, v4, v17
	ds_write_b16 v68, v4 offset:28080
	v_sub_f32_e32 v4, v33, v31
	v_add_f32_e32 v1, v1, v4
	v_fma_f32 v4, v1, 0.5, -v33
	v_cvt_pk_bf16_f32 v4, v4, v17
	ds_write_b16 v68, v4 offset:29120
	v_sub_f32_e32 v4, v34, v32
	v_add_f32_e32 v1, v1, v4
	v_fma_f32 v4, v1, 0.5, -v34
	v_cvt_pk_bf16_f32 v4, v4, v17
	ds_write_b16 v68, v4 offset:30160
	v_sub_f32_e32 v4, v35, v33
	v_add_f32_e32 v1, v1, v4
	v_fma_f32 v4, v1, 0.5, -v35
	v_cvt_pk_bf16_f32 v4, v4, v17
	ds_write_b16 v68, v4 offset:31200
	v_sub_f32_e32 v4, v36, v34
	v_add_f32_e32 v1, v1, v4
	v_fma_f32 v4, v1, 0.5, -v36
	v_cvt_pk_bf16_f32 v4, v4, v17
	ds_write_b16 v68, v4 offset:32240
	v_sub_f32_e32 v4, v37, v35
	v_add_f32_e32 v1, v1, v4
	v_fma_f32 v4, v1, 0.5, -v37
	v_cvt_pk_bf16_f32 v4, v4, v17
	ds_write_b16 v68, v4 offset:33280
	v_sub_f32_e32 v4, v38, v36
	v_add_f32_e32 v1, v1, v4
	v_fma_f32 v4, v1, 0.5, -v38
	v_cvt_pk_bf16_f32 v4, v4, v17
	ds_write_b16 v68, v4 offset:34320
	v_sub_f32_e32 v4, v39, v37
	v_add_f32_e32 v1, v1, v4
	v_fma_f32 v4, v1, 0.5, -v39
	v_cvt_pk_bf16_f32 v4, v4, v17
	ds_write_b16 v68, v4 offset:35360
	v_sub_f32_e32 v4, v40, v38
	v_add_f32_e32 v1, v1, v4
	v_fma_f32 v4, v1, 0.5, -v40
	v_cvt_pk_bf16_f32 v4, v4, v17
	ds_write_b16 v68, v4 offset:36400
	v_sub_f32_e32 v4, v41, v39
	v_add_f32_e32 v1, v1, v4
	v_fma_f32 v4, v1, 0.5, -v41
	v_cvt_pk_bf16_f32 v4, v4, v17
	ds_write_b16 v68, v4 offset:37440
	v_sub_f32_e32 v4, v42, v40
	v_add_f32_e32 v1, v1, v4
	v_fma_f32 v4, v1, 0.5, -v42
	v_cvt_pk_bf16_f32 v4, v4, v17
	ds_write_b16 v68, v4 offset:38480
	v_sub_f32_e32 v4, v43, v41
	v_add_f32_e32 v1, v1, v4
	v_fma_f32 v4, v1, 0.5, -v43
	v_cvt_pk_bf16_f32 v4, v4, v17
	ds_write_b16 v68, v4 offset:39520
	v_sub_f32_e32 v4, v44, v42
	v_add_f32_e32 v1, v1, v4
	v_fma_f32 v4, v1, 0.5, -v44
	v_cvt_pk_bf16_f32 v4, v4, v17
	ds_write_b16 v68, v4 offset:40560
	v_sub_f32_e32 v4, v45, v43
	v_add_f32_e32 v1, v1, v4
	v_fma_f32 v4, v1, 0.5, -v45
	v_cvt_pk_bf16_f32 v4, v4, v17
	ds_write_b16 v68, v4 offset:41600
	v_sub_f32_e32 v4, v46, v44
	v_add_f32_e32 v1, v1, v4
	v_fma_f32 v4, v1, 0.5, -v46
	v_cvt_pk_bf16_f32 v4, v4, v17
	ds_write_b16 v68, v4 offset:42640
	v_sub_f32_e32 v4, v47, v45
	v_add_f32_e32 v1, v1, v4
	v_fma_f32 v4, v1, 0.5, -v47
	v_cvt_pk_bf16_f32 v4, v4, v17
	ds_write_b16 v68, v4 offset:43680
	v_sub_f32_e32 v4, v48, v46
	v_add_f32_e32 v1, v1, v4
	v_fma_f32 v4, v1, 0.5, -v48
	v_cvt_pk_bf16_f32 v4, v4, v17
	ds_write_b16 v68, v4 offset:44720
	v_sub_f32_e32 v4, v49, v47
	v_add_f32_e32 v1, v1, v4
	v_fma_f32 v4, v1, 0.5, -v49
	v_cvt_pk_bf16_f32 v4, v4, v17
	ds_write_b16 v68, v4 offset:45760
	v_sub_f32_e32 v4, v50, v48
	v_add_f32_e32 v1, v1, v4
	v_fma_f32 v4, v1, 0.5, -v50
	v_cvt_pk_bf16_f32 v4, v4, v17
	ds_write_b16 v68, v4 offset:46800
	v_sub_f32_e32 v4, v51, v49
	v_add_f32_e32 v1, v1, v4
	v_fma_f32 v4, v1, 0.5, -v51
	v_cvt_pk_bf16_f32 v4, v4, v17
	ds_write_b16 v68, v4 offset:47840
	v_sub_f32_e32 v4, v52, v50
	v_add_f32_e32 v1, v1, v4
	v_fma_f32 v4, v1, 0.5, -v52
	v_cvt_pk_bf16_f32 v4, v4, v17
	ds_write_b16 v68, v4 offset:48880
	v_sub_f32_e32 v4, v53, v51
	v_add_f32_e32 v1, v1, v4
	v_fma_f32 v4, v1, 0.5, -v53
	v_cvt_pk_bf16_f32 v4, v4, v17
	ds_write_b16 v68, v4 offset:49920
	v_sub_f32_e32 v4, v54, v52
	v_add_f32_e32 v1, v1, v4
	v_fma_f32 v4, v1, 0.5, -v54
	v_cvt_pk_bf16_f32 v4, v4, v17
	ds_write_b16 v68, v4 offset:50960
	v_sub_f32_e32 v4, v55, v53
	v_add_f32_e32 v1, v1, v4
	v_fma_f32 v4, v1, 0.5, -v55
	v_cvt_pk_bf16_f32 v4, v4, v17
	ds_write_b16 v68, v4 offset:52000
	v_sub_f32_e32 v4, v56, v54
	v_add_f32_e32 v1, v1, v4
	v_fma_f32 v4, v1, 0.5, -v56
	v_cvt_pk_bf16_f32 v4, v4, v17
	ds_write_b16 v68, v4 offset:53040
	v_sub_f32_e32 v4, v57, v55
	v_add_f32_e32 v1, v1, v4
	v_fma_f32 v4, v1, 0.5, -v57
	v_cvt_pk_bf16_f32 v4, v4, v17
	ds_write_b16 v68, v4 offset:54080
	v_sub_f32_e32 v4, v58, v56
	v_add_f32_e32 v1, v1, v4
	v_fma_f32 v4, v1, 0.5, -v58
	v_cvt_pk_bf16_f32 v4, v4, v17
	ds_write_b16 v68, v4 offset:55120
	v_sub_f32_e32 v4, v59, v57
	v_add_f32_e32 v1, v1, v4
	v_fma_f32 v4, v1, 0.5, -v59
	v_cvt_pk_bf16_f32 v4, v4, v17
	ds_write_b16 v68, v4 offset:56160
	v_sub_f32_e32 v4, v60, v58
	v_add_f32_e32 v1, v1, v4
	v_fma_f32 v4, v1, 0.5, -v60
	v_cvt_pk_bf16_f32 v4, v4, v17
	ds_write_b16 v68, v4 offset:57200
	v_sub_f32_e32 v4, v62, v59
	v_add_f32_e32 v1, v1, v4
	v_fma_f32 v4, v1, 0.5, -v62
	v_cvt_pk_bf16_f32 v4, v4, v17
	ds_write_b16 v68, v4 offset:58240
	v_sub_f32_e32 v4, v64, v60
	v_add_f32_e32 v1, v1, v4
	v_fma_f32 v4, v1, 0.5, -v64
	v_cvt_pk_bf16_f32 v4, v4, v17
	ds_write_b16 v68, v4 offset:59280
	v_sub_f32_e32 v4, v61, v62
	v_add_f32_e32 v1, v1, v4
	v_fma_f32 v4, v1, 0.5, -v61
	v_cvt_pk_bf16_f32 v4, v4, v17
	ds_write_b16 v68, v4 offset:60320
	v_sub_f32_e32 v4, v63, v64
	v_add_f32_e32 v1, v1, v4
	v_fma_f32 v4, v1, 0.5, -v63
	v_cvt_pk_bf16_f32 v4, v4, v17
	ds_write_b16 v68, v4 offset:61360
	v_sub_f32_e32 v4, v66, v61
	v_add_f32_e32 v1, v1, v4
	v_fma_f32 v4, v1, 0.5, -v66
	v_cvt_pk_bf16_f32 v4, v4, v17
	ds_write_b16 v68, v4 offset:62400
	v_sub_f32_e32 v4, v3, v63
	v_add_f32_e32 v1, v1, v4
	v_fma_f32 v4, v1, 0.5, -v3
	v_cvt_pk_bf16_f32 v4, v4, v17
	ds_write_b16 v68, v4 offset:63440
	v_sub_f32_e32 v4, v65, v66
	v_add_f32_e32 v1, v1, v4
	v_sub_f32_e32 v3, v2, v3
	v_fma_f32 v4, v1, 0.5, -v65
	v_add_f32_e32 v1, v1, v3
	v_fma_f32 v1, v1, 0.5, -v2
	v_cvt_pk_bf16_f32 v69, v69, v17
	ds_write_b16 v68, v69
	v_cvt_pk_bf16_f32 v67, v67, v17
	ds_write_b16 v68, v67 offset:1040
	v_cvt_pk_bf16_f32 v4, v4, v17
	ds_write_b16 v68, v4 offset:64480
	v_cvt_pk_bf16_f32 v1, v1, v17
.LBB0_674:
	s_or_b64 exec, exec, s[4:5]
	v_bfe_u32 v52, v0, 4, 2
	v_and_b32_e32 v6, 0xffffffcf, v0
	v_readlane_b32 s4, v255, 43
	v_lshl_add_u32 v2, v0, 1, 0
	v_lshlrev_b32_e32 v16, 4, v52
	v_readlane_b32 s5, v255, 44
	v_ashrrev_i32_e32 v7, 31, v6
	ds_write_b16 v2, v1 offset:65520
	v_lshl_add_u64 v[22:23], s[4:5], 0, v[16:17]
	v_lshlrev_b64 v[2:3], 8, v[6:7]
	v_and_b32_e32 v53, 15, v0
	v_and_b32_e32 v54, 64, v0
	v_and_b32_e32 v50, 0xffffff80, v0
	v_lshl_add_u64 v[4:5], v[22:23], 0, v[2:3]
	v_or_b32_e32 v2, 16, v6
	v_or_b32_e32 v6, 32, v6
	v_or_b32_e32 v0, 48, v0
	v_ashrrev_i32_e32 v3, 31, v2
	v_ashrrev_i32_e32 v7, 31, v6
	v_ashrrev_i32_e32 v1, 31, v0
	v_lshlrev_b64 v[2:3], 8, v[2:3]
	v_lshlrev_b64 v[6:7], 8, v[6:7]
	v_lshlrev_b64 v[0:1], 8, v[0:1]
	v_lshl_add_u64 v[2:3], v[22:23], 0, v[2:3]
	v_lshl_add_u64 v[6:7], v[22:23], 0, v[6:7]
	v_lshl_add_u64 v[0:1], v[22:23], 0, v[0:1]
	s_waitcnt lgkmcnt(0)
	s_barrier
	global_load_dwordx4 v[8:11], v[4:5], off
	global_load_dwordx4 v[18:21], v[6:7], off
	global_load_dwordx4 v[12:15], v[2:3], off
	global_load_dwordx4 v[22:25], v[0:1], off
	v_lshl_add_u32 v26, v50, 1, 0
	v_mul_u32_u24_e32 v27, 0x410, v53
	v_add3_u32 v16, v26, v16, v27
	ds_read_b128 v[26:29], v16
	ds_read_b128 v[42:45], v16 offset:16640
	ds_read_b128 v[64:67], v16 offset:33280
	ds_read_b128 v[84:87], v16 offset:49920
	v_readlane_b32 s8, v255, 37
	v_readlane_b32 s9, v255, 38
	v_ashrrev_i32_e32 v51, 31, v50
	v_lshl_or_b32 v52, v52, 2, v54
	v_or_b32_e32 v53, s18, v53
	s_waitcnt vmcnt(0) lgkmcnt(0)
	v_mfma_f32_16x16x32_bf16 v[30:33], v[8:11], v[26:29], 0
	v_mfma_f32_16x16x32_bf16 v[34:37], v[12:15], v[26:29], 0
	v_mfma_f32_16x16x32_bf16 v[38:41], v[18:21], v[26:29], 0
	v_mfma_f32_16x16x32_bf16 v[26:29], v[22:25], v[26:29], 0
	v_mfma_f32_16x16x32_bf16 v[46:49], v[8:11], v[42:45], 0
	v_mfma_f32_16x16x32_bf16 v[56:59], v[12:15], v[42:45], 0
	v_mfma_f32_16x16x32_bf16 v[60:63], v[18:21], v[42:45], 0
	v_mfma_f32_16x16x32_bf16 v[42:45], v[22:25], v[42:45], 0
	v_mfma_f32_16x16x32_bf16 v[68:71], v[8:11], v[64:67], 0
	v_mfma_f32_16x16x32_bf16 v[72:75], v[12:15], v[64:67], 0
	v_mfma_f32_16x16x32_bf16 v[80:83], v[18:21], v[64:67], 0
	v_mfma_f32_16x16x32_bf16 v[64:67], v[22:25], v[64:67], 0
	v_mfma_f32_16x16x32_bf16 v[8:11], v[8:11], v[84:87], 0
	v_mfma_f32_16x16x32_bf16 v[12:15], v[12:15], v[84:87], 0
	v_mfma_f32_16x16x32_bf16 v[18:21], v[18:21], v[84:87], 0
	v_mfma_f32_16x16x32_bf16 v[22:25], v[22:25], v[84:87], 0
	global_load_dwordx4 v[84:87], v[4:5], off offset:64
	global_load_dwordx4 v[88:91], v[2:3], off offset:64
	global_load_dwordx4 v[92:95], v[6:7], off offset:64
	global_load_dwordx4 v[96:99], v[0:1], off offset:64
	ds_read_b128 v[100:103], v16 offset:64
	s_waitcnt vmcnt(0) lgkmcnt(0)
	v_mfma_f32_16x16x32_bf16 v[30:33], v[84:87], v[100:103], v[30:33]
	v_mfma_f32_16x16x32_bf16 v[34:37], v[88:91], v[100:103], v[34:37]
	v_mfma_f32_16x16x32_bf16 v[38:41], v[92:95], v[100:103], v[38:41]
	v_mfma_f32_16x16x32_bf16 v[26:29], v[96:99], v[100:103], v[26:29]
	ds_read_b128 v[100:103], v16 offset:16704
	s_waitcnt lgkmcnt(0)
	v_mfma_f32_16x16x32_bf16 v[46:49], v[84:87], v[100:103], v[46:49]
	v_mfma_f32_16x16x32_bf16 v[56:59], v[88:91], v[100:103], v[56:59]
	v_mfma_f32_16x16x32_bf16 v[60:63], v[92:95], v[100:103], v[60:63]
	v_mfma_f32_16x16x32_bf16 v[42:45], v[96:99], v[100:103], v[42:45]
	ds_read_b128 v[100:103], v16 offset:33344
	s_waitcnt lgkmcnt(0)
	v_mfma_f32_16x16x32_bf16 v[68:71], v[84:87], v[100:103], v[68:71]
	v_mfma_f32_16x16x32_bf16 v[72:75], v[88:91], v[100:103], v[72:75]
	v_mfma_f32_16x16x32_bf16 v[80:83], v[92:95], v[100:103], v[80:83]
	v_mfma_f32_16x16x32_bf16 v[64:67], v[96:99], v[100:103], v[64:67]
	ds_read_b128 v[100:103], v16 offset:49984
	s_waitcnt lgkmcnt(0)
	v_mfma_f32_16x16x32_bf16 v[8:11], v[84:87], v[100:103], v[8:11]
	v_mfma_f32_16x16x32_bf16 v[12:15], v[88:91], v[100:103], v[12:15]
	v_mfma_f32_16x16x32_bf16 v[18:21], v[92:95], v[100:103], v[18:21]
	v_mfma_f32_16x16x32_bf16 v[22:25], v[96:99], v[100:103], v[22:25]
	global_load_dwordx4 v[84:87], v[4:5], off offset:128
	global_load_dwordx4 v[88:91], v[2:3], off offset:128
	global_load_dwordx4 v[92:95], v[6:7], off offset:128
	global_load_dwordx4 v[96:99], v[0:1], off offset:128
	ds_read_b128 v[100:103], v16 offset:128
	s_waitcnt vmcnt(0) lgkmcnt(0)
	v_mfma_f32_16x16x32_bf16 v[30:33], v[84:87], v[100:103], v[30:33]
	v_mfma_f32_16x16x32_bf16 v[34:37], v[88:91], v[100:103], v[34:37]
	v_mfma_f32_16x16x32_bf16 v[38:41], v[92:95], v[100:103], v[38:41]
	v_mfma_f32_16x16x32_bf16 v[100:103], v[96:99], v[100:103], v[26:29]
	s_nop 2
	ds_read_b128 v[26:29], v16 offset:16768
	s_waitcnt lgkmcnt(0)
	v_mfma_f32_16x16x32_bf16 v[46:49], v[84:87], v[26:29], v[46:49]
	v_mfma_f32_16x16x32_bf16 v[56:59], v[88:91], v[26:29], v[56:59]
	v_mfma_f32_16x16x32_bf16 v[60:63], v[92:95], v[26:29], v[60:63]
	v_mfma_f32_16x16x32_bf16 v[42:45], v[96:99], v[26:29], v[42:45]
	ds_read_b128 v[26:29], v16 offset:33408
	s_waitcnt lgkmcnt(0)
	v_mfma_f32_16x16x32_bf16 v[68:71], v[84:87], v[26:29], v[68:71]
	v_mfma_f32_16x16x32_bf16 v[72:75], v[88:91], v[26:29], v[72:75]
	v_mfma_f32_16x16x32_bf16 v[80:83], v[92:95], v[26:29], v[80:83]
	v_mfma_f32_16x16x32_bf16 v[64:67], v[96:99], v[26:29], v[64:67]
	ds_read_b128 v[26:29], v16 offset:50048
	s_waitcnt lgkmcnt(0)
	v_mfma_f32_16x16x32_bf16 v[18:21], v[92:95], v[26:29], v[18:21]
	v_mfma_f32_16x16x32_bf16 v[92:95], v[96:99], v[26:29], v[22:25]
	global_load_dwordx4 v[96:99], v[4:5], off offset:192
	global_load_dwordx4 v[104:107], v[2:3], off offset:192
	global_load_dwordx4 v[108:111], v[6:7], off offset:192
	s_nop 0
	global_load_dwordx4 v[0:3], v[0:1], off offset:192
	ds_read_b128 v[4:7], v16 offset:192
	v_mfma_f32_16x16x32_bf16 v[84:87], v[84:87], v[26:29], v[8:11]
	v_mfma_f32_16x16x32_bf16 v[88:91], v[88:91], v[26:29], v[12:15]
	s_waitcnt vmcnt(0) lgkmcnt(0)
	v_mfma_f32_16x16x32_bf16 v[112:115], v[96:99], v[4:7], v[30:33]
	v_mfma_f32_16x16x32_bf16 v[34:37], v[104:107], v[4:7], v[34:37]
	v_mfma_f32_16x16x32_bf16 v[26:29], v[108:111], v[4:7], v[38:41]
	v_mfma_f32_16x16x32_bf16 v[8:11], v[0:3], v[4:7], v[100:103]
	ds_read_b128 v[4:7], v16 offset:16832
	s_waitcnt lgkmcnt(0)
	v_mfma_f32_16x16x32_bf16 v[100:103], v[96:99], v[4:7], v[46:49]
	v_mfma_f32_16x16x32_bf16 v[38:41], v[104:107], v[4:7], v[56:59]
	v_mfma_f32_16x16x32_bf16 v[30:33], v[108:111], v[4:7], v[60:63]
	s_nop 1
	ds_read_b128 v[56:59], v16 offset:50112
	v_mfma_f32_16x16x32_bf16 v[12:15], v[0:3], v[4:7], v[42:45]
	ds_read_b128 v[4:7], v16 offset:33472
	s_mov_b32 s4, 0
	s_ashr_i32 s5, s4, 31
	s_lshl_b64 s[4:5], s[4:5], 3
	s_add_u32 s4, s0, s4
	s_addc_u32 s5, s1, s5
	s_load_dwordx2 s[4:5], s[4:5], 0xb8
	s_waitcnt lgkmcnt(0)
	v_mfma_f32_16x16x32_bf16 v[60:63], v[96:99], v[4:7], v[68:71]
	v_lshlrev_b32_e32 v16, 2, v52
	s_add_u32 s4, s4, s8
	s_addc_u32 s5, s5, s9
	v_mfma_f32_16x16x32_bf16 v[42:45], v[104:107], v[4:7], v[72:75]
	v_mfma_f32_16x16x32_bf16 v[22:25], v[108:111], v[4:7], v[80:83]
	v_mfma_f32_16x16x32_bf16 v[4:7], v[0:3], v[4:7], v[64:67]
	v_mfma_f32_16x16x32_bf16 v[64:67], v[96:99], v[56:59], v[84:87]
	v_mfma_f32_16x16x32_bf16 v[46:49], v[104:107], v[56:59], v[88:91]
	v_mfma_f32_16x16x32_bf16 v[18:21], v[108:111], v[56:59], v[18:21]
	v_mfma_f32_16x16x32_bf16 v[0:3], v[0:3], v[56:59], v[92:95]
	v_lshl_add_u64 v[56:57], v[50:51], 2, s[4:5]
	v_lshl_add_u64 v[54:55], v[56:57], 0, v[16:17]
	global_load_dwordx4 v[68:71], v[54:55], off
	v_readlane_b32 s4, v255, 45
	v_readlane_b32 s5, v255, 46
	v_lshlrev_b32_e32 v16, 1, v52
	s_waitcnt vmcnt(0)
	v_mul_f32_e32 v52, v103, v71
	v_lshl_add_u64 v[50:51], v[50:51], 1, s[4:5]
	v_lshl_add_u64 v[56:57], v[50:51], 0, v[16:17]
	v_mul_f32_e32 v16, v112, v68
	v_mul_f32_e32 v50, v113, v69
	v_cvt_pk_bf16_f32 v50, v16, v50
	v_mul_f32_e32 v16, v114, v70
	v_mul_f32_e32 v51, v115, v71
	v_cvt_pk_bf16_f32 v51, v16, v51
	v_lshlrev_b32_e32 v16, 10, v53
	v_lshl_add_u64 v[58:59], v[56:57], 0, v[16:17]
	global_store_dwordx2 v[58:59], v[50:51], off
	v_mul_f32_e32 v50, v100, v68
	v_mul_f32_e32 v51, v101, v69
	v_cvt_pk_bf16_f32 v50, v50, v51
	v_mul_f32_e32 v51, v102, v70
	v_cvt_pk_bf16_f32 v51, v51, v52
	v_or_b32_e32 v52, 0x4000, v16
	v_mov_b32_e32 v53, v17
	v_lshl_add_u64 v[72:73], v[56:57], 0, v[52:53]
	global_store_dwordx2 v[72:73], v[50:51], off
	v_mul_f32_e32 v50, v60, v68
	v_mul_f32_e32 v51, v61, v69
	v_cvt_pk_bf16_f32 v60, v50, v51
	v_mul_f32_e32 v50, v62, v70
	v_mul_f32_e32 v51, v63, v71
	v_cvt_pk_bf16_f32 v61, v50, v51
	v_or_b32_e32 v50, 0x8000, v16
	v_mov_b32_e32 v51, v17
	v_lshl_add_u64 v[62:63], v[56:57], 0, v[50:51]
	global_store_dwordx2 v[62:63], v[60:61], off
	v_mul_f32_e32 v60, v64, v68
	v_mul_f32_e32 v61, v65, v69
	v_cvt_pk_bf16_f32 v60, v60, v61
	v_mul_f32_e32 v61, v66, v70
	v_mul_f32_e32 v62, v67, v71
	v_or_b32_e32 v16, 0xc000, v16
	v_cvt_pk_bf16_f32 v61, v61, v62
	v_lshl_add_u64 v[62:63], v[56:57], 0, v[16:17]
	global_store_dwordx2 v[62:63], v[60:61], off
	global_load_dwordx4 v[60:63], v[54:55], off offset:64
	v_lshl_add_u64 v[64:65], v[56:57], 0, 32
	s_mov_b64 s[4:5], 0x60
	s_waitcnt vmcnt(0)
	v_mul_f32_e32 v34, v34, v60
	v_mul_f32_e32 v35, v35, v61
	v_cvt_pk_bf16_f32 v34, v34, v35
	v_mul_f32_e32 v35, v36, v62
	v_mul_f32_e32 v36, v37, v63
	v_cvt_pk_bf16_f32 v35, v35, v36
	global_store_dwordx2 v[58:59], v[34:35], off offset:32
	v_mul_f32_e32 v34, v38, v60
	v_mul_f32_e32 v35, v39, v61
	v_cvt_pk_bf16_f32 v34, v34, v35
	v_mul_f32_e32 v35, v40, v62
	v_mul_f32_e32 v36, v41, v63
	v_cvt_pk_bf16_f32 v35, v35, v36
	v_lshl_add_u64 v[36:37], v[64:65], 0, v[52:53]
	global_store_dwordx2 v[36:37], v[34:35], off
	v_mul_f32_e32 v34, v42, v60
	v_mul_f32_e32 v35, v43, v61
	v_cvt_pk_bf16_f32 v34, v34, v35
	v_mul_f32_e32 v35, v44, v62
	v_mul_f32_e32 v36, v45, v63
	v_cvt_pk_bf16_f32 v35, v35, v36
	v_lshl_add_u64 v[36:37], v[64:65], 0, v[50:51]
	global_store_dwordx2 v[36:37], v[34:35], off
	v_mul_f32_e32 v34, v46, v60
	v_mul_f32_e32 v35, v47, v61
	v_cvt_pk_bf16_f32 v34, v34, v35
	v_mul_f32_e32 v35, v48, v62
	v_mul_f32_e32 v36, v49, v63
	v_cvt_pk_bf16_f32 v35, v35, v36
	v_lshl_add_u64 v[36:37], v[64:65], 0, v[16:17]
	global_store_dwordx2 v[36:37], v[34:35], off
	global_load_dwordx4 v[34:37], v[54:55], off offset:128
	v_lshl_add_u64 v[38:39], v[56:57], 0, 64
	s_waitcnt vmcnt(0)
	v_mul_f32_e32 v26, v26, v34
	v_mul_f32_e32 v27, v27, v35
	v_cvt_pk_bf16_f32 v26, v26, v27
	v_mul_f32_e32 v27, v28, v36
	v_mul_f32_e32 v28, v29, v37
	v_cvt_pk_bf16_f32 v27, v27, v28
	global_store_dwordx2 v[58:59], v[26:27], off offset:64
	v_mul_f32_e32 v26, v30, v34
	v_mul_f32_e32 v27, v31, v35
	v_mul_f32_e32 v22, v22, v34
	v_mul_f32_e32 v23, v23, v35
	v_mul_f32_e32 v18, v18, v34
	v_mul_f32_e32 v19, v19, v35
	v_cvt_pk_bf16_f32 v26, v26, v27
	v_mul_f32_e32 v27, v32, v36
	v_mul_f32_e32 v28, v33, v37
	v_cvt_pk_bf16_f32 v22, v22, v23
	v_mul_f32_e32 v23, v24, v36
	v_mul_f32_e32 v24, v25, v37
	v_cvt_pk_bf16_f32 v18, v18, v19
	v_mul_f32_e32 v19, v20, v36
	v_mul_f32_e32 v20, v21, v37
	v_cvt_pk_bf16_f32 v27, v27, v28
	v_lshl_add_u64 v[28:29], v[38:39], 0, v[52:53]
	v_cvt_pk_bf16_f32 v23, v23, v24
	v_lshl_add_u64 v[24:25], v[38:39], 0, v[50:51]
	v_cvt_pk_bf16_f32 v19, v19, v20
	v_lshl_add_u64 v[20:21], v[38:39], 0, v[16:17]
	global_store_dwordx2 v[28:29], v[26:27], off
	global_store_dwordx2 v[24:25], v[22:23], off
	global_store_dwordx2 v[20:21], v[18:19], off
	global_load_dwordx4 v[18:21], v[54:55], off offset:192
	v_lshl_add_u64 v[22:23], v[56:57], 0, s[4:5]
	s_waitcnt vmcnt(0)
	v_mul_f32_e32 v8, v8, v18
	v_mul_f32_e32 v9, v9, v19
	v_cvt_pk_bf16_f32 v8, v8, v9
	v_mul_f32_e32 v9, v10, v20
	v_mul_f32_e32 v10, v11, v21
	v_cvt_pk_bf16_f32 v9, v9, v10
	global_store_dwordx2 v[58:59], v[8:9], off offset:96
	v_mul_f32_e32 v8, v12, v18
	v_mul_f32_e32 v9, v13, v19
	v_mul_f32_e32 v4, v4, v18
	v_mul_f32_e32 v5, v5, v19
	v_mul_f32_e32 v0, v0, v18
	v_mul_f32_e32 v1, v1, v19
	v_cvt_pk_bf16_f32 v8, v8, v9
	v_mul_f32_e32 v9, v14, v20
	v_mul_f32_e32 v10, v15, v21
	v_cvt_pk_bf16_f32 v4, v4, v5
	v_mul_f32_e32 v5, v6, v20
	v_mul_f32_e32 v6, v7, v21
	v_cvt_pk_bf16_f32 v0, v0, v1
	v_mul_f32_e32 v1, v2, v20
	v_mul_f32_e32 v2, v3, v21
	v_cvt_pk_bf16_f32 v9, v9, v10
	v_lshl_add_u64 v[10:11], v[22:23], 0, v[52:53]
	v_cvt_pk_bf16_f32 v5, v5, v6
	v_lshl_add_u64 v[6:7], v[22:23], 0, v[50:51]
	v_cvt_pk_bf16_f32 v1, v1, v2
	v_lshl_add_u64 v[2:3], v[22:23], 0, v[16:17]
	global_store_dwordx2 v[10:11], v[8:9], off
	global_store_dwordx2 v[6:7], v[4:5], off
	global_store_dwordx2 v[2:3], v[0:1], off
	s_waitcnt lgkmcnt(0)
	s_barrier

.LBB0_680:
	s_mov_b32 s4, 0
	s_ashr_i32 s5, s4, 31
	s_lshl_b64 s[4:5], s[4:5], 3
	v_lshl_add_u64 v[0:1], s[90:91], 0, v[34:35]
	s_add_u32 s4, s0, s4
	v_add_co_u32_e32 v6, vcc, s86, v0
	s_addc_u32 s5, s1, s5
	s_nop 0
	v_addc_co_u32_e32 v7, vcc, 0, v1, vcc
	s_load_dwordx2 s[4:5], s[4:5], 0x38
	s_load_dwordx2 s[98:99], s[0:1], 0x48
	s_load_dwordx2 s[100:101], s[0:1], 0x50
	s_mov_b32 s8, 0
	s_ashr_i32 s9, s8, 31
	s_lshl_b64 s[8:9], s[8:9], 3
	s_add_u32 s8, s0, s8
	s_addc_u32 s9, s1, s9
	s_load_dwordx2 s[8:9], s[8:9], 0x40
	s_mov_b32 s2, 0x190c0000
	s_waitcnt lgkmcnt(0)
	v_lshl_add_u64 v[70:71], s[4:5], 0, v[40:41]
	v_lshl_add_u64 v[72:73], s[8:9], 0, v[40:41]
	v_lshl_add_u64 v[70:71], v[70:71], 0, s[42:43]
	v_lshl_add_u64 v[72:73], v[72:73], 0, s[42:43]
	v_lshl_add_u64 v[74:75], s[98:99], 0, v[42:43]
	v_lshl_add_u64 v[76:77], s[100:101], 0, v[44:45]
	v_lshl_add_u64 v[194:195], s[90:91], 0, v[48:49]
	v_lshl_add_u64 v[76:77], v[76:77], 0, s[42:43]
	v_add_co_u32_e32 v194, vcc, s86, v194
	s_nop 1
	v_addc_co_u32_e32 v195, vcc, 0, v195, vcc
	global_load_dwordx4 v[82:85], v[6:7], off offset:1024
	global_load_dwordx4 v[130:133], v[72:73], off
	global_load_dwordx4 v[98:101], v[70:71], off
	global_load_dwordx4 v[102:105], v[70:71], off offset:16
	global_load_dwordx4 v[134:137], v[72:73], off offset:16
	global_load_dwordx4 v[86:89], v[6:7], off offset:1088
	global_load_dwordx4 v[106:109], v[70:71], off offset:128
	global_load_dwordx4 v[138:141], v[72:73], off offset:128
	global_load_dwordx4 v[110:113], v[70:71], off offset:144
	global_load_dwordx4 v[142:145], v[72:73], off offset:144
	global_load_dwordx4 v[90:93], v[6:7], off offset:1152
	global_load_dwordx4 v[114:117], v[70:71], off offset:256
	global_load_dwordx4 v[146:149], v[72:73], off offset:256
	global_load_dwordx4 v[118:121], v[70:71], off offset:272
	global_load_dwordx4 v[150:153], v[72:73], off offset:272
	global_load_dwordx4 v[94:97], v[6:7], off offset:1216
	global_load_dwordx4 v[122:125], v[70:71], off offset:384
	global_load_dwordx4 v[154:157], v[72:73], off offset:384
	global_load_dwordx4 v[126:129], v[70:71], off offset:400
	global_load_dwordx4 v[158:161], v[72:73], off offset:400
	global_load_dwordx4 v[162:165], v[74:75], off offset:-64
	global_load_dwordx4 v[166:169], v[74:75], off offset:-48
	global_load_dwordx4 v[170:173], v[74:75], off offset:-32
	global_load_dwordx4 v[174:177], v[74:75], off offset:-16
	global_load_dwordx4 v[178:181], v[74:75], off
	global_load_dwordx4 v[182:185], v[74:75], off offset:16
	global_load_dwordx4 v[186:189], v[74:75], off offset:32
	global_load_dwordx4 v[190:193], v[74:75], off offset:48
	global_load_dword v224, v[76:77], off
	global_load_dwordx2 v[208:209], v[194:195], off
	global_load_dwordx2 v[210:211], v[194:195], off offset:32
	global_load_dwordx2 v[212:213], v[194:195], off offset:64
	global_load_dwordx2 v[214:215], v[194:195], off offset:96
	global_load_dwordx2 v[216:217], v[194:195], off offset:128
	global_load_dwordx2 v[218:219], v[194:195], off offset:160
	global_load_dwordx2 v[220:221], v[194:195], off offset:192
	global_load_dwordx2 v[222:223], v[194:195], off offset:224
	s_waitcnt vmcnt(0)
	v_mov_b64_e32 v[0:1], v[82:83]
	v_mov_b64_e32 v[2:3], v[84:85]
	v_lshl_add_u64 v[8:9], s[8:9], 0, v[40:41]
	v_lshl_add_u64 v[8:9], v[8:9], 0, s[42:43]
	v_mov_b64_e32 v[18:19], v[130:131]
	v_mov_b64_e32 v[20:21], v[132:133]
	v_lshlrev_b32_e32 v4, 16, v0
	v_mul_f32_e32 v5, 0x3d372713, v4
	v_mul_f32_e32 v5, v5, v4
	v_fma_f32 v5, v5, v4, v4
	v_mul_f32_e32 v5, 0xbfcc422a, v5
	v_mul_f32_e32 v5, 0x3fb8aa3b, v5
	v_exp_f32_e32 v5, v5
	v_and_b32_e32 v0, 0xffff0000, v0
	v_add_f32_e32 v5, 1.0, v5
	v_rcp_f32_e32 v5, v5
	s_nop 0
	v_fma_f32 v4, v5, v4, -v37
	v_mul_f32_e32 v14, v36, v4
	v_lshl_add_u64 v[4:5], s[4:5], 0, v[40:41]
	v_lshl_add_u64 v[4:5], v[4:5], 0, s[42:43]
	v_mov_b64_e32 v[10:11], v[98:99]
	v_mov_b64_e32 v[12:13], v[100:101]
	v_fma_f32 v10, v10, v14, v18
	v_cvt_pk_bf16_f32 v10, v10, v17
	ds_write_b16 v16, v10 offset:34816
	v_mul_f32_e32 v10, 0x3d372713, v0
	v_mul_f32_e32 v10, v10, v0
	v_fma_f32 v10, v10, v0, v0
	v_mul_f32_e32 v10, 0xbfcc422a, v10
	v_mul_f32_e32 v10, 0x3fb8aa3b, v10
	v_exp_f32_e32 v10, v10
	s_nop 0
	v_add_f32_e32 v10, 1.0, v10
	v_rcp_f32_e32 v10, v10
	s_nop 0
	v_fma_f32 v0, v10, v0, -v37
	v_mul_f32_e32 v0, v36, v0
	v_fma_f32 v0, v11, v0, v19
	v_cvt_pk_bf16_f32 v0, v0, v17
	ds_write_b16 v39, v0 offset:34816
	v_lshlrev_b32_e32 v0, 16, v1
	v_mul_f32_e32 v10, 0x3d372713, v0
	v_mul_f32_e32 v10, v10, v0
	v_fma_f32 v10, v10, v0, v0
	v_mul_f32_e32 v10, 0xbfcc422a, v10
	v_mul_f32_e32 v10, 0x3fb8aa3b, v10
	v_exp_f32_e32 v10, v10
	s_nop 0
	v_add_f32_e32 v10, 1.0, v10
	v_rcp_f32_e32 v10, v10
	s_nop 0
	v_fma_f32 v0, v10, v0, -v37
	v_mul_f32_e32 v0, v36, v0
	v_fma_f32 v0, v12, v0, v20
	v_cvt_pk_bf16_f32 v0, v0, v17
	ds_write_b16 v39, v0 offset:35088
	v_and_b32_e32 v0, 0xffff0000, v1
	v_mul_f32_e32 v1, 0x3d372713, v0
	v_mul_f32_e32 v1, v1, v0
	v_fma_f32 v1, v1, v0, v0
	v_mul_f32_e32 v1, 0xbfcc422a, v1
	v_mul_f32_e32 v1, 0x3fb8aa3b, v1
	v_exp_f32_e32 v1, v1
	s_nop 0
	v_add_f32_e32 v1, 1.0, v1
	v_rcp_f32_e32 v1, v1
	s_nop 0
	v_fma_f32 v0, v1, v0, -v37
	v_mul_f32_e32 v0, v36, v0
	v_fmac_f32_e32 v21, v13, v0
	v_cvt_pk_bf16_f32 v0, v21, v17
	ds_write_b16 v39, v0 offset:35360
	v_mov_b64_e32 v[10:11], v[102:103]
	v_mov_b64_e32 v[12:13], v[104:105]
	v_mov_b64_e32 v[18:19], v[134:135]
	v_mov_b64_e32 v[20:21], v[136:137]
	v_lshlrev_b32_e32 v0, 16, v2
	v_mul_f32_e32 v1, 0x3d372713, v0
	v_mul_f32_e32 v1, v1, v0
	v_fma_f32 v1, v1, v0, v0
	v_mul_f32_e32 v1, 0xbfcc422a, v1
	v_mul_f32_e32 v1, 0x3fb8aa3b, v1
	v_exp_f32_e32 v1, v1
	s_nop 0
	v_add_f32_e32 v1, 1.0, v1
	v_rcp_f32_e32 v1, v1
	s_nop 0
	v_fma_f32 v0, v1, v0, -v37
	v_mul_f32_e32 v0, v36, v0
	s_waitcnt vmcnt(0)
	v_fma_f32 v0, v0, v10, v18
	v_cvt_pk_bf16_f32 v0, v0, v17
	ds_write_b16 v39, v0 offset:35632
	v_and_b32_e32 v0, 0xffff0000, v2
	v_mul_f32_e32 v1, 0x3d372713, v0
	v_mul_f32_e32 v1, v1, v0
	v_fma_f32 v1, v1, v0, v0
	v_mul_f32_e32 v1, 0xbfcc422a, v1
	v_mul_f32_e32 v1, 0x3fb8aa3b, v1
	v_exp_f32_e32 v1, v1
	s_nop 0
	v_add_f32_e32 v1, 1.0, v1
	v_rcp_f32_e32 v1, v1
	s_nop 0
	v_fma_f32 v0, v1, v0, -v37
	v_mul_f32_e32 v0, v36, v0
	v_fma_f32 v0, v0, v11, v19
	v_cvt_pk_bf16_f32 v0, v0, v17
	ds_write_b16 v39, v0 offset:35904
	v_lshlrev_b32_e32 v0, 16, v3
	v_mul_f32_e32 v1, 0x3d372713, v0
	v_mul_f32_e32 v1, v1, v0
	v_fma_f32 v1, v1, v0, v0
	v_mul_f32_e32 v1, 0xbfcc422a, v1
	v_mul_f32_e32 v1, 0x3fb8aa3b, v1
	v_exp_f32_e32 v1, v1
	s_nop 0
	v_add_f32_e32 v1, 1.0, v1
	v_rcp_f32_e32 v1, v1
	s_nop 0
	v_fma_f32 v0, v1, v0, -v37
	v_mul_f32_e32 v0, v36, v0
	v_fma_f32 v0, v0, v12, v20
	v_cvt_pk_bf16_f32 v0, v0, v17
	ds_write_b16 v39, v0 offset:36176
	v_and_b32_e32 v0, 0xffff0000, v3
	v_mul_f32_e32 v1, 0x3d372713, v0
	v_mul_f32_e32 v1, v1, v0
	v_fma_f32 v1, v1, v0, v0
	v_mul_f32_e32 v1, 0xbfcc422a, v1
	v_mul_f32_e32 v1, 0x3fb8aa3b, v1
	v_exp_f32_e32 v1, v1
	s_nop 0
	v_add_f32_e32 v1, 1.0, v1
	v_rcp_f32_e32 v1, v1
	s_nop 0
	v_fma_f32 v0, v1, v0, -v37
	v_mul_f32_e32 v0, v36, v0
	v_fmac_f32_e32 v21, v0, v13
	v_cvt_pk_bf16_f32 v0, v21, v17
	ds_write_b16 v39, v0 offset:36448
	v_mov_b64_e32 v[0:1], v[86:87]
	v_mov_b64_e32 v[2:3], v[88:89]
	s_waitcnt lgkmcnt(0)
	v_lshlrev_b32_e32 v10, 16, v0
	v_mul_f32_e32 v11, 0x3d372713, v10
	v_mul_f32_e32 v11, v11, v10
	v_fma_f32 v11, v11, v10, v10
	v_mul_f32_e32 v11, 0xbfcc422a, v11
	v_mul_f32_e32 v11, 0x3fb8aa3b, v11
	v_exp_f32_e32 v11, v11
	v_and_b32_e32 v0, 0xffff0000, v0
	v_add_f32_e32 v11, 1.0, v11
	v_rcp_f32_e32 v11, v11
	s_nop 0
	v_fma_f32 v10, v11, v10, -v37
	v_mul_f32_e32 v14, v36, v10
	v_mov_b64_e32 v[10:11], v[106:107]
	v_mov_b64_e32 v[12:13], v[108:109]
	v_mov_b64_e32 v[18:19], v[138:139]
	v_mov_b64_e32 v[20:21], v[140:141]
	v_fma_f32 v10, v10, v14, v18
	v_cvt_pk_bf16_f32 v10, v10, v17
	ds_write_b16 v39, v10 offset:43248
	v_mul_f32_e32 v10, 0x3d372713, v0
	v_mul_f32_e32 v10, v10, v0
	v_fma_f32 v10, v10, v0, v0
	v_mul_f32_e32 v10, 0xbfcc422a, v10
	v_mul_f32_e32 v10, 0x3fb8aa3b, v10
	v_exp_f32_e32 v10, v10
	s_nop 0
	v_add_f32_e32 v10, 1.0, v10
	v_rcp_f32_e32 v10, v10
	s_nop 0
	v_fma_f32 v0, v10, v0, -v37
	v_mul_f32_e32 v0, v36, v0
	v_fma_f32 v0, v11, v0, v19
	v_cvt_pk_bf16_f32 v0, v0, v17
	ds_write_b16 v39, v0 offset:43520
	v_lshlrev_b32_e32 v0, 16, v1
	v_mul_f32_e32 v10, 0x3d372713, v0
	v_mul_f32_e32 v10, v10, v0
	v_fma_f32 v10, v10, v0, v0
	v_mul_f32_e32 v10, 0xbfcc422a, v10
	v_mul_f32_e32 v10, 0x3fb8aa3b, v10
	v_exp_f32_e32 v10, v10
	s_nop 0
	v_add_f32_e32 v10, 1.0, v10
	v_rcp_f32_e32 v10, v10
	s_nop 0
	v_fma_f32 v0, v10, v0, -v37
	v_mul_f32_e32 v0, v36, v0
	v_fma_f32 v0, v12, v0, v20
	v_cvt_pk_bf16_f32 v0, v0, v17
	ds_write_b16 v39, v0 offset:43792
	v_and_b32_e32 v0, 0xffff0000, v1
	v_mul_f32_e32 v1, 0x3d372713, v0
	v_mul_f32_e32 v1, v1, v0
	v_fma_f32 v1, v1, v0, v0
	v_mul_f32_e32 v1, 0xbfcc422a, v1
	v_mul_f32_e32 v1, 0x3fb8aa3b, v1
	v_exp_f32_e32 v1, v1
	s_nop 0
	v_add_f32_e32 v1, 1.0, v1
	v_rcp_f32_e32 v1, v1
	s_nop 0
	v_fma_f32 v0, v1, v0, -v37
	v_mul_f32_e32 v0, v36, v0
	v_fmac_f32_e32 v21, v13, v0
	v_cvt_pk_bf16_f32 v0, v21, v17
	ds_write_b16 v39, v0 offset:44064
	v_mov_b64_e32 v[10:11], v[110:111]
	v_mov_b64_e32 v[12:13], v[112:113]
	v_mov_b64_e32 v[18:19], v[142:143]
	v_mov_b64_e32 v[20:21], v[144:145]
	v_lshlrev_b32_e32 v0, 16, v2
	v_mul_f32_e32 v1, 0x3d372713, v0
	v_mul_f32_e32 v1, v1, v0
	v_fma_f32 v1, v1, v0, v0
	v_mul_f32_e32 v1, 0xbfcc422a, v1
	v_mul_f32_e32 v1, 0x3fb8aa3b, v1
	v_exp_f32_e32 v1, v1
	s_nop 0
	v_add_f32_e32 v1, 1.0, v1
	v_rcp_f32_e32 v1, v1
	s_nop 0
	v_fma_f32 v0, v1, v0, -v37
	v_mul_f32_e32 v0, v36, v0
	s_waitcnt vmcnt(0)
	v_fma_f32 v0, v0, v10, v18
	v_cvt_pk_bf16_f32 v0, v0, v17
	ds_write_b16 v39, v0 offset:44336
	v_and_b32_e32 v0, 0xffff0000, v2
	v_mul_f32_e32 v1, 0x3d372713, v0
	v_mul_f32_e32 v1, v1, v0
	v_fma_f32 v1, v1, v0, v0
	v_mul_f32_e32 v1, 0xbfcc422a, v1
	v_mul_f32_e32 v1, 0x3fb8aa3b, v1
	v_exp_f32_e32 v1, v1
	s_nop 0
	v_add_f32_e32 v1, 1.0, v1
	v_rcp_f32_e32 v1, v1
	s_nop 0
	v_fma_f32 v0, v1, v0, -v37
	v_mul_f32_e32 v0, v36, v0
	v_fma_f32 v0, v0, v11, v19
	v_cvt_pk_bf16_f32 v0, v0, v17
	ds_write_b16 v39, v0 offset:44608
	v_lshlrev_b32_e32 v0, 16, v3
	v_mul_f32_e32 v1, 0x3d372713, v0
	v_mul_f32_e32 v1, v1, v0
	v_fma_f32 v1, v1, v0, v0
	v_mul_f32_e32 v1, 0xbfcc422a, v1
	v_mul_f32_e32 v1, 0x3fb8aa3b, v1
	v_exp_f32_e32 v1, v1
	s_nop 0
	v_add_f32_e32 v1, 1.0, v1
	v_rcp_f32_e32 v1, v1
	s_nop 0
	v_fma_f32 v0, v1, v0, -v37
	v_mul_f32_e32 v0, v36, v0
	v_fma_f32 v0, v0, v12, v20
	v_cvt_pk_bf16_f32 v0, v0, v17
	ds_write_b16 v39, v0 offset:44880
	v_and_b32_e32 v0, 0xffff0000, v3
	v_mul_f32_e32 v1, 0x3d372713, v0
	v_mul_f32_e32 v1, v1, v0
	v_fma_f32 v1, v1, v0, v0
	v_mul_f32_e32 v1, 0xbfcc422a, v1
	v_mul_f32_e32 v1, 0x3fb8aa3b, v1
	v_exp_f32_e32 v1, v1
	s_nop 0
	v_add_f32_e32 v1, 1.0, v1
	v_rcp_f32_e32 v1, v1
	s_nop 0
	v_fma_f32 v0, v1, v0, -v37
	v_mul_f32_e32 v0, v36, v0
	v_fmac_f32_e32 v21, v0, v13
	v_cvt_pk_bf16_f32 v0, v21, v17
	ds_write_b16 v39, v0 offset:45152
	v_mov_b64_e32 v[0:1], v[90:91]
	v_mov_b64_e32 v[2:3], v[92:93]
	s_waitcnt lgkmcnt(0)
	v_lshlrev_b32_e32 v10, 16, v0
	v_mul_f32_e32 v11, 0x3d372713, v10
	v_mul_f32_e32 v11, v11, v10
	v_fma_f32 v11, v11, v10, v10
	v_mul_f32_e32 v11, 0xbfcc422a, v11
	v_mul_f32_e32 v11, 0x3fb8aa3b, v11
	v_exp_f32_e32 v11, v11
	v_and_b32_e32 v0, 0xffff0000, v0
	v_add_f32_e32 v11, 1.0, v11
	v_rcp_f32_e32 v11, v11
	s_nop 0
	v_fma_f32 v10, v11, v10, -v37
	v_mul_f32_e32 v14, v36, v10
	v_mov_b64_e32 v[10:11], v[114:115]
	v_mov_b64_e32 v[12:13], v[116:117]
	v_mov_b64_e32 v[18:19], v[146:147]
	v_mov_b64_e32 v[20:21], v[148:149]
	v_fma_f32 v10, v10, v14, v18
	v_cvt_pk_bf16_f32 v10, v10, v17
	ds_write_b16 v39, v10 offset:51952
	v_mul_f32_e32 v10, 0x3d372713, v0
	v_mul_f32_e32 v10, v10, v0
	v_fma_f32 v10, v10, v0, v0
	v_mul_f32_e32 v10, 0xbfcc422a, v10
	v_mul_f32_e32 v10, 0x3fb8aa3b, v10
	v_exp_f32_e32 v10, v10
	s_nop 0
	v_add_f32_e32 v10, 1.0, v10
	v_rcp_f32_e32 v10, v10
	s_nop 0
	v_fma_f32 v0, v10, v0, -v37
	v_mul_f32_e32 v0, v36, v0
	v_fma_f32 v0, v11, v0, v19
	v_cvt_pk_bf16_f32 v0, v0, v17
	ds_write_b16 v39, v0 offset:52224
	v_lshlrev_b32_e32 v0, 16, v1
	v_mul_f32_e32 v10, 0x3d372713, v0
	v_mul_f32_e32 v10, v10, v0
	v_fma_f32 v10, v10, v0, v0
	v_mul_f32_e32 v10, 0xbfcc422a, v10
	v_mul_f32_e32 v10, 0x3fb8aa3b, v10
	v_exp_f32_e32 v10, v10
	s_nop 0
	v_add_f32_e32 v10, 1.0, v10
	v_rcp_f32_e32 v10, v10
	s_nop 0
	v_fma_f32 v0, v10, v0, -v37
	v_mul_f32_e32 v0, v36, v0
	v_fma_f32 v0, v12, v0, v20
	v_cvt_pk_bf16_f32 v0, v0, v17
	ds_write_b16 v39, v0 offset:52496
	v_and_b32_e32 v0, 0xffff0000, v1
	v_mul_f32_e32 v1, 0x3d372713, v0
	v_mul_f32_e32 v1, v1, v0
	v_fma_f32 v1, v1, v0, v0
	v_mul_f32_e32 v1, 0xbfcc422a, v1
	v_mul_f32_e32 v1, 0x3fb8aa3b, v1
	v_exp_f32_e32 v1, v1
	s_nop 0
	v_add_f32_e32 v1, 1.0, v1
	v_rcp_f32_e32 v1, v1
	s_nop 0
	v_fma_f32 v0, v1, v0, -v37
	v_mul_f32_e32 v0, v36, v0
	v_fmac_f32_e32 v21, v13, v0
	v_cvt_pk_bf16_f32 v0, v21, v17
	ds_write_b16 v39, v0 offset:52768
	v_mov_b64_e32 v[10:11], v[118:119]
	v_mov_b64_e32 v[12:13], v[120:121]
	v_mov_b64_e32 v[18:19], v[150:151]
	v_mov_b64_e32 v[20:21], v[152:153]
	v_lshlrev_b32_e32 v0, 16, v2
	v_mul_f32_e32 v1, 0x3d372713, v0
	v_mul_f32_e32 v1, v1, v0
	v_fma_f32 v1, v1, v0, v0
	v_mul_f32_e32 v1, 0xbfcc422a, v1
	v_mul_f32_e32 v1, 0x3fb8aa3b, v1
	v_exp_f32_e32 v1, v1
	s_nop 0
	v_add_f32_e32 v1, 1.0, v1
	v_rcp_f32_e32 v1, v1
	s_nop 0
	v_fma_f32 v0, v1, v0, -v37
	v_mul_f32_e32 v0, v36, v0
	s_waitcnt vmcnt(0)
	v_fma_f32 v0, v0, v10, v18
	v_cvt_pk_bf16_f32 v0, v0, v17
	ds_write_b16 v39, v0 offset:53040
	v_and_b32_e32 v0, 0xffff0000, v2
	v_mul_f32_e32 v1, 0x3d372713, v0
	v_mul_f32_e32 v1, v1, v0
	v_fma_f32 v1, v1, v0, v0
	v_mul_f32_e32 v1, 0xbfcc422a, v1
	v_mul_f32_e32 v1, 0x3fb8aa3b, v1
	v_exp_f32_e32 v1, v1
	s_nop 0
	v_add_f32_e32 v1, 1.0, v1
	v_rcp_f32_e32 v1, v1
	s_nop 0
	v_fma_f32 v0, v1, v0, -v37
	v_mul_f32_e32 v0, v36, v0
	v_fma_f32 v0, v0, v11, v19
	v_cvt_pk_bf16_f32 v0, v0, v17
	ds_write_b16 v39, v0 offset:53312
	v_lshlrev_b32_e32 v0, 16, v3
	v_mul_f32_e32 v1, 0x3d372713, v0
	v_mul_f32_e32 v1, v1, v0
	v_fma_f32 v1, v1, v0, v0
	v_mul_f32_e32 v1, 0xbfcc422a, v1
	v_mul_f32_e32 v1, 0x3fb8aa3b, v1
	v_exp_f32_e32 v1, v1
	s_nop 0
	v_add_f32_e32 v1, 1.0, v1
	v_rcp_f32_e32 v1, v1
	s_nop 0
	v_fma_f32 v0, v1, v0, -v37
	v_mul_f32_e32 v0, v36, v0
	v_fma_f32 v0, v0, v12, v20
	v_cvt_pk_bf16_f32 v0, v0, v17
	ds_write_b16 v39, v0 offset:53584
	v_and_b32_e32 v0, 0xffff0000, v3
	v_mul_f32_e32 v1, 0x3d372713, v0
	v_mul_f32_e32 v1, v1, v0
	v_fma_f32 v1, v1, v0, v0
	v_mul_f32_e32 v1, 0xbfcc422a, v1
	v_mul_f32_e32 v1, 0x3fb8aa3b, v1
	v_exp_f32_e32 v1, v1
	s_nop 0
	v_add_f32_e32 v1, 1.0, v1
	v_rcp_f32_e32 v1, v1
	s_nop 0
	v_fma_f32 v0, v1, v0, -v37
	v_mul_f32_e32 v0, v36, v0
	v_fmac_f32_e32 v21, v0, v13
	v_cvt_pk_bf16_f32 v0, v21, v17
	ds_write_b16 v39, v0 offset:53856
	v_mov_b64_e32 v[0:1], v[94:95]
	v_mov_b64_e32 v[2:3], v[96:97]
	v_mov_b64_e32 v[10:11], v[122:123]
	v_mov_b64_e32 v[12:13], v[124:125]
	v_mov_b64_e32 v[18:19], v[154:155]
	v_mov_b64_e32 v[20:21], v[156:157]
	s_waitcnt lgkmcnt(0)
	v_lshlrev_b32_e32 v6, 16, v0
	v_mul_f32_e32 v7, 0x3d372713, v6
	v_mul_f32_e32 v7, v7, v6
	v_fma_f32 v7, v7, v6, v6
	v_mul_f32_e32 v7, 0xbfcc422a, v7
	v_mul_f32_e32 v7, 0x3fb8aa3b, v7
	v_exp_f32_e32 v7, v7
	v_and_b32_e32 v0, 0xffff0000, v0
	v_add_f32_e32 v7, 1.0, v7
	v_rcp_f32_e32 v7, v7
	s_nop 0
	v_fma_f32 v6, v7, v6, -v37
	v_mul_f32_e32 v6, v36, v6
	v_fma_f32 v6, v10, v6, v18
	v_cvt_pk_bf16_f32 v6, v6, v17
	ds_write_b16 v39, v6 offset:60656
	v_mul_f32_e32 v6, 0x3d372713, v0
	v_mul_f32_e32 v6, v6, v0
	v_fma_f32 v6, v6, v0, v0
	v_mul_f32_e32 v6, 0xbfcc422a, v6
	v_mul_f32_e32 v6, 0x3fb8aa3b, v6
	v_exp_f32_e32 v6, v6
	s_nop 0
	v_add_f32_e32 v6, 1.0, v6
	v_rcp_f32_e32 v6, v6
	s_nop 0
	v_fma_f32 v0, v6, v0, -v37
	v_mul_f32_e32 v0, v36, v0
	v_fma_f32 v0, v11, v0, v19
	v_cvt_pk_bf16_f32 v0, v0, v17
	ds_write_b16 v39, v0 offset:60928
	v_lshlrev_b32_e32 v0, 16, v1
	v_mul_f32_e32 v6, 0x3d372713, v0
	v_mul_f32_e32 v6, v6, v0
	v_fma_f32 v6, v6, v0, v0
	v_mul_f32_e32 v6, 0xbfcc422a, v6
	v_mul_f32_e32 v6, 0x3fb8aa3b, v6
	v_exp_f32_e32 v6, v6
	s_nop 0
	v_add_f32_e32 v6, 1.0, v6
	v_rcp_f32_e32 v6, v6
	s_nop 0
	v_fma_f32 v0, v6, v0, -v37
	v_mul_f32_e32 v0, v36, v0
	v_fma_f32 v0, v12, v0, v20
	v_cvt_pk_bf16_f32 v0, v0, v17
	ds_write_b16 v39, v0 offset:61200
	v_and_b32_e32 v0, 0xffff0000, v1
	v_mul_f32_e32 v1, 0x3d372713, v0
	v_mul_f32_e32 v1, v1, v0
	v_fma_f32 v1, v1, v0, v0
	v_mul_f32_e32 v1, 0xbfcc422a, v1
	v_mul_f32_e32 v1, 0x3fb8aa3b, v1
	v_exp_f32_e32 v1, v1
	s_nop 0
	v_add_f32_e32 v1, 1.0, v1
	v_rcp_f32_e32 v1, v1
	s_nop 0
	v_fma_f32 v0, v1, v0, -v37
	v_mul_f32_e32 v0, v36, v0
	v_fmac_f32_e32 v21, v13, v0
	v_cvt_pk_bf16_f32 v0, v21, v17
	ds_write_b16 v39, v0 offset:61472
	v_mov_b64_e32 v[4:5], v[126:127]
	v_mov_b64_e32 v[6:7], v[128:129]
	s_nop 0
	v_mov_b64_e32 v[8:9], v[158:159]
	v_mov_b64_e32 v[10:11], v[160:161]
	v_lshlrev_b32_e32 v0, 16, v2
	v_mul_f32_e32 v1, 0x3d372713, v0
	v_mul_f32_e32 v1, v1, v0
	v_fma_f32 v1, v1, v0, v0
	v_mul_f32_e32 v1, 0xbfcc422a, v1
	v_mul_f32_e32 v1, 0x3fb8aa3b, v1
	v_exp_f32_e32 v1, v1
	s_nop 0
	v_add_f32_e32 v1, 1.0, v1
	v_rcp_f32_e32 v1, v1
	s_nop 0
	v_fma_f32 v0, v1, v0, -v37
	v_mul_f32_e32 v0, v36, v0
	s_waitcnt vmcnt(0)
	v_fma_f32 v0, v0, v4, v8
	v_cvt_pk_bf16_f32 v0, v0, v17
	ds_write_b16 v39, v0 offset:61744
	v_and_b32_e32 v0, 0xffff0000, v2
	v_mul_f32_e32 v1, 0x3d372713, v0
	v_mul_f32_e32 v1, v1, v0
	v_fma_f32 v1, v1, v0, v0
	v_mul_f32_e32 v1, 0xbfcc422a, v1
	v_mul_f32_e32 v1, 0x3fb8aa3b, v1
	v_exp_f32_e32 v1, v1
	s_nop 0
	v_add_f32_e32 v1, 1.0, v1
	v_rcp_f32_e32 v1, v1
	s_nop 0
	v_fma_f32 v0, v1, v0, -v37
	v_mul_f32_e32 v0, v36, v0
	v_fma_f32 v0, v0, v5, v9
	v_cvt_pk_bf16_f32 v0, v0, v17
	ds_write_b16 v39, v0 offset:62016
	v_lshlrev_b32_e32 v0, 16, v3
	v_mul_f32_e32 v1, 0x3d372713, v0
	v_mul_f32_e32 v1, v1, v0
	v_fma_f32 v1, v1, v0, v0
	v_mul_f32_e32 v1, 0xbfcc422a, v1
	v_mul_f32_e32 v1, 0x3fb8aa3b, v1
	v_exp_f32_e32 v1, v1
	s_nop 0
	v_add_f32_e32 v1, 1.0, v1
	v_rcp_f32_e32 v1, v1
	s_nop 0
	v_fma_f32 v0, v1, v0, -v37
	v_mul_f32_e32 v0, v36, v0
	v_fma_f32 v0, v0, v6, v10
	v_cvt_pk_bf16_f32 v0, v0, v17
	ds_write_b16 v39, v0 offset:62288
	v_and_b32_e32 v0, 0xffff0000, v3
	v_mul_f32_e32 v1, 0x3d372713, v0
	v_mul_f32_e32 v1, v1, v0
	v_fma_f32 v1, v1, v0, v0
	v_mul_f32_e32 v1, 0xbfcc422a, v1
	v_mul_f32_e32 v1, 0x3fb8aa3b, v1
	v_exp_f32_e32 v1, v1
	s_nop 0
	v_add_f32_e32 v1, 1.0, v1
	v_rcp_f32_e32 v1, v1
	s_nop 0
	v_fma_f32 v0, v1, v0, -v37
	v_mul_f32_e32 v0, v36, v0
	v_fmac_f32_e32 v11, v0, v7
	v_cvt_pk_bf16_f32 v0, v11, v17
	ds_write_b16 v39, v0 offset:62560
	s_mov_b32 s4, 0
	s_ashr_i32 s5, s4, 31
	s_lshl_b64 s[4:5], s[4:5], 3
	s_add_u32 s4, s0, s4
	s_addc_u32 s5, s1, s5
	s_load_dwordx2 s[4:5], s[4:5], 0x48
	s_waitcnt lgkmcnt(0)
	v_lshl_add_u64 v[4:5], s[4:5], 0, v[42:43]
	v_mov_b64_e32 v[0:1], v[162:163]
	v_mov_b64_e32 v[2:3], v[164:165]
	v_lshl_add_u64 v[42:43], v[42:43], 0, s[14:15]
	v_cndmask_b32_e64 v2, v2, 0, s[40:41]
	v_cndmask_b32_e64 v3, v3, 0, s[40:41]
	v_cndmask_b32_e64 v0, v0, 0, s[40:41]
	v_cndmask_b32_e64 v1, v1, 0, s[40:41]
	v_cvt_pk_bf16_f32 v6, v0, v1
	v_cvt_pk_bf16_f32 v7, v2, v3
	v_mov_b64_e32 v[0:1], v[166:167]
	v_mov_b64_e32 v[2:3], v[168:169]
	v_cndmask_b32_e64 v0, v0, 0, s[40:41]
	v_cndmask_b32_e64 v1, v1, 0, s[40:41]
	v_cndmask_b32_e64 v2, v2, 0, s[40:41]
	v_cndmask_b32_e64 v3, v3, 0, s[40:41]
	v_cvt_pk_bf16_f32 v0, v0, v1
	v_cvt_pk_bf16_f32 v1, v2, v3
	ds_write2_b64 v56, v[6:7], v[0:1] offset1:1
	v_mov_b64_e32 v[0:1], v[170:171]
	v_mov_b64_e32 v[2:3], v[172:173]
	v_cndmask_b32_e64 v2, v2, 0, s[40:41]
	v_cndmask_b32_e64 v3, v3, 0, s[40:41]
	v_cndmask_b32_e64 v0, v0, 0, s[40:41]
	v_cndmask_b32_e64 v1, v1, 0, s[40:41]
	v_cvt_pk_bf16_f32 v6, v0, v1
	v_cvt_pk_bf16_f32 v7, v2, v3
	v_mov_b64_e32 v[0:1], v[174:175]
	v_mov_b64_e32 v[2:3], v[176:177]
	v_cndmask_b32_e64 v0, v0, 0, s[40:41]
	v_cndmask_b32_e64 v1, v1, 0, s[40:41]
	v_cndmask_b32_e64 v2, v2, 0, s[40:41]
	v_cndmask_b32_e64 v3, v3, 0, s[40:41]
	v_cvt_pk_bf16_f32 v0, v0, v1
	v_cvt_pk_bf16_f32 v1, v2, v3
	ds_write2_b64 v56, v[6:7], v[0:1] offset0:2 offset1:3
	v_mov_b64_e32 v[0:1], v[178:179]
	v_mov_b64_e32 v[2:3], v[180:181]
	v_cndmask_b32_e64 v2, v2, 0, s[40:41]
	v_cndmask_b32_e64 v3, v3, 0, s[40:41]
	v_cndmask_b32_e64 v0, v0, 0, s[40:41]
	v_cndmask_b32_e64 v1, v1, 0, s[40:41]
	v_cvt_pk_bf16_f32 v6, v0, v1
	v_cvt_pk_bf16_f32 v7, v2, v3
	v_mov_b64_e32 v[0:1], v[182:183]
	v_mov_b64_e32 v[2:3], v[184:185]
	v_cndmask_b32_e64 v0, v0, 0, s[40:41]
	v_cndmask_b32_e64 v1, v1, 0, s[40:41]
	v_cndmask_b32_e64 v2, v2, 0, s[40:41]
	v_cndmask_b32_e64 v3, v3, 0, s[40:41]
	v_cvt_pk_bf16_f32 v0, v0, v1
	v_cvt_pk_bf16_f32 v1, v2, v3
	ds_write2_b64 v56, v[6:7], v[0:1] offset0:4 offset1:5
	v_mov_b64_e32 v[0:1], v[186:187]
	v_mov_b64_e32 v[2:3], v[188:189]
	v_cndmask_b32_e64 v2, v2, 0, s[40:41]
	v_cndmask_b32_e64 v3, v3, 0, s[40:41]
	v_cndmask_b32_e64 v0, v0, 0, s[40:41]
	v_cndmask_b32_e64 v1, v1, 0, s[40:41]
	v_cvt_pk_bf16_f32 v6, v0, v1
	v_cvt_pk_bf16_f32 v7, v2, v3
	v_mov_b64_e32 v[0:1], v[190:191]
	v_mov_b64_e32 v[2:3], v[192:193]
	v_cndmask_b32_e64 v0, v0, 0, s[40:41]
	v_cndmask_b32_e64 v1, v1, 0, s[40:41]
	v_cndmask_b32_e64 v2, v2, 0, s[40:41]
	v_cndmask_b32_e64 v3, v3, 0, s[40:41]
	v_cvt_pk_bf16_f32 v0, v0, v1
	v_cvt_pk_bf16_f32 v1, v2, v3
	ds_write2_b64 v56, v[6:7], v[0:1] offset0:6 offset1:7
	s_waitcnt lgkmcnt(0)
	s_barrier
	ds_read_b128 v[0:3], v38
	ds_read_b128 v[4:7], v57 offset:34816
	ds_read_b128 v[8:11], v57 offset:39168
	ds_read_b128 v[12:15], v57 offset:43520
	ds_read_b128 v[18:21], v57 offset:47872
	ds_read_b128 v[22:25], v57 offset:52224
	ds_read_b128 v[26:29], v57 offset:56576
	ds_read_b128 v[30:33], v57 offset:60928
	ds_read_b128 v[50:53], v57 offset:65280
	s_waitcnt lgkmcnt(7)
	v_mfma_f32_16x16x32_bf16 v[4:7], v[4:7], v[0:3], 0
	s_waitcnt lgkmcnt(6)
	v_mfma_f32_16x16x32_bf16 v[8:11], v[8:11], v[0:3], 0
	s_waitcnt lgkmcnt(5)
	v_mfma_f32_16x16x32_bf16 v[12:15], v[12:15], v[0:3], 0
	s_waitcnt lgkmcnt(4)
	v_mfma_f32_16x16x32_bf16 v[18:21], v[18:21], v[0:3], 0
	s_waitcnt lgkmcnt(3)
	v_mfma_f32_16x16x32_bf16 v[22:25], v[22:25], v[0:3], 0
	s_waitcnt lgkmcnt(2)
	v_mfma_f32_16x16x32_bf16 v[26:29], v[26:29], v[0:3], 0
	s_waitcnt lgkmcnt(1)
	v_mfma_f32_16x16x32_bf16 v[30:33], v[30:33], v[0:3], 0
	s_waitcnt lgkmcnt(0)
	v_mfma_f32_16x16x32_bf16 v[0:3], v[50:53], v[0:3], 0
	ds_read_b128 v[50:53], v38 offset:64
	ds_read_b128 v[58:61], v57 offset:34880
	s_waitcnt lgkmcnt(0)
	v_mfma_f32_16x16x32_bf16 v[4:7], v[58:61], v[50:53], v[4:7]
	ds_read_b128 v[58:61], v57 offset:39232
	s_waitcnt lgkmcnt(0)
	v_mfma_f32_16x16x32_bf16 v[8:11], v[58:61], v[50:53], v[8:11]
	ds_read_b128 v[58:61], v57 offset:43584
	s_waitcnt lgkmcnt(0)
	v_mfma_f32_16x16x32_bf16 v[12:15], v[58:61], v[50:53], v[12:15]
	ds_read_b128 v[58:61], v57 offset:47936
	s_waitcnt lgkmcnt(0)
	v_mfma_f32_16x16x32_bf16 v[18:21], v[58:61], v[50:53], v[18:21]
	ds_read_b128 v[58:61], v57 offset:52288
	s_waitcnt lgkmcnt(0)
	v_mfma_f32_16x16x32_bf16 v[22:25], v[58:61], v[50:53], v[22:25]
	ds_read_b128 v[58:61], v57 offset:56640
	s_waitcnt lgkmcnt(0)
	v_mfma_f32_16x16x32_bf16 v[26:29], v[58:61], v[50:53], v[26:29]
	ds_read_b128 v[58:61], v57 offset:60992
	s_waitcnt lgkmcnt(0)
	v_mfma_f32_16x16x32_bf16 v[30:33], v[58:61], v[50:53], v[30:33]
	ds_read_b128 v[58:61], v57 offset:65344
	s_waitcnt lgkmcnt(0)
	v_mfma_f32_16x16x32_bf16 v[0:3], v[58:61], v[50:53], v[0:3]
	ds_read_b128 v[50:53], v38 offset:128
	ds_read_b128 v[58:61], v57 offset:34944
	s_waitcnt lgkmcnt(0)
	v_mfma_f32_16x16x32_bf16 v[4:7], v[58:61], v[50:53], v[4:7]
	ds_read_b128 v[58:61], v57 offset:39296
	s_waitcnt lgkmcnt(0)
	v_mfma_f32_16x16x32_bf16 v[8:11], v[58:61], v[50:53], v[8:11]
	ds_read_b128 v[58:61], v57 offset:43648
	s_waitcnt lgkmcnt(0)
	v_mfma_f32_16x16x32_bf16 v[12:15], v[58:61], v[50:53], v[12:15]
	ds_read_b128 v[58:61], v57 offset:48000
	s_waitcnt lgkmcnt(0)
	v_mfma_f32_16x16x32_bf16 v[18:21], v[58:61], v[50:53], v[18:21]
	ds_read_b128 v[58:61], v57 offset:52352
	s_waitcnt lgkmcnt(0)
	v_mfma_f32_16x16x32_bf16 v[58:61], v[58:61], v[50:53], v[22:25]
	s_nop 2
	ds_read_b128 v[22:25], v57 offset:56704
	s_waitcnt lgkmcnt(0)
	v_mfma_f32_16x16x32_bf16 v[62:65], v[22:25], v[50:53], v[26:29]
	ds_read_b128 v[22:25], v57 offset:61056
	s_waitcnt lgkmcnt(0)
	v_mfma_f32_16x16x32_bf16 v[66:69], v[22:25], v[50:53], v[30:33]
	ds_read_b128 v[22:25], v57 offset:65408
	s_waitcnt lgkmcnt(0)
	v_mfma_f32_16x16x32_bf16 v[0:3], v[22:25], v[50:53], v[0:3]
	ds_read_b128 v[50:53], v38 offset:192
	ds_read_b128 v[22:25], v57 offset:35008
	s_waitcnt lgkmcnt(0)
	v_mfma_f32_16x16x32_bf16 v[30:33], v[22:25], v[50:53], v[4:7]
	s_nop 2
	ds_read_b128 v[4:7], v57 offset:39360
	s_waitcnt lgkmcnt(0)
	v_mfma_f32_16x16x32_bf16 v[26:29], v[4:7], v[50:53], v[8:11]
	ds_read_b128 v[4:7], v57 offset:43712
	s_waitcnt lgkmcnt(0)
	v_mfma_f32_16x16x32_bf16 v[22:25], v[4:7], v[50:53], v[12:15]
	ds_read_b128 v[4:7], v57 offset:48064
	s_waitcnt lgkmcnt(0)
	v_mfma_f32_16x16x32_bf16 v[18:21], v[4:7], v[50:53], v[18:21]
	ds_read_b128 v[4:7], v57 offset:52416
	s_waitcnt lgkmcnt(0)
	v_mfma_f32_16x16x32_bf16 v[12:15], v[4:7], v[50:53], v[58:61]
	ds_read_b128 v[4:7], v57 offset:56768
	s_nop 1
	ds_read_b128 v[58:61], v57 offset:65472
	s_waitcnt lgkmcnt(1)
	v_mfma_f32_16x16x32_bf16 v[8:11], v[4:7], v[50:53], v[62:65]
	ds_read_b128 v[4:7], v57 offset:61120
	s_mov_b32 s4, 0
	s_ashr_i32 s5, s4, 31
	s_lshl_b64 s[4:5], s[4:5], 3
	s_add_u32 s4, s0, s4
	s_addc_u32 s5, s1, s5
	s_load_dwordx2 s[4:5], s[4:5], 0x50
	s_waitcnt lgkmcnt(0)
	v_mfma_f32_16x16x32_bf16 v[4:7], v[4:7], v[50:53], v[66:69]
	v_mfma_f32_16x16x32_bf16 v[0:3], v[58:61], v[50:53], v[0:3]
	v_lshl_add_u64 v[50:51], s[4:5], 0, v[44:45]
	v_lshl_add_u64 v[50:51], v[50:51], 0, s[42:43]
	v_mov_b32_e32 v58, v224
	v_lshl_add_u64 v[50:51], s[90:91], 0, v[48:49]
	v_add_co_u32_e32 v50, vcc, s86, v50
	v_lshl_add_u64 v[52:53], s[90:91], 0, v[46:47]
	s_nop 0
	v_addc_co_u32_e32 v51, vcc, 0, v51, vcc
	v_mov_b64_e32 v[54:55], v[208:209]
	s_add_u32 s42, s42, 0x200
	s_addc_u32 s43, s43, 0
	s_add_u32 s90, s90, 0x100
	s_addc_u32 s91, s91, 0
	s_cmpk_eq_i32 s42, 0x800
	v_add_f32_e32 v30, v30, v58
	v_add_f32_e32 v31, v31, v58
	v_add_f32_e32 v26, v26, v58
	v_add_f32_e32 v27, v27, v58
	v_add_f32_e32 v22, v22, v58
	v_add_f32_e32 v23, v23, v58
	v_add_f32_e32 v18, v18, v58
	s_waitcnt lgkmcnt(0)
	v_lshlrev_b32_e32 v59, 16, v54
	v_mul_f32_e32 v60, 0x3d372713, v59
	v_mul_f32_e32 v60, v60, v59
	v_fma_f32 v60, v60, v59, v59
	v_mul_f32_e32 v60, 0xbfcc422a, v60
	v_mul_f32_e32 v60, 0x3fb8aa3b, v60
	v_exp_f32_e32 v60, v60
	v_and_b32_e32 v54, 0xffff0000, v54
	v_add_f32_e32 v19, v19, v58
	v_add_f32_e32 v12, v12, v58
	v_add_f32_e32 v60, 1.0, v60
	v_rcp_f32_e32 v60, v60
	v_add_f32_e32 v13, v13, v58
	v_add_f32_e32 v8, v8, v58
	v_add_f32_e32 v9, v9, v58
	v_mul_f32_e32 v59, v60, v59
	v_mul_f32_e32 v30, v30, v59
	v_mul_f32_e32 v59, 0x3d372713, v54
	v_mul_f32_e32 v59, v59, v54
	v_fma_f32 v59, v59, v54, v54
	v_mul_f32_e32 v59, 0xbfcc422a, v59
	v_mul_f32_e32 v59, 0x3fb8aa3b, v59
	v_exp_f32_e32 v59, v59
	v_add_f32_e32 v4, v4, v58
	v_add_f32_e32 v5, v5, v58
	v_add_f32_e32 v0, v0, v58
	v_add_f32_e32 v59, 1.0, v59
	v_rcp_f32_e32 v59, v59
	v_add_f32_e32 v1, v1, v58
	v_mul_f32_e32 v54, v59, v54
	v_mul_f32_e32 v31, v31, v54
	v_cvt_pk_bf16_f32 v54, v30, v31
	v_lshlrev_b32_e32 v31, 16, v55
	v_add_f32_e32 v30, v32, v58
	v_mul_f32_e32 v32, 0x3d372713, v31
	v_mul_f32_e32 v32, v32, v31
	v_fma_f32 v32, v32, v31, v31
	v_mul_f32_e32 v32, 0xbfcc422a, v32
	v_mul_f32_e32 v32, 0x3fb8aa3b, v32
	v_exp_f32_e32 v32, v32
	s_nop 0
	v_add_f32_e32 v32, 1.0, v32
	v_rcp_f32_e32 v32, v32
	s_nop 0
	v_mul_f32_e32 v31, v32, v31
	v_and_b32_e32 v32, 0xffff0000, v55
	v_mul_f32_e32 v30, v30, v31
	v_add_f32_e32 v31, v33, v58
	v_mul_f32_e32 v33, 0x3d372713, v32
	v_mul_f32_e32 v33, v33, v32
	v_fma_f32 v33, v33, v32, v32
	v_mul_f32_e32 v33, 0xbfcc422a, v33
	v_mul_f32_e32 v33, 0x3fb8aa3b, v33
	v_exp_f32_e32 v33, v33
	s_nop 0
	v_add_f32_e32 v33, 1.0, v33
	v_rcp_f32_e32 v33, v33
	s_nop 0
	v_mul_f32_e32 v32, v33, v32
	v_mul_f32_e32 v31, v31, v32
	v_cvt_pk_bf16_f32 v55, v30, v31
	v_add_co_u32_e32 v30, vcc, s2, v52
	s_nop 1
	v_addc_co_u32_e32 v31, vcc, 0, v53, vcc
	global_store_dwordx2 v[30:31], v[54:55], off
	v_mov_b64_e32 v[32:33], v[210:211]
	s_waitcnt lgkmcnt(0)
	v_lshlrev_b32_e32 v52, 16, v32
	v_mul_f32_e32 v53, 0x3d372713, v52
	v_mul_f32_e32 v53, v53, v52
	v_fma_f32 v53, v53, v52, v52
	v_mul_f32_e32 v53, 0xbfcc422a, v53
	v_mul_f32_e32 v53, 0x3fb8aa3b, v53
	v_exp_f32_e32 v53, v53
	v_and_b32_e32 v32, 0xffff0000, v32
	v_add_f32_e32 v53, 1.0, v53
	v_rcp_f32_e32 v53, v53
	s_nop 0
	v_mul_f32_e32 v52, v53, v52
	v_mul_f32_e32 v26, v26, v52
	v_mul_f32_e32 v52, 0x3d372713, v32
	v_mul_f32_e32 v52, v52, v32
	v_fma_f32 v52, v52, v32, v32
	v_mul_f32_e32 v52, 0xbfcc422a, v52
	v_mul_f32_e32 v52, 0x3fb8aa3b, v52
	v_exp_f32_e32 v52, v52
	s_nop 0
	v_add_f32_e32 v52, 1.0, v52
	v_rcp_f32_e32 v52, v52
	s_nop 0
	v_mul_f32_e32 v32, v52, v32
	v_mul_f32_e32 v27, v27, v32
	v_cvt_pk_bf16_f32 v26, v26, v27
	v_add_f32_e32 v27, v28, v58
	v_lshlrev_b32_e32 v28, 16, v33
	v_mul_f32_e32 v32, 0x3d372713, v28
	v_mul_f32_e32 v32, v32, v28
	v_fma_f32 v32, v32, v28, v28
	v_mul_f32_e32 v32, 0xbfcc422a, v32
	v_mul_f32_e32 v32, 0x3fb8aa3b, v32
	v_exp_f32_e32 v32, v32
	s_nop 0
	v_add_f32_e32 v32, 1.0, v32
	v_rcp_f32_e32 v32, v32
	s_nop 0
	v_mul_f32_e32 v28, v32, v28
	v_mul_f32_e32 v27, v27, v28
	v_add_f32_e32 v28, v29, v58
	v_and_b32_e32 v29, 0xffff0000, v33
	v_mul_f32_e32 v32, 0x3d372713, v29
	v_mul_f32_e32 v32, v32, v29
	v_fma_f32 v32, v32, v29, v29
	v_mul_f32_e32 v32, 0xbfcc422a, v32
	v_mul_f32_e32 v32, 0x3fb8aa3b, v32
	v_exp_f32_e32 v32, v32
	s_nop 0
	v_add_f32_e32 v32, 1.0, v32
	v_rcp_f32_e32 v32, v32
	s_nop 0
	v_mul_f32_e32 v29, v32, v29
	v_mul_f32_e32 v28, v28, v29
	v_cvt_pk_bf16_f32 v27, v27, v28
	global_store_dwordx2 v[30:31], v[26:27], off offset:32
	v_mov_b64_e32 v[26:27], v[212:213]
	s_waitcnt lgkmcnt(0)
	v_lshlrev_b32_e32 v28, 16, v26
	v_mul_f32_e32 v29, 0x3d372713, v28
	v_mul_f32_e32 v29, v29, v28
	v_fma_f32 v29, v29, v28, v28
	v_mul_f32_e32 v29, 0xbfcc422a, v29
	v_mul_f32_e32 v29, 0x3fb8aa3b, v29
	v_exp_f32_e32 v29, v29
	v_and_b32_e32 v26, 0xffff0000, v26
	v_add_f32_e32 v29, 1.0, v29
	v_rcp_f32_e32 v29, v29
	s_nop 0
	v_mul_f32_e32 v28, v29, v28
	v_mul_f32_e32 v22, v22, v28
	v_mul_f32_e32 v28, 0x3d372713, v26
	v_mul_f32_e32 v28, v28, v26
	v_fma_f32 v28, v28, v26, v26
	v_mul_f32_e32 v28, 0xbfcc422a, v28
	v_mul_f32_e32 v28, 0x3fb8aa3b, v28
	v_exp_f32_e32 v28, v28
	s_nop 0
	v_add_f32_e32 v28, 1.0, v28
	v_rcp_f32_e32 v28, v28
	s_nop 0
	v_mul_f32_e32 v26, v28, v26
	v_mul_f32_e32 v23, v23, v26
	v_cvt_pk_bf16_f32 v22, v22, v23
	v_add_f32_e32 v23, v24, v58
	v_lshlrev_b32_e32 v24, 16, v27
	v_mul_f32_e32 v26, 0x3d372713, v24
	v_mul_f32_e32 v26, v26, v24
	v_fma_f32 v26, v26, v24, v24
	v_mul_f32_e32 v26, 0xbfcc422a, v26
	v_mul_f32_e32 v26, 0x3fb8aa3b, v26
	v_exp_f32_e32 v26, v26
	s_nop 0
	v_add_f32_e32 v26, 1.0, v26
	v_rcp_f32_e32 v26, v26
	s_nop 0
	v_mul_f32_e32 v24, v26, v24
	v_mul_f32_e32 v23, v23, v24
	v_add_f32_e32 v24, v25, v58
	v_and_b32_e32 v25, 0xffff0000, v27
	v_mul_f32_e32 v26, 0x3d372713, v25
	v_mul_f32_e32 v26, v26, v25
	v_fma_f32 v26, v26, v25, v25
	v_mul_f32_e32 v26, 0xbfcc422a, v26
	v_mul_f32_e32 v26, 0x3fb8aa3b, v26
	v_exp_f32_e32 v26, v26
	s_nop 0
	v_add_f32_e32 v26, 1.0, v26
	v_rcp_f32_e32 v26, v26
	s_nop 0
	v_mul_f32_e32 v25, v26, v25
	v_mul_f32_e32 v24, v24, v25
	v_cvt_pk_bf16_f32 v23, v23, v24
	global_store_dwordx2 v[30:31], v[22:23], off offset:64
	v_mov_b64_e32 v[22:23], v[214:215]
	s_waitcnt lgkmcnt(0)
	v_lshlrev_b32_e32 v24, 16, v22
	v_mul_f32_e32 v25, 0x3d372713, v24
	v_mul_f32_e32 v25, v25, v24
	v_fma_f32 v25, v25, v24, v24
	v_mul_f32_e32 v25, 0xbfcc422a, v25
	v_mul_f32_e32 v25, 0x3fb8aa3b, v25
	v_exp_f32_e32 v25, v25
	v_and_b32_e32 v22, 0xffff0000, v22
	v_add_f32_e32 v25, 1.0, v25
	v_rcp_f32_e32 v25, v25
	s_nop 0
	v_mul_f32_e32 v24, v25, v24
	v_mul_f32_e32 v18, v18, v24
	v_mul_f32_e32 v24, 0x3d372713, v22
	v_mul_f32_e32 v24, v24, v22
	v_fma_f32 v24, v24, v22, v22
	v_mul_f32_e32 v24, 0xbfcc422a, v24
	v_mul_f32_e32 v24, 0x3fb8aa3b, v24
	v_exp_f32_e32 v24, v24
	s_nop 0
	v_add_f32_e32 v24, 1.0, v24
	v_rcp_f32_e32 v24, v24
	s_nop 0
	v_mul_f32_e32 v22, v24, v22
	v_mul_f32_e32 v19, v19, v22
	v_cvt_pk_bf16_f32 v18, v18, v19
	v_add_f32_e32 v19, v20, v58
	v_lshlrev_b32_e32 v20, 16, v23
	v_mul_f32_e32 v22, 0x3d372713, v20
	v_mul_f32_e32 v22, v22, v20
	v_fma_f32 v22, v22, v20, v20
	v_mul_f32_e32 v22, 0xbfcc422a, v22
	v_mul_f32_e32 v22, 0x3fb8aa3b, v22
	v_exp_f32_e32 v22, v22
	s_nop 0
	v_add_f32_e32 v22, 1.0, v22
	v_rcp_f32_e32 v22, v22
	s_nop 0
	v_mul_f32_e32 v20, v22, v20
	v_mul_f32_e32 v19, v19, v20
	v_add_f32_e32 v20, v21, v58
	v_and_b32_e32 v21, 0xffff0000, v23
	v_mul_f32_e32 v22, 0x3d372713, v21
	v_mul_f32_e32 v22, v22, v21
	v_fma_f32 v22, v22, v21, v21
	v_mul_f32_e32 v22, 0xbfcc422a, v22
	v_mul_f32_e32 v22, 0x3fb8aa3b, v22
	v_exp_f32_e32 v22, v22
	s_nop 0
	v_add_f32_e32 v22, 1.0, v22
	v_rcp_f32_e32 v22, v22
	s_nop 0
	v_mul_f32_e32 v21, v22, v21
	v_mul_f32_e32 v20, v20, v21
	v_cvt_pk_bf16_f32 v19, v19, v20
	global_store_dwordx2 v[30:31], v[18:19], off offset:96
	v_mov_b64_e32 v[18:19], v[216:217]
	s_waitcnt lgkmcnt(0)
	v_lshlrev_b32_e32 v20, 16, v18
	v_mul_f32_e32 v21, 0x3d372713, v20
	v_mul_f32_e32 v21, v21, v20
	v_fma_f32 v21, v21, v20, v20
	v_mul_f32_e32 v21, 0xbfcc422a, v21
	v_mul_f32_e32 v21, 0x3fb8aa3b, v21
	v_exp_f32_e32 v21, v21
	v_and_b32_e32 v18, 0xffff0000, v18
	v_add_f32_e32 v21, 1.0, v21
	v_rcp_f32_e32 v21, v21
	s_nop 0
	v_mul_f32_e32 v20, v21, v20
	v_mul_f32_e32 v12, v12, v20
	v_mul_f32_e32 v20, 0x3d372713, v18
	v_mul_f32_e32 v20, v20, v18
	v_fma_f32 v20, v20, v18, v18
	v_mul_f32_e32 v20, 0xbfcc422a, v20
	v_mul_f32_e32 v20, 0x3fb8aa3b, v20
	v_exp_f32_e32 v20, v20
	s_nop 0
	v_add_f32_e32 v20, 1.0, v20
	v_rcp_f32_e32 v20, v20
	s_nop 0
	v_mul_f32_e32 v18, v20, v18
	v_mul_f32_e32 v13, v13, v18
	v_cvt_pk_bf16_f32 v12, v12, v13
	v_add_f32_e32 v13, v14, v58
	v_lshlrev_b32_e32 v14, 16, v19
	v_mul_f32_e32 v18, 0x3d372713, v14
	v_mul_f32_e32 v18, v18, v14
	v_fma_f32 v18, v18, v14, v14
	v_mul_f32_e32 v18, 0xbfcc422a, v18
	v_mul_f32_e32 v18, 0x3fb8aa3b, v18
	v_exp_f32_e32 v18, v18
	s_nop 0
	v_add_f32_e32 v18, 1.0, v18
	v_rcp_f32_e32 v18, v18
	s_nop 0
	v_mul_f32_e32 v14, v18, v14
	v_mul_f32_e32 v13, v13, v14
	v_add_f32_e32 v14, v15, v58
	v_and_b32_e32 v15, 0xffff0000, v19
	v_mul_f32_e32 v18, 0x3d372713, v15
	v_mul_f32_e32 v18, v18, v15
	v_fma_f32 v18, v18, v15, v15
	v_mul_f32_e32 v18, 0xbfcc422a, v18
	v_mul_f32_e32 v18, 0x3fb8aa3b, v18
	v_exp_f32_e32 v18, v18
	s_nop 0
	v_add_f32_e32 v18, 1.0, v18
	v_rcp_f32_e32 v18, v18
	s_nop 0
	v_mul_f32_e32 v15, v18, v15
	v_mul_f32_e32 v14, v14, v15
	v_cvt_pk_bf16_f32 v13, v13, v14
	global_store_dwordx2 v[30:31], v[12:13], off offset:128
	v_mov_b64_e32 v[12:13], v[218:219]
	s_waitcnt lgkmcnt(0)
	v_lshlrev_b32_e32 v14, 16, v12
	v_mul_f32_e32 v15, 0x3d372713, v14
	v_mul_f32_e32 v15, v15, v14
	v_fma_f32 v15, v15, v14, v14
	v_mul_f32_e32 v15, 0xbfcc422a, v15
	v_mul_f32_e32 v15, 0x3fb8aa3b, v15
	v_exp_f32_e32 v15, v15
	v_and_b32_e32 v12, 0xffff0000, v12
	v_add_f32_e32 v15, 1.0, v15
	v_rcp_f32_e32 v15, v15
	s_nop 0
	v_mul_f32_e32 v14, v15, v14
	v_mul_f32_e32 v8, v8, v14
	v_mul_f32_e32 v14, 0x3d372713, v12
	v_mul_f32_e32 v14, v14, v12
	v_fma_f32 v14, v14, v12, v12
	v_mul_f32_e32 v14, 0xbfcc422a, v14
	v_mul_f32_e32 v14, 0x3fb8aa3b, v14
	v_exp_f32_e32 v14, v14
	s_nop 0
	v_add_f32_e32 v14, 1.0, v14
	v_rcp_f32_e32 v14, v14
	s_nop 0
	v_mul_f32_e32 v12, v14, v12
	v_mul_f32_e32 v9, v9, v12
	v_cvt_pk_bf16_f32 v8, v8, v9
	v_add_f32_e32 v9, v10, v58
	v_lshlrev_b32_e32 v10, 16, v13
	v_mul_f32_e32 v12, 0x3d372713, v10
	v_mul_f32_e32 v12, v12, v10
	v_fma_f32 v12, v12, v10, v10
	v_mul_f32_e32 v12, 0xbfcc422a, v12
	v_mul_f32_e32 v12, 0x3fb8aa3b, v12
	v_exp_f32_e32 v12, v12
	s_nop 0
	v_add_f32_e32 v12, 1.0, v12
	v_rcp_f32_e32 v12, v12
	s_nop 0
	v_mul_f32_e32 v10, v12, v10
	v_mul_f32_e32 v9, v9, v10
	v_add_f32_e32 v10, v11, v58
	v_and_b32_e32 v11, 0xffff0000, v13
	v_mul_f32_e32 v12, 0x3d372713, v11
	v_mul_f32_e32 v12, v12, v11
	v_fma_f32 v12, v12, v11, v11
	v_mul_f32_e32 v12, 0xbfcc422a, v12
	v_mul_f32_e32 v12, 0x3fb8aa3b, v12
	v_exp_f32_e32 v12, v12
	s_nop 0
	v_add_f32_e32 v12, 1.0, v12
	v_rcp_f32_e32 v12, v12
	s_nop 0
	v_mul_f32_e32 v11, v12, v11
	v_mul_f32_e32 v10, v10, v11
	v_cvt_pk_bf16_f32 v9, v9, v10
	global_store_dwordx2 v[30:31], v[8:9], off offset:160
	v_mov_b64_e32 v[8:9], v[220:221]
	s_waitcnt lgkmcnt(0)
	v_lshlrev_b32_e32 v10, 16, v8
	v_mul_f32_e32 v11, 0x3d372713, v10
	v_mul_f32_e32 v11, v11, v10
	v_fma_f32 v11, v11, v10, v10
	v_mul_f32_e32 v11, 0xbfcc422a, v11
	v_mul_f32_e32 v11, 0x3fb8aa3b, v11
	v_exp_f32_e32 v11, v11
	v_and_b32_e32 v8, 0xffff0000, v8
	v_add_f32_e32 v11, 1.0, v11
	v_rcp_f32_e32 v11, v11
	s_nop 0
	v_mul_f32_e32 v10, v11, v10
	v_mul_f32_e32 v4, v4, v10
	v_mul_f32_e32 v10, 0x3d372713, v8
	v_mul_f32_e32 v10, v10, v8
	v_fma_f32 v10, v10, v8, v8
	v_mul_f32_e32 v10, 0xbfcc422a, v10
	v_mul_f32_e32 v10, 0x3fb8aa3b, v10
	v_exp_f32_e32 v10, v10
	s_nop 0
	v_add_f32_e32 v10, 1.0, v10
	v_rcp_f32_e32 v10, v10
	s_nop 0
	v_mul_f32_e32 v8, v10, v8
	v_mul_f32_e32 v5, v5, v8
	v_cvt_pk_bf16_f32 v4, v4, v5
	v_add_f32_e32 v5, v6, v58
	v_lshlrev_b32_e32 v6, 16, v9
	v_mul_f32_e32 v8, 0x3d372713, v6
	v_mul_f32_e32 v8, v8, v6
	v_fma_f32 v8, v8, v6, v6
	v_mul_f32_e32 v8, 0xbfcc422a, v8
	v_mul_f32_e32 v8, 0x3fb8aa3b, v8
	v_exp_f32_e32 v8, v8
	s_nop 0
	v_add_f32_e32 v8, 1.0, v8
	v_rcp_f32_e32 v8, v8
	s_nop 0
	v_mul_f32_e32 v6, v8, v6
	v_mul_f32_e32 v5, v5, v6
	v_add_f32_e32 v6, v7, v58
	v_and_b32_e32 v7, 0xffff0000, v9
	v_mul_f32_e32 v8, 0x3d372713, v7
	v_mul_f32_e32 v8, v8, v7
	v_fma_f32 v8, v8, v7, v7
	v_mul_f32_e32 v8, 0xbfcc422a, v8
	v_mul_f32_e32 v8, 0x3fb8aa3b, v8
	v_exp_f32_e32 v8, v8
	s_nop 0
	v_add_f32_e32 v8, 1.0, v8
	v_rcp_f32_e32 v8, v8
	s_nop 0
	v_mul_f32_e32 v7, v8, v7
	v_mul_f32_e32 v6, v6, v7
	v_cvt_pk_bf16_f32 v5, v5, v6
	global_store_dwordx2 v[30:31], v[4:5], off offset:192
	v_mov_b64_e32 v[4:5], v[222:223]
	s_waitcnt lgkmcnt(0)
	v_lshlrev_b32_e32 v6, 16, v4
	v_mul_f32_e32 v7, 0x3d372713, v6
	v_mul_f32_e32 v7, v7, v6
	v_fma_f32 v7, v7, v6, v6
	v_mul_f32_e32 v7, 0xbfcc422a, v7
	v_mul_f32_e32 v7, 0x3fb8aa3b, v7
	v_exp_f32_e32 v7, v7
	v_and_b32_e32 v4, 0xffff0000, v4
	v_add_f32_e32 v7, 1.0, v7
	v_rcp_f32_e32 v7, v7
	s_nop 0
	v_mul_f32_e32 v6, v7, v6
	v_mul_f32_e32 v0, v0, v6
	v_mul_f32_e32 v6, 0x3d372713, v4
	v_mul_f32_e32 v6, v6, v4
	v_fma_f32 v6, v6, v4, v4
	v_mul_f32_e32 v6, 0xbfcc422a, v6
	v_mul_f32_e32 v6, 0x3fb8aa3b, v6
	v_exp_f32_e32 v6, v6
	s_nop 0
	v_add_f32_e32 v6, 1.0, v6
	v_rcp_f32_e32 v6, v6
	s_nop 0
	v_mul_f32_e32 v4, v6, v4
	v_mul_f32_e32 v1, v1, v4
	v_cvt_pk_bf16_f32 v0, v0, v1
	v_add_f32_e32 v1, v2, v58
	v_lshlrev_b32_e32 v2, 16, v5
	v_mul_f32_e32 v4, 0x3d372713, v2
	v_mul_f32_e32 v4, v4, v2
	v_fma_f32 v4, v4, v2, v2
	v_mul_f32_e32 v4, 0xbfcc422a, v4
	v_mul_f32_e32 v4, 0x3fb8aa3b, v4
	v_exp_f32_e32 v4, v4
	s_nop 0
	v_add_f32_e32 v4, 1.0, v4
	v_rcp_f32_e32 v4, v4
	s_nop 0
	v_mul_f32_e32 v2, v4, v2
	v_mul_f32_e32 v1, v1, v2
	v_add_f32_e32 v2, v3, v58
	v_and_b32_e32 v3, 0xffff0000, v5
	v_mul_f32_e32 v4, 0x3d372713, v3
	v_mul_f32_e32 v4, v4, v3
	v_fma_f32 v4, v4, v3, v3
	v_mul_f32_e32 v4, 0xbfcc422a, v4
	v_mul_f32_e32 v4, 0x3fb8aa3b, v4
	v_exp_f32_e32 v4, v4
	s_nop 0
	v_add_f32_e32 v4, 1.0, v4
	v_rcp_f32_e32 v4, v4
	s_nop 0
	v_mul_f32_e32 v3, v4, v3
	v_mul_f32_e32 v2, v2, v3
	v_cvt_pk_bf16_f32 v1, v1, v2
	global_store_dwordx2 v[30:31], v[0:1], off offset:224
	s_waitcnt lgkmcnt(0)
	s_barrier
	s_cbranch_scc0 .LBB0_680

.LBB0_682:
	v_mov_b32_e32 v72, v228
	v_readlane_b32 s4, v255, 23
	v_ashrrev_i32_e32 v68, 6, v72
	v_and_b32_e32 v71, 15, v72
	v_lshl_or_b32 v58, v68, 7, v71
	v_ashrrev_i32_e32 v59, 31, v58
	v_lshlrev_b64 v[0:1], 7, v[58:59]
	v_or_b32_e32 v8, 16, v58
	v_or_b32_e32 v18, 32, v58
	v_or_b32_e32 v26, 48, v58
	v_or_b32_e32 v34, 64, v58
	v_or_b32_e32 v42, 0x50, v58
	v_or_b32_e32 v50, 0x60, v58
	v_or_b32_e32 v58, 0x70, v58
	v_and_b32_e32 v16, 48, v72
	v_readlane_b32 s5, v255, 24
	v_ashrrev_i32_e32 v9, 31, v8
	v_ashrrev_i32_e32 v19, 31, v18
	v_ashrrev_i32_e32 v27, 31, v26
	v_ashrrev_i32_e32 v35, 31, v34
	v_ashrrev_i32_e32 v43, 31, v42
	v_ashrrev_i32_e32 v51, 31, v50
	v_ashrrev_i32_e32 v59, 31, v58
	v_lshl_add_u64 v[60:61], s[4:5], 0, v[16:17]
	v_lshlrev_b64 v[8:9], 7, v[8:9]
	v_lshlrev_b64 v[18:19], 7, v[18:19]
	v_lshlrev_b64 v[26:27], 7, v[26:27]
	v_lshlrev_b64 v[34:35], 7, v[34:35]
	v_lshlrev_b64 v[42:43], 7, v[42:43]
	v_lshlrev_b64 v[50:51], 7, v[50:51]
	v_lshlrev_b64 v[58:59], 7, v[58:59]
	v_lshl_add_u64 v[4:5], v[60:61], 0, v[0:1]
	v_lshl_add_u64 v[12:13], v[60:61], 0, v[8:9]
	v_lshl_add_u64 v[22:23], v[60:61], 0, v[18:19]
	v_lshl_add_u64 v[30:31], v[60:61], 0, v[26:27]
	v_lshl_add_u64 v[38:39], v[60:61], 0, v[34:35]
	v_lshl_add_u64 v[46:47], v[60:61], 0, v[42:43]
	v_lshl_add_u64 v[54:55], v[60:61], 0, v[50:51]
	v_lshl_add_u64 v[62:63], v[60:61], 0, v[58:59]
	global_load_dwordx4 v[0:3], v[4:5], off
	s_nop 0
	global_load_dwordx4 v[4:7], v[4:5], off offset:64
	s_nop 0
	global_load_dwordx4 v[8:11], v[12:13], off
	s_nop 0
	global_load_dwordx4 v[12:15], v[12:13], off offset:64
	s_nop 0
	global_load_dwordx4 v[18:21], v[22:23], off
	s_nop 0
	global_load_dwordx4 v[22:25], v[22:23], off offset:64
	s_nop 0
	global_load_dwordx4 v[26:29], v[30:31], off
	s_nop 0
	global_load_dwordx4 v[30:33], v[30:31], off offset:64
	s_nop 0
	global_load_dwordx4 v[34:37], v[38:39], off
	s_nop 0
	global_load_dwordx4 v[38:41], v[38:39], off offset:64
	s_nop 0
	global_load_dwordx4 v[42:45], v[46:47], off
	s_nop 0
	global_load_dwordx4 v[46:49], v[46:47], off offset:64
	s_nop 0
	global_load_dwordx4 v[50:53], v[54:55], off
	s_nop 0
	global_load_dwordx4 v[54:57], v[54:55], off offset:64
	s_nop 0
	global_load_dwordx4 v[58:61], v[62:63], off
	s_nop 0
	global_load_dwordx4 v[62:65], v[62:63], off offset:64
	s_mov_b32 s8, 0
	s_ashr_i32 s9, s8, 31
	s_lshl_b32 s4, s28, 6
	s_lshl_b64 s[8:9], s[8:9], 3
	s_add_u32 s8, s0, s8
	s_addc_u32 s9, s1, s9
	s_load_dwordx2 s[8:9], s[8:9], 0x58
	v_readlane_b32 s14, v255, 35
	v_readlane_b32 s15, v255, 36
	v_ashrrev_i32_e32 v73, 31, v72
	s_mul_i32 s2, s28, 0x118000
	s_waitcnt lgkmcnt(0)
	s_add_u32 s8, s8, s14
	s_addc_u32 s9, s9, s15
	v_lshl_add_u64 v[66:67], v[72:73], 2, s[8:9]
	v_add_co_u32_e32 v74, vcc, s68, v66
	v_readlane_b32 s14, v255, 30
	s_nop 0
	v_addc_co_u32_e32 v75, vcc, 0, v67, vcc
	global_load_dword v16, v[66:67], off
	global_load_dword v79, v[66:67], off offset:2048
	global_load_dword v80, v[74:75], off
	global_load_dword v81, v[74:75], off offset:2048
	s_mov_b32 s8, 0
	s_ashr_i32 s9, s8, 31
	s_lshl_b64 s[8:9], s[8:9], 3
	s_add_u32 s8, s0, s8
	s_addc_u32 s9, s1, s9
	s_load_dwordx2 s[8:9], s[8:9], 0x60
	v_add_u32_e32 v66, s14, v72
	v_ashrrev_i32_e32 v67, 31, v66
	v_lshlrev_b64 v[66:67], 2, v[66:67]
	s_mul_hi_i32 s5, s4, 0x4600
	s_waitcnt lgkmcnt(0)
	v_lshl_add_u64 v[74:75], s[8:9], 0, v[66:67]
	global_load_dword v82, v[74:75], off
	s_mov_b32 s8, 0
	s_ashr_i32 s9, s8, 31
	s_lshl_b64 s[8:9], s[8:9], 3
	s_add_u32 s8, s0, s8
	s_addc_u32 s9, s1, s9
	s_load_dwordx2 s[8:9], s[8:9], 0x70
	v_readlane_b32 s15, v255, 31
	s_waitcnt lgkmcnt(0)
	v_lshl_add_u64 v[74:75], s[8:9], 0, v[66:67]
	global_load_dword v83, v[74:75], off
	s_mov_b32 s8, 0
	s_ashr_i32 s9, s8, 31
	s_lshl_b64 s[8:9], s[8:9], 3
	s_add_u32 s8, s0, s8
	s_addc_u32 s9, s1, s9
	s_load_dwordx2 s[8:9], s[8:9], 0x80
	s_waitcnt lgkmcnt(0)
	v_lshl_add_u64 v[74:75], s[8:9], 0, v[66:67]
	global_load_dword v84, v[74:75], off
	s_mov_b32 s8, 0
	s_ashr_i32 s9, s8, 31
	s_lshl_b64 s[8:9], s[8:9], 3
	s_add_u32 s8, s0, s8
	s_addc_u32 s9, s1, s9
	s_load_dwordx2 s[8:9], s[8:9], 0x88
	s_waitcnt lgkmcnt(0)
	v_lshl_add_u64 v[66:67], s[8:9], 0, v[66:67]
	global_load_dword v69, v[66:67], off
	s_add_u32 s8, s94, s2
	s_addc_u32 s9, s95, s5
	v_lshl_add_u64 v[66:67], v[72:73], 1, s[8:9]
	s_add_u32 s100, s8, 0x800
	s_addc_u32 s101, s9, 0
	v_lshlrev_b32_e32 v138, 1, v228
	v_add_u32_e32 v139, 0x4600, v138
	v_add_u32_e32 v140, 0x8c00, v138
	v_add_u32_e32 v141, 0xd200, v138
	v_add_u32_e32 v142, 0x11800, v138
	v_add_u32_e32 v143, 0x15e00, v138
	v_add_u32_e32 v144, 0x1a400, v138
	v_add_u32_e32 v145, 0x1ea00, v138
	v_add_u32_e32 v146, 0x23000, v138
	v_add_u32_e32 v147, 0x27600, v138
	v_add_u32_e32 v148, 0x2bc00, v138
	v_add_u32_e32 v149, 0x30200, v138
	v_add_u32_e32 v150, 0x34800, v138
	v_add_u32_e32 v151, 0x38e00, v138
	v_add_u32_e32 v152, 0x3d400, v138
	v_add_u32_e32 v153, 0x41a00, v138
	global_load_ushort v154, v138, s[100:101]
	global_load_ushort v155, v139, s[100:101]
	global_load_ushort v156, v140, s[100:101]
	global_load_ushort v157, v141, s[100:101]
	global_load_ushort v158, v142, s[100:101]
	global_load_ushort v159, v143, s[100:101]
	global_load_ushort v160, v144, s[100:101]
	global_load_ushort v161, v145, s[100:101]
	global_load_ushort v162, v146, s[100:101]
	global_load_ushort v163, v147, s[100:101]
	global_load_ushort v164, v148, s[100:101]
	global_load_ushort v165, v149, s[100:101]
	global_load_ushort v166, v150, s[100:101]
	global_load_ushort v167, v151, s[100:101]
	global_load_ushort v168, v152, s[100:101]
	global_load_ushort v169, v153, s[100:101]
	global_load_ushort v170, v138, s[100:101] offset:1024
	global_load_ushort v171, v139, s[100:101] offset:1024
	global_load_ushort v172, v140, s[100:101] offset:1024
	global_load_ushort v173, v141, s[100:101] offset:1024
	global_load_ushort v174, v142, s[100:101] offset:1024
	global_load_ushort v175, v143, s[100:101] offset:1024
	global_load_ushort v176, v144, s[100:101] offset:1024
	global_load_ushort v177, v145, s[100:101] offset:1024
	global_load_ushort v178, v146, s[100:101] offset:1024
	global_load_ushort v179, v147, s[100:101] offset:1024
	global_load_ushort v180, v148, s[100:101] offset:1024
	global_load_ushort v181, v149, s[100:101] offset:1024
	global_load_ushort v182, v150, s[100:101] offset:1024
	global_load_ushort v183, v151, s[100:101] offset:1024
	global_load_ushort v184, v152, s[100:101] offset:1024
	global_load_ushort v185, v153, s[100:101] offset:1024
	v_add_u32_e32 v212, 0x0, v138
	v_add_u32_e32 v213, 0x1000, v138
	v_add_u32_e32 v214, 0x2000, v138
	v_add_u32_e32 v215, 0x3000, v138
	s_and_b32 s2, s4, 0x80000fc0
	s_mov_b64 s[8:9], 0x800
	s_cmp_lt_i32 s2, 1
	v_lshl_add_u64 v[66:67], v[66:67], 0, s[8:9]
	s_cbranch_scc1 .LBB0_684
	v_add_co_u32_e32 v74, vcc, 0xffff7400, v66
	s_nop 1
	v_addc_co_u32_e32 v75, vcc, -1, v67, vcc
	global_load_ushort v70, v[74:75], off
	v_add_co_u32_e32 v74, vcc, 0xffff2e00, v66
	s_waitcnt vmcnt(0) lgkmcnt(0)
	v_lshlrev_b32_e32 v91, 16, v70
	v_addc_co_u32_e32 v75, vcc, -1, v67, vcc
	global_load_ushort v74, v[74:75], off
	s_waitcnt vmcnt(0) lgkmcnt(0)
	v_lshlrev_b32_e32 v90, 16, v74
	v_add_co_u32_e32 v74, vcc, 0xffffba00, v66
	s_nop 1
	v_addc_co_u32_e32 v75, vcc, -1, v67, vcc
	global_load_ushort v70, v[74:75], off
	s_waitcnt vmcnt(0) lgkmcnt(0)
	v_lshlrev_b32_e32 v92, 16, v70
	s_branch .LBB0_685

.LBB0_685:
	s_movk_i32 s2, 0x2940
	v_mul_lo_u32 v68, v68, s2
	s_mov_b32 s2, 0xbfb8aa3b
	v_add_u32_e32 v74, 0, v68
	s_waitcnt vmcnt(0)
	v_mul_f32_e64 v68, |v69|, s2
	v_exp_f32_e32 v75, v68
	v_max_f32_e64 v68, -v69, -v69
	v_max_f32_e32 v77, 0, v68
	s_mov_b32 s2, 0x3f2aaaab
	v_add_f32_e32 v70, 1.0, v75
	v_add_f32_e32 v68, -1.0, v70
	v_sub_f32_e32 v69, v68, v70
	v_add_f32_e32 v69, 1.0, v69
	v_sub_f32_e32 v68, v75, v68
	v_add_f32_e32 v85, v68, v69
	v_frexp_mant_f32_e32 v86, v70
	v_cvt_f64_f32_e32 v[68:69], v70
	v_frexp_exp_i32_f64_e32 v68, v[68:69]
	v_cmp_gt_f32_e32 vcc, s2, v86
	s_ashr_i32 s5, s4, 31
	s_lshl_b64 s[4:5], s[4:5], 10
	v_subbrev_co_u32_e32 v86, vcc, 0, v68, vcc
	v_sub_u32_e32 v68, 0, v86
	v_ldexp_f32 v69, v70, v68
	v_add_f32_e32 v70, -1.0, v69
	v_add_f32_e32 v88, 1.0, v69
	v_ldexp_f32 v68, v85, v68
	v_add_f32_e32 v85, 1.0, v70
	v_add_f32_e32 v89, -1.0, v88
	v_sub_f32_e32 v85, v69, v85
	v_sub_f32_e32 v69, v69, v89
	v_add_f32_e32 v85, v68, v85
	v_add_f32_e32 v68, v68, v69
	v_add_f32_e32 v89, v88, v68
	v_rcp_f32_e32 v93, v89
	v_add_f32_e32 v87, v70, v85
	v_sub_f32_e32 v70, v87, v70
	v_sub_f32_e32 v69, v85, v70
	v_sub_f32_e32 v70, v89, v88
	v_mul_f32_e32 v88, v87, v93
	v_sub_f32_e32 v85, v68, v70
	v_mul_f32_e32 v68, v89, v88
	v_fma_f32 v70, v88, v89, -v68
	v_fmac_f32_e32 v70, v88, v85
	v_add_f32_e32 v94, v68, v70
	s_add_u32 s4, s13, s4
	v_sub_f32_e32 v95, v87, v94
	s_addc_u32 s5, s37, s5
	s_ashr_i32 s29, s28, 31
	v_sub_f32_e32 v87, v87, v95
	s_lshl_b64 s[8:9], s[28:29], 11
	v_sub_f32_e32 v68, v94, v68
	v_sub_f32_e32 v87, v87, v94
	s_add_u32 s8, s79, s8
	v_add_f32_e32 v69, v69, v87
	v_sub_f32_e32 v68, v68, v70
	s_addc_u32 s9, s48, s9
	v_add_f32_e32 v87, v68, v69
	v_lshl_add_u64 v[68:69], v[72:73], 2, s[8:9]
	global_load_dword v70, v[68:69], off
	v_add_f32_e32 v94, v95, v87
	v_mul_f32_e32 v96, v93, v94
	v_mul_f32_e32 v97, v89, v96
	v_fma_f32 v68, v96, v89, -v97
	v_fmac_f32_e32 v68, v96, v85
	v_add_f32_e32 v85, v97, v68
	v_sub_f32_e32 v89, v94, v85
	v_sub_f32_e32 v69, v95, v94
	v_sub_f32_e32 v94, v94, v89
	v_add_f32_e32 v69, v87, v69
	v_sub_f32_e32 v87, v85, v97
	v_sub_f32_e32 v85, v94, v85
	v_add_f32_e32 v69, v69, v85
	v_sub_f32_e32 v68, v87, v68
	v_cvt_f32_i32_e32 v86, v86
	v_add_f32_e32 v68, v68, v69
	v_add_f32_e32 v69, v88, v96
	v_add_f32_e32 v68, v89, v68
	v_sub_f32_e32 v85, v69, v88
	v_mul_f32_e32 v68, v93, v68
	v_sub_f32_e32 v85, v96, v85
	v_add_f32_e32 v68, v85, v68
	v_mul_f32_e32 v89, 0x3f317218, v86
	s_mov_b32 s2, 0x3f317218
	v_add_f32_e32 v85, v69, v68
	v_fma_f32 v93, v86, s2, -v89
	v_mul_f32_e32 v87, v85, v85
	v_fmac_f32_e32 v93, 0xb102e308, v86
	v_sub_f32_e32 v69, v85, v69
	v_fmamk_f32 v88, v87, 0x3e9b6dac, v232
	v_sub_f32_e32 v68, v68, v69
	v_add_f32_e32 v69, v89, v93
	v_fmaak_f32 v88, v87, v88, 0x3f2aaada
	v_sub_f32_e32 v86, v69, v89
	v_ldexp_f32 v89, v85, 1
	v_mul_f32_e32 v85, v85, v87
	v_mul_f32_e32 v85, v85, v88
	v_add_f32_e32 v87, v89, v85
	v_sub_f32_e32 v88, v87, v89
	v_ldexp_f32 v68, v68, 1
	v_sub_f32_e32 v85, v85, v88
	v_add_f32_e32 v68, v68, v85
	v_add_f32_e32 v85, v87, v68
	v_sub_f32_e32 v87, v85, v87
	v_sub_f32_e32 v68, v68, v87
	v_add_f32_e32 v87, v69, v85
	v_sub_f32_e32 v88, v87, v69
	v_sub_f32_e32 v89, v87, v88
	v_sub_f32_e32 v86, v93, v86
	v_sub_f32_e32 v69, v69, v89
	v_sub_f32_e32 v85, v85, v88
	v_add_f32_e32 v69, v85, v69
	v_add_f32_e32 v85, v86, v68
	v_sub_f32_e32 v88, v85, v86
	v_sub_f32_e32 v89, v85, v88
	v_add_f32_e32 v69, v85, v69
	v_sub_f32_e32 v86, v86, v89
	v_sub_f32_e32 v68, v68, v88
	v_add_f32_e32 v85, v87, v69
	v_add_f32_e32 v68, v68, v86
	v_sub_f32_e32 v86, v85, v87
	v_sub_f32_e32 v69, v69, v86
	v_add_f32_e32 v68, v68, v69
	s_mov_b32 s2, 0x7f800000
	v_add_f32_e32 v68, v85, v68
	v_cmp_neq_f32_e32 vcc, s2, v75
	s_mov_b32 s2, 0x33800000
	v_and_b32_e32 v76, 63, v72
	v_cndmask_b32_e32 v68, v236, v68, vcc
	v_cmp_ngt_f32_e32 vcc, -1.0, v75
	v_lshl_add_u32 v85, v76, 1, v74
	v_lshl_add_u32 v87, v76, 2, v74
	v_cndmask_b32_e32 v68, v237, v68, vcc
	v_cmp_neq_f32_e32 vcc, -1.0, v75
	s_nop 1
	v_cndmask_b32_e32 v68, v238, v68, vcc
	v_cmp_lt_f32_e64 vcc, |v75|, s2
	s_movk_i32 s2, 0x90
	s_nop 0
	v_cndmask_b32_e32 v68, v68, v75, vcc
	v_add_f32_e32 v75, v77, v68
	v_lshl_add_u64 v[68:69], v[72:73], 1, s[4:5]
	v_mad_u32_u24 v73, v71, s2, v74
	s_movk_i32 s2, 0x204
	v_and_b32_e32 v72, 48, v72
	v_mad_u32_u24 v71, v71, s2, v74
	v_mul_f32_e32 v86, 0xc1000000, v75
	s_mov_b64 s[98:99], s[4:5]
	s_mov_b64 s[4:5], 0
	v_add_u32_e32 v88, v73, v72
	v_add_u32_e32 v89, v71, v72
	s_branch .Llru2_loop

.LBB0_752:
	v_add_co_u32_e32 v6, vcc, 0x4000, v2
	global_load_ushort v5, v[2:3], off
	s_nop 0
	v_addc_co_u32_e32 v7, vcc, 0, v3, vcc
	v_add_co_u32_e32 v10, vcc, 0x8000, v2
	global_load_ushort v6, v[6:7], off offset:1536
	s_nop 0
	v_addc_co_u32_e32 v11, vcc, 0, v3, vcc
	global_load_ushort v7, v[10:11], off offset:3072
	v_add_co_u32_e32 v10, vcc, 0xd000, v2
	s_mov_b32 s8, 0x8c000
	s_nop 0
	v_addc_co_u32_e32 v11, vcc, 0, v3, vcc
	global_load_ushort v9, v[10:11], off offset:512
	v_add_co_u32_e32 v10, vcc, 0x11000, v2
	s_waitcnt vmcnt(0) lgkmcnt(0)
	v_lshlrev_b32_e32 v5, 16, v5
	v_addc_co_u32_e32 v11, vcc, 0, v3, vcc
	v_add_co_u32_e32 v12, vcc, 0x15000, v2
	global_load_ushort v10, v[10:11], off offset:2048
	s_nop 0
	v_addc_co_u32_e32 v13, vcc, 0, v3, vcc
	global_load_ushort v11, v[12:13], off offset:3584
	v_add_co_u32_e32 v12, vcc, s63, v2
	v_lshlrev_b32_e32 v6, 16, v6
	s_nop 0
	v_addc_co_u32_e32 v13, vcc, 0, v3, vcc
	v_add_co_u32_e32 v14, vcc, s64, v2
	global_load_ushort v12, v[12:13], off offset:1024
	s_nop 0
	v_addc_co_u32_e32 v15, vcc, 0, v3, vcc
	global_load_ushort v13, v[14:15], off offset:2560
	v_add_co_u32_e32 v14, vcc, 0x23000, v2
	v_lshlrev_b32_e32 v7, 16, v7
	s_nop 0
	v_addc_co_u32_e32 v15, vcc, 0, v3, vcc
	v_add_co_u32_e32 v18, vcc, 0x27000, v2
	global_load_ushort v14, v[14:15], off
	s_nop 0
	v_addc_co_u32_e32 v19, vcc, 0, v3, vcc
	global_load_ushort v15, v[18:19], off offset:1536
	v_add_co_u32_e32 v18, vcc, 0x2b000, v2
	v_lshlrev_b32_e32 v9, 16, v9
	s_nop 0
	v_addc_co_u32_e32 v19, vcc, 0, v3, vcc
	global_load_ushort v16, v[18:19], off offset:3072
	v_add_co_u32_e32 v18, vcc, 0x30000, v2
	s_waitcnt vmcnt(0) lgkmcnt(0)
	v_lshlrev_b32_e32 v10, 16, v10
	v_addc_co_u32_e32 v19, vcc, 0, v3, vcc
	v_add_co_u32_e32 v20, vcc, 0x34000, v2
	global_load_ushort v18, v[18:19], off offset:512
	s_nop 0
	v_addc_co_u32_e32 v21, vcc, 0, v3, vcc
	global_load_ushort v19, v[20:21], off offset:2048
	v_add_co_u32_e32 v20, vcc, 0x38000, v2
	v_lshlrev_b32_e32 v11, 16, v11
	s_nop 0
	v_addc_co_u32_e32 v21, vcc, 0, v3, vcc
	v_add_co_u32_e32 v22, vcc, 0x3d000, v2
	global_load_ushort v20, v[20:21], off offset:3584
	s_nop 0
	v_addc_co_u32_e32 v23, vcc, 0, v3, vcc
	global_load_ushort v21, v[22:23], off offset:1024
	v_add_co_u32_e32 v22, vcc, 0x41000, v2
	v_lshlrev_b32_e32 v12, 16, v12
	s_nop 0
	v_addc_co_u32_e32 v23, vcc, 0, v3, vcc
	v_add_co_u32_e32 v24, vcc, 0x46000, v2
	global_load_ushort v22, v[22:23], off offset:2560
	s_nop 0
	v_addc_co_u32_e32 v25, vcc, 0, v3, vcc
	global_load_ushort v23, v[24:25], off
	v_add_co_u32_e32 v24, vcc, 0x4a000, v2
	v_lshlrev_b32_e32 v13, 16, v13
	s_nop 0
	v_addc_co_u32_e32 v25, vcc, 0, v3, vcc
	v_add_co_u32_e32 v26, vcc, 0x4e000, v2
	global_load_ushort v24, v[24:25], off offset:1536
	s_nop 0
	v_addc_co_u32_e32 v27, vcc, 0, v3, vcc
	global_load_ushort v25, v[26:27], off offset:3072
	v_add_co_u32_e32 v26, vcc, 0x53000, v2
	v_lshlrev_b32_e32 v14, 16, v14
	s_nop 0
	v_addc_co_u32_e32 v27, vcc, 0, v3, vcc
	v_add_co_u32_e32 v28, vcc, 0x57000, v2
	global_load_ushort v26, v[26:27], off offset:512
	s_nop 0
	v_addc_co_u32_e32 v29, vcc, 0, v3, vcc
	global_load_ushort v27, v[28:29], off offset:2048
	v_add_co_u32_e32 v28, vcc, 0x5b000, v2
	v_lshlrev_b32_e32 v15, 16, v15
	s_nop 0
	v_addc_co_u32_e32 v29, vcc, 0, v3, vcc
	v_add_co_u32_e32 v30, vcc, 0x60000, v2
	global_load_ushort v28, v[28:29], off offset:3584
	s_nop 0
	v_addc_co_u32_e32 v31, vcc, 0, v3, vcc
	global_load_ushort v29, v[30:31], off offset:1024
	v_add_co_u32_e32 v30, vcc, 0x64000, v2
	v_lshlrev_b32_e32 v16, 16, v16
	s_nop 0
	v_addc_co_u32_e32 v31, vcc, 0, v3, vcc
	v_add_co_u32_e32 v32, vcc, 0x69000, v2
	global_load_ushort v30, v[30:31], off offset:2560
	s_nop 0
	v_addc_co_u32_e32 v33, vcc, 0, v3, vcc
	global_load_ushort v31, v[32:33], off
	v_add_co_u32_e32 v32, vcc, 0x6d000, v2
	s_waitcnt vmcnt(0) lgkmcnt(0)
	v_lshlrev_b32_e32 v18, 16, v18
	v_addc_co_u32_e32 v33, vcc, 0, v3, vcc
	v_add_co_u32_e32 v34, vcc, 0x71000, v2
	global_load_ushort v32, v[32:33], off offset:1536
	s_nop 0
	v_addc_co_u32_e32 v35, vcc, 0, v3, vcc
	global_load_ushort v33, v[34:35], off offset:3072
	v_add_co_u32_e32 v34, vcc, 0x76000, v2
	v_lshlrev_b32_e32 v19, 16, v19
	s_nop 0
	v_addc_co_u32_e32 v35, vcc, 0, v3, vcc
	v_add_co_u32_e32 v36, vcc, 0x7a000, v2
	global_load_ushort v34, v[34:35], off offset:512
	s_nop 0
	v_addc_co_u32_e32 v37, vcc, 0, v3, vcc
	global_load_ushort v35, v[36:37], off offset:2048
	v_add_co_u32_e32 v36, vcc, 0x7e000, v2
	v_lshlrev_b32_e32 v20, 16, v20
	s_nop 0
	v_addc_co_u32_e32 v37, vcc, 0, v3, vcc
	v_add_co_u32_e32 v38, vcc, 0x83000, v2
	global_load_ushort v36, v[36:37], off offset:3584
	s_nop 0
	v_addc_co_u32_e32 v39, vcc, 0, v3, vcc
	global_load_ushort v37, v[38:39], off offset:1024
	v_add_co_u32_e32 v38, vcc, 0x87000, v2
	v_lshlrev_b32_e32 v21, 16, v21
	s_nop 0
	v_addc_co_u32_e32 v39, vcc, 0, v3, vcc
	v_add_co_u32_e32 v40, vcc, s8, v2
	global_load_ushort v38, v[38:39], off offset:2560
	s_nop 0
	v_addc_co_u32_e32 v41, vcc, 0, v3, vcc
	global_load_ushort v39, v[40:41], off
	v_add_co_u32_e32 v40, vcc, 0x90000, v2
	s_mov_b32 s8, 0xf5000
	s_nop 0
	v_addc_co_u32_e32 v41, vcc, 0, v3, vcc
	v_add_co_u32_e32 v42, vcc, 0x94000, v2
	global_load_ushort v40, v[40:41], off offset:1536
	s_nop 0
	v_addc_co_u32_e32 v43, vcc, 0, v3, vcc
	global_load_ushort v41, v[42:43], off offset:3072
	v_add_co_u32_e32 v42, vcc, 0x99000, v2
	v_lshlrev_b32_e32 v22, 16, v22
	s_nop 0
	v_addc_co_u32_e32 v43, vcc, 0, v3, vcc
	v_add_co_u32_e32 v44, vcc, 0x9d000, v2
	global_load_ushort v42, v[42:43], off offset:512
	s_nop 0
	v_addc_co_u32_e32 v45, vcc, 0, v3, vcc
	global_load_ushort v43, v[44:45], off offset:2048
	v_add_co_u32_e32 v44, vcc, 0xa1000, v2
	v_lshlrev_b32_e32 v23, 16, v23
	s_nop 0
	v_addc_co_u32_e32 v45, vcc, 0, v3, vcc
	v_add_co_u32_e32 v46, vcc, 0xa6000, v2
	global_load_ushort v44, v[44:45], off offset:3584
	s_nop 0
	v_addc_co_u32_e32 v47, vcc, 0, v3, vcc
	global_load_ushort v45, v[46:47], off offset:1024
	v_add_co_u32_e32 v46, vcc, 0xaa000, v2
	v_lshlrev_b32_e32 v24, 16, v24
	s_nop 0
	v_addc_co_u32_e32 v47, vcc, 0, v3, vcc
	v_add_co_u32_e32 v48, vcc, 0xaf000, v2
	global_load_ushort v46, v[46:47], off offset:2560
	s_nop 0
	v_addc_co_u32_e32 v49, vcc, 0, v3, vcc
	global_load_ushort v47, v[48:49], off
	v_add_co_u32_e32 v48, vcc, 0xb3000, v2
	v_lshlrev_b32_e32 v25, 16, v25
	s_nop 0
	v_addc_co_u32_e32 v49, vcc, 0, v3, vcc
	v_add_co_u32_e32 v50, vcc, 0xb7000, v2
	global_load_ushort v48, v[48:49], off offset:1536
	s_nop 0
	v_addc_co_u32_e32 v51, vcc, 0, v3, vcc
	global_load_ushort v49, v[50:51], off offset:3072
	v_add_co_u32_e32 v50, vcc, 0xbc000, v2
	v_lshlrev_b32_e32 v26, 16, v26
	s_nop 0
	v_addc_co_u32_e32 v51, vcc, 0, v3, vcc
	v_add_co_u32_e32 v52, vcc, 0xc0000, v2
	global_load_ushort v50, v[50:51], off offset:512
	s_nop 0
	v_addc_co_u32_e32 v53, vcc, 0, v3, vcc
	global_load_ushort v51, v[52:53], off offset:2048
	v_add_co_u32_e32 v52, vcc, 0xc4000, v2
	v_lshlrev_b32_e32 v27, 16, v27
	s_nop 0
	v_addc_co_u32_e32 v53, vcc, 0, v3, vcc
	v_add_co_u32_e32 v54, vcc, 0xc9000, v2
	global_load_ushort v52, v[52:53], off offset:3584
	s_nop 0
	v_addc_co_u32_e32 v55, vcc, 0, v3, vcc
	global_load_ushort v53, v[54:55], off offset:1024
	v_add_co_u32_e32 v54, vcc, 0xcd000, v2
	v_lshlrev_b32_e32 v28, 16, v28
	s_nop 0
	v_addc_co_u32_e32 v55, vcc, 0, v3, vcc
	v_add_co_u32_e32 v56, vcc, 0xd2000, v2
	global_load_ushort v54, v[54:55], off offset:2560
	s_nop 0
	v_addc_co_u32_e32 v57, vcc, 0, v3, vcc
	global_load_ushort v55, v[56:57], off
	v_add_co_u32_e32 v56, vcc, 0xd6000, v2
	v_lshlrev_b32_e32 v29, 16, v29
	s_nop 0
	v_addc_co_u32_e32 v57, vcc, 0, v3, vcc
	v_add_co_u32_e32 v58, vcc, 0xda000, v2
	global_load_ushort v56, v[56:57], off offset:1536
	s_nop 0
	v_addc_co_u32_e32 v59, vcc, 0, v3, vcc
	global_load_ushort v57, v[58:59], off offset:3072
	v_add_co_u32_e32 v58, vcc, 0xdf000, v2
	v_lshlrev_b32_e32 v30, 16, v30
	s_nop 0
	v_addc_co_u32_e32 v59, vcc, 0, v3, vcc
	v_add_co_u32_e32 v60, vcc, 0xe3000, v2
	global_load_ushort v58, v[58:59], off offset:512
	s_nop 0
	v_addc_co_u32_e32 v61, vcc, 0, v3, vcc
	global_load_ushort v59, v[60:61], off offset:2048
	v_add_co_u32_e32 v60, vcc, 0xe7000, v2
	v_lshlrev_b32_e32 v31, 16, v31
	s_nop 0
	v_addc_co_u32_e32 v61, vcc, 0, v3, vcc
	v_add_co_u32_e32 v62, vcc, 0xec000, v2
	global_load_ushort v60, v[60:61], off offset:3584
	s_nop 0
	v_addc_co_u32_e32 v63, vcc, 0, v3, vcc
	global_load_ushort v61, v[62:63], off offset:1024
	v_add_co_u32_e32 v62, vcc, 0xf0000, v2
	s_waitcnt vmcnt(0) lgkmcnt(0)
	v_lshlrev_b32_e32 v32, 16, v32
	v_addc_co_u32_e32 v63, vcc, 0, v3, vcc
	v_add_co_u32_e32 v64, vcc, s8, v2
	global_load_ushort v62, v[62:63], off offset:2560
	s_nop 0
	v_addc_co_u32_e32 v65, vcc, 0, v3, vcc
	global_load_ushort v66, v[64:65], off
	s_mov_b32 s8, 0x106000
	v_add_co_u32_e32 v64, vcc, s8, v2
	s_mov_b32 s8, 0xf9000
	s_nop 0
	v_addc_co_u32_e32 v65, vcc, 0, v3, vcc
	global_load_ushort v63, v[64:65], off offset:2048
	v_lshlrev_b32_e32 v33, 16, v33
	v_lshlrev_b32_e32 v34, 16, v34
	v_lshlrev_b32_e32 v35, 16, v35
	v_lshlrev_b32_e32 v36, 16, v36
	v_lshlrev_b32_e32 v37, 16, v37
	v_lshlrev_b32_e32 v38, 16, v38
	v_lshlrev_b32_e32 v39, 16, v39
	v_lshlrev_b32_e32 v40, 16, v40
	v_lshlrev_b32_e32 v41, 16, v41
	v_lshlrev_b32_e32 v42, 16, v42
	v_lshlrev_b32_e32 v43, 16, v43
	v_lshlrev_b32_e32 v44, 16, v44
	v_lshlrev_b32_e32 v45, 16, v45
	v_lshlrev_b32_e32 v46, 16, v46
	v_lshlrev_b32_e32 v47, 16, v47
	v_lshlrev_b32_e32 v48, 16, v48
	v_lshlrev_b32_e32 v49, 16, v49
	v_lshlrev_b32_e32 v50, 16, v50
	v_lshlrev_b32_e32 v51, 16, v51
	v_lshlrev_b32_e32 v52, 16, v52
	v_lshlrev_b32_e32 v53, 16, v53
	v_lshlrev_b32_e32 v54, 16, v54
	v_lshlrev_b32_e32 v55, 16, v55
	v_lshlrev_b32_e32 v56, 16, v56
	v_lshlrev_b32_e32 v57, 16, v57
	v_lshlrev_b32_e32 v58, 16, v58
	v_lshlrev_b32_e32 v59, 16, v59
	v_lshlrev_b32_e32 v60, 16, v60
	v_lshlrev_b32_e32 v61, 16, v61
	s_waitcnt vmcnt(0) lgkmcnt(0)
	v_lshlrev_b32_e32 v62, 16, v62
	v_lshlrev_b32_e32 v64, 16, v66
	v_add_co_u32_e32 v66, vcc, s8, v2
	s_mov_b32 s8, 0x10a000
	s_nop 0
	v_addc_co_u32_e32 v67, vcc, 0, v3, vcc
	global_load_ushort v68, v[66:67], off offset:1536
	v_add_co_u32_e32 v66, vcc, s8, v2
	s_mov_b32 s8, 0xfd000
	s_nop 0
	v_addc_co_u32_e32 v67, vcc, 0, v3, vcc
	global_load_ushort v65, v[66:67], off offset:3584
	v_lshlrev_b32_e32 v63, 16, v63
	s_waitcnt vmcnt(0) lgkmcnt(0)
	v_lshlrev_b32_e32 v66, 16, v68
	v_add_co_u32_e32 v68, vcc, s8, v2
	s_mov_b32 s8, 0x10f000
	s_nop 0
	v_addc_co_u32_e32 v69, vcc, 0, v3, vcc
	global_load_ushort v70, v[68:69], off offset:3072
	v_add_co_u32_e32 v68, vcc, s8, v2
	s_mov_b32 s8, 0x102000
	s_nop 0
	v_addc_co_u32_e32 v69, vcc, 0, v3, vcc
	global_load_ushort v67, v[68:69], off offset:1024
	v_lshlrev_b32_e32 v65, 16, v65
	s_waitcnt vmcnt(0) lgkmcnt(0)
	v_lshlrev_b32_e32 v68, 16, v70
	v_add_co_u32_e32 v70, vcc, s8, v2
	s_mov_b32 s8, 0x113000
	s_nop 0
	v_addc_co_u32_e32 v71, vcc, 0, v3, vcc
	global_load_ushort v69, v[70:71], off offset:512
	v_add_co_u32_e32 v2, vcc, s8, v2
	s_min_u32 s8, s19, 3
	s_nop 0
	v_addc_co_u32_e32 v3, vcc, 0, v3, vcc
	global_load_ushort v2, v[2:3], off offset:2560
	s_add_i32 s8, s8, 1
	v_cvt_f32_ubyte0_e32 v71, s8
	v_lshl_add_u32 v70, v0, 1, 0
	v_lshlrev_b32_e32 v67, 16, v67
	s_waitcnt vmcnt(0) lgkmcnt(0)
	v_lshlrev_b32_e32 v3, 16, v69
	v_add_f32_e32 v69, 0, v5
	v_add_f32_e32 v69, v4, v69
	v_add_f32_e32 v69, v1, v69
	v_add_f32_e32 v69, v8, v69
	v_div_scale_f32 v72, s[8:9], v71, v71, v69
	v_rcp_f32_e32 v73, v72
	s_min_u32 s8, s19, 2
	v_sub_f32_e32 v8, v6, v8
	s_add_i32 s8, s8, 2
	v_fma_f32 v74, -v72, v73, 1.0
	v_fmac_f32_e32 v73, v74, v73
	v_div_scale_f32 v74, vcc, v69, v71, v69
	v_mul_f32_e32 v75, v74, v73
	v_fma_f32 v76, -v72, v75, v74
	v_fmac_f32_e32 v75, v76, v73
	v_fma_f32 v72, -v72, v75, v74
	v_div_fmas_f32 v72, v72, v73, v75
	v_div_fixup_f32 v71, v72, v71, v69
	v_sub_f32_e32 v71, v71, v5
	v_cvt_pk_bf16_f32 v71, v71, v17
	v_add_f32_e32 v8, v8, v69
	v_cvt_f32_ubyte0_e32 v69, s8
	ds_write_b16 v70, v71
	v_div_scale_f32 v71, s[8:9], v69, v69, v8
	v_rcp_f32_e32 v72, v71
	v_sub_f32_e32 v1, v7, v1
	v_add_f32_e32 v1, v1, v8
	v_sub_f32_e32 v4, v9, v4
	v_fma_f32 v73, -v71, v72, 1.0
	v_fmac_f32_e32 v72, v73, v72
	v_div_scale_f32 v73, vcc, v8, v69, v8
	v_mul_f32_e32 v74, v73, v72
	v_fma_f32 v75, -v71, v74, v73
	v_fmac_f32_e32 v74, v75, v72
	v_fma_f32 v71, -v71, v74, v73
	v_div_fmas_f32 v71, v71, v72, v74
	v_div_fixup_f32 v69, v71, v69, v8
	v_sub_f32_e32 v69, v69, v6
	v_cvt_pk_bf16_f32 v69, v69, v17
	v_div_scale_f32 v8, s[8:9], s2, s2, v1
	ds_write_b16 v70, v69 offset:1040
	v_rcp_f32_e32 v69, v8
	v_lshlrev_b32_e32 v2, 16, v2
	v_fma_f32 v71, -v8, v69, 1.0
	v_fmac_f32_e32 v69, v71, v69
	v_div_scale_f32 v71, vcc, v1, s2, v1
	v_mul_f32_e32 v72, v71, v69
	v_fma_f32 v73, -v8, v72, v71
	v_fmac_f32_e32 v72, v73, v69
	v_fma_f32 v8, -v8, v72, v71
	v_div_fmas_f32 v8, v8, v69, v72
	v_div_fixup_f32 v8, v8, s2, v1
	v_add_f32_e32 v1, v4, v1
	s_mov_b32 s2, 0x3e800000
	v_fma_f32 v4, v1, s2, -v9
	v_cvt_pk_bf16_f32 v4, v4, v17
	ds_write_b16 v70, v4 offset:3120
	v_sub_f32_e32 v4, v10, v5
	v_add_f32_e32 v1, v4, v1
	v_fma_f32 v4, v1, s2, -v10
	v_cvt_pk_bf16_f32 v4, v4, v17
	ds_write_b16 v70, v4 offset:4160
	v_sub_f32_e32 v4, v11, v6
	v_add_f32_e32 v1, v4, v1
	v_fma_f32 v4, v1, s2, -v11
	v_cvt_pk_bf16_f32 v4, v4, v17
	ds_write_b16 v70, v4 offset:5200
	v_sub_f32_e32 v4, v12, v7
	v_add_f32_e32 v1, v4, v1
	v_fma_f32 v4, v1, s2, -v12
	v_cvt_pk_bf16_f32 v4, v4, v17
	ds_write_b16 v70, v4 offset:6240
	v_sub_f32_e32 v4, v13, v9
	v_add_f32_e32 v1, v4, v1
	v_fma_f32 v4, v1, s2, -v13
	v_cvt_pk_bf16_f32 v4, v4, v17
	ds_write_b16 v70, v4 offset:7280
	v_sub_f32_e32 v4, v14, v10
	v_add_f32_e32 v1, v4, v1
	v_fma_f32 v4, v1, s2, -v14
	v_cvt_pk_bf16_f32 v4, v4, v17
	ds_write_b16 v70, v4 offset:8320
	v_sub_f32_e32 v4, v15, v11
	v_add_f32_e32 v1, v4, v1
	v_fma_f32 v4, v1, s2, -v15
	v_cvt_pk_bf16_f32 v4, v4, v17
	ds_write_b16 v70, v4 offset:9360
	v_sub_f32_e32 v4, v16, v12
	v_add_f32_e32 v1, v4, v1
	v_fma_f32 v4, v1, s2, -v16
	v_cvt_pk_bf16_f32 v4, v4, v17
	ds_write_b16 v70, v4 offset:10400
	v_sub_f32_e32 v4, v18, v13
	v_add_f32_e32 v1, v4, v1
	v_fma_f32 v4, v1, s2, -v18
	v_cvt_pk_bf16_f32 v4, v4, v17
	ds_write_b16 v70, v4 offset:11440
	v_sub_f32_e32 v4, v19, v14
	v_add_f32_e32 v1, v4, v1
	v_fma_f32 v4, v1, s2, -v19
	v_cvt_pk_bf16_f32 v4, v4, v17
	ds_write_b16 v70, v4 offset:12480
	v_sub_f32_e32 v4, v20, v15
	v_add_f32_e32 v1, v4, v1
	v_fma_f32 v4, v1, s2, -v20
	v_cvt_pk_bf16_f32 v4, v4, v17
	ds_write_b16 v70, v4 offset:13520
	v_sub_f32_e32 v4, v21, v16
	v_add_f32_e32 v1, v4, v1
	v_fma_f32 v4, v1, s2, -v21
	v_cvt_pk_bf16_f32 v4, v4, v17
	ds_write_b16 v70, v4 offset:14560
	v_sub_f32_e32 v4, v22, v18
	v_add_f32_e32 v1, v4, v1
	v_fma_f32 v4, v1, s2, -v22
	v_cvt_pk_bf16_f32 v4, v4, v17
	ds_write_b16 v70, v4 offset:15600
	v_sub_f32_e32 v4, v23, v19
	v_add_f32_e32 v1, v4, v1
	v_fma_f32 v4, v1, s2, -v23
	v_cvt_pk_bf16_f32 v4, v4, v17
	ds_write_b16 v70, v4 offset:16640
	v_sub_f32_e32 v4, v24, v20
	v_add_f32_e32 v1, v4, v1
	v_fma_f32 v4, v1, s2, -v24
	v_cvt_pk_bf16_f32 v4, v4, v17
	ds_write_b16 v70, v4 offset:17680
	v_sub_f32_e32 v4, v25, v21
	v_add_f32_e32 v1, v4, v1
	v_fma_f32 v4, v1, s2, -v25
	v_cvt_pk_bf16_f32 v4, v4, v17
	ds_write_b16 v70, v4 offset:18720
	v_sub_f32_e32 v4, v26, v22
	v_add_f32_e32 v1, v4, v1
	v_fma_f32 v4, v1, s2, -v26
	v_cvt_pk_bf16_f32 v4, v4, v17
	ds_write_b16 v70, v4 offset:19760
	v_sub_f32_e32 v4, v27, v23
	v_add_f32_e32 v1, v4, v1
	v_fma_f32 v4, v1, s2, -v27
	v_cvt_pk_bf16_f32 v4, v4, v17
	ds_write_b16 v70, v4 offset:20800
	v_sub_f32_e32 v4, v28, v24
	v_add_f32_e32 v1, v4, v1
	v_fma_f32 v4, v1, s2, -v28
	v_cvt_pk_bf16_f32 v4, v4, v17
	ds_write_b16 v70, v4 offset:21840
	v_sub_f32_e32 v4, v29, v25
	v_add_f32_e32 v1, v4, v1
	v_fma_f32 v4, v1, s2, -v29
	v_cvt_pk_bf16_f32 v4, v4, v17
	ds_write_b16 v70, v4 offset:22880
	v_sub_f32_e32 v4, v30, v26
	v_add_f32_e32 v1, v4, v1
	v_fma_f32 v4, v1, s2, -v30
	v_cvt_pk_bf16_f32 v4, v4, v17
	ds_write_b16 v70, v4 offset:23920
	v_sub_f32_e32 v4, v31, v27
	v_add_f32_e32 v1, v4, v1
	v_fma_f32 v4, v1, s2, -v31
	v_cvt_pk_bf16_f32 v4, v4, v17
	ds_write_b16 v70, v4 offset:24960
	v_sub_f32_e32 v4, v32, v28
	v_add_f32_e32 v1, v4, v1
	v_fma_f32 v4, v1, s2, -v32
	v_cvt_pk_bf16_f32 v4, v4, v17
	ds_write_b16 v70, v4 offset:26000
	v_sub_f32_e32 v4, v33, v29
	v_add_f32_e32 v1, v4, v1
	v_fma_f32 v4, v1, s2, -v33
	v_cvt_pk_bf16_f32 v4, v4, v17
	ds_write_b16 v70, v4 offset:27040
	v_sub_f32_e32 v4, v34, v30
	v_add_f32_e32 v1, v4, v1
	v_fma_f32 v4, v1, s2, -v34
	v_cvt_pk_bf16_f32 v4, v4, v17
	ds_write_b16 v70, v4 offset:28080
	v_sub_f32_e32 v4, v35, v31
	v_add_f32_e32 v1, v4, v1
	v_fma_f32 v4, v1, s2, -v35
	v_cvt_pk_bf16_f32 v4, v4, v17
	ds_write_b16 v70, v4 offset:29120
	v_sub_f32_e32 v4, v36, v32
	v_add_f32_e32 v1, v4, v1
	v_fma_f32 v4, v1, s2, -v36
	v_cvt_pk_bf16_f32 v4, v4, v17
	ds_write_b16 v70, v4 offset:30160
	v_sub_f32_e32 v4, v37, v33
	v_add_f32_e32 v1, v4, v1
	v_fma_f32 v4, v1, s2, -v37
	v_cvt_pk_bf16_f32 v4, v4, v17
	ds_write_b16 v70, v4 offset:31200
	v_sub_f32_e32 v4, v38, v34
	v_add_f32_e32 v1, v4, v1
	v_fma_f32 v4, v1, s2, -v38
	v_cvt_pk_bf16_f32 v4, v4, v17
	ds_write_b16 v70, v4 offset:32240
	v_sub_f32_e32 v4, v39, v35
	v_add_f32_e32 v1, v4, v1
	v_fma_f32 v4, v1, s2, -v39
	v_cvt_pk_bf16_f32 v4, v4, v17
	ds_write_b16 v70, v4 offset:33280
	v_sub_f32_e32 v4, v40, v36
	v_add_f32_e32 v1, v4, v1
	v_fma_f32 v4, v1, s2, -v40
	v_cvt_pk_bf16_f32 v4, v4, v17
	ds_write_b16 v70, v4 offset:34320
	v_sub_f32_e32 v4, v41, v37
	v_add_f32_e32 v1, v4, v1
	v_fma_f32 v4, v1, s2, -v41
	v_cvt_pk_bf16_f32 v4, v4, v17
	ds_write_b16 v70, v4 offset:35360
	v_sub_f32_e32 v4, v42, v38
	v_add_f32_e32 v1, v4, v1
	v_fma_f32 v4, v1, s2, -v42
	v_cvt_pk_bf16_f32 v4, v4, v17
	ds_write_b16 v70, v4 offset:36400
	v_sub_f32_e32 v4, v43, v39
	v_add_f32_e32 v1, v4, v1
	v_fma_f32 v4, v1, s2, -v43
	v_cvt_pk_bf16_f32 v4, v4, v17
	ds_write_b16 v70, v4 offset:37440
	v_sub_f32_e32 v4, v44, v40
	v_add_f32_e32 v1, v4, v1
	v_fma_f32 v4, v1, s2, -v44
	v_cvt_pk_bf16_f32 v4, v4, v17
	ds_write_b16 v70, v4 offset:38480
	v_sub_f32_e32 v4, v45, v41
	v_add_f32_e32 v1, v4, v1
	v_fma_f32 v4, v1, s2, -v45
	v_cvt_pk_bf16_f32 v4, v4, v17
	ds_write_b16 v70, v4 offset:39520
	v_sub_f32_e32 v4, v46, v42
	v_add_f32_e32 v1, v4, v1
	v_fma_f32 v4, v1, s2, -v46
	v_cvt_pk_bf16_f32 v4, v4, v17
	ds_write_b16 v70, v4 offset:40560
	v_sub_f32_e32 v4, v47, v43
	v_add_f32_e32 v1, v4, v1
	v_fma_f32 v4, v1, s2, -v47
	v_cvt_pk_bf16_f32 v4, v4, v17
	ds_write_b16 v70, v4 offset:41600
	v_sub_f32_e32 v4, v48, v44
	v_add_f32_e32 v1, v4, v1
	v_fma_f32 v4, v1, s2, -v48
	v_cvt_pk_bf16_f32 v4, v4, v17
	ds_write_b16 v70, v4 offset:42640
	v_sub_f32_e32 v4, v49, v45
	v_add_f32_e32 v1, v4, v1
	v_fma_f32 v4, v1, s2, -v49
	v_cvt_pk_bf16_f32 v4, v4, v17
	ds_write_b16 v70, v4 offset:43680
	v_sub_f32_e32 v4, v50, v46
	v_add_f32_e32 v1, v4, v1
	v_fma_f32 v4, v1, s2, -v50
	v_cvt_pk_bf16_f32 v4, v4, v17
	ds_write_b16 v70, v4 offset:44720
	v_sub_f32_e32 v4, v51, v47
	v_add_f32_e32 v1, v4, v1
	v_fma_f32 v4, v1, s2, -v51
	v_cvt_pk_bf16_f32 v4, v4, v17
	ds_write_b16 v70, v4 offset:45760
	v_sub_f32_e32 v4, v52, v48
	v_add_f32_e32 v1, v4, v1
	v_fma_f32 v4, v1, s2, -v52
	v_cvt_pk_bf16_f32 v4, v4, v17
	ds_write_b16 v70, v4 offset:46800
	v_sub_f32_e32 v4, v53, v49
	v_add_f32_e32 v1, v4, v1
	v_fma_f32 v4, v1, s2, -v53
	v_cvt_pk_bf16_f32 v4, v4, v17
	ds_write_b16 v70, v4 offset:47840
	v_sub_f32_e32 v4, v54, v50
	v_add_f32_e32 v1, v4, v1
	v_fma_f32 v4, v1, s2, -v54
	v_cvt_pk_bf16_f32 v4, v4, v17
	ds_write_b16 v70, v4 offset:48880
	v_sub_f32_e32 v4, v55, v51
	v_add_f32_e32 v1, v4, v1
	v_fma_f32 v4, v1, s2, -v55
	v_cvt_pk_bf16_f32 v4, v4, v17
	ds_write_b16 v70, v4 offset:49920
	v_sub_f32_e32 v4, v56, v52
	v_add_f32_e32 v1, v4, v1
	v_fma_f32 v4, v1, s2, -v56
	v_cvt_pk_bf16_f32 v4, v4, v17
	ds_write_b16 v70, v4 offset:50960
	v_sub_f32_e32 v4, v57, v53
	v_add_f32_e32 v1, v4, v1
	v_fma_f32 v4, v1, s2, -v57
	v_cvt_pk_bf16_f32 v4, v4, v17
	ds_write_b16 v70, v4 offset:52000
	v_sub_f32_e32 v4, v58, v54
	v_add_f32_e32 v1, v4, v1
	v_fma_f32 v4, v1, s2, -v58
	v_cvt_pk_bf16_f32 v4, v4, v17
	ds_write_b16 v70, v4 offset:53040
	v_sub_f32_e32 v4, v59, v55
	v_add_f32_e32 v1, v4, v1
	v_fma_f32 v4, v1, s2, -v59
	v_cvt_pk_bf16_f32 v4, v4, v17
	ds_write_b16 v70, v4 offset:54080
	v_sub_f32_e32 v4, v60, v56
	v_add_f32_e32 v1, v4, v1
	v_fma_f32 v4, v1, s2, -v60
	v_cvt_pk_bf16_f32 v4, v4, v17
	ds_write_b16 v70, v4 offset:55120
	v_sub_f32_e32 v4, v61, v57
	v_add_f32_e32 v1, v4, v1
	v_fma_f32 v4, v1, s2, -v61
	v_cvt_pk_bf16_f32 v4, v4, v17
	ds_write_b16 v70, v4 offset:56160
	v_sub_f32_e32 v4, v62, v58
	v_add_f32_e32 v1, v4, v1
	v_fma_f32 v4, v1, s2, -v62
	v_cvt_pk_bf16_f32 v4, v4, v17
	ds_write_b16 v70, v4 offset:57200
	v_sub_f32_e32 v4, v64, v59
	v_add_f32_e32 v1, v4, v1
	v_fma_f32 v4, v1, s2, -v64
	v_cvt_pk_bf16_f32 v4, v4, v17
	ds_write_b16 v70, v4 offset:58240
	v_sub_f32_e32 v4, v66, v60
	v_add_f32_e32 v1, v4, v1
	v_fma_f32 v4, v1, s2, -v66
	v_cvt_pk_bf16_f32 v4, v4, v17
	ds_write_b16 v70, v4 offset:59280
	v_sub_f32_e32 v4, v68, v61
	v_add_f32_e32 v1, v4, v1
	v_fma_f32 v4, v1, s2, -v68
	v_cvt_pk_bf16_f32 v4, v4, v17
	ds_write_b16 v70, v4 offset:60320
	v_sub_f32_e32 v4, v3, v62
	v_add_f32_e32 v1, v4, v1
	v_fma_f32 v4, v1, s2, -v3
	v_cvt_pk_bf16_f32 v4, v4, v17
	ds_write_b16 v70, v4 offset:61360
	v_sub_f32_e32 v4, v63, v64
	v_add_f32_e32 v1, v4, v1
	v_fma_f32 v4, v1, s2, -v63
	v_cvt_pk_bf16_f32 v4, v4, v17
	ds_write_b16 v70, v4 offset:62400
	v_sub_f32_e32 v4, v65, v66
	v_add_f32_e32 v1, v4, v1
	v_fma_f32 v4, v1, s2, -v65
	v_cvt_pk_bf16_f32 v4, v4, v17
	ds_write_b16 v70, v4 offset:63440
	v_sub_f32_e32 v4, v67, v68
	v_add_f32_e32 v1, v4, v1
	v_sub_f32_e32 v3, v2, v3
	v_fma_f32 v4, v1, s2, -v67
	v_add_f32_e32 v1, v3, v1
	v_sub_f32_e32 v8, v8, v7
	v_fma_f32 v1, v1, s2, -v2
	v_cvt_pk_bf16_f32 v8, v8, v17
	ds_write_b16 v70, v8 offset:2080
	v_cvt_pk_bf16_f32 v4, v4, v17
	ds_write_b16 v70, v4 offset:64480
	v_cvt_pk_bf16_f32 v1, v1, v17
	s_or_b64 exec, exec, s[4:5]
	s_andn2_saveexec_b64 s[4:5], s[42:43]
	s_cbranch_execnz .LBB0_670
	s_branch .LBB0_674

.LBB0_759:
	s_or_b64 exec, exec, s[38:39]
	v_cmp_gt_u32_e32 vcc, 4, v105
	v_lshlrev_b64 v[0:1], 9, v[66:67]
	v_mov_b32_e32 v3, v17
	v_cndmask_b32_e32 v2, v239, v235, vcc
	v_lshl_add_u64 v[2:3], s[44:45], 0, v[2:3]
	v_lshlrev_b64 v[8:9], 1, v[0:1]
	v_lshl_add_u64 v[0:1], v[2:3], 0, v[8:9]
	v_lshlrev_b32_e32 v2, 5, v106
	v_and_b32_e32 v13, 0x60, v2
	v_lshl_add_u32 v12, v105, 7, v107
	v_lshl_add_u64 v[0:1], v[0:1], 0, s[52:53]
	v_lshlrev_b32_e32 v2, 1, v13
	v_mov_b32_e32 v3, v17
	s_waitcnt lgkmcnt(0)
	s_barrier
	v_lshl_add_u64 v[10:11], v[0:1], 0, v[2:3]
	ds_read_b128 v[0:3], v12 offset:34816
	ds_read_b128 v[4:7], v12 offset:34832
	s_waitcnt lgkmcnt(0)
	v_cvt_pk_bf16_f32 v0, v0, v1
	v_cvt_pk_bf16_f32 v1, v2, v3
	v_cvt_pk_bf16_f32 v2, v4, v5
	v_cvt_pk_bf16_f32 v3, v6, v7
	global_store_dwordx4 v[10:11], v[0:3], off
	ds_read_b128 v[0:3], v12 offset:34848
	ds_read_b128 v[4:7], v12 offset:34864
	s_waitcnt lgkmcnt(0)
	v_cvt_pk_bf16_f32 v0, v0, v1
	v_cvt_pk_bf16_f32 v1, v2, v3
	v_cvt_pk_bf16_f32 v2, v4, v5
	v_cvt_pk_bf16_f32 v3, v6, v7
	global_store_dwordx4 v[10:11], v[0:3], off offset:16
	ds_read_b128 v[0:3], v12 offset:34880
	ds_read_b128 v[4:7], v12 offset:34896
	s_waitcnt lgkmcnt(0)
	v_cvt_pk_bf16_f32 v0, v0, v1
	v_cvt_pk_bf16_f32 v1, v2, v3
	v_cvt_pk_bf16_f32 v2, v4, v5
	v_cvt_pk_bf16_f32 v3, v6, v7
	global_store_dwordx4 v[10:11], v[0:3], off offset:32
	ds_read_b128 v[0:3], v12 offset:34912
	ds_read_b128 v[4:7], v12 offset:34928
	s_waitcnt lgkmcnt(0)
	v_cvt_pk_bf16_f32 v0, v0, v1
	v_cvt_pk_bf16_f32 v1, v2, v3
	v_cvt_pk_bf16_f32 v2, v4, v5
	v_cvt_pk_bf16_f32 v3, v6, v7
	global_store_dwordx4 v[10:11], v[0:3], off offset:48
	s_movk_i32 s2, 0x88
	s_add_i32 s13, s13, s36
	v_lshrrev_b32_e32 v0, 2, v105
	v_lshl_or_b32 v0, v104, 1, v0
	v_mul_lo_u32 v0, v0, s2
	v_add3_u32 v4, 0, v0, v13
	v_add_u32_e32 v0, 0x4400, v4
	ds_read2_b64 v[0:3], v0 offset1:1
	v_add_u32_e32 v4, 0x4410, v4
	ds_read2_b64 v[4:7], v4 offset1:1
	v_lshl_add_u64 v[8:9], s[40:41], 0, v[8:9]
	s_add_u32 s92, s92, s28
	v_lshl_add_u64 v[8:9], v[8:9], 0, s[52:53]
	s_addc_u32 s93, s93, s29
	v_lshl_add_u64 v[8:9], v[8:9], 0, v[16:17]
	s_cmpk_gt_i32 s13, 0x3ff
	s_waitcnt lgkmcnt(0)
	global_store_dwordx4 v[8:9], v[0:3], off
	global_store_dwordx4 v[8:9], v[4:7], off offset:16
	s_waitcnt lgkmcnt(0)
	s_barrier
	s_cbranch_scc1 .LBB0_877
.LBB0_760:
	s_lshr_b32 s2, s13, 2
	s_and_b32 s37, s13, 3
	v_mov_b32_e32 v106, v228
	s_bfe_u32 s8, s13, 0x60002
	s_lshl_b32 s5, s2, 6
	s_lshl_b32 s4, s37, 7
	s_cmp_lg_u32 s8, 0
	v_ashrrev_i32_e32 v104, 3, v106
	s_cselect_b64 s[8:9], -1, 0
	v_cmp_lt_i32_e32 vcc, 2, v104
	s_waitcnt vmcnt(0)
	v_add_u32_e32 v0, -3, v104
	s_or_b64 vcc, s[8:9], vcc
	v_cndmask_b32_e32 v0, 0, v0, vcc
	v_cndmask_b32_e64 v44, 0, 1.0, vcc
	v_cmp_lt_i32_e32 vcc, 1, v104
	v_add_u32_e32 v4, -2, v104
	s_or_b64 vcc, s[8:9], vcc
	v_cndmask_b32_e32 v4, 0, v4, vcc
	v_cndmask_b32_e64 v42, 0, 1.0, vcc
	v_cmp_lt_i32_e32 vcc, 0, v104
	v_add_u32_e32 v8, -1, v104
	s_or_b64 vcc, s[8:9], vcc
	v_cndmask_b32_e32 v8, 0, v8, vcc
	v_cndmask_b32_e64 v40, 0, 1.0, vcc
	v_cmp_lt_i32_e32 vcc, -1, v104
	s_movk_i32 s2, 0x110
	s_or_b64 vcc, s[8:9], vcc
	v_and_b32_e32 v105, 7, v106
	v_mul_lo_u32 v109, v104, s2
	s_movk_i32 s2, 0x410
	v_cndmask_b32_e32 v14, 0, v104, vcc
	v_lshlrev_b32_e32 v108, 4, v105
	v_mul_lo_u32 v1, v104, s2
	v_add_u32_e32 v0, s5, v0
	v_mov_b64_e32 v[12:13], s[94:95]
	v_add_u32_e32 v4, s5, v4
	v_add_u32_e32 v8, s5, v8
	v_add_u32_e32 v14, s5, v14
	v_add_u32_e32 v107, 0, v1
	v_or_b32_e32 v39, s4, v108
	v_mad_i64_i32 v[0:1], s[38:39], v0, s66, v[12:13]
	v_mad_i64_i32 v[4:5], s[38:39], v4, s66, v[12:13]
	v_mad_i64_i32 v[8:9], s[38:39], v8, s66, v[12:13]
	v_mad_i64_i32 v[12:13], s[8:9], v14, s66, v[12:13]
	v_lshl_add_u64 v[46:47], v[0:1], 0, s[26:27]
	v_lshlrev_b32_e32 v16, 1, v39
	v_lshl_add_u64 v[48:49], v[4:5], 0, s[26:27]
	v_lshl_add_u64 v[50:51], v[8:9], 0, s[26:27]
	v_lshl_add_u64 v[52:53], v[12:13], 0, s[26:27]
	v_lshl_add_u64 v[0:1], v[46:47], 0, v[16:17]
	v_lshl_add_u64 v[4:5], v[48:49], 0, v[16:17]
	v_lshl_add_u64 v[8:9], v[50:51], 0, v[16:17]
	v_lshl_add_u64 v[12:13], v[52:53], 0, v[16:17]
	global_load_dwordx4 v[30:33], v[0:1], off
	s_nop 0
	global_load_dwordx4 v[0:3], v[0:1], off offset:16
	s_nop 0
	global_load_dwordx4 v[26:29], v[4:5], off
	s_nop 0
	global_load_dwordx4 v[4:7], v[4:5], off offset:16
	s_nop 0
	global_load_dwordx4 v[22:25], v[8:9], off
	s_nop 0
	global_load_dwordx4 v[8:11], v[8:9], off offset:16
	s_nop 0
	global_load_dwordx4 v[18:21], v[12:13], off
	s_nop 0
	global_load_dwordx4 v[12:15], v[12:13], off offset:16
	s_mov_b32 s8, 0
	s_ashr_i32 s9, s8, 31
	s_lshl_b64 s[8:9], s[8:9], 3
	s_add_u32 s8, s0, s8
	s_addc_u32 s9, s1, s9
	s_load_dwordx2 s[8:9], s[8:9], 0x90
	v_lshlrev_b32_e32 v41, 2, v39
	v_cndmask_b32_e64 v38, 0, 1.0, vcc
	v_and_b32_e32 v111, 64, v234
	v_or_b32_e32 v16, 0x400, v16
	s_waitcnt lgkmcnt(0)
	s_add_u32 s98, s8, s16
	s_addc_u32 s99, s9, s17
	s_add_u32 s100, s8, s18
	s_addc_u32 s101, s9, s19
	s_add_u32 s30, s8, s22
	s_addc_u32 s31, s9, s23
	s_add_u32 s8, s8, s15
	s_addc_u32 s9, s9, s14
	global_load_dwordx4 v[34:37], v41, s[8:9] offset:48
	global_load_dwordx4 v[54:57], v41, s[8:9] offset:32
	global_load_dwordx4 v[58:61], v41, s[8:9] offset:16
	global_load_dwordx4 v[62:65], v41, s[8:9]
	global_load_dwordx4 v[140:143], v41, s[98:99] offset:48
	global_load_dwordx4 v[144:147], v41, s[98:99] offset:32
	global_load_dwordx4 v[148:151], v41, s[98:99] offset:16
	global_load_dwordx4 v[152:155], v41, s[98:99]
	global_load_dwordx4 v[156:159], v41, s[100:101] offset:48
	global_load_dwordx4 v[160:163], v41, s[100:101] offset:32
	global_load_dwordx4 v[164:167], v41, s[100:101] offset:16
	global_load_dwordx4 v[168:171], v41, s[100:101]
	global_load_dwordx4 v[172:175], v41, s[30:31] offset:48
	global_load_dwordx4 v[176:179], v41, s[30:31] offset:32
	global_load_dwordx4 v[180:183], v41, s[30:31] offset:16
	global_load_dwordx4 v[184:187], v41, s[30:31]
	s_mov_b32 s8, 0
	s_ashr_i32 s9, s8, 31
	s_lshl_b64 s[8:9], s[8:9], 3
	s_add_u32 s8, s0, s8
	s_addc_u32 s9, s1, s9
	s_load_dwordx2 s[8:9], s[8:9], 0x90
	v_lshl_add_u32 v110, v105, 6, v107
	s_waitcnt lgkmcnt(0)
	s_add_u32 s8, s8, s16
	s_addc_u32 s9, s9, s17
	s_waitcnt vmcnt(0)
	v_lshlrev_b32_e32 v43, 16, v30
	v_and_b32_e32 v30, 0xffff0000, v30
	v_lshlrev_b32_e32 v84, 16, v18
	v_and_b32_e32 v18, 0xffff0000, v18
	v_pk_mul_f32 v[58:59], v[44:45], v[58:59] op_sel_hi:[0,1]
	v_pk_mul_f32 v[62:63], v[44:45], v[62:63] op_sel_hi:[0,1]
	v_pk_mul_f32 v[64:65], v[44:45], v[64:65] op_sel_hi:[0,1]
	v_fma_f32 v82, v63, v30, 0
	v_lshlrev_b32_e32 v30, 16, v31
	v_fma_f32 v83, v62, v43, 0
	v_fma_f32 v81, v64, v30, 0
	v_and_b32_e32 v30, 0xffff0000, v31
	v_lshlrev_b32_e32 v43, 16, v32
	v_and_b32_e32 v32, 0xffff0000, v32
	v_fma_f32 v80, v65, v30, 0
	v_pk_mul_f32 v[30:31], v[44:45], v[60:61] op_sel_hi:[0,1]
	v_fma_f32 v78, v59, v32, 0
	v_lshlrev_b32_e32 v32, 16, v33
	v_fma_f32 v45, v30, v32, 0
	v_and_b32_e32 v30, 0xffff0000, v33
	v_fma_f32 v79, v58, v43, 0
	v_fma_f32 v43, v31, v30, 0
	v_pk_mul_f32 v[58:59], v[44:45], v[56:57] op_sel_hi:[0,1]
	v_pk_mul_f32 v[62:63], v[44:45], v[54:55] op_sel_hi:[0,1]
	v_pk_mul_f32 v[54:55], v[44:45], v[36:37] op_sel_hi:[0,1]
	v_pk_mul_f32 v[56:57], v[44:45], v[34:35] op_sel_hi:[0,1]
	v_mov_b64_e32 v[30:31], v[140:141]
	v_mov_b64_e32 v[32:33], v[142:143]
	v_mov_b64_e32 v[34:35], v[144:145]
	v_mov_b64_e32 v[36:37], v[146:147]
	v_mov_b64_e32 v[64:65], v[148:149]
	v_mov_b64_e32 v[66:67], v[150:151]
	v_mov_b64_e32 v[68:69], v[152:153]
	v_mov_b64_e32 v[70:71], v[154:155]
	s_mov_b32 s8, 0
	s_ashr_i32 s9, s8, 31
	s_lshl_b64 s[8:9], s[8:9], 3
	s_add_u32 s8, s0, s8
	s_addc_u32 s9, s1, s9
	s_load_dwordx2 s[8:9], s[8:9], 0x90
	s_waitcnt lgkmcnt(0)
	s_add_u32 s8, s8, s18
	s_addc_u32 s9, s9, s19
	s_waitcnt vmcnt(0)
	v_pk_mul_f32 v[60:61], v[42:43], v[70:71] op_sel_hi:[0,1]
	v_pk_mul_f32 v[68:69], v[42:43], v[68:69] op_sel_hi:[0,1]
	v_lshlrev_b32_e32 v70, 16, v26
	v_and_b32_e32 v26, 0xffff0000, v26
	v_fmac_f32_e32 v82, v69, v26
	v_lshlrev_b32_e32 v26, 16, v27
	v_fmac_f32_e32 v81, v60, v26
	v_and_b32_e32 v26, 0xffff0000, v27
	v_fmac_f32_e32 v80, v61, v26
	v_pk_mul_f32 v[60:61], v[42:43], v[64:65] op_sel_hi:[0,1]
	v_lshlrev_b32_e32 v64, 16, v28
	v_and_b32_e32 v28, 0xffff0000, v28
	v_pk_mul_f32 v[26:27], v[42:43], v[66:67] op_sel_hi:[0,1]
	v_fmac_f32_e32 v78, v61, v28
	v_lshlrev_b32_e32 v28, 16, v29
	v_fmac_f32_e32 v45, v26, v28
	v_and_b32_e32 v26, 0xffff0000, v29
	v_fmac_f32_e32 v43, v27, v26
	v_fmac_f32_e32 v83, v68, v70
	v_fmac_f32_e32 v79, v60, v64
	v_pk_mul_f32 v[66:67], v[42:43], v[36:37] op_sel_hi:[0,1]
	v_pk_mul_f32 v[70:71], v[42:43], v[34:35] op_sel_hi:[0,1]
	v_pk_mul_f32 v[60:61], v[42:43], v[32:33] op_sel_hi:[0,1]
	v_pk_mul_f32 v[64:65], v[42:43], v[30:31] op_sel_hi:[0,1]
	v_mov_b64_e32 v[26:27], v[156:157]
	v_mov_b64_e32 v[28:29], v[158:159]
	v_mov_b64_e32 v[30:31], v[160:161]
	v_mov_b64_e32 v[32:33], v[162:163]
	v_mov_b64_e32 v[34:35], v[164:165]
	v_mov_b64_e32 v[36:37], v[166:167]
	v_mov_b64_e32 v[72:73], v[168:169]
	v_mov_b64_e32 v[74:75], v[170:171]
	s_mov_b32 s8, 0
	s_ashr_i32 s9, s8, 31
	s_lshl_b64 s[8:9], s[8:9], 3
	s_add_u32 s8, s0, s8
	s_addc_u32 s9, s1, s9
	s_load_dwordx2 s[8:9], s[8:9], 0x90
	s_waitcnt lgkmcnt(0)
	s_add_u32 s8, s8, s22
	s_addc_u32 s9, s9, s23
	s_waitcnt vmcnt(2)
	v_pk_mul_f32 v[76:77], v[40:41], v[30:31] op_sel_hi:[0,1]
	s_waitcnt vmcnt(1)
	v_pk_mul_f32 v[34:35], v[40:41], v[34:35] op_sel_hi:[0,1]
	s_waitcnt vmcnt(0)
	v_pk_mul_f32 v[68:69], v[40:41], v[74:75] op_sel_hi:[0,1]
	v_pk_mul_f32 v[72:73], v[40:41], v[72:73] op_sel_hi:[0,1]
	v_lshlrev_b32_e32 v74, 16, v22
	v_and_b32_e32 v22, 0xffff0000, v22
	v_fmac_f32_e32 v82, v73, v22
	v_lshlrev_b32_e32 v22, 16, v23
	v_fmac_f32_e32 v81, v68, v22
	v_and_b32_e32 v22, 0xffff0000, v23
	v_fmac_f32_e32 v80, v69, v22
	v_pk_mul_f32 v[22:23], v[40:41], v[36:37] op_sel_hi:[0,1]
	v_lshlrev_b32_e32 v36, 16, v24
	v_and_b32_e32 v24, 0xffff0000, v24
	v_fmac_f32_e32 v78, v35, v24
	v_lshlrev_b32_e32 v24, 16, v25
	v_fmac_f32_e32 v45, v22, v24
	v_and_b32_e32 v22, 0xffff0000, v25
	v_fmac_f32_e32 v83, v72, v74
	v_fmac_f32_e32 v79, v34, v36
	v_fmac_f32_e32 v43, v23, v22
	v_pk_mul_f32 v[74:75], v[40:41], v[32:33] op_sel_hi:[0,1]
	v_pk_mul_f32 v[68:69], v[40:41], v[28:29] op_sel_hi:[0,1]
	v_pk_mul_f32 v[72:73], v[40:41], v[26:27] op_sel_hi:[0,1]
	v_mov_b64_e32 v[22:23], v[172:173]
	v_mov_b64_e32 v[24:25], v[174:175]
	v_mov_b64_e32 v[26:27], v[176:177]
	v_mov_b64_e32 v[28:29], v[178:179]
	v_mov_b64_e32 v[30:31], v[180:181]
	v_mov_b64_e32 v[32:33], v[182:183]
	v_mov_b64_e32 v[34:35], v[184:185]
	v_mov_b64_e32 v[36:37], v[186:187]
	s_waitcnt vmcnt(2)
	v_pk_mul_f32 v[26:27], v[38:39], v[26:27] op_sel_hi:[0,1]
	s_waitcnt vmcnt(1)
	v_pk_mul_f32 v[30:31], v[38:39], v[30:31] op_sel_hi:[0,1]
	s_waitcnt vmcnt(0)
	v_pk_mul_f32 v[34:35], v[38:39], v[34:35] op_sel_hi:[0,1]
	v_pk_mul_f32 v[36:37], v[38:39], v[36:37] op_sel_hi:[0,1]
	v_fmac_f32_e32 v82, v35, v18
	v_lshlrev_b32_e32 v18, 16, v19
	v_fmac_f32_e32 v81, v36, v18
	v_and_b32_e32 v18, 0xffff0000, v19
	v_fmac_f32_e32 v80, v37, v18
	v_pk_mul_f32 v[18:19], v[38:39], v[32:33] op_sel_hi:[0,1]
	v_lshlrev_b32_e32 v32, 16, v20
	v_and_b32_e32 v20, 0xffff0000, v20
	v_fmac_f32_e32 v83, v34, v84
	v_fmac_f32_e32 v78, v31, v20
	v_lshlrev_b32_e32 v20, 16, v21
	v_fmac_f32_e32 v45, v18, v20
	v_and_b32_e32 v18, 0xffff0000, v21
	v_pk_mul_f32 v[20:21], v[38:39], v[22:23] op_sel_hi:[0,1]
	v_mul_f32_e32 v22, 0xbfb8aa3b, v83
	v_exp_f32_e32 v22, v22
	v_fmac_f32_e32 v79, v30, v32
	v_fmac_f32_e32 v43, v19, v18
	v_and_b32_e32 v23, 0xffff0000, v0
	v_add_f32_e32 v22, 1.0, v22
	v_rcp_f32_e32 v22, v22
	v_pk_mul_f32 v[18:19], v[38:39], v[24:25] op_sel_hi:[0,1]
	v_and_b32_e32 v25, 0xffff0000, v4
	v_lshlrev_b32_e32 v24, 16, v4
	v_mul_f32_e32 v30, v83, v22
	v_mul_f32_e32 v22, 0xbfb8aa3b, v82
	v_exp_f32_e32 v22, v22
	v_lshlrev_b32_e32 v4, 16, v9
	v_pk_mul_f32 v[28:29], v[38:39], v[28:29] op_sel_hi:[0,1]
	v_add_f32_e32 v22, 1.0, v22
	v_rcp_f32_e32 v22, v22
	s_nop 0
	v_mul_f32_e32 v31, v82, v22
	v_mul_f32_e32 v22, 0xbfb8aa3b, v81
	v_exp_f32_e32 v22, v22
	s_nop 0
	v_add_f32_e32 v22, 1.0, v22
	v_rcp_f32_e32 v22, v22
	s_nop 0
	v_mul_f32_e32 v32, v81, v22
	v_mul_f32_e32 v22, 0xbfb8aa3b, v80
	v_exp_f32_e32 v22, v22
	s_nop 0
	v_add_f32_e32 v22, 1.0, v22
	v_rcp_f32_e32 v22, v22
	s_nop 0
	v_mul_f32_e32 v33, v80, v22
	v_mul_f32_e32 v22, 0xbfb8aa3b, v79
	v_exp_f32_e32 v22, v22
	s_nop 0
	v_add_f32_e32 v22, 1.0, v22
	v_rcp_f32_e32 v22, v22
	s_nop 0
	v_mul_f32_e32 v34, v79, v22
	v_mul_f32_e32 v22, 0xbfb8aa3b, v78
	v_exp_f32_e32 v22, v22
	s_nop 0
	v_add_f32_e32 v22, 1.0, v22
	v_rcp_f32_e32 v22, v22
	s_nop 0
	v_mul_f32_e32 v35, v78, v22
	v_mul_f32_e32 v22, 0xbfb8aa3b, v45
	v_exp_f32_e32 v22, v22
	s_nop 0
	v_add_f32_e32 v22, 1.0, v22
	v_rcp_f32_e32 v22, v22
	s_nop 0
	v_mul_f32_e32 v36, v45, v22
	v_mul_f32_e32 v22, 0xbfb8aa3b, v43
	v_exp_f32_e32 v22, v22
	s_nop 0
	v_add_f32_e32 v22, 1.0, v22
	v_rcp_f32_e32 v22, v22
	s_nop 0
	v_mul_f32_e32 v37, v43, v22
	v_lshlrev_b32_e32 v22, 16, v0
	v_pk_fma_f32 v[22:23], v[62:63], v[22:23], 0 op_sel_hi:[1,1,0]
	v_mul_f32_e32 v43, v31, v31
	v_pk_fma_f32 v[22:23], v[70:71], v[24:25], v[22:23]
	v_and_b32_e32 v25, 0xffff0000, v8
	v_lshlrev_b32_e32 v24, 16, v8
	v_pk_fma_f32 v[22:23], v[76:77], v[24:25], v[22:23]
	v_and_b32_e32 v25, 0xffff0000, v12
	v_lshlrev_b32_e32 v24, 16, v12
	v_pk_fma_f32 v[22:23], v[26:27], v[24:25], v[22:23]
	v_fmac_f32_e32 v43, v30, v30
	v_mul_f32_e32 v0, 0xbfb8aa3b, v22
	v_exp_f32_e32 v0, v0
	v_fmac_f32_e32 v43, v32, v32
	v_fmac_f32_e32 v43, v33, v33
	v_fmac_f32_e32 v43, v34, v34
	v_add_f32_e32 v0, 1.0, v0
	v_rcp_f32_e32 v24, v0
	v_mul_f32_e32 v0, 0xbfb8aa3b, v23
	v_exp_f32_e32 v0, v0
	v_fmac_f32_e32 v43, v35, v35
	v_fmac_f32_e32 v43, v36, v36
	v_fmac_f32_e32 v43, v37, v37
	v_add_f32_e32 v0, 1.0, v0
	v_rcp_f32_e32 v25, v0
	s_nop 0
	v_pk_mul_f32 v[22:23], v[22:23], v[24:25]
	s_nop 0
	v_pk_mul_f32 v[24:25], v[22:23], v[22:23]
	s_nop 0
	v_add_f32_e32 v0, v24, v43
	v_add_f32_e32 v8, v25, v0
	v_and_b32_e32 v25, 0xffff0000, v1
	v_lshlrev_b32_e32 v24, 16, v1
	v_pk_fma_f32 v[0:1], v[58:59], v[24:25], 0 op_sel_hi:[1,1,0]
	v_and_b32_e32 v25, 0xffff0000, v5
	v_lshlrev_b32_e32 v24, 16, v5
	v_pk_fma_f32 v[0:1], v[66:67], v[24:25], v[0:1]
	v_and_b32_e32 v5, 0xffff0000, v9
	v_pk_fma_f32 v[0:1], v[74:75], v[4:5], v[0:1]
	v_and_b32_e32 v5, 0xffff0000, v13
	v_lshlrev_b32_e32 v4, 16, v13
	v_pk_fma_f32 v[0:1], v[28:29], v[4:5], v[0:1]
	v_and_b32_e32 v9, 0xffff0000, v6
	v_mul_f32_e32 v4, 0xbfb8aa3b, v0
	v_mul_f32_e32 v5, 0xbfb8aa3b, v1
	v_exp_f32_e32 v4, v4
	v_exp_f32_e32 v5, v5
	v_add_f32_e32 v4, 1.0, v4
	v_add_f32_e32 v5, 1.0, v5
	v_rcp_f32_e32 v4, v4
	v_rcp_f32_e32 v5, v5
	s_nop 0
	v_pk_mul_f32 v[0:1], v[0:1], v[4:5]
	s_nop 0
	v_pk_mul_f32 v[4:5], v[0:1], v[0:1]
	s_nop 0
	v_add_f32_e32 v4, v4, v8
	v_add_f32_e32 v12, v5, v4
	v_and_b32_e32 v5, 0xffff0000, v2
	v_lshlrev_b32_e32 v4, 16, v2
	v_pk_fma_f32 v[4:5], v[56:57], v[4:5], 0 op_sel_hi:[1,1,0]
	v_lshlrev_b32_e32 v8, 16, v6
	v_pk_fma_f32 v[4:5], v[64:65], v[8:9], v[4:5]
	v_and_b32_e32 v9, 0xffff0000, v10
	v_lshlrev_b32_e32 v8, 16, v10
	v_pk_fma_f32 v[4:5], v[72:73], v[8:9], v[4:5]
	v_and_b32_e32 v9, 0xffff0000, v14
	v_lshlrev_b32_e32 v8, 16, v14
	v_pk_fma_f32 v[4:5], v[20:21], v[8:9], v[4:5]
	v_lshlrev_b32_e32 v6, 16, v11
	v_mul_f32_e32 v2, 0xbfb8aa3b, v4
	v_exp_f32_e32 v2, v2
	s_nop 0
	v_add_f32_e32 v2, 1.0, v2
	v_rcp_f32_e32 v8, v2
	v_mul_f32_e32 v2, 0xbfb8aa3b, v5
	v_exp_f32_e32 v2, v2
	s_nop 0
	v_add_f32_e32 v2, 1.0, v2
	v_rcp_f32_e32 v9, v2
	s_nop 0
	v_pk_mul_f32 v[4:5], v[4:5], v[8:9]
	s_nop 0
	v_pk_mul_f32 v[8:9], v[4:5], v[4:5]
	s_nop 0
	v_add_f32_e32 v2, v8, v12
	v_add_f32_e32 v10, v9, v2
	v_and_b32_e32 v9, 0xffff0000, v3
	v_lshlrev_b32_e32 v8, 16, v3
	v_pk_fma_f32 v[2:3], v[54:55], v[8:9], 0 op_sel_hi:[1,1,0]
	v_and_b32_e32 v9, 0xffff0000, v7
	v_lshlrev_b32_e32 v8, 16, v7
	v_pk_fma_f32 v[2:3], v[60:61], v[8:9], v[2:3]
	v_and_b32_e32 v7, 0xffff0000, v11
	v_pk_fma_f32 v[2:3], v[68:69], v[6:7], v[2:3]
	v_and_b32_e32 v7, 0xffff0000, v15
	v_lshlrev_b32_e32 v6, 16, v15
	v_pk_fma_f32 v[2:3], v[18:19], v[6:7], v[2:3]
	v_add_u32_e32 v8, 64, v111
	v_mul_f32_e32 v6, 0xbfb8aa3b, v3
	v_exp_f32_e32 v6, v6
	s_nop 0
	v_add_f32_e32 v6, 1.0, v6
	v_rcp_f32_e32 v7, v6
	v_mul_f32_e32 v6, 0xbfb8aa3b, v2
	v_exp_f32_e32 v6, v6
	s_nop 0
	v_add_f32_e32 v6, 1.0, v6
	v_rcp_f32_e32 v6, v6
	s_nop 0
	v_pk_mul_f32 v[2:3], v[2:3], v[6:7]
	s_nop 0
	v_pk_mul_f32 v[6:7], v[2:3], v[2:3]
	s_nop 0
	v_add_f32_e32 v6, v6, v10
	v_add_f32_e32 v6, v7, v6
	v_xor_b32_e32 v7, 1, v234
	v_cmp_lt_i32_e32 vcc, v7, v8
	s_nop 1
	v_cndmask_b32_e32 v7, v234, v7, vcc
	v_lshlrev_b32_e32 v45, 2, v7
	ds_bpermute_b32 v7, v45, v6
	s_waitcnt lgkmcnt(0)
	v_add_f32_e32 v6, v6, v7
	v_xor_b32_e32 v7, 2, v234
	v_cmp_lt_i32_e32 vcc, v7, v8
	s_nop 1
	v_cndmask_b32_e32 v7, v234, v7, vcc
	v_lshlrev_b32_e32 v112, 2, v7
	ds_bpermute_b32 v7, v112, v6
	s_waitcnt lgkmcnt(0)
	v_add_f32_e32 v6, v6, v7
	v_xor_b32_e32 v7, 4, v234
	v_cmp_lt_i32_e32 vcc, v7, v8
	s_nop 1
	v_cndmask_b32_e32 v7, v234, v7, vcc
	v_lshlrev_b32_e32 v113, 2, v7
	ds_bpermute_b32 v7, v113, v6
	s_waitcnt lgkmcnt(0)
	v_add_f32_e32 v6, v6, v7
	v_add_f32_e32 v6, 0x358637bd, v6
	v_cmp_gt_f32_e32 vcc, s33, v6
	v_mul_f32_e32 v7, 0x4b800000, v6
	s_nop 0
	v_cndmask_b32_e32 v6, v6, v7, vcc
	v_rsq_f32_e32 v6, v6
	s_nop 0
	v_mul_f32_e32 v7, 0x45800000, v6
	v_cndmask_b32_e32 v6, v6, v7, vcc
	v_mul_f32_e32 v6, 0x3db504f3, v6
	v_mul_f32_e32 v7, v30, v6
	v_mul_f32_e32 v8, v31, v6
	v_mul_f32_e32 v9, v32, v6
	v_mul_f32_e32 v10, v33, v6
	v_mul_f32_e32 v11, v34, v6
	v_mul_f32_e32 v12, v35, v6
	v_mul_f32_e32 v13, v36, v6
	v_mul_f32_e32 v14, v37, v6
	v_mul_f32_e32 v15, v22, v6
	v_mul_f32_e32 v18, v23, v6
	v_mul_f32_e32 v0, v0, v6
	v_mul_f32_e32 v1, v1, v6
	v_mul_f32_e32 v4, v4, v6
	v_mul_f32_e32 v5, v5, v6
	v_mul_f32_e32 v2, v2, v6
	v_mul_f32_e32 v3, v3, v6
	v_lshlrev_b32_e32 v6, 5, v105
	v_add3_u32 v43, 0, v6, v109
	v_cvt_pk_bf16_f32 v6, v7, v8
	v_add_u32_e32 v8, 0x4400, v43
	v_cvt_pk_bf16_f32 v7, v9, v10
	ds_write2_b32 v8, v6, v7 offset1:1
	v_cvt_pk_bf16_f32 v6, v11, v12
	v_cvt_pk_bf16_f32 v0, v0, v1
	v_cvt_pk_bf16_f32 v7, v13, v14
	ds_write2_b32 v8, v6, v7 offset0:2 offset1:3
	v_cvt_pk_bf16_f32 v6, v15, v18
	ds_write2_b32 v8, v6, v0 offset0:4 offset1:5
	v_cvt_pk_bf16_f32 v0, v4, v5
	v_cvt_pk_bf16_f32 v1, v2, v3
	ds_write2_b32 v8, v0, v1 offset0:6 offset1:7
	v_lshl_add_u64 v[0:1], v[46:47], 0, v[16:17]
	global_load_dwordx4 v[30:33], v[0:1], off
	global_load_dwordx4 v[12:15], v[0:1], off offset:16
	v_lshl_add_u64 v[0:1], v[48:49], 0, v[16:17]
	global_load_dwordx4 v[26:29], v[0:1], off
	global_load_dwordx4 v[8:11], v[0:1], off offset:16
	v_lshl_add_u64 v[0:1], v[50:51], 0, v[16:17]
	global_load_dwordx4 v[22:25], v[0:1], off
	global_load_dwordx4 v[4:7], v[0:1], off offset:16
	v_lshl_add_u64 v[0:1], v[52:53], 0, v[16:17]
	global_load_dwordx4 v[18:21], v[0:1], off
	s_nop 0
	global_load_dwordx4 v[0:3], v[0:1], off offset:16
	s_mov_b32 s8, 0
	s_ashr_i32 s9, s8, 31
	s_lshl_b64 s[8:9], s[8:9], 3
	s_add_u32 s8, s0, s8
	s_addc_u32 s9, s1, s9
	s_load_dwordx2 s[8:9], s[8:9], 0x90
	s_waitcnt lgkmcnt(0)
	s_add_u32 s98, s8, s16
	s_addc_u32 s99, s9, s17
	s_add_u32 s100, s8, s18
	s_addc_u32 s101, s9, s19
	s_add_u32 s30, s8, s22
	s_addc_u32 s31, s9, s23
	s_add_u32 s8, s8, s15
	s_addc_u32 s9, s9, s14
	global_load_dwordx4 v[58:61], v41, s[8:9] offset:2096
	global_load_dwordx4 v[62:65], v41, s[8:9] offset:2080
	global_load_dwordx4 v[34:37], v41, s[8:9] offset:2064
	global_load_dwordx4 v[54:57], v41, s[8:9] offset:2048
	global_load_dwordx4 v[140:143], v41, s[98:99] offset:2096
	global_load_dwordx4 v[144:147], v41, s[98:99] offset:2080
	global_load_dwordx4 v[148:151], v41, s[98:99] offset:2064
	global_load_dwordx4 v[152:155], v41, s[98:99] offset:2048
	global_load_dwordx4 v[156:159], v41, s[100:101] offset:2096
	global_load_dwordx4 v[160:163], v41, s[100:101] offset:2080
	global_load_dwordx4 v[164:167], v41, s[100:101] offset:2064
	global_load_dwordx4 v[168:171], v41, s[100:101] offset:2048
	global_load_dwordx4 v[172:175], v41, s[30:31] offset:2096
	global_load_dwordx4 v[176:179], v41, s[30:31] offset:2080
	global_load_dwordx4 v[180:183], v41, s[30:31] offset:2064
	global_load_dwordx4 v[184:187], v41, s[30:31] offset:2048
	s_mov_b32 s8, 0
	s_ashr_i32 s9, s8, 31
	s_lshl_b64 s[8:9], s[8:9], 3
	s_add_u32 s8, s0, s8
	s_addc_u32 s9, s1, s9
	s_load_dwordx2 s[8:9], s[8:9], 0x90
	s_waitcnt lgkmcnt(0)
	s_add_u32 s8, s8, s16
	s_addc_u32 s9, s9, s17
	s_waitcnt vmcnt(0)
	v_pk_mul_f32 v[92:93], v[44:45], v[60:61] op_sel_hi:[0,1]
	v_pk_mul_f32 v[74:75], v[44:45], v[58:59] op_sel_hi:[0,1]
	v_pk_mul_f32 v[66:67], v[44:45], v[34:35] op_sel_hi:[0,1]
	v_pk_mul_f32 v[78:79], v[44:45], v[54:55] op_sel_hi:[0,1]
	v_pk_mul_f32 v[34:35], v[44:45], v[64:65] op_sel_hi:[0,1]
	v_pk_mul_f32 v[54:55], v[44:45], v[62:63] op_sel_hi:[0,1]
	v_mov_b64_e32 v[82:83], v[140:141]
	v_mov_b64_e32 v[84:85], v[142:143]
	v_mov_b64_e32 v[58:59], v[144:145]
	v_mov_b64_e32 v[60:61], v[146:147]
	v_mov_b64_e32 v[88:89], v[148:149]
	v_mov_b64_e32 v[90:91], v[150:151]
	v_mov_b64_e32 v[62:63], v[152:153]
	v_mov_b64_e32 v[64:65], v[154:155]
	s_mov_b32 s8, 0
	s_ashr_i32 s9, s8, 31
	s_lshl_b64 s[8:9], s[8:9], 3
	s_add_u32 s8, s0, s8
	s_addc_u32 s9, s1, s9
	s_load_dwordx2 s[8:9], s[8:9], 0x90
	v_pk_mul_f32 v[70:71], v[44:45], v[56:57] op_sel_hi:[0,1]
	v_pk_mul_f32 v[56:57], v[44:45], v[36:37] op_sel_hi:[0,1]
	s_waitcnt lgkmcnt(0)
	s_add_u32 s8, s8, s18
	s_addc_u32 s9, s9, s19
	v_mov_b64_e32 v[100:101], v[156:157]
	v_mov_b64_e32 v[102:103], v[158:159]
	v_mov_b64_e32 v[114:115], v[160:161]
	v_mov_b64_e32 v[116:117], v[162:163]
	v_mov_b64_e32 v[118:119], v[164:165]
	v_mov_b64_e32 v[120:121], v[166:167]
	v_mov_b64_e32 v[94:95], v[168:169]
	v_mov_b64_e32 v[96:97], v[170:171]
	s_mov_b32 s8, 0
	s_ashr_i32 s9, s8, 31
	s_lshl_b64 s[8:9], s[8:9], 3
	s_add_u32 s8, s0, s8
	s_addc_u32 s9, s1, s9
	s_load_dwordx2 s[8:9], s[8:9], 0x90
	s_waitcnt lgkmcnt(0)
	s_add_u32 s8, s8, s22
	s_addc_u32 s9, s9, s23
	s_waitcnt vmcnt(7)
	v_pk_mul_f32 v[98:99], v[42:43], v[84:85] op_sel_hi:[0,1]
	s_waitcnt vmcnt(6)
	v_pk_mul_f32 v[36:37], v[42:43], v[60:61] op_sel_hi:[0,1]
	v_pk_mul_f32 v[60:61], v[42:43], v[58:59] op_sel_hi:[0,1]
	s_waitcnt vmcnt(4)
	v_pk_mul_f32 v[80:81], v[42:43], v[64:65] op_sel_hi:[0,1]
	v_pk_mul_f32 v[84:85], v[42:43], v[82:83] op_sel_hi:[0,1]
	v_pk_mul_f32 v[86:87], v[42:43], v[62:63] op_sel_hi:[0,1]
	v_pk_mul_f32 v[62:63], v[42:43], v[90:91] op_sel_hi:[0,1]
	v_pk_mul_f32 v[72:73], v[42:43], v[88:89] op_sel_hi:[0,1]
	s_waitcnt vmcnt(3)
	v_pk_mul_f32 v[130:131], v[40:41], v[100:101] op_sel_hi:[0,1]
	s_waitcnt vmcnt(2)
	v_pk_mul_f32 v[58:59], v[40:41], v[116:117] op_sel_hi:[0,1]
	s_waitcnt vmcnt(1)
	v_pk_mul_f32 v[68:69], v[40:41], v[120:121] op_sel_hi:[0,1]
	v_pk_mul_f32 v[82:83], v[40:41], v[118:119] op_sel_hi:[0,1]
	v_pk_mul_f32 v[64:65], v[40:41], v[114:115] op_sel_hi:[0,1]
	v_mov_b64_e32 v[114:115], v[172:173]
	v_mov_b64_e32 v[116:117], v[174:175]
	v_mov_b64_e32 v[118:119], v[176:177]
	v_mov_b64_e32 v[120:121], v[178:179]
	v_mov_b64_e32 v[122:123], v[180:181]
	v_mov_b64_e32 v[124:125], v[182:183]
	v_mov_b64_e32 v[126:127], v[184:185]
	v_mov_b64_e32 v[128:129], v[186:187]
	v_pk_mul_f32 v[102:103], v[40:41], v[102:103] op_sel_hi:[0,1]
	s_waitcnt vmcnt(4)
	v_pk_mul_f32 v[88:89], v[40:41], v[96:97] op_sel_hi:[0,1]
	v_pk_mul_f32 v[96:97], v[40:41], v[94:95] op_sel_hi:[0,1]
	s_waitcnt vmcnt(3)
	v_pk_mul_f32 v[114:115], v[38:39], v[114:115] op_sel_hi:[0,1]
	s_waitcnt vmcnt(2)
	v_pk_mul_f32 v[90:91], v[38:39], v[118:119] op_sel_hi:[0,1]
	v_and_b32_e32 v119, 0xffff0000, v14
	v_lshlrev_b32_e32 v118, 16, v14
	v_pk_fma_f32 v[74:75], v[74:75], v[118:119], 0 op_sel_hi:[1,1,0]
	v_and_b32_e32 v119, 0xffff0000, v10
	v_lshlrev_b32_e32 v118, 16, v10
	v_pk_fma_f32 v[74:75], v[84:85], v[118:119], v[74:75]
	v_and_b32_e32 v85, 0xffff0000, v6
	v_lshlrev_b32_e32 v84, 16, v6
	v_pk_fma_f32 v[74:75], v[130:131], v[84:85], v[74:75]
	v_and_b32_e32 v85, 0xffff0000, v2
	v_lshlrev_b32_e32 v84, 16, v2
	v_pk_fma_f32 v[74:75], v[114:115], v[84:85], v[74:75]
	v_and_b32_e32 v115, 0xffff0000, v15
	v_mul_f32_e32 v2, 0xbfb8aa3b, v74
	v_exp_f32_e32 v2, v2
	v_lshlrev_b32_e32 v114, 16, v15
	v_pk_fma_f32 v[14:15], v[92:93], v[114:115], 0 op_sel_hi:[1,1,0]
	v_and_b32_e32 v93, 0xffff0000, v11
	v_add_f32_e32 v2, 1.0, v2
	v_rcp_f32_e32 v84, v2
	v_mul_f32_e32 v2, 0xbfb8aa3b, v75
	v_exp_f32_e32 v2, v2
	v_lshlrev_b32_e32 v92, 16, v11
	v_pk_fma_f32 v[10:11], v[98:99], v[92:93], v[14:15]
	v_and_b32_e32 v15, 0xffff0000, v7
	v_lshlrev_b32_e32 v14, 16, v7
	v_pk_mul_f32 v[116:117], v[38:39], v[116:117] op_sel_hi:[0,1]
	v_add_f32_e32 v2, 1.0, v2
	v_pk_fma_f32 v[6:7], v[102:103], v[14:15], v[10:11]
	v_and_b32_e32 v11, 0xffff0000, v3
	v_lshlrev_b32_e32 v10, 16, v3
	v_rcp_f32_e32 v85, v2
	v_pk_fma_f32 v[2:3], v[116:117], v[10:11], v[6:7]
	v_lshlrev_b32_e32 v10, 16, v30
	v_and_b32_e32 v11, 0xffff0000, v30
	v_lshlrev_b32_e32 v30, 16, v31
	v_and_b32_e32 v31, 0xffff0000, v31
	v_pk_fma_f32 v[10:11], v[78:79], v[10:11], 0 op_sel_hi:[1,1,0]
	v_lshlrev_b32_e32 v14, 16, v26
	v_and_b32_e32 v15, 0xffff0000, v26
	v_pk_fma_f32 v[30:31], v[70:71], v[30:31], 0 op_sel_hi:[1,1,0]
	v_lshlrev_b32_e32 v26, 16, v27
	v_and_b32_e32 v27, 0xffff0000, v27
	v_pk_fma_f32 v[10:11], v[86:87], v[14:15], v[10:11]
	v_lshlrev_b32_e32 v14, 16, v22
	v_and_b32_e32 v15, 0xffff0000, v22
	v_pk_fma_f32 v[26:27], v[80:81], v[26:27], v[30:31]
	v_lshlrev_b32_e32 v22, 16, v23
	v_and_b32_e32 v23, 0xffff0000, v23
	s_waitcnt vmcnt(0)
	v_pk_mul_f32 v[128:129], v[38:39], v[128:129] op_sel_hi:[0,1]
	v_pk_fma_f32 v[10:11], v[96:97], v[14:15], v[10:11]
	v_lshlrev_b32_e32 v14, 16, v18
	v_and_b32_e32 v15, 0xffff0000, v18
	v_pk_fma_f32 v[22:23], v[88:89], v[22:23], v[26:27]
	v_lshlrev_b32_e32 v18, 16, v19
	v_and_b32_e32 v19, 0xffff0000, v19
	v_pk_fma_f32 v[18:19], v[128:129], v[18:19], v[22:23]
	v_lshlrev_b32_e32 v26, 16, v32
	v_mul_f32_e32 v16, 0xbfb8aa3b, v18
	v_exp_f32_e32 v16, v16
	v_and_b32_e32 v27, 0xffff0000, v32
	v_pk_fma_f32 v[26:27], v[66:67], v[26:27], 0 op_sel_hi:[1,1,0]
	v_lshlrev_b32_e32 v30, 16, v28
	v_add_f32_e32 v16, 1.0, v16
	v_rcp_f32_e32 v22, v16
	v_mul_f32_e32 v16, 0xbfb8aa3b, v19
	v_exp_f32_e32 v16, v16
	v_and_b32_e32 v31, 0xffff0000, v28
	v_pk_fma_f32 v[26:27], v[72:73], v[30:31], v[26:27]
	v_lshlrev_b32_e32 v30, 16, v24
	v_and_b32_e32 v31, 0xffff0000, v24
	v_pk_mul_f32 v[100:101], v[38:39], v[122:123] op_sel_hi:[0,1]
	v_pk_fma_f32 v[26:27], v[82:83], v[30:31], v[26:27]
	v_lshlrev_b32_e32 v30, 16, v20
	v_and_b32_e32 v31, 0xffff0000, v20
	v_add_f32_e32 v16, 1.0, v16
	v_pk_fma_f32 v[26:27], v[100:101], v[30:31], v[26:27]
	v_rcp_f32_e32 v23, v16
	v_mul_f32_e32 v16, 0xbfb8aa3b, v26
	v_lshlrev_b32_e32 v32, 16, v33
	v_and_b32_e32 v33, 0xffff0000, v33
	v_exp_f32_e32 v16, v16
	v_pk_fma_f32 v[32:33], v[56:57], v[32:33], 0 op_sel_hi:[1,1,0]
	v_lshlrev_b32_e32 v28, 16, v29
	v_and_b32_e32 v29, 0xffff0000, v29
	v_pk_fma_f32 v[28:29], v[62:63], v[28:29], v[32:33]
	v_lshlrev_b32_e32 v24, 16, v25
	v_and_b32_e32 v25, 0xffff0000, v25
	v_pk_fma_f32 v[24:25], v[68:69], v[24:25], v[28:29]
	v_lshlrev_b32_e32 v28, 16, v12
	v_and_b32_e32 v29, 0xffff0000, v12
	v_pk_fma_f32 v[28:29], v[54:55], v[28:29], 0 op_sel_hi:[1,1,0]
	v_lshlrev_b32_e32 v32, 16, v8
	v_and_b32_e32 v33, 0xffff0000, v8
	v_add_f32_e32 v16, 1.0, v16
	v_pk_fma_f32 v[28:29], v[60:61], v[32:33], v[28:29]
	v_lshlrev_b32_e32 v32, 16, v4
	v_and_b32_e32 v33, 0xffff0000, v4
	v_rcp_f32_e32 v30, v16
	v_mul_f32_e32 v16, 0xbfb8aa3b, v27
	v_pk_fma_f32 v[28:29], v[64:65], v[32:33], v[28:29]
	v_lshlrev_b32_e32 v32, 16, v0
	v_and_b32_e32 v33, 0xffff0000, v0
	v_exp_f32_e32 v16, v16
	v_pk_fma_f32 v[28:29], v[90:91], v[32:33], v[28:29]
	v_pk_mul_f32 v[94:95], v[38:39], v[124:125] op_sel_hi:[0,1]
	v_mul_f32_e32 v0, 0xbfb8aa3b, v28
	v_exp_f32_e32 v0, v0
	v_lshlrev_b32_e32 v20, 16, v21
	v_and_b32_e32 v21, 0xffff0000, v21
	v_pk_mul_f32 v[126:127], v[38:39], v[126:127] op_sel_hi:[0,1]
	v_add_f32_e32 v16, 1.0, v16
	v_pk_fma_f32 v[20:21], v[94:95], v[20:21], v[24:25]
	v_pk_fma_f32 v[10:11], v[126:127], v[14:15], v[10:11]
	v_rcp_f32_e32 v31, v16
	v_mul_f32_e32 v16, 0xbfb8aa3b, v20
	v_mul_f32_e32 v14, 0xbfb8aa3b, v10
	v_mul_f32_e32 v15, 0xbfb8aa3b, v11
	v_exp_f32_e32 v16, v16
	v_add_f32_e32 v0, 1.0, v0
	v_exp_f32_e32 v14, v14
	v_exp_f32_e32 v15, v15
	v_rcp_f32_e32 v32, v0
	v_mul_f32_e32 v0, 0xbfb8aa3b, v29
	v_exp_f32_e32 v0, v0
	v_add_f32_e32 v16, 1.0, v16
	v_lshlrev_b32_e32 v12, 16, v13
	v_and_b32_e32 v13, 0xffff0000, v13
	v_add_f32_e32 v14, 1.0, v14
	v_add_f32_e32 v15, 1.0, v15
	v_rcp_f32_e32 v24, v16
	v_mul_f32_e32 v16, 0xbfb8aa3b, v21
	v_pk_fma_f32 v[12:13], v[34:35], v[12:13], 0 op_sel_hi:[1,1,0]
	v_lshlrev_b32_e32 v8, 16, v9
	v_and_b32_e32 v9, 0xffff0000, v9
	v_rcp_f32_e32 v14, v14
	v_rcp_f32_e32 v15, v15
	v_exp_f32_e32 v16, v16
	v_add_f32_e32 v0, 1.0, v0
	v_pk_fma_f32 v[8:9], v[36:37], v[8:9], v[12:13]
	v_lshlrev_b32_e32 v4, 16, v5
	v_and_b32_e32 v5, 0xffff0000, v5
	v_pk_mul_f32 v[76:77], v[38:39], v[120:121] op_sel_hi:[0,1]
	v_mul_f32_e32 v6, 0xbfb8aa3b, v3
	v_rcp_f32_e32 v33, v0
	v_pk_fma_f32 v[4:5], v[58:59], v[4:5], v[8:9]
	v_lshlrev_b32_e32 v0, 16, v1
	v_and_b32_e32 v1, 0xffff0000, v1
	v_exp_f32_e32 v6, v6
	v_pk_fma_f32 v[0:1], v[76:77], v[0:1], v[4:5]
	v_pk_mul_f32 v[10:11], v[10:11], v[14:15]
	v_mul_f32_e32 v4, 0xbfb8aa3b, v0
	v_mul_f32_e32 v5, 0xbfb8aa3b, v1
	v_add_f32_e32 v16, 1.0, v16
	v_exp_f32_e32 v4, v4
	v_exp_f32_e32 v5, v5
	v_pk_mul_f32 v[14:15], v[10:11], v[10:11]
	v_pk_mul_f32 v[18:19], v[18:19], v[22:23]
	v_rcp_f32_e32 v25, v16
	v_add_f32_e32 v6, 1.0, v6
	v_pk_mul_f32 v[22:23], v[18:19], v[18:19]
	v_add_f32_e32 v8, v14, v15
	v_rcp_f32_e32 v7, v6
	v_mul_f32_e32 v6, 0xbfb8aa3b, v2
	v_pk_mul_f32 v[26:27], v[26:27], v[30:31]
	v_add_f32_e32 v8, v22, v8
	v_exp_f32_e32 v6, v6
	v_pk_mul_f32 v[30:31], v[26:27], v[26:27]
	v_add_f32_e32 v4, 1.0, v4
	v_add_f32_e32 v5, 1.0, v5
	v_add_f32_e32 v8, v23, v8
	v_pk_mul_f32 v[20:21], v[20:21], v[24:25]
	v_rcp_f32_e32 v4, v4
	v_rcp_f32_e32 v5, v5
	v_add_f32_e32 v8, v30, v8
	v_pk_mul_f32 v[24:25], v[20:21], v[20:21]
	v_add_f32_e32 v8, v31, v8
	v_pk_mul_f32 v[28:29], v[28:29], v[32:33]
	v_add_f32_e32 v8, v24, v8
	v_add_f32_e32 v6, 1.0, v6
	v_pk_mul_f32 v[32:33], v[28:29], v[28:29]
	v_add_f32_e32 v8, v25, v8
	v_rcp_f32_e32 v6, v6
	v_pk_mul_f32 v[0:1], v[0:1], v[4:5]
	v_add_f32_e32 v8, v32, v8
	v_pk_mul_f32 v[4:5], v[0:1], v[0:1]
	v_add_f32_e32 v8, v33, v8
	v_pk_mul_f32 v[74:75], v[74:75], v[84:85]
	v_add_f32_e32 v4, v4, v8
	v_pk_mul_f32 v[84:85], v[74:75], v[74:75]
	v_add_f32_e32 v4, v5, v4
	v_pk_mul_f32 v[2:3], v[2:3], v[6:7]
	v_add_f32_e32 v4, v84, v4
	v_pk_mul_f32 v[6:7], v[2:3], v[2:3]
	v_add_f32_e32 v4, v85, v4
	v_add_f32_e32 v4, v6, v4
	v_add_f32_e32 v4, v7, v4
	ds_bpermute_b32 v5, v45, v4
	v_or_b32_e32 v34, 0x400, v39
	s_waitcnt lgkmcnt(0)
	v_add_f32_e32 v4, v4, v5
	ds_bpermute_b32 v5, v112, v4
	s_waitcnt lgkmcnt(0)
	v_add_f32_e32 v4, v4, v5
	ds_bpermute_b32 v5, v113, v4
	s_waitcnt lgkmcnt(0)
	v_add_f32_e32 v4, v4, v5
	v_add_f32_e32 v4, 0x358637bd, v4
	v_cmp_gt_f32_e32 vcc, s33, v4
	v_mul_f32_e32 v5, 0x4b800000, v4
	s_nop 0
	v_cndmask_b32_e32 v4, v4, v5, vcc
	v_rsq_f32_e32 v4, v4
	s_nop 0
	v_mul_f32_e32 v5, 0x45800000, v4
	v_cndmask_b32_e32 v16, v4, v5, vcc
	v_pk_mul_f32 v[4:5], v[10:11], v[16:17] op_sel_hi:[1,0]
	v_pk_mul_f32 v[6:7], v[18:19], v[16:17] op_sel_hi:[1,0]
	v_pk_mul_f32 v[8:9], v[26:27], v[16:17] op_sel_hi:[1,0]
	v_pk_mul_f32 v[10:11], v[20:21], v[16:17] op_sel_hi:[1,0]
	v_pk_mul_f32 v[12:13], v[28:29], v[16:17] op_sel_hi:[1,0]
	v_pk_mul_f32 v[14:15], v[0:1], v[16:17] op_sel_hi:[1,0]
	v_pk_mul_f32 v[0:1], v[74:75], v[16:17] op_sel_hi:[1,0]
	v_pk_mul_f32 v[2:3], v[2:3], v[16:17] op_sel_hi:[1,0]
	v_cvt_pk_bf16_f32 v16, v4, v5
	v_cvt_pk_bf16_f32 v18, v6, v7
	ds_write2_b32 v43, v16, v18 offset1:1
	v_cvt_pk_bf16_f32 v16, v8, v9
	v_cvt_pk_bf16_f32 v18, v10, v11
	ds_write2_b32 v43, v16, v18 offset0:2 offset1:3
	v_cvt_pk_bf16_f32 v16, v12, v13
	v_cvt_pk_bf16_f32 v18, v14, v15
	ds_write2_b32 v43, v16, v18 offset0:4 offset1:5
	v_cvt_pk_bf16_f32 v16, v0, v1
	v_cvt_pk_bf16_f32 v18, v2, v3
	ds_write2_b32 v43, v16, v18 offset0:6 offset1:7
	ds_write_b128 v110, v[4:7] offset:35328
	ds_write_b128 v110, v[8:11] offset:35344
	ds_write_b128 v110, v[12:15] offset:35360
	ds_write_b128 v110, v[0:3] offset:35376
	v_lshlrev_b32_e32 v16, 1, v34
	v_lshl_add_u64 v[0:1], v[46:47], 0, v[16:17]
	global_load_dwordx4 v[12:15], v[0:1], off
	global_load_dwordx4 v[30:33], v[0:1], off offset:16
	v_lshl_add_u64 v[0:1], v[48:49], 0, v[16:17]
	global_load_dwordx4 v[8:11], v[0:1], off
	global_load_dwordx4 v[26:29], v[0:1], off offset:16
	v_lshl_add_u64 v[0:1], v[50:51], 0, v[16:17]
	v_lshl_add_u64 v[18:19], v[52:53], 0, v[16:17]
	global_load_dwordx4 v[4:7], v[0:1], off
	global_load_dwordx4 v[22:25], v[0:1], off offset:16
	s_nop 0
	global_load_dwordx4 v[0:3], v[18:19], off
	s_nop 0
	global_load_dwordx4 v[18:21], v[18:19], off offset:16
	s_mov_b32 s8, 0
	s_ashr_i32 s9, s8, 31
	s_lshl_b64 s[8:9], s[8:9], 3
	s_add_u32 s8, s0, s8
	s_addc_u32 s9, s1, s9
	s_load_dwordx2 s[8:9], s[8:9], 0x90
	v_lshlrev_b32_e32 v16, 2, v34
	v_cmp_gt_u32_e32 vcc, 64, v106
	s_waitcnt lgkmcnt(0)
	s_add_u32 s98, s8, s16
	s_addc_u32 s99, s9, s17
	s_add_u32 s100, s8, s18
	s_addc_u32 s101, s9, s19
	s_add_u32 s30, s8, s22
	s_addc_u32 s31, s9, s23
	s_add_u32 s8, s8, s15
	s_addc_u32 s9, s9, s14
	global_load_dwordx4 v[52:55], v16, s[8:9] offset:48
	global_load_dwordx4 v[56:59], v16, s[8:9] offset:32
	global_load_dwordx4 v[48:51], v16, s[8:9] offset:16
	global_load_dwordx4 v[34:37], v16, s[8:9]
	global_load_dwordx4 v[140:143], v16, s[98:99] offset:48
	global_load_dwordx4 v[144:147], v16, s[98:99] offset:32
	global_load_dwordx4 v[148:151], v16, s[98:99] offset:16
	global_load_dwordx4 v[152:155], v16, s[98:99]
	global_load_dwordx4 v[156:159], v16, s[100:101] offset:48
	global_load_dwordx4 v[160:163], v16, s[100:101] offset:32
	global_load_dwordx4 v[164:167], v16, s[100:101] offset:16
	global_load_dwordx4 v[168:171], v16, s[100:101]
	global_load_dwordx4 v[172:175], v16, s[30:31] offset:48
	global_load_dwordx4 v[176:179], v16, s[30:31] offset:32
	global_load_dwordx4 v[180:183], v16, s[30:31] offset:16
	global_load_dwordx4 v[184:187], v16, s[30:31]
	s_mov_b32 s8, 0
	s_ashr_i32 s9, s8, 31
	s_lshl_b64 s[8:9], s[8:9], 3
	s_add_u32 s8, s0, s8
	s_addc_u32 s9, s1, s9
	s_load_dwordx2 s[8:9], s[8:9], 0x90
	s_waitcnt lgkmcnt(0)
	s_add_u32 s8, s8, s16
	s_addc_u32 s9, s9, s17
	s_waitcnt vmcnt(0)
	v_pk_mul_f32 v[70:71], v[44:45], v[52:53] op_sel_hi:[0,1]
	v_pk_mul_f32 v[56:57], v[44:45], v[56:57] op_sel_hi:[0,1]
	v_pk_mul_f32 v[48:49], v[44:45], v[48:49] op_sel_hi:[0,1]
	v_pk_mul_f32 v[34:35], v[44:45], v[34:35] op_sel_hi:[0,1]
	v_pk_mul_f32 v[36:37], v[44:45], v[36:37] op_sel_hi:[0,1]
	v_pk_mul_f32 v[50:51], v[44:45], v[50:51] op_sel_hi:[0,1]
	v_pk_mul_f32 v[62:63], v[44:45], v[58:59] op_sel_hi:[0,1]
	v_pk_mul_f32 v[78:79], v[44:45], v[54:55] op_sel_hi:[0,1]
	v_mov_b64_e32 v[66:67], v[140:141]
	v_mov_b64_e32 v[68:69], v[142:143]
	v_mov_b64_e32 v[72:73], v[144:145]
	v_mov_b64_e32 v[74:75], v[146:147]
	v_mov_b64_e32 v[58:59], v[148:149]
	v_mov_b64_e32 v[60:61], v[150:151]
	v_mov_b64_e32 v[44:45], v[152:153]
	v_mov_b64_e32 v[46:47], v[154:155]
	s_mov_b32 s8, 0
	s_ashr_i32 s9, s8, 31
	s_lshl_b64 s[8:9], s[8:9], 3
	s_add_u32 s8, s0, s8
	s_addc_u32 s9, s1, s9
	s_load_dwordx2 s[8:9], s[8:9], 0x90
	s_waitcnt lgkmcnt(0)
	s_add_u32 s8, s8, s18
	s_addc_u32 s9, s9, s19
	s_waitcnt vmcnt(3)
	v_pk_mul_f32 v[80:81], v[42:43], v[66:67] op_sel_hi:[0,1]
	s_waitcnt vmcnt(2)
	v_pk_mul_f32 v[64:65], v[42:43], v[72:73] op_sel_hi:[0,1]
	v_pk_mul_f32 v[72:73], v[42:43], v[74:75] op_sel_hi:[0,1]
	v_pk_mul_f32 v[86:87], v[42:43], v[68:69] op_sel_hi:[0,1]
	v_mov_b64_e32 v[88:89], v[156:157]
	v_mov_b64_e32 v[90:91], v[158:159]
	v_mov_b64_e32 v[74:75], v[160:161]
	v_mov_b64_e32 v[76:77], v[162:163]
	v_mov_b64_e32 v[66:67], v[164:165]
	v_mov_b64_e32 v[68:69], v[166:167]
	v_mov_b64_e32 v[82:83], v[168:169]
	v_mov_b64_e32 v[84:85], v[170:171]
	s_mov_b32 s8, 0
	s_ashr_i32 s9, s8, 31
	s_lshl_b64 s[8:9], s[8:9], 3
	s_add_u32 s8, s0, s8
	s_addc_u32 s9, s1, s9
	s_load_dwordx2 s[8:9], s[8:9], 0x90
	s_waitcnt vmcnt(4)
	v_pk_mul_f32 v[44:45], v[42:43], v[44:45] op_sel_hi:[0,1]
	v_pk_mul_f32 v[46:47], v[42:43], v[46:47] op_sel_hi:[0,1]
	v_pk_mul_f32 v[54:55], v[42:43], v[58:59] op_sel_hi:[0,1]
	v_pk_mul_f32 v[58:59], v[42:43], v[60:61] op_sel_hi:[0,1]
	s_waitcnt lgkmcnt(0)
	s_add_u32 s8, s8, s22
	s_addc_u32 s9, s9, s23
	v_mov_b64_e32 v[92:93], v[172:173]
	v_mov_b64_e32 v[94:95], v[174:175]
	v_mov_b64_e32 v[96:97], v[176:177]
	v_mov_b64_e32 v[98:99], v[178:179]
	v_mov_b64_e32 v[100:101], v[180:181]
	v_mov_b64_e32 v[102:103], v[182:183]
	v_mov_b64_e32 v[112:113], v[184:185]
	v_mov_b64_e32 v[114:115], v[186:187]
	s_waitcnt vmcnt(7)
	v_pk_mul_f32 v[88:89], v[40:41], v[88:89] op_sel_hi:[0,1]
	s_waitcnt vmcnt(6)
	v_pk_mul_f32 v[74:75], v[40:41], v[74:75] op_sel_hi:[0,1]
	s_waitcnt vmcnt(5)
	v_pk_mul_f32 v[60:61], v[40:41], v[66:67] op_sel_hi:[0,1]
	s_waitcnt vmcnt(4)
	v_pk_mul_f32 v[42:43], v[40:41], v[82:83] op_sel_hi:[0,1]
	v_pk_mul_f32 v[52:53], v[40:41], v[84:85] op_sel_hi:[0,1]
	v_pk_mul_f32 v[66:67], v[40:41], v[68:69] op_sel_hi:[0,1]
	v_pk_mul_f32 v[82:83], v[40:41], v[76:77] op_sel_hi:[0,1]
	v_pk_mul_f32 v[40:41], v[40:41], v[90:91] op_sel_hi:[0,1]
	s_waitcnt vmcnt(3)
	v_pk_mul_f32 v[92:93], v[38:39], v[92:93] op_sel_hi:[0,1]
	s_waitcnt vmcnt(2)
	v_pk_mul_f32 v[96:97], v[38:39], v[96:97] op_sel_hi:[0,1]
	s_waitcnt vmcnt(1)
	v_pk_mul_f32 v[84:85], v[38:39], v[100:101] op_sel_hi:[0,1]
	s_waitcnt vmcnt(0)
	v_pk_mul_f32 v[68:69], v[38:39], v[112:113] op_sel_hi:[0,1]
	v_pk_mul_f32 v[76:77], v[38:39], v[114:115] op_sel_hi:[0,1]
	v_pk_mul_f32 v[90:91], v[38:39], v[102:103] op_sel_hi:[0,1]
	v_pk_mul_f32 v[98:99], v[38:39], v[98:99] op_sel_hi:[0,1]
	v_pk_mul_f32 v[38:39], v[38:39], v[94:95] op_sel_hi:[0,1]
	v_lshlrev_b32_e32 v94, 16, v33
	v_and_b32_e32 v95, 0xffff0000, v33
	v_pk_fma_f32 v[78:79], v[78:79], v[94:95], 0 op_sel_hi:[1,1,0]
	v_lshlrev_b32_e32 v94, 16, v29
	v_and_b32_e32 v95, 0xffff0000, v29
	v_pk_fma_f32 v[78:79], v[86:87], v[94:95], v[78:79]
	v_lshlrev_b32_e32 v86, 16, v25
	v_and_b32_e32 v87, 0xffff0000, v25
	v_pk_fma_f32 v[40:41], v[40:41], v[86:87], v[78:79]
	v_lshlrev_b32_e32 v78, 16, v21
	v_and_b32_e32 v79, 0xffff0000, v21
	v_pk_fma_f32 v[38:39], v[38:39], v[78:79], v[40:41]
	v_lshlrev_b32_e32 v78, 16, v32
	v_and_b32_e32 v79, 0xffff0000, v32
	v_pk_fma_f32 v[32:33], v[70:71], v[78:79], 0 op_sel_hi:[1,1,0]
	v_lshlrev_b32_e32 v70, 16, v28
	v_and_b32_e32 v71, 0xffff0000, v28
	v_pk_fma_f32 v[28:29], v[80:81], v[70:71], v[32:33]
	v_lshlrev_b32_e32 v32, 16, v24
	v_and_b32_e32 v33, 0xffff0000, v24
	v_pk_fma_f32 v[24:25], v[88:89], v[32:33], v[28:29]
	v_lshlrev_b32_e32 v28, 16, v20
	v_and_b32_e32 v29, 0xffff0000, v20
	v_pk_fma_f32 v[20:21], v[92:93], v[28:29], v[24:25]
	v_lshlrev_b32_e32 v28, 16, v31
	v_and_b32_e32 v29, 0xffff0000, v31
	v_pk_fma_f32 v[28:29], v[62:63], v[28:29], 0 op_sel_hi:[1,1,0]
	v_lshlrev_b32_e32 v62, 16, v30
	v_and_b32_e32 v63, 0xffff0000, v30
	v_pk_fma_f32 v[30:31], v[56:57], v[62:63], 0 op_sel_hi:[1,1,0]
	v_lshlrev_b32_e32 v56, 16, v26
	v_and_b32_e32 v57, 0xffff0000, v26
	v_lshlrev_b32_e32 v32, 16, v27
	v_and_b32_e32 v33, 0xffff0000, v27
	v_pk_fma_f32 v[26:27], v[64:65], v[56:57], v[30:31]
	v_lshlrev_b32_e32 v30, 16, v22
	v_and_b32_e32 v31, 0xffff0000, v22
	v_pk_fma_f32 v[28:29], v[72:73], v[32:33], v[28:29]
	v_lshlrev_b32_e32 v32, 16, v23
	v_and_b32_e32 v33, 0xffff0000, v23
	v_pk_fma_f32 v[22:23], v[74:75], v[30:31], v[26:27]
	v_lshlrev_b32_e32 v26, 16, v18
	v_and_b32_e32 v27, 0xffff0000, v18
	v_pk_fma_f32 v[28:29], v[82:83], v[32:33], v[28:29]
	v_lshlrev_b32_e32 v32, 16, v19
	v_and_b32_e32 v33, 0xffff0000, v19
	v_pk_fma_f32 v[18:19], v[96:97], v[26:27], v[22:23]
	v_lshlrev_b32_e32 v26, 16, v15
	v_and_b32_e32 v27, 0xffff0000, v15
	v_pk_fma_f32 v[26:27], v[50:51], v[26:27], 0 op_sel_hi:[1,1,0]
	v_lshlrev_b32_e32 v50, 16, v14
	v_and_b32_e32 v51, 0xffff0000, v14
	v_mul_f32_e32 v16, 0xbfb8aa3b, v39
	v_lshlrev_b32_e32 v30, 16, v11
	v_and_b32_e32 v31, 0xffff0000, v11
	v_pk_fma_f32 v[14:15], v[48:49], v[50:51], 0 op_sel_hi:[1,1,0]
	v_lshlrev_b32_e32 v48, 16, v10
	v_and_b32_e32 v49, 0xffff0000, v10
	v_exp_f32_e32 v16, v16
	v_pk_fma_f32 v[26:27], v[58:59], v[30:31], v[26:27]
	v_lshlrev_b32_e32 v30, 16, v7
	v_and_b32_e32 v31, 0xffff0000, v7
	v_pk_fma_f32 v[10:11], v[54:55], v[48:49], v[14:15]
	v_lshlrev_b32_e32 v14, 16, v6
	v_and_b32_e32 v15, 0xffff0000, v6
	v_pk_fma_f32 v[26:27], v[66:67], v[30:31], v[26:27]
	v_lshlrev_b32_e32 v30, 16, v3
	v_and_b32_e32 v31, 0xffff0000, v3
	v_pk_fma_f32 v[6:7], v[60:61], v[14:15], v[10:11]
	v_lshlrev_b32_e32 v10, 16, v2
	v_and_b32_e32 v11, 0xffff0000, v2
	v_pk_fma_f32 v[26:27], v[90:91], v[30:31], v[26:27]
	v_pk_fma_f32 v[6:7], v[84:85], v[10:11], v[6:7]
	v_mul_f32_e32 v3, 0xbfb8aa3b, v27
	v_mul_f32_e32 v2, 0xbfb8aa3b, v7
	v_add_f32_e32 v16, 1.0, v16
	v_exp_f32_e32 v3, v3
	v_exp_f32_e32 v2, v2
	v_rcp_f32_e32 v41, v16
	v_mul_f32_e32 v16, 0xbfb8aa3b, v38
	v_exp_f32_e32 v16, v16
	v_add_f32_e32 v3, 1.0, v3
	v_add_f32_e32 v2, 1.0, v2
	v_rcp_f32_e32 v31, v3
	v_mul_f32_e32 v3, 0xbfb8aa3b, v26
	v_rcp_f32_e32 v11, v2
	v_mul_f32_e32 v2, 0xbfb8aa3b, v6
	v_add_f32_e32 v16, 1.0, v16
	v_exp_f32_e32 v3, v3
	v_exp_f32_e32 v2, v2
	v_rcp_f32_e32 v40, v16
	v_mul_f32_e32 v16, 0xbfb8aa3b, v21
	v_exp_f32_e32 v16, v16
	v_add_f32_e32 v3, 1.0, v3
	v_add_f32_e32 v2, 1.0, v2
	v_rcp_f32_e32 v30, v3
	v_rcp_f32_e32 v10, v2
	v_lshlrev_b32_e32 v2, 16, v13
	v_and_b32_e32 v3, 0xffff0000, v13
	v_add_f32_e32 v16, 1.0, v16
	v_pk_fma_f32 v[2:3], v[36:37], v[2:3], 0 op_sel_hi:[1,1,0]
	v_lshlrev_b32_e32 v14, 16, v9
	v_and_b32_e32 v15, 0xffff0000, v9
	v_rcp_f32_e32 v25, v16
	v_mul_f32_e32 v16, 0xbfb8aa3b, v20
	v_pk_fma_f32 v[2:3], v[46:47], v[14:15], v[2:3]
	v_lshlrev_b32_e32 v14, 16, v5
	v_and_b32_e32 v15, 0xffff0000, v5
	v_exp_f32_e32 v16, v16
	v_pk_fma_f32 v[2:3], v[52:53], v[14:15], v[2:3]
	v_lshlrev_b32_e32 v14, 16, v1
	v_and_b32_e32 v15, 0xffff0000, v1
	v_pk_fma_f32 v[2:3], v[76:77], v[14:15], v[2:3]
	v_add_f32_e32 v16, 1.0, v16
	v_mul_f32_e32 v1, 0xbfb8aa3b, v3
	v_exp_f32_e32 v1, v1
	v_pk_fma_f32 v[28:29], v[98:99], v[32:33], v[28:29]
	v_rcp_f32_e32 v24, v16
	v_mul_f32_e32 v16, 0xbfb8aa3b, v29
	v_exp_f32_e32 v16, v16
	v_add_f32_e32 v1, 1.0, v1
	v_rcp_f32_e32 v15, v1
	v_mul_f32_e32 v1, 0xbfb8aa3b, v2
	v_exp_f32_e32 v1, v1
	v_add_f32_e32 v16, 1.0, v16
	v_lshlrev_b32_e32 v36, 16, v12
	v_and_b32_e32 v37, 0xffff0000, v12
	v_rcp_f32_e32 v33, v16
	v_mul_f32_e32 v16, 0xbfb8aa3b, v28
	v_pk_fma_f32 v[12:13], v[34:35], v[36:37], 0 op_sel_hi:[1,1,0]
	v_lshlrev_b32_e32 v34, 16, v8
	v_and_b32_e32 v35, 0xffff0000, v8
	v_exp_f32_e32 v16, v16
	v_pk_fma_f32 v[8:9], v[44:45], v[34:35], v[12:13]
	v_lshlrev_b32_e32 v12, 16, v4
	v_and_b32_e32 v13, 0xffff0000, v4
	v_add_f32_e32 v1, 1.0, v1
	v_pk_fma_f32 v[4:5], v[42:43], v[12:13], v[8:9]
	v_lshlrev_b32_e32 v8, 16, v0
	v_and_b32_e32 v9, 0xffff0000, v0
	v_rcp_f32_e32 v14, v1
	v_pk_fma_f32 v[0:1], v[68:69], v[8:9], v[4:5]
	v_add_f32_e32 v16, 1.0, v16
	v_mul_f32_e32 v4, 0xbfb8aa3b, v1
	v_exp_f32_e32 v4, v4
	v_rcp_f32_e32 v32, v16
	v_mul_f32_e32 v16, 0xbfb8aa3b, v19
	v_exp_f32_e32 v16, v16
	v_add_f32_e32 v4, 1.0, v4
	v_rcp_f32_e32 v5, v4
	v_mul_f32_e32 v4, 0xbfb8aa3b, v0
	v_add_f32_e32 v16, 1.0, v16
	v_exp_f32_e32 v4, v4
	v_rcp_f32_e32 v23, v16
	v_mul_f32_e32 v16, 0xbfb8aa3b, v18
	v_exp_f32_e32 v16, v16
	v_add_f32_e32 v4, 1.0, v4
	v_rcp_f32_e32 v4, v4
	v_pk_mul_f32 v[2:3], v[2:3], v[14:15]
	v_add_f32_e32 v16, 1.0, v16
	v_rcp_f32_e32 v22, v16
	v_pk_mul_f32 v[0:1], v[0:1], v[4:5]
	ds_write_b128 v110, v[0:3] offset:34816
	v_pk_mul_f32 v[0:1], v[6:7], v[10:11]
	v_pk_mul_f32 v[2:3], v[26:27], v[30:31]
	ds_write_b128 v110, v[0:3] offset:34832
	v_pk_mul_f32 v[0:1], v[18:19], v[22:23]
	v_pk_mul_f32 v[2:3], v[28:29], v[32:33]
	ds_write_b128 v110, v[0:3] offset:34848
	v_pk_mul_f32 v[0:1], v[20:21], v[24:25]
	v_pk_mul_f32 v[2:3], v[38:39], v[40:41]
	v_lshl_add_u32 v44, v106, 2, 0
	ds_write_b128 v110, v[0:3] offset:34864
	s_and_saveexec_b64 s[8:9], vcc
	s_cbranch_execz .LBB0_763
	v_or_b32_e32 v0, s5, v106
	v_ashrrev_i32_e32 v1, 31, v0
	v_lshlrev_b64 v[0:1], 5, v[0:1]
	v_lshl_add_u64 v[0:1], s[42:43], 0, v[0:1]
	s_lshl_b32 s52, s37, 2
	v_lshl_add_u64 v[0:1], v[0:1], 0, s[52:53]
	global_load_dword v2, v[0:1], off offset:16
	s_nop 0
	global_load_dword v0, v[0:1], off
	s_mov_b32 s38, 0
	s_ashr_i32 s39, s38, 31
	s_lshl_b64 s[38:39], s[38:39], 3
	s_add_u32 s38, s0, s38
	s_addc_u32 s39, s1, s39
	s_load_dwordx2 s[38:39], s[38:39], 0x98
	s_or_b32 s48, s37, s35
	s_ashr_i32 s49, s48, 31
	s_lshl_b64 s[48:49], s[48:49], 2
	s_mov_b32 s2, 0xbfb8aa3b
	s_waitcnt lgkmcnt(0)
	s_add_u32 s38, s38, s48
	s_addc_u32 s39, s39, s49
	global_load_dword v1, v17, s[38:39]
	s_mov_b32 s38, 0
	s_ashr_i32 s39, s38, 31
	s_lshl_b64 s[38:39], s[38:39], 3
	s_add_u32 s38, s0, s38
	s_addc_u32 s39, s1, s39
	s_load_dwordx2 s[38:39], s[38:39], 0xa0
	s_waitcnt lgkmcnt(0)
	s_add_u32 s38, s38, s48
	s_addc_u32 s39, s39, s49
	global_load_dword v3, v17, s[38:39]
	s_waitcnt vmcnt(0)
	v_mul_f32_e32 v0, 0xbfb8aa3b, v0
	v_exp_f32_e32 v0, v0
	v_mul_f32_e32 v1, 0x3fb8aa3b, v1
	v_exp_f32_e32 v1, v1
	v_add_f32_e32 v0, 1.0, v0
	v_rcp_f32_e32 v0, v0
	v_add_f32_e32 v2, v2, v3
	v_max_f32_e32 v4, 0, v2
	v_mul_f32_e64 v2, |v2|, s2
	v_exp_f32_e32 v5, v2
	s_mov_b32 s2, 0x3f2aaaab
	v_add_f32_e32 v6, 1.0, v5
	v_add_f32_e32 v2, -1.0, v6
	v_sub_f32_e32 v3, v2, v6
	v_add_f32_e32 v3, 1.0, v3
	v_sub_f32_e32 v2, v5, v2
	v_add_f32_e32 v7, v2, v3
	v_frexp_mant_f32_e32 v2, v6
	v_cmp_gt_f32_e32 vcc, s2, v2
	v_cvt_f64_f32_e32 v[2:3], v6
	v_frexp_exp_i32_f64_e32 v2, v[2:3]
	v_subbrev_co_u32_e32 v2, vcc, 0, v2, vcc
	v_sub_u32_e32 v3, 0, v2
	v_ldexp_f32 v6, v6, v3
	v_ldexp_f32 v3, v7, v3
	v_add_f32_e32 v7, -1.0, v6
	v_add_f32_e32 v8, 1.0, v7
	v_sub_f32_e32 v8, v6, v8
	v_add_f32_e32 v8, v3, v8
	v_add_f32_e32 v9, v7, v8
	v_sub_f32_e32 v7, v9, v7
	v_sub_f32_e32 v7, v8, v7
	v_add_f32_e32 v8, 1.0, v6
	v_add_f32_e32 v10, -1.0, v8
	v_sub_f32_e32 v6, v6, v10
	v_add_f32_e32 v3, v3, v6
	v_add_f32_e32 v6, v8, v3
	v_sub_f32_e32 v8, v6, v8
	v_sub_f32_e32 v3, v3, v8
	v_rcp_f32_e32 v8, v6
	v_cvt_f32_i32_e32 v2, v2
	s_mov_b32 s2, 0x3f317218
	v_mul_f32_e32 v10, v9, v8
	v_mul_f32_e32 v11, v6, v10
	v_fma_f32 v12, v10, v6, -v11
	v_fmac_f32_e32 v12, v10, v3
	v_add_f32_e32 v13, v11, v12
	v_sub_f32_e32 v14, v9, v13
	v_sub_f32_e32 v9, v9, v14
	v_sub_f32_e32 v11, v13, v11
	v_sub_f32_e32 v9, v9, v13
	v_add_f32_e32 v7, v7, v9
	v_sub_f32_e32 v9, v11, v12
	v_add_f32_e32 v7, v9, v7
	v_add_f32_e32 v9, v14, v7
	v_mul_f32_e32 v11, v8, v9
	v_mul_f32_e32 v12, v6, v11
	v_fma_f32 v6, v11, v6, -v12
	v_fmac_f32_e32 v6, v11, v3
	v_sub_f32_e32 v3, v14, v9
	v_add_f32_e32 v3, v7, v3
	v_add_f32_e32 v7, v12, v6
	v_sub_f32_e32 v13, v9, v7
	v_sub_f32_e32 v9, v9, v13
	v_sub_f32_e32 v12, v7, v12
	v_sub_f32_e32 v7, v9, v7
	v_add_f32_e32 v3, v3, v7
	v_sub_f32_e32 v6, v12, v6
	v_add_f32_e32 v3, v6, v3
	v_add_f32_e32 v6, v10, v11
	v_add_f32_e32 v3, v13, v3
	v_sub_f32_e32 v7, v6, v10
	v_mul_f32_e32 v3, v8, v3
	v_sub_f32_e32 v7, v11, v7
	v_add_f32_e32 v3, v7, v3
	v_mul_f32_e32 v10, 0x3f317218, v2
	v_add_f32_e32 v7, v6, v3
	v_fma_f32 v11, v2, s2, -v10
	v_mul_f32_e32 v8, v7, v7
	v_fmac_f32_e32 v11, 0xb102e308, v2
	v_sub_f32_e32 v2, v7, v6
	v_fmamk_f32 v9, v8, 0x3e9b6dac, v232
	v_sub_f32_e32 v2, v3, v2
	v_add_f32_e32 v3, v10, v11
	v_fmaak_f32 v9, v8, v9, 0x3f2aaada
	v_sub_f32_e32 v6, v3, v10
	v_ldexp_f32 v10, v7, 1
	v_mul_f32_e32 v7, v7, v8
	v_mul_f32_e32 v7, v7, v9
	v_add_f32_e32 v8, v10, v7
	v_sub_f32_e32 v9, v8, v10
	v_ldexp_f32 v2, v2, 1
	v_sub_f32_e32 v7, v7, v9
	v_add_f32_e32 v2, v2, v7
	v_add_f32_e32 v7, v8, v2
	v_sub_f32_e32 v8, v7, v8
	v_sub_f32_e32 v2, v2, v8
	v_add_f32_e32 v8, v3, v7
	v_sub_f32_e32 v9, v8, v3
	v_sub_f32_e32 v10, v8, v9
	v_sub_f32_e32 v6, v11, v6
	v_sub_f32_e32 v3, v3, v10
	v_sub_f32_e32 v7, v7, v9
	v_add_f32_e32 v3, v7, v3
	v_add_f32_e32 v7, v6, v2
	v_sub_f32_e32 v9, v7, v6
	v_sub_f32_e32 v10, v7, v9
	v_sub_f32_e32 v6, v6, v10
	v_sub_f32_e32 v2, v2, v9
	v_add_f32_e32 v3, v7, v3
	v_add_f32_e32 v2, v2, v6
	v_add_f32_e32 v6, v8, v3
	v_sub_f32_e32 v7, v6, v8
	v_sub_f32_e32 v3, v3, v7
	v_add_f32_e32 v2, v2, v3
	s_mov_b32 s2, 0x7f800000
	v_add_f32_e32 v2, v6, v2
	v_cmp_neq_f32_e32 vcc, s2, v5
	s_mov_b32 s2, 0x33800000
	s_nop 0
	v_cndmask_b32_e32 v2, v236, v2, vcc
	v_cmp_ngt_f32_e32 vcc, -1.0, v5
	s_nop 1
	v_cndmask_b32_e32 v2, v237, v2, vcc
	v_cmp_neq_f32_e32 vcc, -1.0, v5
	s_nop 1
	v_cndmask_b32_e32 v2, v238, v2, vcc
	v_cmp_lt_f32_e64 vcc, |v5|, s2
	s_nop 1
	v_cndmask_b32_e32 v2, v2, v5, vcc
	v_add_f32_e32 v2, v4, v2
	v_add_u32_e32 v4, -1, v234
	v_cmp_lt_i32_e32 vcc, v4, v111
	v_mul_f32_e64 v3, v2, -v1
	s_nop 0
	v_cndmask_b32_e32 v4, v4, v234, vcc
	v_lshlrev_b32_e32 v4, 2, v4
	ds_bpermute_b32 v4, v4, v3
	v_cmp_eq_u32_e32 vcc, 0, v106
	s_waitcnt lgkmcnt(0)
	v_fma_f32 v1, v2, -v1, v4
	v_add_u32_e32 v2, -2, v234
	v_cndmask_b32_e32 v1, v1, v3, vcc
	v_cmp_lt_i32_e32 vcc, v2, v111
	v_add_u32_e32 v3, 0x1cc00, v44
	s_nop 0
	v_cndmask_b32_e32 v2, v2, v234, vcc
	v_lshlrev_b32_e32 v2, 2, v2
	ds_bpermute_b32 v2, v2, v1
	v_cmp_gt_u32_e32 vcc, 2, v106
	s_waitcnt lgkmcnt(0)
	v_add_f32_e32 v2, v1, v2
	v_cndmask_b32_e32 v1, v2, v1, vcc
	v_add_u32_e32 v2, -4, v234
	v_cmp_lt_i32_e32 vcc, v2, v111
	s_nop 1
	v_cndmask_b32_e32 v2, v2, v234, vcc
	v_lshlrev_b32_e32 v2, 2, v2
	ds_bpermute_b32 v2, v2, v1
	v_cmp_gt_u32_e32 vcc, 4, v106
	s_waitcnt lgkmcnt(0)
	v_add_f32_e32 v2, v1, v2
	v_cndmask_b32_e32 v1, v2, v1, vcc
	v_add_u32_e32 v2, -8, v234
	v_cmp_lt_i32_e32 vcc, v2, v111
	s_nop 1
	v_cndmask_b32_e32 v2, v2, v234, vcc
	v_lshlrev_b32_e32 v2, 2, v2
	ds_bpermute_b32 v2, v2, v1
	v_cmp_gt_u32_e32 vcc, 8, v106
	s_waitcnt lgkmcnt(0)
	v_add_f32_e32 v2, v1, v2
	v_cndmask_b32_e32 v1, v2, v1, vcc
	v_add_u32_e32 v2, -16, v234
	v_cmp_lt_i32_e32 vcc, v2, v111
	s_nop 1
	v_cndmask_b32_e32 v2, v2, v234, vcc
	v_lshlrev_b32_e32 v2, 2, v2
	ds_bpermute_b32 v2, v2, v1
	v_cmp_gt_u32_e32 vcc, 16, v106
	s_waitcnt lgkmcnt(0)
	v_add_f32_e32 v2, v1, v2
	v_cndmask_b32_e32 v2, v2, v1, vcc
	v_subrev_u32_e32 v1, 32, v234
	v_cmp_lt_i32_e32 vcc, v1, v111
	s_nop 1
	v_cndmask_b32_e32 v1, v1, v234, vcc
	v_lshlrev_b32_e32 v1, 2, v1
	ds_bpermute_b32 v1, v1, v2
	v_cmp_gt_u32_e32 vcc, 32, v106
	s_waitcnt lgkmcnt(0)
	v_add_f32_e32 v1, v2, v1
	v_cndmask_b32_e32 v2, v1, v2, vcc
	ds_write_b32 v3, v2
	v_add_u32_e32 v2, 0x1cd00, v44
	v_cmp_eq_u32_e32 vcc, 63, v106
	ds_write_b32 v2, v0
	s_and_b64 exec, exec, vcc
	s_cbranch_execz .LBB0_763
	v_mul_f32_e32 v0, 0x3fb8aa3b, v1
	v_exp_f32_e32 v2, v0
	v_mov_b64_e32 v[0:1], s[92:93]
	global_store_dword v[0:1], v2, off
.LBB0_763:
	s_or_b64 exec, exec, s[8:9]
	v_lshlrev_b32_e32 v0, 2, v104
	s_add_i32 s2, 0, 0x1cc00
	v_add_u32_e32 v1, s2, v0
	v_readlane_b32 s9, v255, 3
	s_waitcnt lgkmcnt(0)
	s_barrier
	s_add_i32 s8, 0, 0x1cd00
	ds_read_b32 v45, v1
	v_mov_b32_e32 v1, s9
	v_add_u32_e32 v0, s8, v0
	ds_read_b32 v46, v1
	ds_read_b32 v16, v0
	ds_read_b128 v[4:7], v110 offset:34816
	s_waitcnt lgkmcnt(0)
	v_mul_f32_e32 v0, 0x3fb8aa3b, v45
	v_exp_f32_e32 v28, v0
	ds_read_b128 v[8:11], v110 offset:34832
	ds_read_b128 v[12:15], v110 offset:34848
	ds_read_b128 v[0:3], v110 offset:35328
	v_add_u32_e32 v66, s5, v104
	v_pk_mul_f32 v[4:5], v[16:17], v[4:5] op_sel_hi:[0,1]
	v_pk_mul_f32 v[6:7], v[16:17], v[6:7] op_sel_hi:[0,1]
	ds_write_b128 v110, v[4:7] offset:34816
	ds_read_b128 v[4:7], v110 offset:35344
	v_mul_f32_e32 v26, v16, v28
	s_waitcnt lgkmcnt(0)
	v_pk_mul_f32 v[8:9], v[16:17], v[8:9] op_sel_hi:[0,1]
	v_pk_mul_f32 v[10:11], v[16:17], v[10:11] op_sel_hi:[0,1]
	v_pk_mul_f32 v[20:21], v[2:3], v[26:27] op_sel_hi:[1,0]
	v_pk_mul_f32 v[18:19], v[0:1], v[26:27] op_sel_hi:[1,0]
	ds_write_b128 v110, v[8:11] offset:34832
	v_pk_mul_f32 v[10:11], v[26:27], v[6:7] op_sel_hi:[0,1]
	v_pk_mul_f32 v[8:9], v[26:27], v[4:5] op_sel_hi:[0,1]
	ds_write_b128 v110, v[18:21] offset:35328
	ds_write_b128 v110, v[8:11] offset:35344
	ds_read_b128 v[8:11], v110 offset:35360
	ds_read_b128 v[18:21], v110 offset:34864
	v_pk_mul_f32 v[12:13], v[16:17], v[12:13] op_sel_hi:[0,1]
	v_pk_mul_f32 v[14:15], v[16:17], v[14:15] op_sel_hi:[0,1]
	ds_write_b128 v110, v[12:15] offset:34848
	ds_read_b128 v[12:15], v110 offset:35376
	s_waitcnt lgkmcnt(0)
	v_pk_mul_f32 v[24:25], v[26:27], v[10:11] op_sel_hi:[0,1]
	v_pk_mul_f32 v[22:23], v[26:27], v[8:9] op_sel_hi:[0,1]
	v_pk_mul_f32 v[18:19], v[16:17], v[18:19] op_sel_hi:[0,1]
	v_pk_mul_f32 v[20:21], v[16:17], v[20:21] op_sel_hi:[0,1]
	v_lshlrev_b32_e32 v16, 1, v108
	ds_write_b128 v110, v[22:25] offset:35360
	v_add3_u32 v22, 0, v109, v16
	ds_write_b128 v110, v[18:21] offset:34864
	v_pk_mul_f32 v[18:19], v[26:27], v[12:13] op_sel_hi:[0,1]
	v_pk_mul_f32 v[20:21], v[26:27], v[14:15] op_sel_hi:[0,1]
	v_add_u32_e32 v26, 0x4400, v22
	ds_read2_b32 v[22:23], v26 offset1:1
	ds_write_b128 v110, v[18:21] offset:35376
	ds_read2_b32 v[20:21], v26 offset0:2 offset1:3
	ds_read2_b32 v[24:25], v26 offset0:4 offset1:5
	ds_read2_b32 v[26:27], v26 offset0:6 offset1:7
	v_ashrrev_i32_e32 v67, 31, v66
	s_lshl_b32 s52, s4, 1
	s_waitcnt lgkmcnt(0)
	v_lshlrev_b32_e32 v18, 16, v22
	v_and_b32_e32 v19, 0xffff0000, v22
	v_mul_f32_e32 v18, v28, v18
	v_mul_f32_e32 v19, v28, v19
	v_cvt_pk_bf16_f32 v18, v18, v19
	v_lshlrev_b32_e32 v19, 16, v23
	v_and_b32_e32 v22, 0xffff0000, v23
	v_mul_f32_e32 v19, v28, v19
	v_mul_f32_e32 v22, v28, v22
	v_cvt_pk_bf16_f32 v19, v19, v22
	v_lshlrev_b32_e32 v22, 16, v20
	v_and_b32_e32 v20, 0xffff0000, v20
	v_mul_f32_e32 v22, v28, v22
	v_mul_f32_e32 v20, v28, v20
	v_cvt_pk_bf16_f32 v20, v22, v20
	v_lshlrev_b32_e32 v22, 16, v21
	v_and_b32_e32 v21, 0xffff0000, v21
	v_mul_f32_e32 v22, v28, v22
	v_mul_f32_e32 v21, v28, v21
	v_cvt_pk_bf16_f32 v21, v22, v21
	v_lshlrev_b32_e32 v22, 16, v24
	v_and_b32_e32 v23, 0xffff0000, v24
	v_mul_f32_e32 v22, v28, v22
	v_mul_f32_e32 v23, v28, v23
	v_cvt_pk_bf16_f32 v22, v22, v23
	v_lshlrev_b32_e32 v23, 16, v25
	v_and_b32_e32 v24, 0xffff0000, v25
	v_mul_f32_e32 v23, v28, v23
	v_mul_f32_e32 v24, v28, v24
	v_cvt_pk_bf16_f32 v23, v23, v24
	v_lshlrev_b32_e32 v24, 16, v26
	v_and_b32_e32 v25, 0xffff0000, v26
	v_mul_f32_e32 v24, v28, v24
	v_mul_f32_e32 v25, v28, v25
	v_cvt_pk_bf16_f32 v24, v24, v25
	v_lshlrev_b32_e32 v25, 16, v27
	v_and_b32_e32 v26, 0xffff0000, v27
	v_mul_f32_e32 v25, v28, v25
	v_mul_f32_e32 v26, v28, v26
	v_cvt_pk_bf16_f32 v25, v25, v26
	v_lshlrev_b64 v[26:27], 10, v[66:67]
	v_lshl_add_u64 v[26:27], s[96:97], 0, v[26:27]
	v_lshl_add_u64 v[26:27], v[26:27], 0, s[52:53]
	v_lshl_add_u64 v[26:27], v[26:27], 0, v[16:17]
	s_add_i32 s9, 0, 0x4400
	global_store_dwordx4 v[26:27], v[18:21], off
	global_store_dwordx4 v[26:27], v[22:25], off offset:16
	v_and_b32_e32 v51, 48, v106
	v_mov_b32_e32 v18, s9
	s_movk_i32 s9, 0x100
	v_and_b32_e32 v52, 15, v106
	v_cmp_gt_u32_e32 vcc, s9, v106
	v_add_u32_e32 v53, 0, v51
	s_movk_i32 s9, 0x110
	v_mad_u32_u24 v43, v52, s9, v53
	ds_read_b128 v[26:29], v43
	v_lshrrev_b32_e32 v42, 2, v106
	v_and_or_b32 v47, v42, 48, v52
	v_cndmask_b32_e64 v18, v18, 0, vcc
	v_mul_u32_u24_e32 v19, 0x110, v47
	v_add3_u32 v49, v18, v19, v51
	ds_read_b128 v[22:25], v49
	ds_read_b128 v[18:21], v49 offset:64
	v_lshlrev_b32_e32 v50, 2, v47
	v_add_u32_e32 v30, s8, v50
	ds_read_b32 v48, v30
	s_waitcnt lgkmcnt(0)
	v_mfma_f32_16x16x32_bf16 v[26:29], v[26:29], v[22:25], 0
	ds_read_b128 v[30:33], v43 offset:64
	ds_read_b128 v[34:37], v43 offset:128
	s_waitcnt lgkmcnt(0)
	v_mfma_f32_16x16x32_bf16 v[38:41], v[30:33], v[18:21], v[26:29]
	ds_read_b128 v[54:57], v43 offset:192
	ds_read_b128 v[30:33], v49 offset:128
	s_nop 1
	ds_read_b128 v[26:29], v49 offset:192
	v_add_u32_e32 v43, s2, v50
	ds_read_b32 v49, v43
	s_waitcnt lgkmcnt(0)
	v_mfma_f32_16x16x32_bf16 v[34:37], v[34:37], v[30:33], v[38:41]
	s_movk_i32 s2, 0xff
	v_and_b32_e32 v50, 12, v42
	v_cmp_lt_u32_e32 vcc, s2, v106
	v_mfma_f32_16x16x32_bf16 v[38:41], v[54:57], v[26:29], v[34:37]
	v_cmp_ge_u32_e64 s[38:39], v47, v50
	s_nop 2
	v_mov_b32_e32 v35, 0
	s_and_saveexec_b64 s[8:9], s[38:39]
	s_cbranch_execz .LBB0_765
	v_lshl_add_u32 v34, v50, 2, 0
	v_add_u32_e32 v34, 0x1cc00, v34
	ds_read_b32 v34, v34
	s_waitcnt lgkmcnt(0)
	v_sub_f32_e32 v34, v49, v34
	v_mul_f32_e32 v34, 0x3fb8aa3b, v34
	v_exp_f32_e32 v35, v34

.LBB0_781:
	s_or_b64 exec, exec, s[8:9]
	v_or_b32_e32 v38, s5, v47
	v_ashrrev_i32_e32 v39, 31, v38
	v_lshlrev_b64 v[38:39], 9, v[38:39]
	v_lshl_add_u64 v[38:39], s[54:55], 0, v[38:39]
	s_mov_b32 s5, s53
	v_lshl_add_u64 v[38:39], v[38:39], 0, s[4:5]
	v_lshlrev_b32_e32 v40, 1, v50
	v_mov_b32_e32 v41, v17
	v_lshl_add_u64 v[42:43], v[38:39], 0, v[40:41]
	s_and_saveexec_b64 s[4:5], vcc
	s_xor_b64 s[4:5], exec, s[4:5]
	s_cbranch_execz .LBB0_783
	v_cvt_pk_bf16_f32 v34, v34, v35
	v_cvt_pk_bf16_f32 v35, v36, v37
	global_store_dwordx2 v[42:43], v[34:35], off

.LBB0_822:
	v_cvt_pk_bf16_f32 v34, v34, v35
	v_cvt_pk_bf16_f32 v35, v36, v37
	global_store_dwordx2 v[42:43], v[34:35], off offset:32
	s_andn2_saveexec_b64 s[4:5], s[4:5]
	s_cbranch_execnz .LBB0_810
	s_branch .LBB0_811

.LBB0_850:
	v_cvt_pk_bf16_f32 v34, v34, v35
	v_cvt_pk_bf16_f32 v35, v36, v37
	global_store_dwordx2 v[42:43], v[34:35], off offset:64
	s_andn2_saveexec_b64 s[4:5], s[4:5]
	s_cbranch_execnz .LBB0_838
	s_branch .LBB0_839

.LBB0_876:
	v_cvt_pk_bf16_f32 v18, v18, v19
	v_cvt_pk_bf16_f32 v19, v20, v21
	global_store_dwordx2 v[42:43], v[18:19], off offset:96
	s_andn2_saveexec_b64 s[4:5], s[4:5]
	s_cbranch_execnz .LBB0_866
	s_branch .LBB0_867

.LBB0_879:
	v_add_co_u32_e32 v4, vcc, 0xffef8800, v0
	s_movk_i32 s2, 0xc000
	s_nop 0
	v_addc_co_u32_e32 v5, vcc, -1, v1, vcc
	global_load_dword v6, v[4:5], off
	v_add_co_u32_e32 v4, vcc, 0xfff78800, v0
	s_add_i32 s8, s8, 16
	s_nop 0
	v_addc_co_u32_e32 v5, vcc, -1, v1, vcc
	global_load_dword v7, v[4:5], off
	v_add_co_u32_e32 v4, vcc, 0xffef9000, v0
	s_cmp_gt_u32 s8, 47
	s_nop 0
	v_addc_co_u32_e32 v5, vcc, -1, v1, vcc
	global_load_dword v8, v[4:5], off
	v_add_co_u32_e32 v4, vcc, 0xfff79000, v0
	s_waitcnt vmcnt(0) lgkmcnt(0)
	v_fmac_f32_e32 v7, v3, v6
	v_addc_co_u32_e32 v5, vcc, -1, v1, vcc
	global_load_dword v9, v[4:5], off
	v_add_co_u32_e32 v4, vcc, 0xffef9800, v0
	s_waitcnt vmcnt(0) lgkmcnt(0)
	v_fmac_f32_e32 v9, v7, v8
	v_addc_co_u32_e32 v5, vcc, -1, v1, vcc
	global_load_dword v10, v[4:5], off
	v_add_co_u32_e32 v4, vcc, 0xfff79800, v0
	s_nop 1
	v_addc_co_u32_e32 v5, vcc, -1, v1, vcc
	global_load_dword v11, v[4:5], off
	v_add_co_u32_e32 v4, vcc, 0xffefa000, v0
	s_waitcnt vmcnt(0) lgkmcnt(0)
	v_fmac_f32_e32 v11, v9, v10
	v_addc_co_u32_e32 v5, vcc, -1, v1, vcc
	global_load_dword v12, v[4:5], off
	v_add_co_u32_e32 v4, vcc, 0xfff7a000, v0
	s_nop 1
	v_addc_co_u32_e32 v5, vcc, -1, v1, vcc
	global_load_dword v13, v[4:5], off
	v_add_co_u32_e32 v4, vcc, 0xffefa800, v0
	s_waitcnt vmcnt(0) lgkmcnt(0)
	v_fmac_f32_e32 v13, v11, v12
	v_addc_co_u32_e32 v5, vcc, -1, v1, vcc
	global_load_dword v14, v[4:5], off
	v_add_co_u32_e32 v4, vcc, 0xfff7a800, v0
	s_nop 1
	v_addc_co_u32_e32 v5, vcc, -1, v1, vcc
	global_load_dword v15, v[4:5], off
	v_add_co_u32_e32 v4, vcc, 0xffefb000, v0
	s_waitcnt vmcnt(0) lgkmcnt(0)
	v_fmac_f32_e32 v15, v13, v14
	v_addc_co_u32_e32 v5, vcc, -1, v1, vcc
	global_load_dword v16, v[4:5], off
	v_add_co_u32_e32 v4, vcc, 0xfff7b000, v0
	s_nop 1
	v_addc_co_u32_e32 v5, vcc, -1, v1, vcc
	global_load_dword v18, v[4:5], off
	v_add_co_u32_e32 v4, vcc, 0xffefb800, v0
	s_waitcnt vmcnt(0) lgkmcnt(0)
	v_fmac_f32_e32 v18, v15, v16
	v_addc_co_u32_e32 v5, vcc, -1, v1, vcc
	global_load_dword v19, v[4:5], off
	v_add_co_u32_e32 v4, vcc, 0xfff7b800, v0
	s_nop 1
	v_addc_co_u32_e32 v5, vcc, -1, v1, vcc
	global_load_dword v20, v[4:5], off
	v_add_co_u32_e32 v4, vcc, 0xffefc000, v0
	s_waitcnt vmcnt(0) lgkmcnt(0)
	v_fmac_f32_e32 v20, v18, v19
	v_addc_co_u32_e32 v5, vcc, -1, v1, vcc
	global_load_dword v21, v[4:5], off
	v_add_co_u32_e32 v4, vcc, 0xfff7c000, v0
	s_nop 1
	v_addc_co_u32_e32 v5, vcc, -1, v1, vcc
	global_load_dword v22, v[4:5], off
	v_add_co_u32_e32 v4, vcc, 0xffefc800, v0
	s_waitcnt vmcnt(0) lgkmcnt(0)
	v_fmac_f32_e32 v22, v20, v21
	v_addc_co_u32_e32 v5, vcc, -1, v1, vcc
	global_load_dword v23, v[4:5], off
	v_add_co_u32_e32 v4, vcc, 0xfff7c800, v0
	s_nop 1
	v_addc_co_u32_e32 v5, vcc, -1, v1, vcc
	global_load_dword v24, v[4:5], off
	v_add_co_u32_e32 v4, vcc, 0xffefd000, v0
	s_waitcnt vmcnt(0) lgkmcnt(0)
	v_fmac_f32_e32 v24, v22, v23
	v_addc_co_u32_e32 v5, vcc, -1, v1, vcc
	global_load_dword v25, v[4:5], off
	v_add_co_u32_e32 v4, vcc, 0xfff7d000, v0
	s_nop 1
	v_addc_co_u32_e32 v5, vcc, -1, v1, vcc
	global_load_dword v26, v[4:5], off
	v_add_co_u32_e32 v4, vcc, 0xffefd800, v0
	s_waitcnt vmcnt(0) lgkmcnt(0)
	v_fmac_f32_e32 v26, v24, v25
	v_addc_co_u32_e32 v5, vcc, -1, v1, vcc
	global_load_dword v27, v[4:5], off
	v_add_co_u32_e32 v4, vcc, 0xfff7d800, v0
	s_nop 1
	v_addc_co_u32_e32 v5, vcc, -1, v1, vcc
	global_load_dword v28, v[4:5], off
	v_add_co_u32_e32 v4, vcc, 0xffefe000, v0
	s_waitcnt vmcnt(0) lgkmcnt(0)
	v_fmac_f32_e32 v28, v26, v27
	v_addc_co_u32_e32 v5, vcc, -1, v1, vcc
	global_load_dword v29, v[4:5], off
	v_add_co_u32_e32 v4, vcc, 0xfff7e000, v0
	s_nop 1
	v_addc_co_u32_e32 v5, vcc, -1, v1, vcc
	global_load_dword v30, v[4:5], off
	v_add_co_u32_e32 v4, vcc, 0xffefe800, v0
	s_waitcnt vmcnt(0) lgkmcnt(0)
	v_fmac_f32_e32 v30, v28, v29
	v_addc_co_u32_e32 v5, vcc, -1, v1, vcc
	global_load_dword v31, v[4:5], off
	v_add_co_u32_e32 v4, vcc, 0xfff7e800, v0
	s_nop 1
	v_addc_co_u32_e32 v5, vcc, -1, v1, vcc
	global_load_dword v32, v[4:5], off
	v_add_co_u32_e32 v4, vcc, 0xffeff000, v0
	s_waitcnt vmcnt(0) lgkmcnt(0)
	v_fmac_f32_e32 v32, v30, v31
	v_addc_co_u32_e32 v5, vcc, -1, v1, vcc
	global_load_dword v33, v[4:5], off
	v_add_co_u32_e32 v4, vcc, 0xfff7f000, v0
	s_nop 1
	v_addc_co_u32_e32 v5, vcc, -1, v1, vcc
	global_load_dword v34, v[4:5], off
	v_add_co_u32_e32 v4, vcc, 0xffeff800, v0
	s_waitcnt vmcnt(0) lgkmcnt(0)
	v_fmac_f32_e32 v34, v32, v33
	v_addc_co_u32_e32 v5, vcc, -1, v1, vcc
	global_load_dword v35, v[4:5], off
	v_add_co_u32_e32 v4, vcc, 0xfff7f800, v0
	s_nop 1
	v_addc_co_u32_e32 v5, vcc, -1, v1, vcc
	global_load_dword v36, v[4:5], off
	v_add_co_u32_e32 v4, vcc, 0xfff00000, v0
	s_waitcnt vmcnt(0) lgkmcnt(0)
	v_fmac_f32_e32 v36, v34, v35
	v_addc_co_u32_e32 v5, vcc, -1, v1, vcc
	global_load_dword v37, v[4:5], off
	v_add_co_u32_e32 v4, vcc, 0xfff80000, v0
	global_store_dword v[0:1], v36, off
	s_nop 0
	v_addc_co_u32_e32 v5, vcc, -1, v1, vcc
	global_load_dword v2, v[4:5], off
	v_add_co_u32_e32 v4, vcc, 0xffff8800, v0
	s_waitcnt vmcnt(0) lgkmcnt(0)
	v_fmac_f32_e32 v2, v36, v37
	v_addc_co_u32_e32 v5, vcc, -1, v1, vcc
	global_store_dword v[4:5], v3, off
	v_add_co_u32_e32 v4, vcc, 0xffff9000, v0
	v_mov_b32_e32 v3, v2
	s_nop 0
	v_addc_co_u32_e32 v5, vcc, -1, v1, vcc
	global_store_dword v[4:5], v7, off
	v_add_co_u32_e32 v4, vcc, 0xffff9800, v0
	s_nop 1
	v_addc_co_u32_e32 v5, vcc, -1, v1, vcc
	global_store_dword v[4:5], v9, off
	v_add_co_u32_e32 v4, vcc, 0xffffa000, v0
	s_nop 1
	v_addc_co_u32_e32 v5, vcc, -1, v1, vcc
	global_store_dword v[4:5], v11, off
	v_add_co_u32_e32 v4, vcc, 0xffffa800, v0
	s_nop 1
	v_addc_co_u32_e32 v5, vcc, -1, v1, vcc
	global_store_dword v[4:5], v13, off
	v_add_co_u32_e32 v4, vcc, 0xffffb000, v0
	s_nop 1
	v_addc_co_u32_e32 v5, vcc, -1, v1, vcc
	global_store_dword v[4:5], v15, off
	v_add_co_u32_e32 v4, vcc, 0xffffb800, v0
	s_nop 1
	v_addc_co_u32_e32 v5, vcc, -1, v1, vcc
	global_store_dword v[4:5], v18, off
	v_add_co_u32_e32 v4, vcc, s2, v0
	s_nop 1
	v_addc_co_u32_e32 v5, vcc, -1, v1, vcc
	global_store_dword v[4:5], v20, off
	v_add_co_u32_e32 v4, vcc, 0xffffc800, v0
	s_nop 1
	v_addc_co_u32_e32 v5, vcc, -1, v1, vcc
	global_store_dword v[4:5], v22, off
	v_add_co_u32_e32 v4, vcc, 0xffffd000, v0
	s_nop 1
	v_addc_co_u32_e32 v5, vcc, -1, v1, vcc
	global_store_dword v[4:5], v24, off
	v_add_co_u32_e32 v4, vcc, 0xffffd800, v0
	s_nop 1
	v_addc_co_u32_e32 v5, vcc, -1, v1, vcc
	global_store_dword v[4:5], v26, off
	v_add_co_u32_e32 v4, vcc, 0xffffe000, v0
	s_nop 1
	v_addc_co_u32_e32 v5, vcc, -1, v1, vcc
	global_store_dword v[4:5], v28, off
	v_add_co_u32_e32 v4, vcc, 0xffffe800, v0
	s_nop 1
	v_addc_co_u32_e32 v5, vcc, -1, v1, vcc
	global_store_dword v[4:5], v30, off
	v_add_co_u32_e32 v4, vcc, 0xfffff000, v0
	s_nop 1
	v_addc_co_u32_e32 v5, vcc, -1, v1, vcc
	global_store_dword v[4:5], v32, off
	v_add_co_u32_e32 v4, vcc, 0xfffff800, v0
	s_nop 1
	v_addc_co_u32_e32 v5, vcc, -1, v1, vcc
	v_lshl_add_u64 v[0:1], v[0:1], 0, s[12:13]
	global_store_dword v[4:5], v34, off
	s_cbranch_scc0 .LBB0_879

.LBB0_884:
	s_ashr_i32 s39, s38, 31
	s_lshl_b64 s[14:15], s[38:39], 9
	v_lshl_add_u64 v[0:1], s[14:15], 0, v[66:67]
	v_lshlrev_b64 v[0:1], 2, v[0:1]
	s_add_i32 s38, s38, s36
	s_add_i32 s22, s22, s23
	v_lshl_add_u64 v[2:3], s[8:9], 0, v[0:1]
	v_lshl_add_u64 v[0:1], s[4:5], 0, v[0:1]
	s_cmpk_gt_i32 s38, 0xff
	global_store_dword v[0:1], v116, off
	global_store_dword v[2:3], v110, off
	s_cbranch_scc1 .LBB0_953
.LBB0_885:
	v_mov_b32_e32 v66, v228
	s_lshl_b32 s2, s38, 6
	v_ashrrev_i32_e32 v69, 6, v66
	v_and_b32_e32 v68, 15, v66
	v_lshl_or_b32 v58, v69, 7, v68
	v_ashrrev_i32_e32 v59, 31, v58
	s_waitcnt vmcnt(0)
	v_lshlrev_b64 v[0:1], 7, v[58:59]
	v_or_b32_e32 v8, 16, v58
	v_or_b32_e32 v18, 32, v58
	v_or_b32_e32 v26, 48, v58
	s_waitcnt lgkmcnt(0)
	v_or_b32_e32 v34, 64, v58
	v_or_b32_e32 v42, 0x50, v58
	v_or_b32_e32 v50, 0x60, v58
	v_or_b32_e32 v58, 0x70, v58
	v_and_b32_e32 v16, 48, v66
	v_ashrrev_i32_e32 v9, 31, v8
	v_ashrrev_i32_e32 v19, 31, v18
	v_ashrrev_i32_e32 v27, 31, v26
	v_ashrrev_i32_e32 v35, 31, v34
	v_ashrrev_i32_e32 v43, 31, v42
	v_ashrrev_i32_e32 v51, 31, v50
	v_ashrrev_i32_e32 v59, 31, v58
	v_lshl_add_u64 v[60:61], s[50:51], 0, v[16:17]
	v_lshlrev_b64 v[8:9], 7, v[8:9]
	v_lshlrev_b64 v[18:19], 7, v[18:19]
	v_lshlrev_b64 v[26:27], 7, v[26:27]
	v_lshlrev_b64 v[34:35], 7, v[34:35]
	v_lshlrev_b64 v[42:43], 7, v[42:43]
	v_lshlrev_b64 v[50:51], 7, v[50:51]
	v_lshlrev_b64 v[58:59], 7, v[58:59]
	v_lshl_add_u64 v[4:5], v[60:61], 0, v[0:1]
	v_lshl_add_u64 v[12:13], v[60:61], 0, v[8:9]
	v_lshl_add_u64 v[22:23], v[60:61], 0, v[18:19]
	v_lshl_add_u64 v[30:31], v[60:61], 0, v[26:27]
	v_lshl_add_u64 v[38:39], v[60:61], 0, v[34:35]
	v_lshl_add_u64 v[46:47], v[60:61], 0, v[42:43]
	v_lshl_add_u64 v[54:55], v[60:61], 0, v[50:51]
	v_lshl_add_u64 v[62:63], v[60:61], 0, v[58:59]
	global_load_dwordx4 v[0:3], v[4:5], off
	s_nop 0
	global_load_dwordx4 v[4:7], v[4:5], off offset:64
	s_nop 0
	global_load_dwordx4 v[8:11], v[12:13], off
	s_nop 0
	global_load_dwordx4 v[12:15], v[12:13], off offset:64
	s_nop 0
	global_load_dwordx4 v[18:21], v[22:23], off
	s_nop 0
	global_load_dwordx4 v[22:25], v[22:23], off offset:64
	s_nop 0
	global_load_dwordx4 v[26:29], v[30:31], off
	s_nop 0
	global_load_dwordx4 v[30:33], v[30:31], off offset:64
	s_nop 0
	global_load_dwordx4 v[34:37], v[38:39], off
	s_nop 0
	global_load_dwordx4 v[38:41], v[38:39], off offset:64
	s_nop 0
	global_load_dwordx4 v[42:45], v[46:47], off
	s_nop 0
	global_load_dwordx4 v[46:49], v[46:47], off offset:64
	s_nop 0
	global_load_dwordx4 v[50:53], v[54:55], off
	s_nop 0
	global_load_dwordx4 v[54:57], v[54:55], off offset:64
	s_nop 0
	global_load_dwordx4 v[58:61], v[62:63], off
	s_nop 0
	global_load_dwordx4 v[62:65], v[62:63], off offset:64
	s_mov_b32 s14, 0
	s_ashr_i32 s15, s14, 31
	s_lshl_b64 s[14:15], s[14:15], 3
	s_add_u32 s14, s0, s14
	s_addc_u32 s15, s1, s15
	s_load_dwordx2 s[14:15], s[14:15], 0x58
	v_ashrrev_i32_e32 v67, 31, v66
	v_mov_b32_e32 v110, 0
	v_mov_b32_e32 v129, 0
	v_mov_b32_e32 v126, 0
	s_waitcnt lgkmcnt(0)
	s_add_u32 s14, s14, s28
	s_addc_u32 s15, s15, s29
	v_lshl_add_u64 v[70:71], v[66:67], 2, s[14:15]
	v_add_co_u32_e32 v72, vcc, s68, v70
	v_mov_b32_e32 v127, 0
	s_nop 0
	v_addc_co_u32_e32 v73, vcc, 0, v71, vcc
	global_load_dword v16, v[70:71], off
	global_load_dword v104, v[70:71], off offset:2048
	global_load_dword v105, v[72:73], off
	global_load_dword v106, v[72:73], off offset:2048
	s_mov_b32 s14, 0
	s_ashr_i32 s15, s14, 31
	s_lshl_b64 s[14:15], s[14:15], 3
	s_add_u32 s14, s0, s14
	s_addc_u32 s15, s1, s15
	s_load_dwordx2 s[14:15], s[14:15], 0x60
	v_add_u32_e32 v70, s13, v66
	v_ashrrev_i32_e32 v71, 31, v70
	v_lshlrev_b64 v[70:71], 2, v[70:71]
	s_waitcnt lgkmcnt(0)
	v_lshl_add_u64 v[72:73], s[14:15], 0, v[70:71]
	global_load_dword v107, v[72:73], off
	s_mov_b32 s14, 0
	s_ashr_i32 s15, s14, 31
	s_lshl_b64 s[14:15], s[14:15], 3
	s_add_u32 s14, s0, s14
	s_addc_u32 s15, s1, s15
	s_load_dwordx2 s[14:15], s[14:15], 0x70
	s_waitcnt lgkmcnt(0)
	v_lshl_add_u64 v[72:73], s[14:15], 0, v[70:71]
	global_load_dword v108, v[72:73], off
	s_mov_b32 s14, 0
	s_ashr_i32 s15, s14, 31
	s_lshl_b64 s[14:15], s[14:15], 3
	s_add_u32 s14, s0, s14
	s_addc_u32 s15, s1, s15
	s_load_dwordx2 s[14:15], s[14:15], 0x80
	s_waitcnt lgkmcnt(0)
	v_lshl_add_u64 v[72:73], s[14:15], 0, v[70:71]
	global_load_dword v109, v[72:73], off
	s_mov_b32 s14, 0
	s_ashr_i32 s15, s14, 31
	s_lshl_b64 s[14:15], s[14:15], 3
	s_add_u32 s14, s0, s14
	s_addc_u32 s15, s1, s15
	s_load_dwordx2 s[14:15], s[14:15], 0x88
	s_and_b32 s12, s2, 0x80000fc0
	s_cmp_lt_i32 s12, 1
	s_waitcnt lgkmcnt(0)
	v_lshl_add_u64 v[70:71], s[14:15], 0, v[70:71]
	global_load_dword v70, v[70:71], off
	s_cbranch_scc1 .LBB0_887
	s_mul_hi_i32 s12, s2, 0x4600
	s_mulk_i32 s2, 0x4600
	s_add_u32 s14, s94, s2
	s_addc_u32 s15, s95, s12
	v_lshl_add_u64 v[72:73], v[66:67], 1, s[14:15]
	v_add_co_u32_e32 v74, vcc, 0xffff7c00, v72
	s_nop 1
	v_addc_co_u32_e32 v75, vcc, -1, v73, vcc
	global_load_ushort v71, v[74:75], off
	v_add_co_u32_e32 v74, vcc, 0xffff3600, v72
	s_waitcnt vmcnt(0) lgkmcnt(0)
	v_lshlrev_b32_e32 v127, 16, v71
	v_addc_co_u32_e32 v75, vcc, -1, v73, vcc
	v_add_co_u32_e32 v72, vcc, 0xffffc200, v72
	global_load_ushort v74, v[74:75], off
	s_nop 0
	v_addc_co_u32_e32 v73, vcc, -1, v73, vcc
	global_load_ushort v71, v[72:73], off
	s_waitcnt vmcnt(0) lgkmcnt(0)
	v_lshlrev_b32_e32 v126, 16, v74
	v_lshlrev_b32_e32 v129, 16, v71

.LBB0_889:
	v_lshl_add_u64 v[70:71], v[68:69], 0, s[14:15]
	global_load_ushort v72, v[70:71], off
	v_fma_f32 v117, v16, v126, v107
	v_fmac_f32_e32 v117, v104, v127
	v_fmac_f32_e32 v117, v105, v129
	v_fma_f32 v118, v16, v127, v107
	v_fmac_f32_e32 v118, v104, v129
	v_fma_f32 v119, v16, v129, v107
	s_waitcnt vmcnt(0) lgkmcnt(0)
	v_lshlrev_b32_e32 v74, 16, v72
	v_fmac_f32_e32 v117, v106, v74
	v_cvt_pk_bf16_f32 v72, v117, v17
	ds_write_b16 v111, v72
	v_add_co_u32_e32 v72, vcc, s62, v70
	v_fmac_f32_e32 v118, v105, v74
	s_nop 0
	v_addc_co_u32_e32 v73, vcc, 0, v71, vcc
	global_load_ushort v72, v[72:73], off offset:1536
	v_fmac_f32_e32 v119, v104, v74
	v_fma_f32 v120, v16, v74, v107
	s_waitcnt vmcnt(0) lgkmcnt(0)
	v_lshlrev_b32_e32 v75, 16, v72
	v_fmac_f32_e32 v118, v106, v75
	v_cvt_pk_bf16_f32 v72, v118, v17
	ds_write_b16 v111, v72 offset:144
	v_add_co_u32_e32 v72, vcc, s47, v70
	v_fmac_f32_e32 v119, v105, v75
	s_nop 0
	v_addc_co_u32_e32 v73, vcc, 0, v71, vcc
	global_load_ushort v72, v[72:73], off offset:3072
	v_fmac_f32_e32 v120, v104, v75
	v_fma_f32 v121, v16, v75, v107
	s_waitcnt vmcnt(0) lgkmcnt(0)
	v_lshlrev_b32_e32 v76, 16, v72
	v_fmac_f32_e32 v119, v106, v76
	v_cvt_pk_bf16_f32 v72, v119, v17
	ds_write_b16 v111, v72 offset:288
	v_add_co_u32_e32 v72, vcc, s67, v70
	v_fmac_f32_e32 v120, v105, v76
	s_nop 0
	v_addc_co_u32_e32 v73, vcc, 0, v71, vcc
	global_load_ushort v72, v[72:73], off offset:512
	v_fmac_f32_e32 v121, v104, v76
	v_fma_f32 v122, v16, v76, v107
	s_waitcnt vmcnt(0) lgkmcnt(0)
	v_lshlrev_b32_e32 v77, 16, v72
	v_fmac_f32_e32 v120, v106, v77
	v_cvt_pk_bf16_f32 v72, v120, v17
	ds_write_b16 v111, v72 offset:432
	v_add_co_u32_e32 v72, vcc, s69, v70
	v_fmac_f32_e32 v121, v105, v77
	s_nop 0
	v_addc_co_u32_e32 v73, vcc, 0, v71, vcc
	global_load_ushort v72, v[72:73], off offset:2048
	v_fmac_f32_e32 v122, v104, v77
	v_fma_f32 v123, v16, v77, v107
	s_waitcnt vmcnt(0) lgkmcnt(0)
	v_lshlrev_b32_e32 v74, 16, v72
	v_fmac_f32_e32 v121, v106, v74
	v_cvt_pk_bf16_f32 v72, v121, v17
	ds_write_b16 v111, v72 offset:576
	v_add_co_u32_e32 v72, vcc, s70, v70
	v_fmac_f32_e32 v122, v105, v74
	s_nop 0
	v_addc_co_u32_e32 v73, vcc, 0, v71, vcc
	global_load_ushort v72, v[72:73], off offset:3584
	v_fmac_f32_e32 v123, v104, v74
	v_fma_f32 v124, v16, v74, v107
	s_waitcnt vmcnt(0) lgkmcnt(0)
	v_lshlrev_b32_e32 v75, 16, v72
	v_fmac_f32_e32 v122, v106, v75
	v_cvt_pk_bf16_f32 v72, v122, v17
	ds_write_b16 v111, v72 offset:720
	v_add_co_u32_e32 v72, vcc, s63, v70
	v_fmac_f32_e32 v123, v105, v75
	s_nop 0
	v_addc_co_u32_e32 v73, vcc, 0, v71, vcc
	global_load_ushort v72, v[72:73], off offset:1024
	v_fmac_f32_e32 v124, v104, v75
	v_fma_f32 v125, v16, v75, v107
	s_waitcnt vmcnt(0) lgkmcnt(0)
	v_lshlrev_b32_e32 v76, 16, v72
	v_fmac_f32_e32 v123, v106, v76
	v_cvt_pk_bf16_f32 v72, v123, v17
	ds_write_b16 v111, v72 offset:864
	v_add_co_u32_e32 v72, vcc, s64, v70
	v_fmac_f32_e32 v124, v105, v76
	s_nop 0
	v_addc_co_u32_e32 v73, vcc, 0, v71, vcc
	global_load_ushort v72, v[72:73], off offset:2560
	v_fmac_f32_e32 v125, v104, v76
	v_fma_f32 v128, v16, v76, v107
	s_waitcnt vmcnt(0) lgkmcnt(0)
	v_lshlrev_b32_e32 v77, 16, v72
	v_fmac_f32_e32 v124, v106, v77
	v_cvt_pk_bf16_f32 v72, v124, v17
	ds_write_b16 v111, v72 offset:1008
	v_add_co_u32_e32 v72, vcc, s71, v70
	v_fmac_f32_e32 v125, v105, v77
	s_nop 0
	v_addc_co_u32_e32 v73, vcc, 0, v71, vcc
	global_load_ushort v72, v[72:73], off
	v_fmac_f32_e32 v128, v104, v77
	v_fma_f32 v130, v16, v77, v107
	s_waitcnt vmcnt(0) lgkmcnt(0)
	v_lshlrev_b32_e32 v74, 16, v72
	v_fmac_f32_e32 v125, v106, v74
	v_cvt_pk_bf16_f32 v72, v125, v17
	ds_write_b16 v111, v72 offset:1152
	v_add_co_u32_e32 v72, vcc, s72, v70
	v_fmac_f32_e32 v128, v105, v74
	s_nop 0
	v_addc_co_u32_e32 v73, vcc, 0, v71, vcc
	global_load_ushort v72, v[72:73], off offset:1536
	v_fmac_f32_e32 v130, v104, v74
	v_fma_f32 v131, v16, v74, v107
	s_waitcnt vmcnt(0) lgkmcnt(0)
	v_lshlrev_b32_e32 v75, 16, v72
	v_fmac_f32_e32 v128, v106, v75
	v_cvt_pk_bf16_f32 v72, v128, v17
	ds_write_b16 v111, v72 offset:1296
	v_add_co_u32_e32 v72, vcc, s73, v70
	v_fmac_f32_e32 v130, v105, v75
	s_nop 0
	v_addc_co_u32_e32 v73, vcc, 0, v71, vcc
	global_load_ushort v72, v[72:73], off offset:3072
	v_fmac_f32_e32 v131, v104, v75
	v_fma_f32 v132, v16, v75, v107
	s_waitcnt vmcnt(0) lgkmcnt(0)
	v_lshlrev_b32_e32 v76, 16, v72
	v_fmac_f32_e32 v130, v106, v76
	v_cvt_pk_bf16_f32 v72, v130, v17
	ds_write_b16 v111, v72 offset:1440
	v_add_co_u32_e32 v72, vcc, s74, v70
	v_fmac_f32_e32 v131, v105, v76
	s_nop 0
	v_addc_co_u32_e32 v73, vcc, 0, v71, vcc
	global_load_ushort v72, v[72:73], off offset:512
	v_fmac_f32_e32 v132, v104, v76
	v_fma_f32 v133, v16, v76, v107
	s_waitcnt vmcnt(0) lgkmcnt(0)
	v_lshlrev_b32_e32 v77, 16, v72
	v_fmac_f32_e32 v131, v106, v77
	v_cvt_pk_bf16_f32 v72, v131, v17
	ds_write_b16 v111, v72 offset:1584
	v_add_co_u32_e32 v72, vcc, s75, v70
	v_fmac_f32_e32 v132, v105, v77
	s_nop 0
	v_addc_co_u32_e32 v73, vcc, 0, v71, vcc
	global_load_ushort v72, v[72:73], off offset:2048
	v_fmac_f32_e32 v133, v104, v77
	v_fma_f32 v134, v16, v77, v107
	s_waitcnt vmcnt(0) lgkmcnt(0)
	v_lshlrev_b32_e32 v74, 16, v72
	v_fmac_f32_e32 v132, v106, v74
	v_cvt_pk_bf16_f32 v72, v132, v17
	ds_write_b16 v111, v72 offset:1728
	v_add_co_u32_e32 v72, vcc, s76, v70
	v_fmac_f32_e32 v133, v105, v74
	s_nop 0
	v_addc_co_u32_e32 v73, vcc, 0, v71, vcc
	global_load_ushort v72, v[72:73], off offset:3584
	v_fmac_f32_e32 v134, v104, v74
	s_waitcnt vmcnt(0) lgkmcnt(0)
	v_lshlrev_b32_e32 v126, 16, v72
	v_fmac_f32_e32 v133, v106, v126
	v_cvt_pk_bf16_f32 v72, v133, v17
	ds_write_b16 v111, v72 offset:1872
	v_add_co_u32_e32 v72, vcc, s77, v70
	v_fmac_f32_e32 v134, v105, v126
	s_nop 0
	v_addc_co_u32_e32 v73, vcc, 0, v71, vcc
	global_load_ushort v72, v[72:73], off offset:1024
	v_add_co_u32_e32 v70, vcc, s78, v70
	s_waitcnt vmcnt(0) lgkmcnt(0)
	v_lshlrev_b32_e32 v127, 16, v72
	v_fmac_f32_e32 v134, v106, v127
	v_cvt_pk_bf16_f32 v72, v134, v17
	ds_write_b16 v111, v72 offset:2016
	v_addc_co_u32_e32 v71, vcc, 0, v71, vcc
	global_load_ushort v70, v[70:71], off offset:2560
	v_fma_f32 v71, v16, v74, v107
	v_fmac_f32_e32 v71, v104, v126
	v_fmac_f32_e32 v71, v105, v127
	s_waitcnt vmcnt(0) lgkmcnt(0)
	v_lshlrev_b32_e32 v129, 16, v70
	v_fmac_f32_e32 v71, v106, v129
	v_cvt_pk_bf16_f32 v70, v71, v17
	ds_write_b16 v111, v70 offset:2160
	s_waitcnt lgkmcnt(0)
	s_barrier
	ds_read_b128 v[72:75], v114
	ds_read_b128 v[136:139], v114 offset:64
	s_waitcnt lgkmcnt(1)
	v_mfma_f32_16x16x32_bf16 v[76:79], v[0:3], v[72:75], 0
	v_add_u32_e32 v70, 0x900, v115
	v_mfma_f32_16x16x32_bf16 v[80:83], v[8:11], v[72:75], 0
	v_mfma_f32_16x16x32_bf16 v[84:87], v[18:21], v[72:75], 0
	s_waitcnt lgkmcnt(0)
	v_mfma_f32_16x16x32_bf16 v[76:79], v[4:7], v[136:139], v[76:79]
	v_mfma_f32_16x16x32_bf16 v[88:91], v[26:29], v[72:75], 0
	v_mfma_f32_16x16x32_bf16 v[80:83], v[12:15], v[136:139], v[80:83]
	s_nop 5
	ds_write2_b32 v70, v76, v77 offset1:1
	v_add_u32_e32 v70, 0x908, v115
	ds_write2_b32 v70, v78, v79 offset1:1
	v_mfma_f32_16x16x32_bf16 v[92:95], v[34:37], v[72:75], 0
	v_add_u32_e32 v70, 0x940, v115
	ds_write2_b32 v70, v80, v81 offset1:1
	v_add_u32_e32 v70, 0x948, v115
	v_mfma_f32_16x16x32_bf16 v[84:87], v[22:25], v[136:139], v[84:87]
	ds_write2_b32 v70, v82, v83 offset1:1
	v_add_u32_e32 v70, 0x980, v115
	v_mfma_f32_16x16x32_bf16 v[96:99], v[42:45], v[72:75], 0
	v_mfma_f32_16x16x32_bf16 v[88:91], v[30:33], v[136:139], v[88:91]
	s_nop 3
	ds_write2_b32 v70, v84, v85 offset1:1
	v_add_u32_e32 v70, 0x988, v115
	ds_write2_b32 v70, v86, v87 offset1:1
	v_mfma_f32_16x16x32_bf16 v[100:103], v[50:53], v[72:75], 0
	v_add_u32_e32 v70, 0x9c0, v115
	ds_write2_b32 v70, v88, v89 offset1:1
	v_add_u32_e32 v70, 0x9c8, v115
	v_mfma_f32_16x16x32_bf16 v[92:95], v[38:41], v[136:139], v[92:95]
	ds_write2_b32 v70, v90, v91 offset1:1
	v_add_u32_e32 v70, 0xa00, v115
	v_mfma_f32_16x16x32_bf16 v[72:75], v[58:61], v[72:75], 0
	v_mfma_f32_16x16x32_bf16 v[96:99], v[46:49], v[136:139], v[96:99]
	s_nop 3
	ds_write2_b32 v70, v92, v93 offset1:1
	v_add_u32_e32 v70, 0xa08, v115
	ds_write2_b32 v70, v94, v95 offset1:1
	v_mfma_f32_16x16x32_bf16 v[100:103], v[54:57], v[136:139], v[100:103]
	v_add_u32_e32 v70, 0xa40, v115
	ds_write2_b32 v70, v96, v97 offset1:1
	v_add_u32_e32 v70, 0xa48, v115
	v_mfma_f32_16x16x32_bf16 v[72:75], v[62:65], v[136:139], v[72:75]
	ds_write2_b32 v70, v98, v99 offset1:1
	v_add_u32_e32 v70, 0xa80, v115
	s_nop 1
	ds_write2_b32 v70, v100, v101 offset1:1
	v_add_u32_e32 v70, 0xa88, v115
	ds_write2_b32 v70, v102, v103 offset1:1
	v_add_u32_e32 v70, 0xac0, v115
	ds_write2_b32 v70, v72, v73 offset1:1
	v_add_u32_e32 v70, 0xac8, v115
	ds_write2_b32 v70, v74, v75 offset1:1
	s_waitcnt lgkmcnt(0)
	s_barrier
	ds_read2st64_b32 v[72:73], v113 offset0:9 offset1:10
	s_waitcnt lgkmcnt(0)
	v_add_f32_e32 v70, v108, v72
	v_mul_f32_e32 v70, 0xbfb8aa3b, v70
	v_exp_f32_e32 v70, v70
	s_nop 0
	v_add_f32_e32 v70, 1.0, v70
	v_rcp_f32_e32 v70, v70
	s_nop 0
	v_mul_f32_e32 v72, v112, v70
	v_mul_f32_e32 v70, 0x3fb8aa3b, v72
	v_exp_f32_e32 v70, v70
	v_add_f32_e32 v72, v72, v72
	v_cmp_nlt_f32_e32 vcc, s80, v72
	s_and_saveexec_b64 s[16:17], vcc
	s_xor_b64 s[16:17], exec, s[16:17]
	v_fma_f32 v135, -v70, v70, 1.0
	s_andn2_saveexec_b64 s[16:17], s[16:17]
	v_fmamk_f32 v74, v72, 0x3d2aaaab, v233
	v_fma_f32 v74, v72, v74, 0.5
	v_fma_f32 v74, v72, v74, 1.0
	v_mul_f32_e64 v135, v74, -v72
	s_or_b64 exec, exec, s[16:17]
	v_add_u32_e32 v72, 4, v113
	ds_read2st64_b32 v[74:75], v72 offset0:11 offset1:12
	s_waitcnt lgkmcnt(0)
	v_add_f32_e32 v72, v108, v74
	v_mul_f32_e32 v72, 0xbfb8aa3b, v72
	v_exp_f32_e32 v72, v72
	s_nop 0
	v_add_f32_e32 v72, 1.0, v72
	v_rcp_f32_e32 v72, v72
	s_nop 0
	v_mul_f32_e32 v72, v112, v72
	v_mul_f32_e32 v74, 0x3fb8aa3b, v72
	v_exp_f32_e32 v74, v74
	v_add_f32_e32 v72, v72, v72
	v_cmp_nlt_f32_e32 vcc, s80, v72
	s_and_saveexec_b64 s[16:17], vcc
	s_xor_b64 s[16:17], exec, s[16:17]
	v_fma_f32 v136, -v74, v74, 1.0
	s_andn2_saveexec_b64 s[16:17], s[16:17]
	v_fmamk_f32 v76, v72, 0x3d2aaaab, v233
	v_fma_f32 v76, v72, v76, 0.5
	v_fma_f32 v76, v72, v76, 1.0
	v_mul_f32_e64 v136, v76, -v72
	s_or_b64 exec, exec, s[16:17]
	v_add_u32_e32 v72, 8, v113
	ds_read2st64_b32 v[76:77], v72 offset0:13 offset1:14
	s_waitcnt lgkmcnt(0)
	v_add_f32_e32 v72, v108, v76
	v_mul_f32_e32 v72, 0xbfb8aa3b, v72
	v_exp_f32_e32 v72, v72
	s_nop 0
	v_add_f32_e32 v72, 1.0, v72
	v_rcp_f32_e32 v72, v72
	s_nop 0
	v_mul_f32_e32 v72, v112, v72
	v_mul_f32_e32 v76, 0x3fb8aa3b, v72
	v_exp_f32_e32 v76, v76
	v_add_f32_e32 v72, v72, v72
	v_cmp_nlt_f32_e32 vcc, s80, v72
	s_and_saveexec_b64 s[16:17], vcc
	s_xor_b64 s[16:17], exec, s[16:17]
	v_fma_f32 v137, -v76, v76, 1.0
	s_andn2_saveexec_b64 s[16:17], s[16:17]
	v_fmamk_f32 v78, v72, 0x3d2aaaab, v233
	v_fma_f32 v78, v72, v78, 0.5
	v_fma_f32 v78, v72, v78, 1.0
	v_mul_f32_e64 v137, v78, -v72
	s_or_b64 exec, exec, s[16:17]
	v_add_u32_e32 v72, 12, v113
	ds_read2st64_b32 v[78:79], v72 offset0:15 offset1:16
	s_waitcnt lgkmcnt(0)
	v_add_f32_e32 v72, v108, v78
	v_mul_f32_e32 v72, 0xbfb8aa3b, v72
	v_exp_f32_e32 v72, v72
	s_nop 0
	v_add_f32_e32 v72, 1.0, v72
	v_rcp_f32_e32 v72, v72
	s_nop 0
	v_mul_f32_e32 v72, v112, v72
	v_mul_f32_e32 v78, 0x3fb8aa3b, v72
	v_exp_f32_e32 v78, v78
	v_add_f32_e32 v72, v72, v72
	v_cmp_nlt_f32_e32 vcc, s80, v72
	s_and_saveexec_b64 s[16:17], vcc
	s_xor_b64 s[16:17], exec, s[16:17]
	v_fma_f32 v138, -v78, v78, 1.0
	s_andn2_saveexec_b64 s[16:17], s[16:17]
	v_fmamk_f32 v80, v72, 0x3d2aaaab, v233
	v_fma_f32 v80, v72, v80, 0.5
	v_fma_f32 v80, v72, v80, 1.0
	v_mul_f32_e64 v138, v80, -v72
	s_or_b64 exec, exec, s[16:17]
	v_add_u32_e32 v72, 16, v113
	ds_read2st64_b32 v[80:81], v72 offset0:17 offset1:18
	s_waitcnt lgkmcnt(0)
	v_add_f32_e32 v72, v108, v80
	v_mul_f32_e32 v72, 0xbfb8aa3b, v72
	v_exp_f32_e32 v72, v72
	s_nop 0
	v_add_f32_e32 v72, 1.0, v72
	v_rcp_f32_e32 v72, v72
	s_nop 0
	v_mul_f32_e32 v72, v112, v72
	v_mul_f32_e32 v80, 0x3fb8aa3b, v72
	v_exp_f32_e32 v80, v80
	v_add_f32_e32 v72, v72, v72
	v_cmp_nlt_f32_e32 vcc, s80, v72
	s_and_saveexec_b64 s[16:17], vcc
	s_xor_b64 s[16:17], exec, s[16:17]
	v_fma_f32 v139, -v80, v80, 1.0
	s_andn2_saveexec_b64 s[16:17], s[16:17]
	v_fmamk_f32 v82, v72, 0x3d2aaaab, v233
	v_fma_f32 v82, v72, v82, 0.5
	v_fma_f32 v82, v72, v82, 1.0
	v_mul_f32_e64 v139, v82, -v72
	s_or_b64 exec, exec, s[16:17]
	v_add_u32_e32 v72, 20, v113
	ds_read2st64_b32 v[82:83], v72 offset0:19 offset1:20
	s_waitcnt lgkmcnt(0)
	v_add_f32_e32 v72, v108, v82
	v_mul_f32_e32 v72, 0xbfb8aa3b, v72
	v_exp_f32_e32 v72, v72
	s_nop 0
	v_add_f32_e32 v72, 1.0, v72
	v_rcp_f32_e32 v72, v72
	s_nop 0
	v_mul_f32_e32 v72, v112, v72
	v_mul_f32_e32 v82, 0x3fb8aa3b, v72
	v_exp_f32_e32 v82, v82
	v_add_f32_e32 v72, v72, v72
	v_cmp_nlt_f32_e32 vcc, s80, v72
	s_and_saveexec_b64 s[16:17], vcc
	s_xor_b64 s[16:17], exec, s[16:17]
	v_fma_f32 v140, -v82, v82, 1.0
	s_andn2_saveexec_b64 s[16:17], s[16:17]
	v_fmamk_f32 v84, v72, 0x3d2aaaab, v233
	v_fma_f32 v84, v72, v84, 0.5
	v_fma_f32 v84, v72, v84, 1.0
	v_mul_f32_e64 v140, v84, -v72
	s_or_b64 exec, exec, s[16:17]
	v_add_u32_e32 v72, 24, v113
	ds_read2st64_b32 v[84:85], v72 offset0:21 offset1:22
	s_waitcnt lgkmcnt(0)
	v_add_f32_e32 v72, v108, v84
	v_mul_f32_e32 v72, 0xbfb8aa3b, v72
	v_exp_f32_e32 v72, v72
	s_nop 0
	v_add_f32_e32 v72, 1.0, v72
	v_rcp_f32_e32 v72, v72
	s_nop 0
	v_mul_f32_e32 v72, v112, v72
	v_mul_f32_e32 v84, 0x3fb8aa3b, v72
	v_exp_f32_e32 v84, v84
	v_add_f32_e32 v72, v72, v72
	v_cmp_nlt_f32_e32 vcc, s80, v72
	s_and_saveexec_b64 s[16:17], vcc
	s_xor_b64 s[16:17], exec, s[16:17]
	v_fma_f32 v141, -v84, v84, 1.0
	s_andn2_saveexec_b64 s[16:17], s[16:17]
	v_fmamk_f32 v86, v72, 0x3d2aaaab, v233
	v_fma_f32 v86, v72, v86, 0.5
	v_fma_f32 v86, v72, v86, 1.0
	v_mul_f32_e64 v141, v86, -v72
	s_or_b64 exec, exec, s[16:17]
	v_add_u32_e32 v72, 28, v113
	ds_read2st64_b32 v[86:87], v72 offset0:23 offset1:24
	s_waitcnt lgkmcnt(0)
	v_add_f32_e32 v72, v108, v86
	v_mul_f32_e32 v72, 0xbfb8aa3b, v72
	v_exp_f32_e32 v72, v72
	s_nop 0
	v_add_f32_e32 v72, 1.0, v72
	v_rcp_f32_e32 v72, v72
	s_nop 0
	v_mul_f32_e32 v72, v112, v72
	v_mul_f32_e32 v86, 0x3fb8aa3b, v72
	v_exp_f32_e32 v86, v86
	v_add_f32_e32 v72, v72, v72
	v_cmp_nlt_f32_e32 vcc, s80, v72
	s_and_saveexec_b64 s[16:17], vcc
	s_xor_b64 s[16:17], exec, s[16:17]
	v_fma_f32 v142, -v86, v86, 1.0
	s_andn2_saveexec_b64 s[16:17], s[16:17]
	v_fmamk_f32 v88, v72, 0x3d2aaaab, v233
	v_fma_f32 v88, v72, v88, 0.5
	v_fma_f32 v88, v72, v88, 1.0
	v_mul_f32_e64 v142, v88, -v72
	s_or_b64 exec, exec, s[16:17]
	v_add_u32_e32 v72, 32, v113
	ds_read2st64_b32 v[88:89], v72 offset0:25 offset1:26
	s_waitcnt lgkmcnt(0)
	v_add_f32_e32 v72, v108, v88
	v_mul_f32_e32 v72, 0xbfb8aa3b, v72
	v_exp_f32_e32 v72, v72
	s_nop 0
	v_add_f32_e32 v72, 1.0, v72
	v_rcp_f32_e32 v72, v72
	s_nop 0
	v_mul_f32_e32 v72, v112, v72
	v_mul_f32_e32 v88, 0x3fb8aa3b, v72
	v_exp_f32_e32 v88, v88
	v_add_f32_e32 v72, v72, v72
	v_cmp_nlt_f32_e32 vcc, s80, v72
	s_and_saveexec_b64 s[16:17], vcc
	s_xor_b64 s[16:17], exec, s[16:17]
	v_fma_f32 v143, -v88, v88, 1.0
	s_andn2_saveexec_b64 s[16:17], s[16:17]
	v_fmamk_f32 v90, v72, 0x3d2aaaab, v233
	v_fma_f32 v90, v72, v90, 0.5
	v_fma_f32 v90, v72, v90, 1.0
	v_mul_f32_e64 v143, v90, -v72
	s_or_b64 exec, exec, s[16:17]
	v_add_u32_e32 v72, 36, v113
	ds_read2st64_b32 v[90:91], v72 offset0:27 offset1:28
	s_waitcnt lgkmcnt(0)
	v_add_f32_e32 v72, v108, v90
	v_mul_f32_e32 v72, 0xbfb8aa3b, v72
	v_exp_f32_e32 v72, v72
	s_nop 0
	v_add_f32_e32 v72, 1.0, v72
	v_rcp_f32_e32 v72, v72
	s_nop 0
	v_mul_f32_e32 v72, v112, v72
	v_mul_f32_e32 v90, 0x3fb8aa3b, v72
	v_exp_f32_e32 v90, v90
	v_add_f32_e32 v72, v72, v72
	v_cmp_nlt_f32_e32 vcc, s80, v72
	s_and_saveexec_b64 s[16:17], vcc
	s_xor_b64 s[16:17], exec, s[16:17]
	v_fma_f32 v144, -v90, v90, 1.0
	s_andn2_saveexec_b64 s[16:17], s[16:17]
	v_fmamk_f32 v92, v72, 0x3d2aaaab, v233
	v_fma_f32 v92, v72, v92, 0.5
	v_fma_f32 v92, v72, v92, 1.0
	v_mul_f32_e64 v144, v92, -v72
	s_or_b64 exec, exec, s[16:17]
	v_add_u32_e32 v72, 40, v113
	ds_read2st64_b32 v[92:93], v72 offset0:29 offset1:30
	s_waitcnt lgkmcnt(0)
	v_add_f32_e32 v72, v108, v92
	v_mul_f32_e32 v72, 0xbfb8aa3b, v72
	v_exp_f32_e32 v72, v72
	s_nop 0
	v_add_f32_e32 v72, 1.0, v72
	v_rcp_f32_e32 v72, v72
	s_nop 0
	v_mul_f32_e32 v72, v112, v72
	v_mul_f32_e32 v92, 0x3fb8aa3b, v72
	v_exp_f32_e32 v92, v92
	v_add_f32_e32 v72, v72, v72
	v_cmp_nlt_f32_e32 vcc, s80, v72
	s_and_saveexec_b64 s[16:17], vcc
	s_xor_b64 s[16:17], exec, s[16:17]
	v_fma_f32 v145, -v92, v92, 1.0
	s_andn2_saveexec_b64 s[16:17], s[16:17]
	v_fmamk_f32 v94, v72, 0x3d2aaaab, v233
	v_fma_f32 v94, v72, v94, 0.5
	v_fma_f32 v94, v72, v94, 1.0
	v_mul_f32_e64 v145, v94, -v72
	s_or_b64 exec, exec, s[16:17]
	v_add_u32_e32 v72, 44, v113
	ds_read2st64_b32 v[94:95], v72 offset0:31 offset1:32
	s_waitcnt lgkmcnt(0)
	v_add_f32_e32 v72, v108, v94
	v_mul_f32_e32 v72, 0xbfb8aa3b, v72
	v_exp_f32_e32 v72, v72
	s_nop 0
	v_add_f32_e32 v72, 1.0, v72
	v_rcp_f32_e32 v72, v72
	s_nop 0
	v_mul_f32_e32 v72, v112, v72
	v_mul_f32_e32 v94, 0x3fb8aa3b, v72
	v_exp_f32_e32 v94, v94
	v_add_f32_e32 v72, v72, v72
	v_cmp_nlt_f32_e32 vcc, s80, v72
	s_and_saveexec_b64 s[16:17], vcc
	s_xor_b64 s[16:17], exec, s[16:17]
	v_fma_f32 v146, -v94, v94, 1.0
	s_andn2_saveexec_b64 s[16:17], s[16:17]
	v_fmamk_f32 v96, v72, 0x3d2aaaab, v233
	v_fma_f32 v96, v72, v96, 0.5
	v_fma_f32 v96, v72, v96, 1.0
	v_mul_f32_e64 v146, v96, -v72
	s_or_b64 exec, exec, s[16:17]
	v_add_u32_e32 v72, 48, v113
	ds_read2st64_b32 v[96:97], v72 offset0:33 offset1:34
	s_waitcnt lgkmcnt(0)
	v_add_f32_e32 v72, v108, v96
	v_mul_f32_e32 v72, 0xbfb8aa3b, v72
	v_exp_f32_e32 v72, v72
	s_nop 0
	v_add_f32_e32 v72, 1.0, v72
	v_rcp_f32_e32 v72, v72
	s_nop 0
	v_mul_f32_e32 v72, v112, v72
	v_mul_f32_e32 v96, 0x3fb8aa3b, v72
	v_exp_f32_e32 v96, v96
	v_add_f32_e32 v72, v72, v72
	v_cmp_nlt_f32_e32 vcc, s80, v72
	s_and_saveexec_b64 s[16:17], vcc
	s_xor_b64 s[16:17], exec, s[16:17]
	v_fma_f32 v147, -v96, v96, 1.0
	s_andn2_saveexec_b64 s[16:17], s[16:17]
	v_fmamk_f32 v98, v72, 0x3d2aaaab, v233
	v_fma_f32 v98, v72, v98, 0.5
	v_fma_f32 v98, v72, v98, 1.0
	v_mul_f32_e64 v147, v98, -v72
	s_or_b64 exec, exec, s[16:17]
	v_add_u32_e32 v72, 52, v113
	ds_read2st64_b32 v[98:99], v72 offset0:35 offset1:36
	s_waitcnt lgkmcnt(0)
	v_add_f32_e32 v72, v108, v98
	v_mul_f32_e32 v72, 0xbfb8aa3b, v72
	v_exp_f32_e32 v72, v72
	s_nop 0
	v_add_f32_e32 v72, 1.0, v72
	v_rcp_f32_e32 v72, v72
	s_nop 0
	v_mul_f32_e32 v72, v112, v72
	v_mul_f32_e32 v98, 0x3fb8aa3b, v72
	v_exp_f32_e32 v98, v98
	v_add_f32_e32 v72, v72, v72
	v_cmp_nlt_f32_e32 vcc, s80, v72
	s_and_saveexec_b64 s[16:17], vcc
	s_xor_b64 s[16:17], exec, s[16:17]
	v_fma_f32 v148, -v98, v98, 1.0
	s_andn2_saveexec_b64 s[16:17], s[16:17]
	v_fmamk_f32 v100, v72, 0x3d2aaaab, v233
	v_fma_f32 v100, v72, v100, 0.5
	v_fma_f32 v100, v72, v100, 1.0
	v_mul_f32_e64 v148, v100, -v72
	s_or_b64 exec, exec, s[16:17]
	v_add_u32_e32 v72, 56, v113
	ds_read2st64_b32 v[100:101], v72 offset0:37 offset1:38
	s_waitcnt lgkmcnt(0)
	v_add_f32_e32 v72, v108, v100
	v_mul_f32_e32 v72, 0xbfb8aa3b, v72
	v_exp_f32_e32 v72, v72
	s_nop 0
	v_add_f32_e32 v72, 1.0, v72
	v_rcp_f32_e32 v72, v72
	s_nop 0
	v_mul_f32_e32 v72, v112, v72
	v_mul_f32_e32 v100, 0x3fb8aa3b, v72
	v_exp_f32_e32 v100, v100
	v_add_f32_e32 v72, v72, v72
	v_cmp_nlt_f32_e32 vcc, s80, v72
	s_and_saveexec_b64 s[16:17], vcc
	s_xor_b64 s[16:17], exec, s[16:17]
	v_fma_f32 v149, -v100, v100, 1.0
	s_andn2_saveexec_b64 s[16:17], s[16:17]
	v_fmamk_f32 v102, v72, 0x3d2aaaab, v233
	v_fma_f32 v102, v72, v102, 0.5
	v_fma_f32 v102, v72, v102, 1.0
	v_mul_f32_e64 v149, v102, -v72
	s_or_b64 exec, exec, s[16:17]
	v_add_u32_e32 v72, 60, v113
	ds_read2st64_b32 v[102:103], v72 offset0:39 offset1:40
	s_waitcnt lgkmcnt(0)
	v_add_f32_e32 v72, v108, v102
	v_mul_f32_e32 v72, 0xbfb8aa3b, v72
	v_exp_f32_e32 v72, v72
	s_nop 0
	v_add_f32_e32 v72, 1.0, v72
	v_rcp_f32_e32 v72, v72
	s_nop 0
	v_mul_f32_e32 v102, v112, v72
	v_mul_f32_e32 v72, 0x3fb8aa3b, v102
	v_exp_f32_e32 v72, v72
	v_add_f32_e32 v150, v102, v102
	v_cmp_nlt_f32_e32 vcc, s80, v150
	s_and_saveexec_b64 s[16:17], vcc
	s_xor_b64 s[16:17], exec, s[16:17]
	v_fma_f32 v102, -v72, v72, 1.0
	s_andn2_saveexec_b64 s[16:17], s[16:17]
	s_cbranch_execz .LBB0_888
	v_fmamk_f32 v102, v150, 0x3d2aaaab, v233
	v_fma_f32 v102, v150, v102, 0.5
	v_fma_f32 v102, v150, v102, 1.0
	v_mul_f32_e64 v102, v102, -v150
	s_branch .LBB0_888

.LBB0_979:
	s_add_u32 s22, s20, 0xfffc0080
	s_addc_u32 s23, s21, -1
	s_add_i32 s61, 0, 0x10000
	v_add_u32_e32 v144, s61, v147
	ds_read_b128 v[140:143], v144
	ds_read_b128 v[150:153], v144 offset:1024
	ds_read_b128 v[154:157], v144 offset:2048
	ds_read_b128 v[158:161], v144 offset:3072
	s_cmp_eq_u32 s60, 12
	s_cselect_b32 s29, s9, s23
	s_cselect_b32 s28, s56, s22
	s_cselect_b32 s23, s5, s59
	s_cselect_b32 s22, s57, s58
	v_lshl_add_u64 v[144:145], s[20:21], 0, v[138:139]
	s_add_i32 m0, s12, 0xc000
	ds_read_b128 v[162:165], v149
	ds_read_b128 v[166:169], v149 offset:1024
	ds_read_b128 v[170:173], v149 offset:2048
	ds_read_b128 v[174:177], v149 offset:3072
	ds_read_b128 v[178:181], v149 offset:4096
	ds_read_b128 v[182:185], v149 offset:5120
	ds_read_b128 v[186:189], v149 offset:6144
	ds_read_b128 v[190:193], v149 offset:7168
	global_load_lds_dwordx4 v[144:145], off
	v_lshl_add_u64 v[144:145], s[20:21], 0, v[136:137]
	s_add_i32 m0, s12, 0xe000
	s_nop 0
	global_load_lds_dwordx4 v[144:145], off
	s_waitcnt lgkmcnt(8)
	s_barrier
	s_waitcnt lgkmcnt(0)
	s_setprio 1
	s_waitcnt lgkmcnt(0)
	v_mfma_f32_16x16x32_bf16 v[78:81], v[140:143], v[162:165], v[78:81]
	v_mfma_f32_16x16x32_bf16 v[74:77], v[154:157], v[162:165], v[74:77]
	v_mfma_f32_16x16x32_bf16 v[70:73], v[140:143], v[170:173], v[70:73]
	v_mfma_f32_16x16x32_bf16 v[66:69], v[154:157], v[170:173], v[66:69]
	v_mfma_f32_16x16x32_bf16 v[62:65], v[140:143], v[178:181], v[62:65]
	v_mfma_f32_16x16x32_bf16 v[54:57], v[154:157], v[178:181], v[54:57]
	v_mfma_f32_16x16x32_bf16 v[50:53], v[140:143], v[186:189], v[50:53]
	v_mfma_f32_16x16x32_bf16 v[42:45], v[154:157], v[186:189], v[42:45]
	v_mfma_f32_16x16x32_bf16 v[78:81], v[150:153], v[166:169], v[78:81]
	v_mfma_f32_16x16x32_bf16 v[74:77], v[158:161], v[166:169], v[74:77]
	v_mfma_f32_16x16x32_bf16 v[70:73], v[150:153], v[174:177], v[70:73]
	v_mfma_f32_16x16x32_bf16 v[66:69], v[158:161], v[174:177], v[66:69]
	v_mfma_f32_16x16x32_bf16 v[62:65], v[150:153], v[182:185], v[62:65]
	v_mfma_f32_16x16x32_bf16 v[54:57], v[158:161], v[182:185], v[54:57]
	v_mfma_f32_16x16x32_bf16 v[50:53], v[150:153], v[190:193], v[50:53]
	v_mfma_f32_16x16x32_bf16 v[42:45], v[158:161], v[190:193], v[42:45]
	s_setprio 0
	s_barrier
	s_add_i32 s79, 0, 0x14000
	v_add_u32_e32 v144, s79, v147
	s_add_i32 s61, s61, s48
	ds_read_b128 v[194:197], v144
	ds_read_b128 v[208:211], v144 offset:1024
	ds_read_b128 v[212:215], v144 offset:2048
	ds_read_b128 v[216:219], v144 offset:3072
	v_lshl_add_u64 v[144:145], s[22:23], 0, v[16:17]
	s_mov_b32 m0, s61
	v_lshl_add_u64 v[220:221], s[22:23], 0, v[130:131]
	global_load_lds_dwordx4 v[144:145], off
	s_add_i32 m0, s61, 0x2000
	s_nop 0
	global_load_lds_dwordx4 v[220:221], off
	s_barrier
	s_waitcnt lgkmcnt(0)
	s_setprio 1
	s_waitcnt lgkmcnt(0)
	v_mfma_f32_16x16x32_bf16 v[126:129], v[194:197], v[162:165], v[126:129]
	v_mfma_f32_16x16x32_bf16 v[122:125], v[212:215], v[162:165], v[122:125]
	v_mfma_f32_16x16x32_bf16 v[118:121], v[194:197], v[170:173], v[118:121]
	v_mfma_f32_16x16x32_bf16 v[114:117], v[212:215], v[170:173], v[114:117]
	v_mfma_f32_16x16x32_bf16 v[110:113], v[194:197], v[178:181], v[110:113]
	v_mfma_f32_16x16x32_bf16 v[106:109], v[212:215], v[178:181], v[106:109]
	v_mfma_f32_16x16x32_bf16 v[102:105], v[194:197], v[186:189], v[102:105]
	v_mfma_f32_16x16x32_bf16 v[98:101], v[212:215], v[186:189], v[98:101]
	v_mfma_f32_16x16x32_bf16 v[126:129], v[208:211], v[166:169], v[126:129]
	v_mfma_f32_16x16x32_bf16 v[122:125], v[216:219], v[166:169], v[122:125]
	v_mfma_f32_16x16x32_bf16 v[118:121], v[208:211], v[174:177], v[118:121]
	v_mfma_f32_16x16x32_bf16 v[114:117], v[216:219], v[174:177], v[114:117]
	v_mfma_f32_16x16x32_bf16 v[110:113], v[208:211], v[182:185], v[110:113]
	v_mfma_f32_16x16x32_bf16 v[106:109], v[216:219], v[182:185], v[106:109]
	v_mfma_f32_16x16x32_bf16 v[102:105], v[208:211], v[190:193], v[102:105]
	v_mfma_f32_16x16x32_bf16 v[98:101], v[216:219], v[190:193], v[98:101]
	s_setprio 0
	s_mov_b32 m0, s12
	v_lshl_add_u64 v[222:223], s[28:29], 0, v[134:135]
	s_barrier
	ds_read_b128 v[162:165], v149 offset:16384
	ds_read_b128 v[166:169], v149 offset:17408
	ds_read_b128 v[170:173], v149 offset:18432
	ds_read_b128 v[174:177], v149 offset:19456
	ds_read_b128 v[178:181], v149 offset:20480
	ds_read_b128 v[182:185], v149 offset:21504
	ds_read_b128 v[186:189], v149 offset:22528
	ds_read_b128 v[190:193], v149 offset:23552
	global_load_lds_dwordx4 v[222:223], off
	v_lshl_add_u64 v[224:225], s[28:29], 0, v[132:133]
	s_mov_b32 m0, s34
	s_nop 0
	global_load_lds_dwordx4 v[224:225], off
	s_barrier
	s_waitcnt lgkmcnt(0)
	s_setprio 1
	s_waitcnt lgkmcnt(0)
	v_mfma_f32_16x16x32_bf16 v[34:37], v[140:143], v[162:165], v[34:37]
	v_mfma_f32_16x16x32_bf16 v[30:33], v[154:157], v[162:165], v[30:33]
	v_mfma_f32_16x16x32_bf16 v[22:25], v[140:143], v[170:173], v[22:25]
	v_mfma_f32_16x16x32_bf16 v[18:21], v[154:157], v[170:173], v[18:21]
	v_mfma_f32_16x16x32_bf16 v[12:15], v[140:143], v[178:181], v[12:15]
	v_mfma_f32_16x16x32_bf16 v[8:11], v[154:157], v[178:181], v[8:11]
	v_mfma_f32_16x16x32_bf16 v[4:7], v[140:143], v[186:189], v[4:7]
	v_mfma_f32_16x16x32_bf16 v[0:3], v[154:157], v[186:189], v[0:3]
	v_mfma_f32_16x16x32_bf16 v[34:37], v[150:153], v[166:169], v[34:37]
	v_mfma_f32_16x16x32_bf16 v[30:33], v[158:161], v[166:169], v[30:33]
	v_mfma_f32_16x16x32_bf16 v[22:25], v[150:153], v[174:177], v[22:25]
	v_mfma_f32_16x16x32_bf16 v[18:21], v[158:161], v[174:177], v[18:21]
	v_mfma_f32_16x16x32_bf16 v[12:15], v[150:153], v[182:185], v[12:15]
	v_mfma_f32_16x16x32_bf16 v[8:11], v[158:161], v[182:185], v[8:11]
	v_mfma_f32_16x16x32_bf16 v[4:7], v[150:153], v[190:193], v[4:7]
	v_mfma_f32_16x16x32_bf16 v[0:3], v[158:161], v[190:193], v[0:3]
	s_setprio 0
	s_barrier
	s_add_u32 s82, s22, 0x40000
	s_addc_u32 s83, s23, 0
	s_add_i32 s61, s79, s48
	v_lshl_add_u64 v[140:141], s[82:83], 0, v[16:17]
	s_mov_b32 m0, s61
	s_nop 0
	global_load_lds_dwordx4 v[140:141], off
	v_lshl_add_u64 v[140:141], s[82:83], 0, v[130:131]
	s_add_i32 m0, s61, 0x2000
	s_nop 0
	global_load_lds_dwordx4 v[140:141], off
	s_waitcnt vmcnt(6)
	s_barrier
	s_setprio 1
	v_mfma_f32_16x16x32_bf16 v[94:97], v[194:197], v[162:165], v[94:97]
	v_mfma_f32_16x16x32_bf16 v[90:93], v[212:215], v[162:165], v[90:93]
	v_mfma_f32_16x16x32_bf16 v[86:89], v[194:197], v[170:173], v[86:89]
	v_mfma_f32_16x16x32_bf16 v[82:85], v[212:215], v[170:173], v[82:85]
	v_mfma_f32_16x16x32_bf16 v[58:61], v[194:197], v[178:181], v[58:61]
	v_mfma_f32_16x16x32_bf16 v[46:49], v[212:215], v[178:181], v[46:49]
	v_mfma_f32_16x16x32_bf16 v[38:41], v[194:197], v[186:189], v[38:41]
	v_mfma_f32_16x16x32_bf16 v[26:29], v[212:215], v[186:189], v[26:29]
	v_mfma_f32_16x16x32_bf16 v[94:97], v[208:211], v[166:169], v[94:97]
	v_mfma_f32_16x16x32_bf16 v[90:93], v[216:219], v[166:169], v[90:93]
	v_mfma_f32_16x16x32_bf16 v[86:89], v[208:211], v[174:177], v[86:89]
	v_mfma_f32_16x16x32_bf16 v[82:85], v[216:219], v[174:177], v[82:85]
	v_mfma_f32_16x16x32_bf16 v[58:61], v[208:211], v[182:185], v[58:61]
	v_mfma_f32_16x16x32_bf16 v[46:49], v[216:219], v[182:185], v[46:49]
	v_mfma_f32_16x16x32_bf16 v[38:41], v[208:211], v[190:193], v[38:41]
	v_mfma_f32_16x16x32_bf16 v[26:29], v[216:219], v[190:193], v[26:29]
	s_setprio 0
	s_add_i32 s61, 0, 0x18000
	v_add_u32_e32 v158, s61, v147
	s_barrier
	ds_read_b128 v[140:143], v158
	ds_read_b128 v[150:153], v158 offset:1024
	ds_read_b128 v[154:157], v158 offset:2048
	ds_read_b128 v[158:161], v158 offset:3072
	s_add_u32 s28, s28, 0x40000
	s_addc_u32 s29, s29, 0
	s_mov_b32 m0, s49
	v_lshl_add_u64 v[194:195], s[28:29], 0, v[134:135]
	ds_read_b128 v[162:165], v149 offset:32768
	ds_read_b128 v[166:169], v149 offset:33792
	ds_read_b128 v[170:173], v149 offset:34816
	ds_read_b128 v[174:177], v149 offset:35840
	ds_read_b128 v[178:181], v149 offset:36864
	ds_read_b128 v[182:185], v149 offset:37888
	ds_read_b128 v[186:189], v149 offset:38912
	ds_read_b128 v[190:193], v149 offset:39936
	global_load_lds_dwordx4 v[194:195], off
	v_lshl_add_u64 v[194:195], s[28:29], 0, v[132:133]
	s_mov_b32 m0, s50
	s_nop 0
	global_load_lds_dwordx4 v[194:195], off
	s_waitcnt lgkmcnt(8)
	s_barrier
	s_waitcnt lgkmcnt(0)
	s_setprio 1
	s_waitcnt lgkmcnt(0)
	v_mfma_f32_16x16x32_bf16 v[78:81], v[140:143], v[162:165], v[78:81]
	v_mfma_f32_16x16x32_bf16 v[74:77], v[154:157], v[162:165], v[74:77]
	v_mfma_f32_16x16x32_bf16 v[70:73], v[140:143], v[170:173], v[70:73]
	v_mfma_f32_16x16x32_bf16 v[66:69], v[154:157], v[170:173], v[66:69]
	v_mfma_f32_16x16x32_bf16 v[62:65], v[140:143], v[178:181], v[62:65]
	v_mfma_f32_16x16x32_bf16 v[54:57], v[154:157], v[178:181], v[54:57]
	v_mfma_f32_16x16x32_bf16 v[50:53], v[140:143], v[186:189], v[50:53]
	v_mfma_f32_16x16x32_bf16 v[42:45], v[154:157], v[186:189], v[42:45]
	v_mfma_f32_16x16x32_bf16 v[78:81], v[150:153], v[166:169], v[78:81]
	v_mfma_f32_16x16x32_bf16 v[74:77], v[158:161], v[166:169], v[74:77]
	v_mfma_f32_16x16x32_bf16 v[70:73], v[150:153], v[174:177], v[70:73]
	v_mfma_f32_16x16x32_bf16 v[66:69], v[158:161], v[174:177], v[66:69]
	v_mfma_f32_16x16x32_bf16 v[62:65], v[150:153], v[182:185], v[62:65]
	v_mfma_f32_16x16x32_bf16 v[54:57], v[158:161], v[182:185], v[54:57]
	v_mfma_f32_16x16x32_bf16 v[50:53], v[150:153], v[190:193], v[50:53]
	v_mfma_f32_16x16x32_bf16 v[42:45], v[158:161], v[190:193], v[42:45]
	s_setprio 0
	s_barrier
	s_add_i32 s28, 0, 0x1c000
	s_add_i32 s29, s61, s48
	v_add_u32_e32 v216, s28, v147
	v_lshl_add_u64 v[144:145], v[144:145], 0, s[10:11]
	s_mov_b32 m0, s29
	ds_read_b128 v[194:197], v216
	ds_read_b128 v[208:211], v216 offset:1024
	ds_read_b128 v[212:215], v216 offset:2048
	ds_read_b128 v[216:219], v216 offset:3072
	global_load_lds_dwordx4 v[144:145], off
	v_lshl_add_u64 v[144:145], v[220:221], 0, s[10:11]
	s_add_i32 m0, s29, 0x2000
	s_nop 0
	global_load_lds_dwordx4 v[144:145], off
	s_barrier
	s_waitcnt lgkmcnt(0)
	s_setprio 1
	s_waitcnt lgkmcnt(0)
	v_mfma_f32_16x16x32_bf16 v[126:129], v[194:197], v[162:165], v[126:129]
	v_mfma_f32_16x16x32_bf16 v[122:125], v[212:215], v[162:165], v[122:125]
	v_mfma_f32_16x16x32_bf16 v[118:121], v[194:197], v[170:173], v[118:121]
	v_mfma_f32_16x16x32_bf16 v[114:117], v[212:215], v[170:173], v[114:117]
	v_mfma_f32_16x16x32_bf16 v[110:113], v[194:197], v[178:181], v[110:113]
	v_mfma_f32_16x16x32_bf16 v[106:109], v[212:215], v[178:181], v[106:109]
	v_mfma_f32_16x16x32_bf16 v[102:105], v[194:197], v[186:189], v[102:105]
	v_mfma_f32_16x16x32_bf16 v[98:101], v[212:215], v[186:189], v[98:101]
	v_mfma_f32_16x16x32_bf16 v[126:129], v[208:211], v[166:169], v[126:129]
	v_mfma_f32_16x16x32_bf16 v[122:125], v[216:219], v[166:169], v[122:125]
	v_mfma_f32_16x16x32_bf16 v[118:121], v[208:211], v[174:177], v[118:121]
	v_mfma_f32_16x16x32_bf16 v[114:117], v[216:219], v[174:177], v[114:117]
	v_mfma_f32_16x16x32_bf16 v[110:113], v[208:211], v[182:185], v[110:113]
	v_mfma_f32_16x16x32_bf16 v[106:109], v[216:219], v[182:185], v[106:109]
	v_mfma_f32_16x16x32_bf16 v[102:105], v[208:211], v[190:193], v[102:105]
	v_mfma_f32_16x16x32_bf16 v[98:101], v[216:219], v[190:193], v[98:101]
	s_setprio 0
	s_mov_b32 m0, s51
	v_lshl_add_u64 v[144:145], v[222:223], 0, s[10:11]
	s_barrier
	ds_read_b128 v[162:165], v149 offset:49152
	ds_read_b128 v[166:169], v149 offset:50176
	ds_read_b128 v[170:173], v149 offset:51200
	ds_read_b128 v[174:177], v149 offset:52224
	ds_read_b128 v[178:181], v149 offset:53248
	ds_read_b128 v[182:185], v149 offset:54272
	ds_read_b128 v[186:189], v149 offset:55296
	ds_read_b128 v[190:193], v149 offset:56320
	global_load_lds_dwordx4 v[144:145], off
	v_lshl_add_u64 v[144:145], v[224:225], 0, s[10:11]
	s_mov_b32 m0, s52
	s_nop 0
	global_load_lds_dwordx4 v[144:145], off
	s_barrier
	s_waitcnt lgkmcnt(0)
	s_setprio 1
	s_waitcnt lgkmcnt(0)
	v_mfma_f32_16x16x32_bf16 v[34:37], v[140:143], v[162:165], v[34:37]
	v_mfma_f32_16x16x32_bf16 v[30:33], v[154:157], v[162:165], v[30:33]
	v_mfma_f32_16x16x32_bf16 v[22:25], v[140:143], v[170:173], v[22:25]
	v_mfma_f32_16x16x32_bf16 v[18:21], v[154:157], v[170:173], v[18:21]
	v_mfma_f32_16x16x32_bf16 v[12:15], v[140:143], v[178:181], v[12:15]
	v_mfma_f32_16x16x32_bf16 v[8:11], v[154:157], v[178:181], v[8:11]
	v_mfma_f32_16x16x32_bf16 v[4:7], v[140:143], v[186:189], v[4:7]
	v_mfma_f32_16x16x32_bf16 v[0:3], v[154:157], v[186:189], v[0:3]
	v_mfma_f32_16x16x32_bf16 v[34:37], v[150:153], v[166:169], v[34:37]
	v_mfma_f32_16x16x32_bf16 v[30:33], v[158:161], v[166:169], v[30:33]
	v_mfma_f32_16x16x32_bf16 v[22:25], v[150:153], v[174:177], v[22:25]
	v_mfma_f32_16x16x32_bf16 v[18:21], v[158:161], v[174:177], v[18:21]
	v_mfma_f32_16x16x32_bf16 v[12:15], v[150:153], v[182:185], v[12:15]
	v_mfma_f32_16x16x32_bf16 v[8:11], v[158:161], v[182:185], v[8:11]
	v_mfma_f32_16x16x32_bf16 v[4:7], v[150:153], v[190:193], v[4:7]
	v_mfma_f32_16x16x32_bf16 v[0:3], v[158:161], v[190:193], v[0:3]
	s_setprio 0
	s_barrier
	s_add_u32 s22, s22, 0x40080
	s_addc_u32 s23, s23, 0
	s_add_i32 s28, s28, s48
	v_lshl_add_u64 v[140:141], s[22:23], 0, v[16:17]
	s_mov_b32 m0, s28
	s_nop 0
	global_load_lds_dwordx4 v[140:141], off
	v_lshl_add_u64 v[140:141], s[22:23], 0, v[130:131]
	s_add_i32 m0, s28, 0x2000
	s_nop 0
	global_load_lds_dwordx4 v[140:141], off
	s_waitcnt vmcnt(6)
	s_barrier
	s_setprio 1
	v_mfma_f32_16x16x32_bf16 v[94:97], v[194:197], v[162:165], v[94:97]
	v_mfma_f32_16x16x32_bf16 v[90:93], v[212:215], v[162:165], v[90:93]
	v_mfma_f32_16x16x32_bf16 v[86:89], v[194:197], v[170:173], v[86:89]
	v_mfma_f32_16x16x32_bf16 v[82:85], v[212:215], v[170:173], v[82:85]
	v_mfma_f32_16x16x32_bf16 v[58:61], v[194:197], v[178:181], v[58:61]
	v_mfma_f32_16x16x32_bf16 v[46:49], v[212:215], v[178:181], v[46:49]
	v_mfma_f32_16x16x32_bf16 v[38:41], v[194:197], v[186:189], v[38:41]
	v_mfma_f32_16x16x32_bf16 v[26:29], v[212:215], v[186:189], v[26:29]
	v_mfma_f32_16x16x32_bf16 v[94:97], v[208:211], v[166:169], v[94:97]
	v_mfma_f32_16x16x32_bf16 v[90:93], v[216:219], v[166:169], v[90:93]
	v_mfma_f32_16x16x32_bf16 v[86:89], v[208:211], v[174:177], v[86:89]
	v_mfma_f32_16x16x32_bf16 v[82:85], v[216:219], v[174:177], v[82:85]
	v_mfma_f32_16x16x32_bf16 v[58:61], v[208:211], v[182:185], v[58:61]
	v_mfma_f32_16x16x32_bf16 v[46:49], v[216:219], v[182:185], v[46:49]
	v_mfma_f32_16x16x32_bf16 v[38:41], v[208:211], v[190:193], v[38:41]
	v_mfma_f32_16x16x32_bf16 v[26:29], v[216:219], v[190:193], v[26:29]
	s_setprio 0
	s_add_i32 s60, s60, 2
	s_add_u32 s58, s58, 0x100
	s_addc_u32 s59, s59, 0
	s_add_u32 s20, s20, 0x100
	s_addc_u32 s21, s21, 0
	s_cmp_gt_u32 s60, 13
	s_barrier
	s_cbranch_scc0 .LBB0_979
	v_lshl_or_b32 v144, s19, 8, v148
	v_lshl_add_u32 v140, s18, 8, v146
	v_ashrrev_i32_e32 v145, 31, v144
	v_mov_b64_e32 v[142:143], s[94:95]
	v_mad_i64_i32 v[150:151], s[20:21], v140, s66, v[142:143]
	v_lshlrev_b64 v[144:145], 1, v[144:145]
	v_lshl_add_u64 v[154:155], v[150:151], 0, v[144:145]
	v_cvt_pk_bf16_f32 v150, v78, v79
	v_cvt_pk_bf16_f32 v151, v80, v81
	v_cvt_pk_bf16_f32 v152, v74, v75
	v_cvt_pk_bf16_f32 v153, v76, v77
	global_store_dwordx4 v[154:155], v[150:153], off
	v_cvt_pk_bf16_f32 v126, v126, v127
	v_cvt_pk_bf16_f32 v127, v128, v129
	v_cvt_pk_bf16_f32 v128, v122, v123
	v_cvt_pk_bf16_f32 v129, v124, v125
	global_store_dwordx4 v[154:155], v[126:129], off offset:256
	v_or_b32_e32 v122, 16, v140
	v_mad_i64_i32 v[124:125], s[20:21], v122, s66, v[142:143]
	v_lshl_add_u64 v[128:129], v[124:125], 0, v[144:145]
	v_cvt_pk_bf16_f32 v124, v70, v71
	v_cvt_pk_bf16_f32 v125, v72, v73
	v_cvt_pk_bf16_f32 v126, v66, v67
	v_cvt_pk_bf16_f32 v127, v68, v69
	global_store_dwordx4 v[128:129], v[124:127], off
	v_cvt_pk_bf16_f32 v118, v118, v119
	v_cvt_pk_bf16_f32 v119, v120, v121
	v_cvt_pk_bf16_f32 v120, v114, v115
	v_cvt_pk_bf16_f32 v121, v116, v117
	global_store_dwordx4 v[128:129], v[118:121], off offset:256
	v_or_b32_e32 v114, 32, v140
	v_mad_i64_i32 v[116:117], s[20:21], v114, s66, v[142:143]
	v_lshl_add_u64 v[120:121], v[116:117], 0, v[144:145]
	v_cvt_pk_bf16_f32 v116, v62, v63
	v_cvt_pk_bf16_f32 v117, v64, v65
	v_cvt_pk_bf16_f32 v118, v54, v55
	v_cvt_pk_bf16_f32 v119, v56, v57
	global_store_dwordx4 v[120:121], v[116:119], off
	v_cvt_pk_bf16_f32 v110, v110, v111
	v_cvt_pk_bf16_f32 v111, v112, v113
	v_cvt_pk_bf16_f32 v112, v106, v107
	v_cvt_pk_bf16_f32 v113, v108, v109
	global_store_dwordx4 v[120:121], v[110:113], off offset:256
	v_or_b32_e32 v106, 48, v140
	v_mad_i64_i32 v[108:109], s[20:21], v106, s66, v[142:143]
	v_lshl_add_u64 v[112:113], v[108:109], 0, v[144:145]
	v_cvt_pk_bf16_f32 v108, v50, v51
	v_cvt_pk_bf16_f32 v109, v52, v53
	v_cvt_pk_bf16_f32 v110, v42, v43
	v_cvt_pk_bf16_f32 v111, v44, v45
	global_store_dwordx4 v[112:113], v[108:111], off
	v_cvt_pk_bf16_f32 v102, v102, v103
	v_cvt_pk_bf16_f32 v103, v104, v105
	v_cvt_pk_bf16_f32 v104, v98, v99
	v_cvt_pk_bf16_f32 v105, v100, v101
	global_store_dwordx4 v[112:113], v[102:105], off offset:256
	v_add_u32_e32 v98, 0x80, v140
	v_mad_i64_i32 v[100:101], s[20:21], v98, s66, v[142:143]
	v_lshl_add_u64 v[104:105], v[100:101], 0, v[144:145]
	v_cvt_pk_bf16_f32 v100, v34, v35
	v_cvt_pk_bf16_f32 v101, v36, v37
	v_cvt_pk_bf16_f32 v102, v30, v31
	v_cvt_pk_bf16_f32 v103, v32, v33
	global_store_dwordx4 v[104:105], v[100:103], off
	v_cvt_pk_bf16_f32 v94, v94, v95
	v_cvt_pk_bf16_f32 v95, v96, v97
	v_cvt_pk_bf16_f32 v96, v90, v91
	v_cvt_pk_bf16_f32 v97, v92, v93
	global_store_dwordx4 v[104:105], v[94:97], off offset:256
	v_add_u32_e32 v90, 0x90, v140
	v_mad_i64_i32 v[92:93], s[20:21], v90, s66, v[142:143]
	v_lshl_add_u64 v[96:97], v[92:93], 0, v[144:145]
	v_cvt_pk_bf16_f32 v92, v22, v23
	v_cvt_pk_bf16_f32 v93, v24, v25
	v_cvt_pk_bf16_f32 v94, v18, v19
	v_cvt_pk_bf16_f32 v95, v20, v21
	global_store_dwordx4 v[96:97], v[92:95], off
	v_cvt_pk_bf16_f32 v86, v86, v87
	v_cvt_pk_bf16_f32 v87, v88, v89
	v_cvt_pk_bf16_f32 v88, v82, v83
	v_cvt_pk_bf16_f32 v89, v84, v85
	global_store_dwordx4 v[96:97], v[86:89], off offset:256
	v_add_u32_e32 v82, 0xa0, v140
	v_mad_i64_i32 v[84:85], s[20:21], v82, s66, v[142:143]
	v_lshl_add_u64 v[88:89], v[84:85], 0, v[144:145]
	v_cvt_pk_bf16_f32 v84, v12, v13
	v_cvt_pk_bf16_f32 v85, v14, v15
	v_cvt_pk_bf16_f32 v86, v8, v9
	v_cvt_pk_bf16_f32 v87, v10, v11
	global_store_dwordx4 v[88:89], v[84:87], off
	v_cvt_pk_bf16_f32 v58, v58, v59
	v_cvt_pk_bf16_f32 v59, v60, v61
	v_cvt_pk_bf16_f32 v60, v46, v47
	v_cvt_pk_bf16_f32 v61, v48, v49
	global_store_dwordx4 v[88:89], v[58:61], off offset:256
	v_add_u32_e32 v46, 0xb0, v140
	v_mad_i64_i32 v[48:49], s[20:21], v46, s66, v[142:143]
	v_lshl_add_u64 v[48:49], v[48:49], 0, v[144:145]
	v_cvt_pk_bf16_f32 v58, v4, v5
	v_cvt_pk_bf16_f32 v59, v6, v7
	v_cvt_pk_bf16_f32 v60, v0, v1
	v_cvt_pk_bf16_f32 v61, v2, v3
	global_store_dwordx4 v[48:49], v[58:61], off
	v_cvt_pk_bf16_f32 v38, v38, v39
	v_cvt_pk_bf16_f32 v39, v40, v41
	v_cvt_pk_bf16_f32 v40, v26, v27
	v_cvt_pk_bf16_f32 v41, v28, v29
	global_store_dwordx4 v[48:49], v[38:41], off offset:256
	s_cmp_eq_u32 s19, 34
	s_cselect_b64 s[18:19], -1, 0
	s_and_b64 s[20:21], s[38:39], s[18:19]
	s_and_saveexec_b64 s[18:19], s[20:21]
	s_cbranch_execz .LBB0_975
	v_ashrrev_i32_e32 v141, 31, v140
	v_lshlrev_b64 v[26:27], 5, v[140:141]
	v_ashrrev_i32_e32 v123, 31, v122
	v_lshl_add_u64 v[26:27], s[42:43], 0, v[26:27]
	global_store_dwordx4 v[26:27], v[78:81], off
	global_store_dwordx4 v[26:27], v[74:77], off offset:16
	v_lshlrev_b64 v[26:27], 5, v[122:123]
	v_ashrrev_i32_e32 v115, 31, v114
	v_lshl_add_u64 v[26:27], s[42:43], 0, v[26:27]
	global_store_dwordx4 v[26:27], v[70:73], off
	global_store_dwordx4 v[26:27], v[66:69], off offset:16
	v_lshlrev_b64 v[26:27], 5, v[114:115]
	v_ashrrev_i32_e32 v107, 31, v106
	v_lshl_add_u64 v[26:27], s[42:43], 0, v[26:27]
	global_store_dwordx4 v[26:27], v[62:65], off
	global_store_dwordx4 v[26:27], v[54:57], off offset:16
	v_lshlrev_b64 v[26:27], 5, v[106:107]
	v_ashrrev_i32_e32 v99, 31, v98
	v_lshl_add_u64 v[26:27], s[42:43], 0, v[26:27]
	global_store_dwordx4 v[26:27], v[50:53], off
	global_store_dwordx4 v[26:27], v[42:45], off offset:16
	v_lshlrev_b64 v[26:27], 5, v[98:99]
	v_ashrrev_i32_e32 v91, 31, v90
	v_lshl_add_u64 v[26:27], s[42:43], 0, v[26:27]
	global_store_dwordx4 v[26:27], v[34:37], off
	global_store_dwordx4 v[26:27], v[30:33], off offset:16
	v_lshlrev_b64 v[26:27], 5, v[90:91]
	v_ashrrev_i32_e32 v83, 31, v82
	v_lshl_add_u64 v[26:27], s[42:43], 0, v[26:27]
	global_store_dwordx4 v[26:27], v[22:25], off
	global_store_dwordx4 v[26:27], v[18:21], off offset:16
	v_ashrrev_i32_e32 v47, 31, v46
	s_nop 0
	v_lshlrev_b64 v[18:19], 5, v[82:83]
	v_lshl_add_u64 v[18:19], s[42:43], 0, v[18:19]
	global_store_dwordx4 v[18:19], v[12:15], off
	global_store_dwordx4 v[18:19], v[8:11], off offset:16
	s_nop 1
	v_lshlrev_b64 v[8:9], 5, v[46:47]
	v_lshl_add_u64 v[8:9], s[42:43], 0, v[8:9]
	global_store_dwordx4 v[8:9], v[4:7], off
	global_store_dwordx4 v[8:9], v[0:3], off offset:16
	s_branch .LBB0_975

.LBB0_1036:
	ds_write2_b32 v22, v4, v5 offset1:65
	v_add_u32_e32 v4, 0x400, v22
	s_lshr_b32 s18, s42, 6
	ds_write2_b32 v4, v0, v1 offset0:4 offset1:69
	ds_write2_b32 v22, v6, v7 offset0:130 offset1:195
	ds_write2_b32 v4, v2, v3 offset0:134 offset1:199
	v_cvt_f32_u32_e32 v0, s18
	s_sub_i32 s21, 0, s18
	s_abs_i32 s20, s41
	s_ashr_i32 s19, s41, 31
	v_rcp_iflag_f32_e32 v0, v0
	s_waitcnt lgkmcnt(0)
	s_barrier
	v_mul_f32_e32 v0, 0x4f7ffffe, v0
	v_cvt_u32_f32_e32 v0, v0
	ds_read2_b32 v[2:3], v23 offset0:2 offset1:3
	ds_read2_b32 v[4:5], v23 offset0:6 offset1:7
	v_readfirstlane_b32 s22, v0
	s_mul_i32 s21, s21, s22
	s_mul_hi_u32 s21, s22, s21
	s_add_i32 s22, s22, s21
	s_mul_hi_u32 s21, s20, s22
	s_mul_i32 s22, s21, s18
	s_sub_i32 s20, s20, s22
	s_add_i32 s22, s21, 1
	s_sub_i32 s23, s20, s18
	s_cmp_ge_u32 s20, s18
	s_cselect_b32 s21, s22, s21
	s_cselect_b32 s20, s23, s20
	s_add_i32 s22, s21, 1
	s_cmp_ge_u32 s20, s18
	s_cselect_b32 s20, s22, s21
	s_xor_b32 s20, s20, s19
	ds_read2_b32 v[0:1], v23 offset1:1
	s_sub_i32 s19, s20, s19
	s_waitcnt lgkmcnt(0)
	v_cvt_pk_bf16_f32 v0, v0, v1
	v_cvt_pk_bf16_f32 v1, v2, v3
	ds_read2_b32 v[2:3], v23 offset0:4 offset1:5
	s_waitcnt lgkmcnt(0)
	v_cvt_pk_bf16_f32 v2, v2, v3
	v_cvt_pk_bf16_f32 v3, v4, v5
	v_lshl_add_u32 v4, s19, 6, v19
	v_ashrrev_i32_e32 v7, 31, v4
	v_mad_u64_u32 v[4:5], s[20:21], v4, s42, 0
	s_mul_i32 s18, s19, s18
	v_mov_b32_e32 v6, v5
	s_sub_i32 s18, s41, s18
	v_mad_u64_u32 v[6:7], s[20:21], v7, s42, v[6:7]
	s_lshl_b32 s18, s18, 6
	v_mov_b32_e32 v5, v6
	v_lshl_add_u64 v[4:5], v[4:5], 1, s[4:5]
	s_ashr_i32 s19, s18, 31
	v_lshl_add_u64 v[4:5], s[18:19], 1, v[4:5]
	s_add_i32 s43, s43, s2
	v_lshl_add_u64 v[4:5], v[4:5], 0, v[16:17]
	s_add_i32 s4, s43, 0xffffff40
	global_store_dwordx4 v[4:5], v[0:3], off
	s_cmp_ge_i32 s4, s37
	s_mov_b32 s41, s44
	s_mov_b32 s42, s45
	s_mov_b64 s[4:5], s[16:17]
	s_waitcnt vmcnt(0)
	v_mov_b32_e32 v0, v12
	v_mov_b32_e32 v1, v13
	v_mov_b32_e32 v2, v14
	v_mov_b32_e32 v3, v15
	v_mov_b32_e32 v4, v8
	v_mov_b32_e32 v5, v9
	v_mov_b32_e32 v6, v10
	v_mov_b32_e32 v7, v11
	s_waitcnt lgkmcnt(0)
	s_barrier
	s_cbranch_scc1 .LBB0_1075

.LBB0_1109:
	s_lshr_b32 s22, s48, 6
	v_cvt_f32_u32_e32 v20, s22
	ds_write2_b32 v22, v4, v5 offset1:65
	s_sub_i32 s29, 0, s22
	s_abs_i32 s28, s45
	v_rcp_iflag_f32_e32 v5, v20
	s_ashr_i32 s23, s45, 31
	v_add_u32_e32 v4, 0x400, v22
	ds_write2_b32 v22, v6, v7 offset0:130 offset1:195
	v_mul_f32_e32 v5, 0x4f7ffffe, v5
	v_cvt_u32_f32_e32 v5, v5
	ds_write2_b32 v4, v0, v1 offset0:4 offset1:69
	ds_write2_b32 v4, v2, v3 offset0:134 offset1:199
	s_waitcnt lgkmcnt(0)
	s_barrier
	v_readfirstlane_b32 s38, v5
	s_mul_i32 s29, s29, s38
	s_mul_hi_u32 s29, s38, s29
	s_add_i32 s38, s38, s29
	s_mul_hi_u32 s29, s28, s38
	s_mul_i32 s38, s29, s22
	s_sub_i32 s28, s28, s38
	s_add_i32 s39, s29, 1
	s_sub_i32 s38, s28, s22
	s_cmp_ge_u32 s28, s22
	s_cselect_b32 s29, s39, s29
	s_cselect_b32 s28, s38, s28
	s_add_i32 s38, s29, 1
	s_cmp_ge_u32 s28, s22
	ds_read2_b32 v[0:1], v23 offset1:1
	ds_read2_b32 v[2:3], v23 offset0:2 offset1:3
	ds_read2_b32 v[4:5], v23 offset0:4 offset1:5
	ds_read2_b32 v[6:7], v23 offset0:6 offset1:7
	s_cselect_b32 s28, s38, s29
	s_xor_b32 s28, s28, s23
	s_sub_i32 s23, s28, s23
	s_waitcnt lgkmcnt(3)
	v_cvt_pk_bf16_f32 v0, v0, v1
	s_waitcnt lgkmcnt(2)
	v_cvt_pk_bf16_f32 v1, v2, v3
	s_waitcnt lgkmcnt(1)
	v_cvt_pk_bf16_f32 v2, v4, v5
	v_lshl_add_u32 v4, s23, 6, v19
	s_waitcnt lgkmcnt(0)
	v_cvt_pk_bf16_f32 v3, v6, v7
	v_ashrrev_i32_e32 v7, 31, v4
	v_mad_u64_u32 v[4:5], s[28:29], v4, s48, 0
	s_mul_i32 s22, s23, s22
	v_mov_b32_e32 v6, v5
	s_sub_i32 s22, s45, s22
	v_mad_u64_u32 v[6:7], s[28:29], v7, s48, v[6:7]
	s_lshl_b32 s22, s22, 6
	v_mov_b32_e32 v5, v6
	v_lshl_add_u64 v[4:5], v[4:5], 1, s[8:9]
	s_ashr_i32 s23, s22, 31
	v_lshl_add_u64 v[4:5], s[22:23], 1, v[4:5]
	v_lshl_add_u64 v[4:5], v[4:5], 0, v[16:17]
	global_store_dwordx4 v[4:5], v[0:3], off
	s_andn2_b64 vcc, exec, s[18:19]
	s_mov_b32 s45, s49
	s_mov_b32 s48, s50
	s_mov_b64 s[8:9], s[20:21]
	s_waitcnt vmcnt(0)
	v_mov_b32_e32 v0, v12
	v_mov_b32_e32 v1, v13
	v_mov_b32_e32 v2, v14
	v_mov_b32_e32 v3, v15
	v_mov_b32_e32 v4, v8
	v_mov_b32_e32 v5, v9
	v_mov_b32_e32 v6, v10
	v_mov_b32_e32 v7, v11
	s_waitcnt lgkmcnt(0)
	s_barrier
	s_cbranch_vccz .LBB0_1140

.LBB0_1142:
	s_or_b64 exec, exec, s[22:23]
	global_load_dword v6, v[2:3], off
	v_lshlrev_b32_e32 v2, 7, v0
	v_bfe_u32 v1, v0, 7, 7
	v_and_b32_e32 v2, 0x3f80, v2
	v_and_b32_e32 v3, 0xffffc000, v0
	v_or3_b32 v2, v2, v3, v1
	v_ashrrev_i32_e32 v3, 31, v2
	v_lshl_add_u64 v[2:3], v[2:3], 2, s[18:19]
	v_ashrrev_i32_e32 v1, 31, v0
	global_load_dword v7, v[2:3], off
	v_lshlrev_b64 v[2:3], 1, v[0:1]
	s_mov_b32 s2, s46
	v_lshl_add_u64 v[4:5], s[12:13], 0, v[2:3]
	v_lshl_add_u64 v[2:3], s[4:5], 0, v[2:3]
	s_waitcnt vmcnt(0)
	v_cvt_pk_bf16_f32 v1, v6, v17
	global_store_short v[4:5], v1, off
	s_waitcnt vmcnt(0)
	v_cvt_pk_bf16_f32 v1, v7, v17
	global_store_short v[2:3], v1, off
	s_nop 0
	v_lshl_add_u32 v0, s2, 9, v0
	s_mov_b32 s2, 0xffff
	v_cmp_lt_i32_e32 vcc, s2, v0
	s_or_b64 s[20:21], vcc, s[20:21]
	s_andn2_b64 exec, exec, s[20:21]
	s_cbranch_execz .LBB0_1147

.LBB0_1150:
	v_ashrrev_i32_e32 v75, 31, v74
	v_lshlrev_b64 v[18:19], 12, v[74:75]
	v_lshl_add_u64 v[18:19], v[76:77], 0, v[18:19]
	global_load_dwordx4 v[92:95], v[18:19], off
	global_load_dwordx4 v[96:99], v[18:19], off offset:1024
	global_load_dwordx4 v[66:69], v[18:19], off offset:3072
	global_load_dwordx4 v[70:73], v[18:19], off offset:2048
	v_or_b32_e32 v84, 1, v74
	v_min_i32_e32 v18, 0x7fff, v84
	v_ashrrev_i32_e32 v19, 31, v18
	v_lshlrev_b64 v[18:19], 12, v[18:19]
	v_lshl_add_u64 v[18:19], v[76:77], 0, v[18:19]
	global_load_dwordx4 v[62:65], v[18:19], off
	global_load_dwordx4 v[58:61], v[18:19], off offset:1024
	global_load_dwordx4 v[54:57], v[18:19], off offset:2048
	global_load_dwordx4 v[50:53], v[18:19], off offset:3072
	v_or_b32_e32 v82, 2, v74
	v_or_b32_e32 v80, 3, v74
	v_min_i32_e32 v18, 0x7fff, v82
	v_min_i32_e32 v20, 0x7fff, v80
	v_ashrrev_i32_e32 v19, 31, v18
	v_ashrrev_i32_e32 v21, 31, v20
	v_lshlrev_b64 v[18:19], 12, v[18:19]
	v_lshlrev_b64 v[20:21], 12, v[20:21]
	v_lshl_add_u64 v[18:19], v[76:77], 0, v[18:19]
	v_lshl_add_u64 v[20:21], v[76:77], 0, v[20:21]
	global_load_dwordx4 v[46:49], v[18:19], off
	global_load_dwordx4 v[42:45], v[18:19], off offset:1024
	global_load_dwordx4 v[38:41], v[18:19], off offset:2048
	s_waitcnt lgkmcnt(0)
	global_load_dwordx4 v[34:37], v[18:19], off offset:3072
	global_load_dwordx4 v[30:33], v[20:21], off
	global_load_dwordx4 v[26:29], v[20:21], off offset:1024
	global_load_dwordx4 v[22:25], v[20:21], off offset:2048
	s_nop 0
	global_load_dwordx4 v[18:21], v[20:21], off offset:3072
	s_waitcnt vmcnt(0) lgkmcnt(0)
	v_pk_mul_f32 v[100:101], v[94:95], v[94:95]
	v_pk_mul_f32 v[102:103], v[92:93], v[92:93]
	v_pk_mul_f32 v[104:105], v[98:99], v[98:99]
	v_pk_mul_f32 v[106:107], v[96:97], v[96:97]
	v_pk_mov_b32 v[110:111], v[102:103], v[100:101] op_sel:[1,0]
	v_mov_b32_e32 v103, v101
	v_pk_mov_b32 v[100:101], v[106:107], v[104:105] op_sel:[1,0]
	v_mov_b32_e32 v107, v105
	v_mul_f32_e32 v16, v71, v71
	v_mul_f32_e32 v108, v73, v73
	v_pk_add_f32 v[102:103], v[110:111], v[102:103]
	v_pk_add_f32 v[100:101], v[100:101], v[106:107]
	v_mul_f32_e32 v81, v66, v66
	v_mul_f32_e32 v83, v67, v67
	v_mul_f32_e32 v85, v68, v68
	v_mul_f32_e32 v112, v69, v69
	v_pk_fma_f32 v[104:105], v[70:71], v[70:71], v[16:17] op_sel_hi:[1,1,0]
	v_pk_fma_f32 v[108:109], v[72:73], v[72:73], v[108:109] op_sel_hi:[1,1,0]
	v_pk_add_f32 v[102:103], v[102:103], v[102:103] op_sel:[0,1] op_sel_hi:[1,0]
	v_pk_add_f32 v[100:101], v[100:101], v[100:101] op_sel:[0,1] op_sel_hi:[1,0]
	v_mov_b32_e32 v105, v85
	v_mov_b32_e32 v109, v112
	v_mov_b32_e32 v103, v81
	v_mov_b32_e32 v101, v83
	v_pk_add_f32 v[104:105], v[104:105], v[108:109]
	v_pk_add_f32 v[100:101], v[102:103], v[100:101]
	v_mul_f32_e32 v16, v63, v63
	v_pk_add_f32 v[100:101], v[100:101], v[104:105]
	v_mul_f32_e32 v85, v65, v65
	v_add_f32_e32 v81, v100, v101
	ds_bpermute_b32 v83, v86, v81
	v_mul_f32_e32 v106, v59, v59
	v_mul_f32_e32 v107, v61, v61
	v_mul_f32_e32 v100, v55, v55
	v_mul_f32_e32 v101, v57, v57
	s_waitcnt lgkmcnt(0)
	v_add_f32_e32 v81, v81, v83
	ds_bpermute_b32 v83, v87, v81
	v_fmac_f32_e32 v16, v62, v62
	v_fmac_f32_e32 v85, v64, v64
	v_fmac_f32_e32 v106, v58, v58
	v_fmac_f32_e32 v107, v60, v60
	s_waitcnt lgkmcnt(0)
	v_add_f32_e32 v81, v81, v83
	ds_bpermute_b32 v83, v88, v81
	v_mul_f32_e32 v102, v51, v51
	v_mul_f32_e32 v103, v53, v53
	v_fmac_f32_e32 v100, v54, v54
	v_fmac_f32_e32 v101, v56, v56
	s_waitcnt lgkmcnt(0)
	v_add_f32_e32 v81, v81, v83
	ds_bpermute_b32 v83, v89, v81
	v_add_f32_e32 v16, v16, v85
	v_add_f32_e32 v85, v106, v107
	v_fmac_f32_e32 v102, v50, v50
	v_fmac_f32_e32 v103, v52, v52
	s_waitcnt lgkmcnt(0)
	v_add_f32_e32 v81, v81, v83
	ds_bpermute_b32 v83, v90, v81
	v_add_f32_e32 v100, v100, v101
	v_add_f32_e32 v16, v16, v85
	v_add_f32_e32 v101, v102, v103
	v_add_f32_e32 v16, v16, v100
	s_waitcnt lgkmcnt(0)
	v_add_f32_e32 v81, v81, v83
	v_add_f32_e32 v16, v16, v101
	ds_bpermute_b32 v83, v91, v81
	ds_bpermute_b32 v85, v86, v16
	v_lshlrev_b64 v[100:101], 11, v[74:75]
	v_lshl_add_u64 v[100:101], v[78:79], 0, v[100:101]
	s_waitcnt lgkmcnt(1)
	v_add_f32_e32 v81, v81, v83
	s_waitcnt lgkmcnt(0)
	v_add_f32_e32 v16, v16, v85
	v_fmamk_f32 v81, v81, 0x3a800000, v231
	ds_bpermute_b32 v75, v87, v16
	v_mul_f32_e32 v83, 0x4b800000, v81
	v_cmp_gt_f32_e32 vcc, s33, v81
	s_waitcnt lgkmcnt(0)
	v_add_f32_e32 v16, v16, v75
	v_cndmask_b32_e32 v81, v81, v83, vcc
	v_rsq_f32_e32 v81, v81
	ds_bpermute_b32 v75, v88, v16
	v_mul_f32_e32 v83, 0x45800000, v81
	v_cndmask_b32_e32 v81, v81, v83, vcc
	v_mul_f32_e32 v83, v92, v81
	v_mul_f32_e32 v85, v93, v81
	v_mul_f32_e32 v92, v94, v81
	v_mul_f32_e32 v93, v95, v81
	v_mul_f32_e32 v70, v70, v81
	v_mul_f32_e32 v71, v71, v81
	v_mul_f32_e32 v94, v96, v81
	v_mul_f32_e32 v95, v97, v81
	v_mul_f32_e32 v96, v98, v81
	v_mul_f32_e32 v97, v99, v81
	v_mul_f32_e32 v83, v0, v83
	v_mul_f32_e32 v85, v1, v85
	v_mul_f32_e32 v92, v2, v92
	v_mul_f32_e32 v93, v3, v93
	v_mul_f32_e32 v98, v8, v70
	v_mul_f32_e32 v99, v9, v71
	v_cvt_pk_bf16_f32 v70, v83, v85
	v_cvt_pk_bf16_f32 v71, v92, v93
	v_mul_f32_e32 v94, v4, v94
	v_mul_f32_e32 v95, v5, v95
	v_mul_f32_e32 v96, v6, v96
	v_mul_f32_e32 v97, v7, v97
	v_cvt_pk_bf16_f32 v92, v94, v95
	v_cvt_pk_bf16_f32 v93, v96, v97
	global_store_dwordx2 v[100:101], v[70:71], off
	global_store_dwordx2 v[100:101], v[92:93], off offset:512
	v_mul_f32_e32 v70, v73, v81
	v_mul_f32_e32 v72, v72, v81
	v_mul_f32_e32 v70, v11, v70
	s_waitcnt lgkmcnt(0)
	v_add_f32_e32 v16, v16, v75
	v_mul_f32_e32 v102, v10, v72
	v_cvt_pk_bf16_f32 v73, v102, v70
	ds_bpermute_b32 v70, v89, v16
	v_mul_f32_e32 v66, v66, v81
	v_mul_f32_e32 v66, v12, v66
	v_mul_f32_e32 v67, v67, v81
	v_mul_f32_e32 v67, v13, v67
	s_waitcnt lgkmcnt(0)
	v_add_f32_e32 v16, v16, v70
	ds_bpermute_b32 v71, v90, v16
	v_cvt_pk_bf16_f32 v70, v66, v67
	v_mul_f32_e32 v66, v68, v81
	v_mul_f32_e32 v67, v14, v66
	v_mul_f32_e32 v68, v69, v81
	s_waitcnt lgkmcnt(0)
	v_add_f32_e32 v16, v16, v71
	ds_bpermute_b32 v66, v91, v16
	v_cmp_gt_i32_e32 vcc, s47, v84
	v_cvt_pk_bf16_f32 v72, v98, v99
	global_store_dwordx2 v[100:101], v[72:73], off offset:1024
	v_mul_f32_e32 v68, v15, v68
	v_cvt_pk_bf16_f32 v71, v67, v68
	global_store_dwordx2 v[100:101], v[70:71], off offset:1536
	s_and_saveexec_b64 s[12:13], vcc
	s_cbranch_execz .LBB0_1152
	s_waitcnt lgkmcnt(0)
	v_add_f32_e32 v16, v16, v66
	v_fmamk_f32 v16, v16, 0x3a800000, v231
	v_mul_f32_e32 v66, 0x4b800000, v16
	v_cmp_gt_f32_e32 vcc, s33, v16
	v_ashrrev_i32_e32 v85, 31, v84
	s_nop 0
	v_cndmask_b32_e32 v16, v16, v66, vcc
	v_rsq_f32_e32 v16, v16
	v_lshlrev_b64 v[66:67], 11, v[84:85]
	v_lshl_add_u64 v[66:67], v[78:79], 0, v[66:67]
	v_mul_f32_e32 v68, 0x45800000, v16
	v_cndmask_b32_e32 v16, v16, v68, vcc
	v_mul_f32_e32 v62, v62, v16
	v_mul_f32_e32 v63, v63, v16
	v_mul_f32_e32 v58, v58, v16
	v_mul_f32_e32 v59, v59, v16
	v_mul_f32_e32 v54, v54, v16
	v_mul_f32_e32 v55, v55, v16
	v_mul_f32_e32 v50, v50, v16
	v_mul_f32_e32 v51, v51, v16
	v_mul_f32_e32 v62, v0, v62
	v_mul_f32_e32 v63, v1, v63
	v_mul_f32_e32 v58, v4, v58
	v_mul_f32_e32 v59, v5, v59
	v_mul_f32_e32 v54, v8, v54
	v_mul_f32_e32 v55, v9, v55
	v_mul_f32_e32 v50, v12, v50
	v_mul_f32_e32 v51, v13, v51
	v_cvt_pk_bf16_f32 v62, v62, v63
	v_mul_f32_e32 v63, v64, v16
	v_cvt_pk_bf16_f32 v58, v58, v59
	v_mul_f32_e32 v59, v60, v16
	v_cvt_pk_bf16_f32 v54, v54, v55
	v_mul_f32_e32 v55, v56, v16
	v_cvt_pk_bf16_f32 v50, v50, v51
	v_mul_f32_e32 v51, v52, v16
	v_mul_f32_e32 v63, v2, v63
	v_mul_f32_e32 v64, v65, v16
	v_mul_f32_e32 v59, v6, v59
	v_mul_f32_e32 v60, v61, v16
	v_mul_f32_e32 v55, v10, v55
	v_mul_f32_e32 v56, v57, v16
	v_mul_f32_e32 v51, v14, v51
	v_mul_f32_e32 v16, v53, v16
	v_mul_f32_e32 v64, v3, v64
	v_cvt_pk_bf16_f32 v63, v63, v64
	global_store_dwordx2 v[66:67], v[62:63], off
	v_mul_f32_e32 v60, v7, v60
	v_cvt_pk_bf16_f32 v59, v59, v60
	global_store_dwordx2 v[66:67], v[58:59], off offset:512
	v_mul_f32_e32 v56, v11, v56
	v_cvt_pk_bf16_f32 v55, v55, v56
	global_store_dwordx2 v[66:67], v[54:55], off offset:1024
	v_mul_f32_e32 v16, v15, v16
	v_cvt_pk_bf16_f32 v51, v51, v16
	global_store_dwordx2 v[66:67], v[50:51], off offset:1536
.LBB0_1152:
	s_or_b64 exec, exec, s[12:13]
	v_mul_f32_e32 v16, v47, v47
	v_mul_f32_e32 v50, v49, v49
	v_fmac_f32_e32 v16, v46, v46
	v_fmac_f32_e32 v50, v48, v48
	v_add_f32_e32 v16, v16, v50
	v_mul_f32_e32 v50, v43, v43
	v_mul_f32_e32 v51, v45, v45
	v_fmac_f32_e32 v50, v42, v42
	v_fmac_f32_e32 v51, v44, v44
	v_add_f32_e32 v50, v50, v51
	v_add_f32_e32 v16, v16, v50
	v_mul_f32_e32 v50, v39, v39
	v_mul_f32_e32 v51, v41, v41
	v_fmac_f32_e32 v50, v38, v38
	v_fmac_f32_e32 v51, v40, v40
	v_add_f32_e32 v50, v50, v51
	v_add_f32_e32 v16, v16, v50
	v_mul_f32_e32 v50, v35, v35
	v_mul_f32_e32 v51, v37, v37
	v_fmac_f32_e32 v50, v34, v34
	v_fmac_f32_e32 v51, v36, v36
	v_add_f32_e32 v50, v50, v51
	v_add_f32_e32 v16, v16, v50
	ds_bpermute_b32 v50, v86, v16
	v_cmp_gt_i32_e32 vcc, s47, v82
	s_waitcnt lgkmcnt(0)
	v_add_f32_e32 v16, v16, v50
	ds_bpermute_b32 v50, v87, v16
	s_waitcnt lgkmcnt(0)
	v_add_f32_e32 v16, v16, v50
	ds_bpermute_b32 v50, v88, v16
	s_waitcnt lgkmcnt(0)
	v_add_f32_e32 v16, v16, v50
	ds_bpermute_b32 v50, v89, v16
	s_waitcnt lgkmcnt(0)
	v_add_f32_e32 v16, v16, v50
	ds_bpermute_b32 v50, v90, v16
	s_waitcnt lgkmcnt(0)
	v_add_f32_e32 v16, v16, v50
	ds_bpermute_b32 v50, v91, v16
	s_and_saveexec_b64 s[12:13], vcc
	s_cbranch_execz .LBB0_1154
	s_waitcnt lgkmcnt(0)
	v_add_f32_e32 v16, v16, v50
	v_fmamk_f32 v16, v16, 0x3a800000, v231
	v_mul_f32_e32 v50, 0x4b800000, v16
	v_cmp_gt_f32_e32 vcc, s33, v16
	v_ashrrev_i32_e32 v83, 31, v82
	s_nop 0
	v_cndmask_b32_e32 v16, v16, v50, vcc
	v_rsq_f32_e32 v16, v16
	v_lshlrev_b64 v[50:51], 11, v[82:83]
	v_lshl_add_u64 v[50:51], v[78:79], 0, v[50:51]
	v_mul_f32_e32 v52, 0x45800000, v16
	v_cndmask_b32_e32 v16, v16, v52, vcc
	v_mul_f32_e32 v46, v46, v16
	v_mul_f32_e32 v47, v47, v16
	v_mul_f32_e32 v42, v42, v16
	v_mul_f32_e32 v43, v43, v16
	v_mul_f32_e32 v38, v38, v16
	v_mul_f32_e32 v39, v39, v16
	v_mul_f32_e32 v34, v34, v16
	v_mul_f32_e32 v35, v35, v16
	v_mul_f32_e32 v46, v0, v46
	v_mul_f32_e32 v47, v1, v47
	v_mul_f32_e32 v42, v4, v42
	v_mul_f32_e32 v43, v5, v43
	v_mul_f32_e32 v38, v8, v38
	v_mul_f32_e32 v39, v9, v39
	v_mul_f32_e32 v34, v12, v34
	v_mul_f32_e32 v35, v13, v35
	v_cvt_pk_bf16_f32 v46, v46, v47
	v_mul_f32_e32 v47, v48, v16
	v_cvt_pk_bf16_f32 v42, v42, v43
	v_mul_f32_e32 v43, v44, v16
	v_cvt_pk_bf16_f32 v38, v38, v39
	v_mul_f32_e32 v39, v40, v16
	v_cvt_pk_bf16_f32 v34, v34, v35
	v_mul_f32_e32 v35, v36, v16
	v_mul_f32_e32 v47, v2, v47
	v_mul_f32_e32 v48, v49, v16
	v_mul_f32_e32 v43, v6, v43
	v_mul_f32_e32 v44, v45, v16
	v_mul_f32_e32 v39, v10, v39
	v_mul_f32_e32 v40, v41, v16
	v_mul_f32_e32 v35, v14, v35
	v_mul_f32_e32 v16, v37, v16
	v_mul_f32_e32 v48, v3, v48
	v_cvt_pk_bf16_f32 v47, v47, v48
	global_store_dwordx2 v[50:51], v[46:47], off
	v_mul_f32_e32 v44, v7, v44
	v_cvt_pk_bf16_f32 v43, v43, v44
	global_store_dwordx2 v[50:51], v[42:43], off offset:512
	v_mul_f32_e32 v40, v11, v40
	v_cvt_pk_bf16_f32 v39, v39, v40
	global_store_dwordx2 v[50:51], v[38:39], off offset:1024
	v_mul_f32_e32 v16, v15, v16
	v_cvt_pk_bf16_f32 v35, v35, v16
	global_store_dwordx2 v[50:51], v[34:35], off offset:1536
.LBB0_1154:
	s_or_b64 exec, exec, s[12:13]
	v_mul_f32_e32 v16, v31, v31
	v_mul_f32_e32 v34, v33, v33
	v_fmac_f32_e32 v16, v30, v30
	v_fmac_f32_e32 v34, v32, v32
	v_add_f32_e32 v16, v16, v34
	v_mul_f32_e32 v34, v27, v27
	v_mul_f32_e32 v35, v29, v29
	v_fmac_f32_e32 v34, v26, v26
	v_fmac_f32_e32 v35, v28, v28
	v_add_f32_e32 v34, v34, v35
	v_add_f32_e32 v16, v16, v34
	v_mul_f32_e32 v34, v23, v23
	v_mul_f32_e32 v35, v25, v25
	v_fmac_f32_e32 v34, v22, v22
	v_fmac_f32_e32 v35, v24, v24
	v_add_f32_e32 v34, v34, v35
	v_add_f32_e32 v16, v16, v34
	v_mul_f32_e32 v34, v19, v19
	v_mul_f32_e32 v35, v21, v21
	v_fmac_f32_e32 v34, v18, v18
	v_fmac_f32_e32 v35, v20, v20
	v_add_f32_e32 v34, v34, v35
	v_add_f32_e32 v16, v16, v34
	ds_bpermute_b32 v34, v86, v16
	v_cmp_gt_i32_e32 vcc, s47, v80
	s_waitcnt lgkmcnt(0)
	v_add_f32_e32 v16, v16, v34
	ds_bpermute_b32 v34, v87, v16
	s_waitcnt lgkmcnt(0)
	v_add_f32_e32 v16, v16, v34
	ds_bpermute_b32 v34, v88, v16
	s_waitcnt lgkmcnt(0)
	v_add_f32_e32 v16, v16, v34
	ds_bpermute_b32 v34, v89, v16
	s_waitcnt lgkmcnt(0)
	v_add_f32_e32 v16, v16, v34
	ds_bpermute_b32 v34, v90, v16
	s_waitcnt lgkmcnt(0)
	v_add_f32_e32 v16, v16, v34
	ds_bpermute_b32 v34, v91, v16
	s_and_saveexec_b64 s[12:13], vcc
	s_cbranch_execz .LBB0_1149
	s_waitcnt lgkmcnt(0)
	v_add_f32_e32 v16, v16, v34
	v_fmamk_f32 v16, v16, 0x3a800000, v231
	v_mul_f32_e32 v34, 0x4b800000, v16
	v_cmp_gt_f32_e32 vcc, s33, v16
	v_ashrrev_i32_e32 v81, 31, v80
	s_nop 0
	v_cndmask_b32_e32 v16, v16, v34, vcc
	v_rsq_f32_e32 v16, v16
	v_lshlrev_b64 v[34:35], 11, v[80:81]
	v_lshl_add_u64 v[34:35], v[78:79], 0, v[34:35]
	v_mul_f32_e32 v36, 0x45800000, v16
	v_cndmask_b32_e32 v16, v16, v36, vcc
	v_mul_f32_e32 v30, v30, v16
	v_mul_f32_e32 v31, v31, v16
	v_mul_f32_e32 v26, v26, v16
	v_mul_f32_e32 v27, v27, v16
	v_mul_f32_e32 v22, v22, v16
	v_mul_f32_e32 v23, v23, v16
	v_mul_f32_e32 v18, v18, v16
	v_mul_f32_e32 v19, v19, v16
	v_mul_f32_e32 v30, v0, v30
	v_mul_f32_e32 v31, v1, v31
	v_mul_f32_e32 v26, v4, v26
	v_mul_f32_e32 v27, v5, v27
	v_mul_f32_e32 v22, v8, v22
	v_mul_f32_e32 v23, v9, v23
	v_mul_f32_e32 v18, v12, v18
	v_mul_f32_e32 v19, v13, v19
	v_cvt_pk_bf16_f32 v30, v30, v31
	v_mul_f32_e32 v31, v32, v16
	v_cvt_pk_bf16_f32 v26, v26, v27
	v_mul_f32_e32 v27, v28, v16
	v_cvt_pk_bf16_f32 v22, v22, v23
	v_mul_f32_e32 v23, v24, v16
	v_cvt_pk_bf16_f32 v18, v18, v19
	v_mul_f32_e32 v19, v20, v16
	v_mul_f32_e32 v31, v2, v31
	v_mul_f32_e32 v32, v33, v16
	v_mul_f32_e32 v27, v6, v27
	v_mul_f32_e32 v28, v29, v16
	v_mul_f32_e32 v23, v10, v23
	v_mul_f32_e32 v24, v25, v16
	v_mul_f32_e32 v19, v14, v19
	v_mul_f32_e32 v16, v21, v16
	v_mul_f32_e32 v32, v3, v32
	v_cvt_pk_bf16_f32 v31, v31, v32
	global_store_dwordx2 v[34:35], v[30:31], off
	v_mul_f32_e32 v28, v7, v28
	v_cvt_pk_bf16_f32 v27, v27, v28
	global_store_dwordx2 v[34:35], v[26:27], off offset:512
	v_mul_f32_e32 v24, v11, v24
	v_cvt_pk_bf16_f32 v23, v23, v24
	global_store_dwordx2 v[34:35], v[22:23], off offset:1024
	v_mul_f32_e32 v16, v15, v16
	v_cvt_pk_bf16_f32 v19, v19, v16
	global_store_dwordx2 v[34:35], v[18:19], off offset:1536
	s_branch .LBB0_1149

.LBB0_1162:
	v_ashrrev_i32_e32 v67, 31, v66
	s_waitcnt lgkmcnt(0)
	v_lshlrev_b64 v[18:19], 12, v[66:67]
	v_lshl_add_u64 v[38:39], v[68:69], 0, v[18:19]
	global_load_dwordx4 v[34:37], v[38:39], off
	global_load_dwordx4 v[40:43], v[38:39], off offset:1024
	global_load_dwordx4 v[50:53], v[38:39], off offset:3072
	global_load_dwordx4 v[54:57], v[38:39], off offset:2048
	v_or_b32_e32 v70, 1, v66
	v_min_i32_e32 v18, 0x7fff, v70
	v_ashrrev_i32_e32 v19, 31, v18
	v_lshlrev_b64 v[18:19], 12, v[18:19]
	v_lshl_add_u64 v[30:31], v[68:69], 0, v[18:19]
	global_load_dwordx4 v[22:25], v[30:31], off
	global_load_dwordx4 v[18:21], v[30:31], off offset:1024
	v_or_b32_e32 v74, 2, v66
	v_or_b32_e32 v72, 3, v66
	s_waitcnt vmcnt(0) lgkmcnt(0)
	v_pk_mul_f32 v[26:27], v[36:37], v[36:37]
	v_pk_mul_f32 v[28:29], v[34:35], v[34:35]
	v_pk_mul_f32 v[32:33], v[42:43], v[42:43]
	v_pk_mul_f32 v[44:45], v[40:41], v[40:41]
	v_pk_mov_b32 v[46:47], v[28:29], v[26:27] op_sel:[1,0]
	v_mov_b32_e32 v29, v27
	v_pk_mov_b32 v[26:27], v[44:45], v[32:33] op_sel:[1,0]
	v_mov_b32_e32 v45, v33
	v_pk_add_f32 v[32:33], v[46:47], v[28:29]
	v_mul_f32_e32 v28, v55, v55
	v_pk_add_f32 v[44:45], v[26:27], v[44:45]
	v_mul_f32_e32 v26, v57, v57
	v_mul_f32_e32 v48, v52, v52
	v_mul_f32_e32 v49, v53, v53
	v_pk_fma_f32 v[28:29], v[54:55], v[54:55], v[28:29] op_sel_hi:[1,1,0]
	v_pk_fma_f32 v[26:27], v[56:57], v[56:57], v[26:27] op_sel_hi:[1,1,0]
	v_mov_b32_e32 v29, v48
	v_mov_b32_e32 v27, v49
	v_mul_f32_e32 v48, v50, v50
	v_pk_add_f32 v[32:33], v[32:33], v[32:33] op_sel:[0,1] op_sel_hi:[1,0]
	v_pk_add_f32 v[46:47], v[28:29], v[26:27]
	global_load_dwordx4 v[26:29], v[30:31], off offset:2048
	v_mov_b32_e32 v33, v48
	v_mul_f32_e32 v48, v51, v51
	v_pk_add_f32 v[44:45], v[44:45], v[44:45] op_sel:[0,1] op_sel_hi:[1,0]
	s_waitcnt vmcnt(0) lgkmcnt(0)
	v_mul_f32_e32 v49, v29, v29
	v_mov_b32_e32 v45, v48
	v_pk_add_f32 v[44:45], v[32:33], v[44:45]
	global_load_dwordx4 v[30:33], v[30:31], off offset:3072
	v_pk_add_f32 v[44:45], v[44:45], v[46:47]
	v_mul_f32_e32 v48, v23, v23
	v_add_f32_e32 v44, v44, v45
	ds_bpermute_b32 v45, v16, v44
	v_mul_f32_e32 v46, v25, v25
	v_fmac_f32_e32 v48, v22, v22
	v_fmac_f32_e32 v46, v24, v24
	v_mul_f32_e32 v47, v19, v19
	s_waitcnt lgkmcnt(0)
	v_add_f32_e32 v44, v44, v45
	ds_bpermute_b32 v45, v76, v44
	v_add_f32_e32 v46, v48, v46
	v_mul_f32_e32 v48, v21, v21
	v_fmac_f32_e32 v47, v18, v18
	v_fmac_f32_e32 v48, v20, v20
	s_waitcnt lgkmcnt(0)
	v_add_f32_e32 v44, v44, v45
	ds_bpermute_b32 v45, v77, v44
	v_add_f32_e32 v47, v47, v48
	v_mul_f32_e32 v48, v27, v27
	v_fmac_f32_e32 v48, v26, v26
	v_fmac_f32_e32 v49, v28, v28
	v_add_f32_e32 v48, v48, v49
	s_waitcnt lgkmcnt(0)
	v_add_f32_e32 v44, v44, v45
	v_add_f32_e32 v46, v46, v47
	ds_bpermute_b32 v45, v78, v44
	v_add_f32_e32 v46, v46, v48
	s_waitcnt lgkmcnt(0)
	v_add_f32_e32 v44, v44, v45
	ds_bpermute_b32 v45, v79, v44
	s_waitcnt lgkmcnt(0)
	v_add_f32_e32 v44, v44, v45
	ds_bpermute_b32 v45, v80, v44
	s_waitcnt lgkmcnt(0)
	v_add_f32_e32 v44, v44, v45
	v_fmamk_f32 v44, v44, 0x3a800000, v231
	v_mul_f32_e32 v45, 0x4b800000, v44
	v_cmp_gt_f32_e32 vcc, s33, v44
	s_waitcnt vmcnt(0)
	v_mul_f32_e32 v49, v31, v31
	v_mul_f32_e32 v58, v33, v33
	v_fmac_f32_e32 v49, v30, v30
	v_fmac_f32_e32 v58, v32, v32
	v_add_f32_e32 v49, v49, v58
	v_add_f32_e32 v46, v46, v49
	ds_bpermute_b32 v47, v16, v46
	v_cndmask_b32_e32 v44, v44, v45, vcc
	v_rsq_f32_e32 v44, v44
	s_waitcnt lgkmcnt(0)
	v_add_f32_e32 v46, v46, v47
	ds_bpermute_b32 v47, v76, v46
	v_mul_f32_e32 v45, 0x45800000, v44
	v_cndmask_b32_e32 v58, v44, v45, vcc
	v_cmp_gt_i32_e32 vcc, s47, v70
	s_waitcnt lgkmcnt(0)
	v_add_f32_e32 v46, v46, v47
	ds_bpermute_b32 v47, v77, v46
	s_waitcnt lgkmcnt(0)
	v_add_f32_e32 v46, v46, v47
	ds_bpermute_b32 v47, v78, v46
	s_waitcnt lgkmcnt(0)
	v_add_f32_e32 v59, v46, v47
	v_pk_mul_f32 v[44:45], v[50:51], v[58:59] op_sel_hi:[1,0]
	v_pk_mul_f32 v[50:51], v[52:53], v[58:59] op_sel_hi:[1,0]
	ds_bpermute_b32 v53, v79, v59
	v_pk_mul_f32 v[34:35], v[34:35], v[58:59] op_sel_hi:[1,0]
	v_pk_mul_f32 v[36:37], v[36:37], v[58:59] op_sel_hi:[1,0]
	v_pk_mul_f32 v[40:41], v[40:41], v[58:59] op_sel_hi:[1,0]
	v_pk_mul_f32 v[36:37], v[2:3], v[36:37]
	v_pk_mul_f32 v[34:35], v[0:1], v[34:35]
	v_min_i32_e32 v52, 0x7fff, v74
	v_pk_mul_f32 v[46:47], v[42:43], v[58:59] op_sel_hi:[1,0]
	v_pk_mul_f32 v[42:43], v[54:55], v[58:59] op_sel_hi:[1,0]
	global_store_dwordx4 v[38:39], v[34:37], off
	s_waitcnt lgkmcnt(0)
	v_add_f32_e32 v67, v59, v53
	v_ashrrev_i32_e32 v53, 31, v52
	v_pk_mul_f32 v[34:35], v[4:5], v[40:41]
	v_pk_mul_f32 v[40:41], v[12:13], v[44:45]
	v_min_i32_e32 v44, 0x7fff, v72
	v_pk_mul_f32 v[48:49], v[56:57], v[58:59] op_sel_hi:[1,0]
	v_pk_mul_f32 v[36:37], v[6:7], v[46:47]
	v_pk_mul_f32 v[46:47], v[8:9], v[42:43]
	v_pk_mul_f32 v[42:43], v[14:15], v[50:51]
	v_ashrrev_i32_e32 v45, 31, v44
	v_lshlrev_b64 v[50:51], 12, v[52:53]
	v_pk_mul_f32 v[48:49], v[10:11], v[48:49]
	v_lshlrev_b64 v[44:45], 12, v[44:45]
	v_lshl_add_u64 v[50:51], v[68:69], 0, v[50:51]
	global_store_dwordx4 v[38:39], v[34:37], off offset:1024
	global_store_dwordx4 v[38:39], v[46:49], off offset:2048
	v_lshl_add_u64 v[82:83], v[68:69], 0, v[44:45]
	global_load_dwordx4 v[62:65], v[50:51], off
	global_load_dwordx4 v[58:61], v[50:51], off offset:1024
	ds_bpermute_b32 v71, v80, v67
	global_store_dwordx4 v[38:39], v[40:43], off offset:3072
	global_load_dwordx4 v[54:57], v[50:51], off offset:2048
	s_nop 0
	global_load_dwordx4 v[50:53], v[50:51], off offset:3072
	s_nop 0
	global_load_dwordx4 v[46:49], v[82:83], off
	global_load_dwordx4 v[42:45], v[82:83], off offset:1024
	global_load_dwordx4 v[38:41], v[82:83], off offset:2048
	global_load_dwordx4 v[34:37], v[82:83], off offset:3072
	s_and_saveexec_b64 s[12:13], vcc
	s_cbranch_execz .LBB0_1164
	s_waitcnt lgkmcnt(0)
	v_add_f32_e32 v67, v67, v71
	v_fmamk_f32 v67, v67, 0x3a800000, v231
	v_mul_f32_e32 v71, 0x4b800000, v67
	v_cmp_gt_f32_e32 vcc, s33, v67
	s_nop 1
	v_cndmask_b32_e32 v67, v67, v71, vcc
	v_rsq_f32_e32 v67, v67
	v_ashrrev_i32_e32 v71, 31, v70
	v_lshlrev_b64 v[70:71], 12, v[70:71]
	v_lshl_add_u64 v[70:71], v[68:69], 0, v[70:71]
	v_mul_f32_e32 v73, 0x45800000, v67
	v_cndmask_b32_e32 v82, v67, v73, vcc
	v_pk_mul_f32 v[18:19], v[18:19], v[82:83] op_sel_hi:[1,0]
	v_pk_mul_f32 v[20:21], v[20:21], v[82:83] op_sel_hi:[1,0]
	v_pk_mul_f32 v[18:19], v[4:5], v[18:19]
	v_pk_mul_f32 v[20:21], v[6:7], v[20:21]
	global_store_dwordx4 v[70:71], v[18:21], off offset:1024
	v_pk_mul_f32 v[22:23], v[22:23], v[82:83] op_sel_hi:[1,0]
	v_pk_mul_f32 v[24:25], v[24:25], v[82:83] op_sel_hi:[1,0]
	v_pk_mul_f32 v[18:19], v[26:27], v[82:83] op_sel_hi:[1,0]
	v_pk_mul_f32 v[20:21], v[28:29], v[82:83] op_sel_hi:[1,0]
	v_pk_mul_f32 v[18:19], v[8:9], v[18:19]
	v_pk_mul_f32 v[20:21], v[10:11], v[20:21]
	global_store_dwordx4 v[70:71], v[18:21], off offset:2048
	v_pk_mul_f32 v[24:25], v[2:3], v[24:25]
	v_pk_mul_f32 v[22:23], v[0:1], v[22:23]
	v_pk_mul_f32 v[18:19], v[30:31], v[82:83] op_sel_hi:[1,0]
	v_pk_mul_f32 v[20:21], v[32:33], v[82:83] op_sel_hi:[1,0]
	v_pk_mul_f32 v[18:19], v[12:13], v[18:19]
	v_pk_mul_f32 v[20:21], v[14:15], v[20:21]
	global_store_dwordx4 v[70:71], v[22:25], off
	global_store_dwordx4 v[70:71], v[18:21], off offset:3072
.LBB0_1164:
	s_or_b64 exec, exec, s[12:13]
	s_waitcnt vmcnt(0) lgkmcnt(0)
	v_mul_f32_e32 v18, v63, v63
	v_mul_f32_e32 v19, v65, v65
	v_fmac_f32_e32 v18, v62, v62
	v_fmac_f32_e32 v19, v64, v64
	v_add_f32_e32 v18, v18, v19
	v_mul_f32_e32 v19, v59, v59
	v_mul_f32_e32 v20, v61, v61
	v_fmac_f32_e32 v19, v58, v58
	v_fmac_f32_e32 v20, v60, v60
	v_add_f32_e32 v19, v19, v20
	v_add_f32_e32 v18, v18, v19
	v_mul_f32_e32 v19, v55, v55
	v_mul_f32_e32 v20, v57, v57
	v_fmac_f32_e32 v19, v54, v54
	v_fmac_f32_e32 v20, v56, v56
	v_add_f32_e32 v19, v19, v20
	v_add_f32_e32 v18, v18, v19
	v_mul_f32_e32 v19, v51, v51
	v_mul_f32_e32 v20, v53, v53
	v_fmac_f32_e32 v19, v50, v50
	v_fmac_f32_e32 v20, v52, v52
	v_add_f32_e32 v19, v19, v20
	v_add_f32_e32 v18, v18, v19
	ds_bpermute_b32 v19, v16, v18
	v_cmp_gt_i32_e32 vcc, s47, v74
	s_waitcnt lgkmcnt(0)
	v_add_f32_e32 v18, v18, v19
	ds_bpermute_b32 v19, v76, v18
	s_waitcnt lgkmcnt(0)
	v_add_f32_e32 v18, v18, v19
	ds_bpermute_b32 v19, v77, v18
	s_waitcnt lgkmcnt(0)
	v_add_f32_e32 v18, v18, v19
	ds_bpermute_b32 v19, v78, v18
	s_waitcnt lgkmcnt(0)
	v_add_f32_e32 v18, v18, v19
	ds_bpermute_b32 v19, v79, v18
	s_waitcnt lgkmcnt(0)
	v_add_f32_e32 v18, v18, v19
	ds_bpermute_b32 v19, v80, v18
	s_and_saveexec_b64 s[12:13], vcc
	s_cbranch_execz .LBB0_1166
	s_waitcnt lgkmcnt(0)
	v_add_f32_e32 v18, v18, v19
	v_fmamk_f32 v18, v18, 0x3a800000, v231
	v_mul_f32_e32 v19, 0x4b800000, v18
	v_cmp_gt_f32_e32 vcc, s33, v18
	v_ashrrev_i32_e32 v75, 31, v74
	s_nop 0
	v_cndmask_b32_e32 v18, v18, v19, vcc
	v_rsq_f32_e32 v20, v18
	v_lshlrev_b64 v[18:19], 12, v[74:75]
	v_lshl_add_u64 v[22:23], v[68:69], 0, v[18:19]
	v_mul_f32_e32 v18, 0x45800000, v20
	v_cndmask_b32_e32 v24, v20, v18, vcc
	v_pk_mul_f32 v[18:19], v[62:63], v[24:25] op_sel_hi:[1,0]
	v_pk_mul_f32 v[20:21], v[64:65], v[24:25] op_sel_hi:[1,0]
	v_pk_mul_f32 v[18:19], v[0:1], v[18:19]
	v_pk_mul_f32 v[20:21], v[2:3], v[20:21]
	global_store_dwordx4 v[22:23], v[18:21], off
	s_nop 1
	v_pk_mul_f32 v[18:19], v[58:59], v[24:25] op_sel_hi:[1,0]
	v_pk_mul_f32 v[20:21], v[60:61], v[24:25] op_sel_hi:[1,0]
	v_pk_mul_f32 v[18:19], v[4:5], v[18:19]
	v_pk_mul_f32 v[20:21], v[6:7], v[20:21]
	global_store_dwordx4 v[22:23], v[18:21], off offset:1024
	s_nop 1
	v_pk_mul_f32 v[18:19], v[54:55], v[24:25] op_sel_hi:[1,0]
	v_pk_mul_f32 v[20:21], v[56:57], v[24:25] op_sel_hi:[1,0]
	v_pk_mul_f32 v[18:19], v[8:9], v[18:19]
	v_pk_mul_f32 v[20:21], v[10:11], v[20:21]
	global_store_dwordx4 v[22:23], v[18:21], off offset:2048
	s_nop 1
	v_pk_mul_f32 v[18:19], v[50:51], v[24:25] op_sel_hi:[1,0]
	v_pk_mul_f32 v[20:21], v[52:53], v[24:25] op_sel_hi:[1,0]
	v_pk_mul_f32 v[18:19], v[12:13], v[18:19]
	v_pk_mul_f32 v[20:21], v[14:15], v[20:21]
	global_store_dwordx4 v[22:23], v[18:21], off offset:3072
.LBB0_1166:
	s_or_b64 exec, exec, s[12:13]
	s_nop 0
	v_mul_f32_e32 v18, v47, v47
	s_waitcnt lgkmcnt(0)
	v_mul_f32_e32 v19, v49, v49
	v_fmac_f32_e32 v18, v46, v46
	v_fmac_f32_e32 v19, v48, v48
	v_add_f32_e32 v18, v18, v19
	v_mul_f32_e32 v19, v43, v43
	v_mul_f32_e32 v20, v45, v45
	v_fmac_f32_e32 v19, v42, v42
	v_fmac_f32_e32 v20, v44, v44
	v_add_f32_e32 v19, v19, v20
	v_add_f32_e32 v18, v18, v19
	v_mul_f32_e32 v19, v39, v39
	v_mul_f32_e32 v20, v41, v41
	v_fmac_f32_e32 v19, v38, v38
	v_fmac_f32_e32 v20, v40, v40
	v_add_f32_e32 v19, v19, v20
	v_add_f32_e32 v18, v18, v19
	v_mul_f32_e32 v19, v35, v35
	v_mul_f32_e32 v20, v37, v37
	v_fmac_f32_e32 v19, v34, v34
	v_fmac_f32_e32 v20, v36, v36
	v_add_f32_e32 v19, v19, v20
	v_add_f32_e32 v18, v18, v19
	ds_bpermute_b32 v19, v16, v18
	v_cmp_gt_i32_e32 vcc, s47, v72
	s_waitcnt lgkmcnt(0)
	v_add_f32_e32 v18, v18, v19
	ds_bpermute_b32 v19, v76, v18
	s_waitcnt lgkmcnt(0)
	v_add_f32_e32 v18, v18, v19
	ds_bpermute_b32 v19, v77, v18
	s_waitcnt lgkmcnt(0)
	v_add_f32_e32 v18, v18, v19
	ds_bpermute_b32 v19, v78, v18
	s_waitcnt lgkmcnt(0)
	v_add_f32_e32 v18, v18, v19
	ds_bpermute_b32 v19, v79, v18
	s_waitcnt lgkmcnt(0)
	v_add_f32_e32 v18, v18, v19
	ds_bpermute_b32 v19, v80, v18
	s_and_saveexec_b64 s[12:13], vcc
	s_cbranch_execz .LBB0_1161
	s_waitcnt lgkmcnt(0)
	v_add_f32_e32 v18, v18, v19
	v_fmamk_f32 v18, v18, 0x3a800000, v231
	v_mul_f32_e32 v19, 0x4b800000, v18
	v_cmp_gt_f32_e32 vcc, s33, v18
	v_ashrrev_i32_e32 v73, 31, v72
	s_nop 0
	v_cndmask_b32_e32 v18, v18, v19, vcc
	v_rsq_f32_e32 v20, v18
	v_lshlrev_b64 v[18:19], 12, v[72:73]
	v_lshl_add_u64 v[22:23], v[68:69], 0, v[18:19]
	v_mul_f32_e32 v18, 0x45800000, v20
	v_cndmask_b32_e32 v24, v20, v18, vcc
	v_pk_mul_f32 v[18:19], v[46:47], v[24:25] op_sel_hi:[1,0]
	v_pk_mul_f32 v[20:21], v[48:49], v[24:25] op_sel_hi:[1,0]
	v_pk_mul_f32 v[18:19], v[0:1], v[18:19]
	v_pk_mul_f32 v[20:21], v[2:3], v[20:21]
	global_store_dwordx4 v[22:23], v[18:21], off
	s_nop 1
	v_pk_mul_f32 v[18:19], v[42:43], v[24:25] op_sel_hi:[1,0]
	v_pk_mul_f32 v[20:21], v[44:45], v[24:25] op_sel_hi:[1,0]
	v_pk_mul_f32 v[18:19], v[4:5], v[18:19]
	v_pk_mul_f32 v[20:21], v[6:7], v[20:21]
	global_store_dwordx4 v[22:23], v[18:21], off offset:1024
	s_nop 1
	v_pk_mul_f32 v[18:19], v[38:39], v[24:25] op_sel_hi:[1,0]
	v_pk_mul_f32 v[20:21], v[40:41], v[24:25] op_sel_hi:[1,0]
	v_pk_mul_f32 v[18:19], v[8:9], v[18:19]
	v_pk_mul_f32 v[20:21], v[10:11], v[20:21]
	global_store_dwordx4 v[22:23], v[18:21], off offset:2048
	s_nop 1
	v_pk_mul_f32 v[18:19], v[34:35], v[24:25] op_sel_hi:[1,0]
	v_pk_mul_f32 v[20:21], v[36:37], v[24:25] op_sel_hi:[1,0]
	v_pk_mul_f32 v[18:19], v[12:13], v[18:19]
	v_pk_mul_f32 v[20:21], v[14:15], v[20:21]
	global_store_dwordx4 v[22:23], v[18:21], off offset:3072
	s_branch .LBB0_1161
